# v27 + K-loop: wave priority 2 after its MFMA block (loader/epilogue role above the MMA wave), mid-block prio toggle removed
# speedup vs baseline: 1.0049x; 1.0049x over previous
.Lpeel_13:
	ds_read_b128 v[152:155], v149
	ds_read_b128 v[156:159], v149 offset:1024
	s_add_i32 s37, s25, 2
	s_add_u32 s40, s38, 0xfff80080
	s_addc_u32 s41, s39, -1
	s_cmp_eq_u32 s36, s25
	s_cselect_b32 s43, s27, s41
	s_cselect_b32 s42, s26, s40
	s_cselect_b32 s41, s29, s23
	s_cselect_b32 s40, s28, s21
	v_lshl_add_u64 v[144:145], s[38:39], 0, v[140:141]
	s_add_i32 m0, s35, 0xc000
	global_load_lds_dwordx4 v[144:145], off
	v_lshl_add_u64 v[144:145], s[38:39], 0, v[142:143]
	s_add_i32 m0, s35, 0xe000
	s_nop 0
	global_load_lds_dwordx4 v[144:145], off
	s_waitcnt vmcnt(8)
	s_waitcnt lgkmcnt(0)
	s_barrier
	s_setprio 1
	s_waitcnt lgkmcnt(0)
	v_mfma_f32_16x16x32_bf16 v[126:129], v[152:155], v[184:187], 0
	v_mfma_f32_16x16x32_bf16 v[122:125], v[160:163], v[184:187], 0
	v_mfma_f32_16x16x32_bf16 v[110:113], v[152:155], v[196:199], 0
	v_mfma_f32_16x16x32_bf16 v[106:109], v[160:163], v[196:199], 0
	v_mfma_f32_16x16x32_bf16 v[94:97], v[152:155], v[204:207], 0
	v_mfma_f32_16x16x32_bf16 v[90:93], v[160:163], v[204:207], 0
	v_mfma_f32_16x16x32_bf16 v[78:81], v[152:155], v[212:215], 0
	v_mfma_f32_16x16x32_bf16 v[74:77], v[160:163], v[212:215], 0
	v_mfma_f32_16x16x32_bf16 v[126:129], v[156:159], v[188:191], v[126:129]
	v_mfma_f32_16x16x32_bf16 v[122:125], v[164:167], v[188:191], v[122:125]
	v_mfma_f32_16x16x32_bf16 v[110:113], v[156:159], v[200:203], v[110:113]
	v_mfma_f32_16x16x32_bf16 v[106:109], v[164:167], v[200:203], v[106:109]
	v_mfma_f32_16x16x32_bf16 v[94:97], v[156:159], v[208:211], v[94:97]
	v_mfma_f32_16x16x32_bf16 v[90:93], v[164:167], v[208:211], v[90:93]
	v_mfma_f32_16x16x32_bf16 v[78:81], v[156:159], v[216:219], v[78:81]
	v_mfma_f32_16x16x32_bf16 v[74:77], v[164:167], v[216:219], v[74:77]
	v_mfma_f32_16x16x32_bf16 v[118:121], v[168:171], v[184:187], 0
	v_mfma_f32_16x16x32_bf16 v[114:117], v[176:179], v[184:187], 0
	v_mfma_f32_16x16x32_bf16 v[102:105], v[168:171], v[196:199], 0
	v_mfma_f32_16x16x32_bf16 v[98:101], v[176:179], v[196:199], 0
	v_mfma_f32_16x16x32_bf16 v[86:89], v[168:171], v[204:207], 0
	v_mfma_f32_16x16x32_bf16 v[82:85], v[176:179], v[204:207], 0
	v_mfma_f32_16x16x32_bf16 v[70:73], v[168:171], v[212:215], 0
	v_mfma_f32_16x16x32_bf16 v[66:69], v[176:179], v[212:215], 0
	v_mfma_f32_16x16x32_bf16 v[118:121], v[172:175], v[188:191], v[118:121]
	v_mfma_f32_16x16x32_bf16 v[114:117], v[180:183], v[188:191], v[114:117]
	v_mfma_f32_16x16x32_bf16 v[102:105], v[172:175], v[200:203], v[102:105]
	v_mfma_f32_16x16x32_bf16 v[98:101], v[180:183], v[200:203], v[98:101]
	v_mfma_f32_16x16x32_bf16 v[86:89], v[172:175], v[208:211], v[86:89]
	v_mfma_f32_16x16x32_bf16 v[82:85], v[180:183], v[208:211], v[82:85]
	v_mfma_f32_16x16x32_bf16 v[70:73], v[172:175], v[216:219], v[70:73]
	v_mfma_f32_16x16x32_bf16 v[66:69], v[180:183], v[216:219], v[66:69]
	s_setprio 2
	s_barrier
	s_add_i32 s25, s54, s33
	v_lshl_add_u64 v[144:145], s[40:41], 0, v[132:133]
	s_mov_b32 m0, s25
	ds_read_b128 v[184:187], v151 offset:16384
	ds_read_b128 v[188:191], v151 offset:17408
	ds_read_b128 v[196:199], v151 offset:18432
	ds_read_b128 v[200:203], v151 offset:19456
	ds_read_b128 v[204:207], v151 offset:20480
	ds_read_b128 v[208:211], v151 offset:21504
	ds_read_b128 v[212:215], v151 offset:22528
	ds_read_b128 v[216:219], v151 offset:23552
	global_load_lds_dwordx4 v[144:145], off
	s_add_i32 m0, s25, 0x2000
	s_add_u32 s44, s40, 0x80000
	v_lshl_add_u64 v[192:193], s[40:41], 0, v[136:137]
	s_addc_u32 s45, s41, 0
	s_add_i32 s25, s55, s33
	global_load_lds_dwordx4 v[192:193], off
	v_lshl_add_u64 v[220:221], s[44:45], 0, v[132:133]
	s_mov_b32 m0, s25
	v_lshl_add_u64 v[222:223], s[42:43], 0, v[134:135]
	global_load_lds_dwordx4 v[220:221], off
	v_lshl_add_u64 v[220:221], s[44:45], 0, v[136:137]
	s_add_i32 m0, s25, 0x2000
	s_nop 0
	global_load_lds_dwordx4 v[220:221], off
	v_lshl_add_u64 v[220:221], s[42:43], 0, v[130:131]
	s_mov_b32 m0, s35
	s_nop 0
	global_load_lds_dwordx4 v[220:221], off
	s_mov_b32 m0, s47
	s_nop 0
	global_load_lds_dwordx4 v[222:223], off
	s_waitcnt vmcnt(8)
	s_waitcnt lgkmcnt(0)
	s_barrier
	s_setprio 1
	s_waitcnt lgkmcnt(0)
	v_mfma_f32_16x16x32_bf16 v[62:65], v[152:155], v[184:187], 0
	v_mfma_f32_16x16x32_bf16 v[58:61], v[160:163], v[184:187], 0
	v_mfma_f32_16x16x32_bf16 v[46:49], v[152:155], v[196:199], 0
	v_mfma_f32_16x16x32_bf16 v[42:45], v[160:163], v[196:199], 0
	v_mfma_f32_16x16x32_bf16 v[30:33], v[152:155], v[204:207], 0
	v_mfma_f32_16x16x32_bf16 v[26:29], v[160:163], v[204:207], 0
	v_mfma_f32_16x16x32_bf16 v[14:17], v[152:155], v[212:215], 0
	v_mfma_f32_16x16x32_bf16 v[10:13], v[160:163], v[212:215], 0
	v_mfma_f32_16x16x32_bf16 v[62:65], v[156:159], v[188:191], v[62:65]
	v_mfma_f32_16x16x32_bf16 v[58:61], v[164:167], v[188:191], v[58:61]
	v_mfma_f32_16x16x32_bf16 v[46:49], v[156:159], v[200:203], v[46:49]
	v_mfma_f32_16x16x32_bf16 v[42:45], v[164:167], v[200:203], v[42:45]
	v_mfma_f32_16x16x32_bf16 v[30:33], v[156:159], v[208:211], v[30:33]
	v_mfma_f32_16x16x32_bf16 v[26:29], v[164:167], v[208:211], v[26:29]
	v_mfma_f32_16x16x32_bf16 v[14:17], v[156:159], v[216:219], v[14:17]
	v_mfma_f32_16x16x32_bf16 v[10:13], v[164:167], v[216:219], v[10:13]
	v_mfma_f32_16x16x32_bf16 v[54:57], v[168:171], v[184:187], 0
	v_mfma_f32_16x16x32_bf16 v[50:53], v[176:179], v[184:187], 0
	v_mfma_f32_16x16x32_bf16 v[38:41], v[168:171], v[196:199], 0
	v_mfma_f32_16x16x32_bf16 v[34:37], v[176:179], v[196:199], 0
	v_mfma_f32_16x16x32_bf16 v[22:25], v[168:171], v[204:207], 0
	v_mfma_f32_16x16x32_bf16 v[18:21], v[176:179], v[204:207], 0
	v_mfma_f32_16x16x32_bf16 v[6:9], v[168:171], v[212:215], 0
	v_mfma_f32_16x16x32_bf16 v[2:5], v[176:179], v[212:215], 0
	v_mfma_f32_16x16x32_bf16 v[54:57], v[172:175], v[188:191], v[54:57]
	v_mfma_f32_16x16x32_bf16 v[50:53], v[180:183], v[188:191], v[50:53]
	v_mfma_f32_16x16x32_bf16 v[38:41], v[172:175], v[200:203], v[38:41]
	v_mfma_f32_16x16x32_bf16 v[34:37], v[180:183], v[200:203], v[34:37]
	v_mfma_f32_16x16x32_bf16 v[22:25], v[172:175], v[208:211], v[22:25]
	v_mfma_f32_16x16x32_bf16 v[18:21], v[180:183], v[208:211], v[18:21]
	v_mfma_f32_16x16x32_bf16 v[6:9], v[172:175], v[216:219], v[6:9]
	v_mfma_f32_16x16x32_bf16 v[2:5], v[180:183], v[216:219], v[2:5]
	s_setprio 2
	s_barrier
	s_add_i32 s25, 0, 0x18000
	s_add_i32 s44, 0, 0x1c000
	v_add_u32_e32 v164, s25, v147
	v_add_u32_e32 v180, s44, v147
	ds_read_b128 v[152:155], v164
	ds_read_b128 v[156:159], v164 offset:1024
	ds_read_b128 v[160:163], v164 offset:2048
	ds_read_b128 v[164:167], v164 offset:3072
	ds_read_b128 v[168:171], v180
	ds_read_b128 v[172:175], v180 offset:1024
	ds_read_b128 v[176:179], v180 offset:2048
	ds_read_b128 v[180:183], v180 offset:3072
	s_add_u32 s42, s42, 0x80000
	s_addc_u32 s43, s43, 0
	s_mov_b32 m0, s48
	v_lshl_add_u64 v[224:225], s[42:43], 0, v[130:131]
	ds_read_b128 v[184:187], v151 offset:32768
	ds_read_b128 v[188:191], v151 offset:33792
	ds_read_b128 v[196:199], v151 offset:34816
	ds_read_b128 v[200:203], v151 offset:35840
	ds_read_b128 v[204:207], v151 offset:36864
	ds_read_b128 v[208:211], v151 offset:37888
	ds_read_b128 v[212:215], v151 offset:38912
	ds_read_b128 v[216:219], v151 offset:39936
	global_load_lds_dwordx4 v[224:225], off
	v_lshl_add_u64 v[224:225], s[42:43], 0, v[134:135]
	s_mov_b32 m0, s49
	s_nop 0
	global_load_lds_dwordx4 v[224:225], off
	s_waitcnt vmcnt(8)
	s_waitcnt lgkmcnt(0)
	s_barrier
	s_setprio 1
	s_waitcnt lgkmcnt(0)
	v_mfma_f32_16x16x32_bf16 v[126:129], v[152:155], v[184:187], v[126:129]
	v_mfma_f32_16x16x32_bf16 v[122:125], v[160:163], v[184:187], v[122:125]
	v_mfma_f32_16x16x32_bf16 v[110:113], v[152:155], v[196:199], v[110:113]
	v_mfma_f32_16x16x32_bf16 v[106:109], v[160:163], v[196:199], v[106:109]
	v_mfma_f32_16x16x32_bf16 v[94:97], v[152:155], v[204:207], v[94:97]
	v_mfma_f32_16x16x32_bf16 v[90:93], v[160:163], v[204:207], v[90:93]
	v_mfma_f32_16x16x32_bf16 v[78:81], v[152:155], v[212:215], v[78:81]
	v_mfma_f32_16x16x32_bf16 v[74:77], v[160:163], v[212:215], v[74:77]
	v_mfma_f32_16x16x32_bf16 v[126:129], v[156:159], v[188:191], v[126:129]
	v_mfma_f32_16x16x32_bf16 v[122:125], v[164:167], v[188:191], v[122:125]
	v_mfma_f32_16x16x32_bf16 v[110:113], v[156:159], v[200:203], v[110:113]
	v_mfma_f32_16x16x32_bf16 v[106:109], v[164:167], v[200:203], v[106:109]
	v_mfma_f32_16x16x32_bf16 v[94:97], v[156:159], v[208:211], v[94:97]
	v_mfma_f32_16x16x32_bf16 v[90:93], v[164:167], v[208:211], v[90:93]
	v_mfma_f32_16x16x32_bf16 v[78:81], v[156:159], v[216:219], v[78:81]
	v_mfma_f32_16x16x32_bf16 v[74:77], v[164:167], v[216:219], v[74:77]
	v_mfma_f32_16x16x32_bf16 v[118:121], v[168:171], v[184:187], v[118:121]
	v_mfma_f32_16x16x32_bf16 v[114:117], v[176:179], v[184:187], v[114:117]
	v_mfma_f32_16x16x32_bf16 v[102:105], v[168:171], v[196:199], v[102:105]
	v_mfma_f32_16x16x32_bf16 v[98:101], v[176:179], v[196:199], v[98:101]
	v_mfma_f32_16x16x32_bf16 v[86:89], v[168:171], v[204:207], v[86:89]
	v_mfma_f32_16x16x32_bf16 v[82:85], v[176:179], v[204:207], v[82:85]
	v_mfma_f32_16x16x32_bf16 v[70:73], v[168:171], v[212:215], v[70:73]
	v_mfma_f32_16x16x32_bf16 v[66:69], v[176:179], v[212:215], v[66:69]
	v_mfma_f32_16x16x32_bf16 v[118:121], v[172:175], v[188:191], v[118:121]
	v_mfma_f32_16x16x32_bf16 v[114:117], v[180:183], v[188:191], v[114:117]
	v_mfma_f32_16x16x32_bf16 v[102:105], v[172:175], v[200:203], v[102:105]
	v_mfma_f32_16x16x32_bf16 v[98:101], v[180:183], v[200:203], v[98:101]
	v_mfma_f32_16x16x32_bf16 v[86:89], v[172:175], v[208:211], v[86:89]
	v_mfma_f32_16x16x32_bf16 v[82:85], v[180:183], v[208:211], v[82:85]
	v_mfma_f32_16x16x32_bf16 v[70:73], v[172:175], v[216:219], v[70:73]
	v_mfma_f32_16x16x32_bf16 v[66:69], v[180:183], v[216:219], v[66:69]
	s_setprio 2
	s_barrier
	s_add_i32 s25, s25, s33
	v_lshl_add_u64 v[144:145], v[144:145], 0, s[16:17]
	s_mov_b32 m0, s25
	ds_read_b128 v[184:187], v151 offset:49152
	ds_read_b128 v[188:191], v151 offset:50176
	ds_read_b128 v[196:199], v151 offset:51200
	ds_read_b128 v[200:203], v151 offset:52224
	ds_read_b128 v[204:207], v151 offset:53248
	ds_read_b128 v[208:211], v151 offset:54272
	ds_read_b128 v[212:215], v151 offset:55296
	ds_read_b128 v[216:219], v151 offset:56320
	global_load_lds_dwordx4 v[144:145], off
	s_add_i32 m0, s25, 0x2000
	s_add_u32 s40, s40, 0x80080
	v_lshl_add_u64 v[144:145], v[192:193], 0, s[16:17]
	s_addc_u32 s41, s41, 0
	s_add_i32 s25, s44, s33
	global_load_lds_dwordx4 v[144:145], off
	v_lshl_add_u64 v[144:145], s[40:41], 0, v[132:133]
	s_mov_b32 m0, s25
	s_nop 0
	global_load_lds_dwordx4 v[144:145], off
	v_lshl_add_u64 v[144:145], s[40:41], 0, v[136:137]
	s_add_i32 m0, s25, 0x2000
	s_nop 0
	global_load_lds_dwordx4 v[144:145], off
	v_lshl_add_u64 v[144:145], v[220:221], 0, s[16:17]
	s_mov_b32 m0, s50
	s_nop 0
	global_load_lds_dwordx4 v[144:145], off
	v_lshl_add_u64 v[144:145], v[222:223], 0, s[16:17]
	s_mov_b32 m0, s51
	s_nop 0
	global_load_lds_dwordx4 v[144:145], off
	s_waitcnt vmcnt(8)
	s_waitcnt lgkmcnt(0)
	s_barrier
	s_setprio 1
	s_waitcnt lgkmcnt(0)
	v_mfma_f32_16x16x32_bf16 v[62:65], v[152:155], v[184:187], v[62:65]
	v_mfma_f32_16x16x32_bf16 v[58:61], v[160:163], v[184:187], v[58:61]
	v_mfma_f32_16x16x32_bf16 v[46:49], v[152:155], v[196:199], v[46:49]
	v_mfma_f32_16x16x32_bf16 v[42:45], v[160:163], v[196:199], v[42:45]
	v_mfma_f32_16x16x32_bf16 v[30:33], v[152:155], v[204:207], v[30:33]
	v_mfma_f32_16x16x32_bf16 v[26:29], v[160:163], v[204:207], v[26:29]
	v_mfma_f32_16x16x32_bf16 v[14:17], v[152:155], v[212:215], v[14:17]
	v_mfma_f32_16x16x32_bf16 v[10:13], v[160:163], v[212:215], v[10:13]
	v_mfma_f32_16x16x32_bf16 v[62:65], v[156:159], v[188:191], v[62:65]
	v_mfma_f32_16x16x32_bf16 v[58:61], v[164:167], v[188:191], v[58:61]
	v_mfma_f32_16x16x32_bf16 v[46:49], v[156:159], v[200:203], v[46:49]
	v_mfma_f32_16x16x32_bf16 v[42:45], v[164:167], v[200:203], v[42:45]
	v_mfma_f32_16x16x32_bf16 v[30:33], v[156:159], v[208:211], v[30:33]
	v_mfma_f32_16x16x32_bf16 v[26:29], v[164:167], v[208:211], v[26:29]
	v_mfma_f32_16x16x32_bf16 v[14:17], v[156:159], v[216:219], v[14:17]
	v_mfma_f32_16x16x32_bf16 v[10:13], v[164:167], v[216:219], v[10:13]
	v_mfma_f32_16x16x32_bf16 v[54:57], v[168:171], v[184:187], v[54:57]
	v_mfma_f32_16x16x32_bf16 v[50:53], v[176:179], v[184:187], v[50:53]
	v_mfma_f32_16x16x32_bf16 v[38:41], v[168:171], v[196:199], v[38:41]
	v_mfma_f32_16x16x32_bf16 v[34:37], v[176:179], v[196:199], v[34:37]
	v_mfma_f32_16x16x32_bf16 v[22:25], v[168:171], v[204:207], v[22:25]
	v_mfma_f32_16x16x32_bf16 v[18:21], v[176:179], v[204:207], v[18:21]
	v_mfma_f32_16x16x32_bf16 v[6:9], v[168:171], v[212:215], v[6:9]
	v_mfma_f32_16x16x32_bf16 v[2:5], v[176:179], v[212:215], v[2:5]
	v_mfma_f32_16x16x32_bf16 v[54:57], v[172:175], v[188:191], v[54:57]
	v_mfma_f32_16x16x32_bf16 v[50:53], v[180:183], v[188:191], v[50:53]
	v_mfma_f32_16x16x32_bf16 v[38:41], v[172:175], v[200:203], v[38:41]
	v_mfma_f32_16x16x32_bf16 v[34:37], v[180:183], v[200:203], v[34:37]
	v_mfma_f32_16x16x32_bf16 v[22:25], v[172:175], v[208:211], v[22:25]
	v_mfma_f32_16x16x32_bf16 v[18:21], v[180:183], v[208:211], v[18:21]
	v_mfma_f32_16x16x32_bf16 v[6:9], v[172:175], v[216:219], v[6:9]
	v_mfma_f32_16x16x32_bf16 v[2:5], v[180:183], v[216:219], v[2:5]
	s_setprio 2
	s_barrier
	s_add_u32 s38, s38, 0x100
	s_addc_u32 s39, s39, 0
	s_add_u32 s21, s21, 0x100
	s_addc_u32 s23, s23, 0
	s_cmp_ge_i32 s37, s62
	s_mov_b32 s25, s37
	s_cbranch_scc0 .LBB0_221
	s_branch .Lpeeldone_13
.LBB0_221:
	ds_read_b128 v[152:155], v149
	ds_read_b128 v[156:159], v149 offset:1024
	ds_read_b128 v[160:163], v149 offset:2048
	ds_read_b128 v[164:167], v149 offset:3072
	ds_read_b128 v[168:171], v150
	ds_read_b128 v[172:175], v150 offset:1024
	ds_read_b128 v[176:179], v150 offset:2048
	ds_read_b128 v[180:183], v150 offset:3072
	s_add_i32 s37, s25, 2
	s_add_u32 s40, s38, 0xfff80080
	s_addc_u32 s41, s39, -1
	s_cmp_eq_u32 s36, s25
	s_cselect_b32 s43, s27, s41
	s_cselect_b32 s42, s26, s40
	s_cselect_b32 s41, s29, s23
	s_cselect_b32 s40, s28, s21
	v_lshl_add_u64 v[144:145], s[38:39], 0, v[140:141]
	s_add_i32 m0, s35, 0xc000
	ds_read_b128 v[184:187], v151
	ds_read_b128 v[188:191], v151 offset:1024
	ds_read_b128 v[196:199], v151 offset:2048
	ds_read_b128 v[200:203], v151 offset:3072
	ds_read_b128 v[204:207], v151 offset:4096
	ds_read_b128 v[208:211], v151 offset:5120
	ds_read_b128 v[212:215], v151 offset:6144
	ds_read_b128 v[216:219], v151 offset:7168
	global_load_lds_dwordx4 v[144:145], off
	v_lshl_add_u64 v[144:145], s[38:39], 0, v[142:143]
	s_add_i32 m0, s35, 0xe000
	s_nop 0
	global_load_lds_dwordx4 v[144:145], off
	s_waitcnt vmcnt(8)
	s_waitcnt lgkmcnt(0)
	s_barrier
	s_setprio 1
	s_waitcnt lgkmcnt(0)
	v_mfma_f32_16x16x32_bf16 v[126:129], v[152:155], v[184:187], v[126:129]
	v_mfma_f32_16x16x32_bf16 v[122:125], v[160:163], v[184:187], v[122:125]
	v_mfma_f32_16x16x32_bf16 v[110:113], v[152:155], v[196:199], v[110:113]
	v_mfma_f32_16x16x32_bf16 v[106:109], v[160:163], v[196:199], v[106:109]
	v_mfma_f32_16x16x32_bf16 v[94:97], v[152:155], v[204:207], v[94:97]
	v_mfma_f32_16x16x32_bf16 v[90:93], v[160:163], v[204:207], v[90:93]
	v_mfma_f32_16x16x32_bf16 v[78:81], v[152:155], v[212:215], v[78:81]
	v_mfma_f32_16x16x32_bf16 v[74:77], v[160:163], v[212:215], v[74:77]
	v_mfma_f32_16x16x32_bf16 v[126:129], v[156:159], v[188:191], v[126:129]
	v_mfma_f32_16x16x32_bf16 v[122:125], v[164:167], v[188:191], v[122:125]
	v_mfma_f32_16x16x32_bf16 v[110:113], v[156:159], v[200:203], v[110:113]
	v_mfma_f32_16x16x32_bf16 v[106:109], v[164:167], v[200:203], v[106:109]
	v_mfma_f32_16x16x32_bf16 v[94:97], v[156:159], v[208:211], v[94:97]
	v_mfma_f32_16x16x32_bf16 v[90:93], v[164:167], v[208:211], v[90:93]
	v_mfma_f32_16x16x32_bf16 v[78:81], v[156:159], v[216:219], v[78:81]
	v_mfma_f32_16x16x32_bf16 v[74:77], v[164:167], v[216:219], v[74:77]
	v_mfma_f32_16x16x32_bf16 v[118:121], v[168:171], v[184:187], v[118:121]
	v_mfma_f32_16x16x32_bf16 v[114:117], v[176:179], v[184:187], v[114:117]
	v_mfma_f32_16x16x32_bf16 v[102:105], v[168:171], v[196:199], v[102:105]
	v_mfma_f32_16x16x32_bf16 v[98:101], v[176:179], v[196:199], v[98:101]
	v_mfma_f32_16x16x32_bf16 v[86:89], v[168:171], v[204:207], v[86:89]
	v_mfma_f32_16x16x32_bf16 v[82:85], v[176:179], v[204:207], v[82:85]
	v_mfma_f32_16x16x32_bf16 v[70:73], v[168:171], v[212:215], v[70:73]
	v_mfma_f32_16x16x32_bf16 v[66:69], v[176:179], v[212:215], v[66:69]
	v_mfma_f32_16x16x32_bf16 v[118:121], v[172:175], v[188:191], v[118:121]
	v_mfma_f32_16x16x32_bf16 v[114:117], v[180:183], v[188:191], v[114:117]
	v_mfma_f32_16x16x32_bf16 v[102:105], v[172:175], v[200:203], v[102:105]
	v_mfma_f32_16x16x32_bf16 v[98:101], v[180:183], v[200:203], v[98:101]
	v_mfma_f32_16x16x32_bf16 v[86:89], v[172:175], v[208:211], v[86:89]
	v_mfma_f32_16x16x32_bf16 v[82:85], v[180:183], v[208:211], v[82:85]
	v_mfma_f32_16x16x32_bf16 v[70:73], v[172:175], v[216:219], v[70:73]
	v_mfma_f32_16x16x32_bf16 v[66:69], v[180:183], v[216:219], v[66:69]
	s_setprio 2
	s_barrier
	s_add_i32 s25, s54, s33
	v_lshl_add_u64 v[144:145], s[40:41], 0, v[132:133]
	s_mov_b32 m0, s25
	ds_read_b128 v[184:187], v151 offset:16384
	ds_read_b128 v[188:191], v151 offset:17408
	ds_read_b128 v[196:199], v151 offset:18432
	ds_read_b128 v[200:203], v151 offset:19456
	ds_read_b128 v[204:207], v151 offset:20480
	ds_read_b128 v[208:211], v151 offset:21504
	ds_read_b128 v[212:215], v151 offset:22528
	ds_read_b128 v[216:219], v151 offset:23552
	global_load_lds_dwordx4 v[144:145], off
	s_add_i32 m0, s25, 0x2000
	s_add_u32 s44, s40, 0x80000
	v_lshl_add_u64 v[192:193], s[40:41], 0, v[136:137]
	s_addc_u32 s45, s41, 0
	s_add_i32 s25, s55, s33
	global_load_lds_dwordx4 v[192:193], off
	v_lshl_add_u64 v[220:221], s[44:45], 0, v[132:133]
	s_mov_b32 m0, s25
	v_lshl_add_u64 v[222:223], s[42:43], 0, v[134:135]
	global_load_lds_dwordx4 v[220:221], off
	v_lshl_add_u64 v[220:221], s[44:45], 0, v[136:137]
	s_add_i32 m0, s25, 0x2000
	s_nop 0
	global_load_lds_dwordx4 v[220:221], off
	v_lshl_add_u64 v[220:221], s[42:43], 0, v[130:131]
	s_mov_b32 m0, s35
	s_nop 0
	global_load_lds_dwordx4 v[220:221], off
	s_mov_b32 m0, s47
	s_nop 0
	global_load_lds_dwordx4 v[222:223], off
	s_waitcnt vmcnt(8)
	s_waitcnt lgkmcnt(0)
	s_barrier
	s_setprio 1
	s_waitcnt lgkmcnt(0)
	v_mfma_f32_16x16x32_bf16 v[62:65], v[152:155], v[184:187], v[62:65]
	v_mfma_f32_16x16x32_bf16 v[58:61], v[160:163], v[184:187], v[58:61]
	v_mfma_f32_16x16x32_bf16 v[46:49], v[152:155], v[196:199], v[46:49]
	v_mfma_f32_16x16x32_bf16 v[42:45], v[160:163], v[196:199], v[42:45]
	v_mfma_f32_16x16x32_bf16 v[30:33], v[152:155], v[204:207], v[30:33]
	v_mfma_f32_16x16x32_bf16 v[26:29], v[160:163], v[204:207], v[26:29]
	v_mfma_f32_16x16x32_bf16 v[14:17], v[152:155], v[212:215], v[14:17]
	v_mfma_f32_16x16x32_bf16 v[10:13], v[160:163], v[212:215], v[10:13]
	v_mfma_f32_16x16x32_bf16 v[62:65], v[156:159], v[188:191], v[62:65]
	v_mfma_f32_16x16x32_bf16 v[58:61], v[164:167], v[188:191], v[58:61]
	v_mfma_f32_16x16x32_bf16 v[46:49], v[156:159], v[200:203], v[46:49]
	v_mfma_f32_16x16x32_bf16 v[42:45], v[164:167], v[200:203], v[42:45]
	v_mfma_f32_16x16x32_bf16 v[30:33], v[156:159], v[208:211], v[30:33]
	v_mfma_f32_16x16x32_bf16 v[26:29], v[164:167], v[208:211], v[26:29]
	v_mfma_f32_16x16x32_bf16 v[14:17], v[156:159], v[216:219], v[14:17]
	v_mfma_f32_16x16x32_bf16 v[10:13], v[164:167], v[216:219], v[10:13]
	v_mfma_f32_16x16x32_bf16 v[54:57], v[168:171], v[184:187], v[54:57]
	v_mfma_f32_16x16x32_bf16 v[50:53], v[176:179], v[184:187], v[50:53]
	v_mfma_f32_16x16x32_bf16 v[38:41], v[168:171], v[196:199], v[38:41]
	v_mfma_f32_16x16x32_bf16 v[34:37], v[176:179], v[196:199], v[34:37]
	v_mfma_f32_16x16x32_bf16 v[22:25], v[168:171], v[204:207], v[22:25]
	v_mfma_f32_16x16x32_bf16 v[18:21], v[176:179], v[204:207], v[18:21]
	v_mfma_f32_16x16x32_bf16 v[6:9], v[168:171], v[212:215], v[6:9]
	v_mfma_f32_16x16x32_bf16 v[2:5], v[176:179], v[212:215], v[2:5]
	v_mfma_f32_16x16x32_bf16 v[54:57], v[172:175], v[188:191], v[54:57]
	v_mfma_f32_16x16x32_bf16 v[50:53], v[180:183], v[188:191], v[50:53]
	v_mfma_f32_16x16x32_bf16 v[38:41], v[172:175], v[200:203], v[38:41]
	v_mfma_f32_16x16x32_bf16 v[34:37], v[180:183], v[200:203], v[34:37]
	v_mfma_f32_16x16x32_bf16 v[22:25], v[172:175], v[208:211], v[22:25]
	v_mfma_f32_16x16x32_bf16 v[18:21], v[180:183], v[208:211], v[18:21]
	v_mfma_f32_16x16x32_bf16 v[6:9], v[172:175], v[216:219], v[6:9]
	v_mfma_f32_16x16x32_bf16 v[2:5], v[180:183], v[216:219], v[2:5]
	s_setprio 2
	s_barrier
	s_add_i32 s25, 0, 0x18000
	s_add_i32 s44, 0, 0x1c000
	v_add_u32_e32 v164, s25, v147
	v_add_u32_e32 v180, s44, v147
	ds_read_b128 v[152:155], v164
	ds_read_b128 v[156:159], v164 offset:1024
	ds_read_b128 v[160:163], v164 offset:2048
	ds_read_b128 v[164:167], v164 offset:3072
	ds_read_b128 v[168:171], v180
	ds_read_b128 v[172:175], v180 offset:1024
	ds_read_b128 v[176:179], v180 offset:2048
	ds_read_b128 v[180:183], v180 offset:3072
	s_add_u32 s42, s42, 0x80000
	s_addc_u32 s43, s43, 0
	s_mov_b32 m0, s48
	v_lshl_add_u64 v[224:225], s[42:43], 0, v[130:131]
	ds_read_b128 v[184:187], v151 offset:32768
	ds_read_b128 v[188:191], v151 offset:33792
	ds_read_b128 v[196:199], v151 offset:34816
	ds_read_b128 v[200:203], v151 offset:35840
	ds_read_b128 v[204:207], v151 offset:36864
	ds_read_b128 v[208:211], v151 offset:37888
	ds_read_b128 v[212:215], v151 offset:38912
	ds_read_b128 v[216:219], v151 offset:39936
	global_load_lds_dwordx4 v[224:225], off
	v_lshl_add_u64 v[224:225], s[42:43], 0, v[134:135]
	s_mov_b32 m0, s49
	s_nop 0
	global_load_lds_dwordx4 v[224:225], off
	s_waitcnt vmcnt(8)
	s_waitcnt lgkmcnt(0)
	s_barrier
	s_setprio 1
	s_waitcnt lgkmcnt(0)
	v_mfma_f32_16x16x32_bf16 v[126:129], v[152:155], v[184:187], v[126:129]
	v_mfma_f32_16x16x32_bf16 v[122:125], v[160:163], v[184:187], v[122:125]
	v_mfma_f32_16x16x32_bf16 v[110:113], v[152:155], v[196:199], v[110:113]
	v_mfma_f32_16x16x32_bf16 v[106:109], v[160:163], v[196:199], v[106:109]
	v_mfma_f32_16x16x32_bf16 v[94:97], v[152:155], v[204:207], v[94:97]
	v_mfma_f32_16x16x32_bf16 v[90:93], v[160:163], v[204:207], v[90:93]
	v_mfma_f32_16x16x32_bf16 v[78:81], v[152:155], v[212:215], v[78:81]
	v_mfma_f32_16x16x32_bf16 v[74:77], v[160:163], v[212:215], v[74:77]
	v_mfma_f32_16x16x32_bf16 v[126:129], v[156:159], v[188:191], v[126:129]
	v_mfma_f32_16x16x32_bf16 v[122:125], v[164:167], v[188:191], v[122:125]
	v_mfma_f32_16x16x32_bf16 v[110:113], v[156:159], v[200:203], v[110:113]
	v_mfma_f32_16x16x32_bf16 v[106:109], v[164:167], v[200:203], v[106:109]
	v_mfma_f32_16x16x32_bf16 v[94:97], v[156:159], v[208:211], v[94:97]
	v_mfma_f32_16x16x32_bf16 v[90:93], v[164:167], v[208:211], v[90:93]
	v_mfma_f32_16x16x32_bf16 v[78:81], v[156:159], v[216:219], v[78:81]
	v_mfma_f32_16x16x32_bf16 v[74:77], v[164:167], v[216:219], v[74:77]
	v_mfma_f32_16x16x32_bf16 v[118:121], v[168:171], v[184:187], v[118:121]
	v_mfma_f32_16x16x32_bf16 v[114:117], v[176:179], v[184:187], v[114:117]
	v_mfma_f32_16x16x32_bf16 v[102:105], v[168:171], v[196:199], v[102:105]
	v_mfma_f32_16x16x32_bf16 v[98:101], v[176:179], v[196:199], v[98:101]
	v_mfma_f32_16x16x32_bf16 v[86:89], v[168:171], v[204:207], v[86:89]
	v_mfma_f32_16x16x32_bf16 v[82:85], v[176:179], v[204:207], v[82:85]
	v_mfma_f32_16x16x32_bf16 v[70:73], v[168:171], v[212:215], v[70:73]
	v_mfma_f32_16x16x32_bf16 v[66:69], v[176:179], v[212:215], v[66:69]
	v_mfma_f32_16x16x32_bf16 v[118:121], v[172:175], v[188:191], v[118:121]
	v_mfma_f32_16x16x32_bf16 v[114:117], v[180:183], v[188:191], v[114:117]
	v_mfma_f32_16x16x32_bf16 v[102:105], v[172:175], v[200:203], v[102:105]
	v_mfma_f32_16x16x32_bf16 v[98:101], v[180:183], v[200:203], v[98:101]
	v_mfma_f32_16x16x32_bf16 v[86:89], v[172:175], v[208:211], v[86:89]
	v_mfma_f32_16x16x32_bf16 v[82:85], v[180:183], v[208:211], v[82:85]
	v_mfma_f32_16x16x32_bf16 v[70:73], v[172:175], v[216:219], v[70:73]
	v_mfma_f32_16x16x32_bf16 v[66:69], v[180:183], v[216:219], v[66:69]
	s_setprio 2
	s_barrier
	s_add_i32 s25, s25, s33
	v_lshl_add_u64 v[144:145], v[144:145], 0, s[16:17]
	s_mov_b32 m0, s25
	ds_read_b128 v[184:187], v151 offset:49152
	ds_read_b128 v[188:191], v151 offset:50176
	ds_read_b128 v[196:199], v151 offset:51200
	ds_read_b128 v[200:203], v151 offset:52224
	ds_read_b128 v[204:207], v151 offset:53248
	ds_read_b128 v[208:211], v151 offset:54272
	ds_read_b128 v[212:215], v151 offset:55296
	ds_read_b128 v[216:219], v151 offset:56320
	global_load_lds_dwordx4 v[144:145], off
	s_add_i32 m0, s25, 0x2000
	s_add_u32 s40, s40, 0x80080
	v_lshl_add_u64 v[144:145], v[192:193], 0, s[16:17]
	s_addc_u32 s41, s41, 0
	s_add_i32 s25, s44, s33
	global_load_lds_dwordx4 v[144:145], off
	v_lshl_add_u64 v[144:145], s[40:41], 0, v[132:133]
	s_mov_b32 m0, s25
	s_nop 0
	global_load_lds_dwordx4 v[144:145], off
	v_lshl_add_u64 v[144:145], s[40:41], 0, v[136:137]
	s_add_i32 m0, s25, 0x2000
	s_nop 0
	global_load_lds_dwordx4 v[144:145], off
	v_lshl_add_u64 v[144:145], v[220:221], 0, s[16:17]
	s_mov_b32 m0, s50
	s_nop 0
	global_load_lds_dwordx4 v[144:145], off
	v_lshl_add_u64 v[144:145], v[222:223], 0, s[16:17]
	s_mov_b32 m0, s51
	s_nop 0
	global_load_lds_dwordx4 v[144:145], off
	s_waitcnt vmcnt(8)
	s_waitcnt lgkmcnt(0)
	s_barrier
	s_setprio 1
	s_waitcnt lgkmcnt(0)
	v_mfma_f32_16x16x32_bf16 v[62:65], v[152:155], v[184:187], v[62:65]
	v_mfma_f32_16x16x32_bf16 v[58:61], v[160:163], v[184:187], v[58:61]
	v_mfma_f32_16x16x32_bf16 v[46:49], v[152:155], v[196:199], v[46:49]
	v_mfma_f32_16x16x32_bf16 v[42:45], v[160:163], v[196:199], v[42:45]
	v_mfma_f32_16x16x32_bf16 v[30:33], v[152:155], v[204:207], v[30:33]
	v_mfma_f32_16x16x32_bf16 v[26:29], v[160:163], v[204:207], v[26:29]
	v_mfma_f32_16x16x32_bf16 v[14:17], v[152:155], v[212:215], v[14:17]
	v_mfma_f32_16x16x32_bf16 v[10:13], v[160:163], v[212:215], v[10:13]
	v_mfma_f32_16x16x32_bf16 v[62:65], v[156:159], v[188:191], v[62:65]
	v_mfma_f32_16x16x32_bf16 v[58:61], v[164:167], v[188:191], v[58:61]
	v_mfma_f32_16x16x32_bf16 v[46:49], v[156:159], v[200:203], v[46:49]
	v_mfma_f32_16x16x32_bf16 v[42:45], v[164:167], v[200:203], v[42:45]
	v_mfma_f32_16x16x32_bf16 v[30:33], v[156:159], v[208:211], v[30:33]
	v_mfma_f32_16x16x32_bf16 v[26:29], v[164:167], v[208:211], v[26:29]
	v_mfma_f32_16x16x32_bf16 v[14:17], v[156:159], v[216:219], v[14:17]
	v_mfma_f32_16x16x32_bf16 v[10:13], v[164:167], v[216:219], v[10:13]
	v_mfma_f32_16x16x32_bf16 v[54:57], v[168:171], v[184:187], v[54:57]
	v_mfma_f32_16x16x32_bf16 v[50:53], v[176:179], v[184:187], v[50:53]
	v_mfma_f32_16x16x32_bf16 v[38:41], v[168:171], v[196:199], v[38:41]
	v_mfma_f32_16x16x32_bf16 v[34:37], v[176:179], v[196:199], v[34:37]
	v_mfma_f32_16x16x32_bf16 v[22:25], v[168:171], v[204:207], v[22:25]
	v_mfma_f32_16x16x32_bf16 v[18:21], v[176:179], v[204:207], v[18:21]
	v_mfma_f32_16x16x32_bf16 v[6:9], v[168:171], v[212:215], v[6:9]
	v_mfma_f32_16x16x32_bf16 v[2:5], v[176:179], v[212:215], v[2:5]
	v_mfma_f32_16x16x32_bf16 v[54:57], v[172:175], v[188:191], v[54:57]
	v_mfma_f32_16x16x32_bf16 v[50:53], v[180:183], v[188:191], v[50:53]
	v_mfma_f32_16x16x32_bf16 v[38:41], v[172:175], v[200:203], v[38:41]
	v_mfma_f32_16x16x32_bf16 v[34:37], v[180:183], v[200:203], v[34:37]
	v_mfma_f32_16x16x32_bf16 v[22:25], v[172:175], v[208:211], v[22:25]
	v_mfma_f32_16x16x32_bf16 v[18:21], v[180:183], v[208:211], v[18:21]
	v_mfma_f32_16x16x32_bf16 v[6:9], v[172:175], v[216:219], v[6:9]
	v_mfma_f32_16x16x32_bf16 v[2:5], v[180:183], v[216:219], v[2:5]
	s_setprio 2
	s_barrier
	s_add_u32 s38, s38, 0x100
	s_addc_u32 s39, s39, 0
	s_add_u32 s21, s21, 0x100
	s_addc_u32 s23, s23, 0
	s_cmp_ge_i32 s37, s62
	s_mov_b32 s25, s37
	s_cbranch_scc0 .LBB0_221

.Lpeel_12:
	ds_read_b128 v[130:133], v215
	ds_read_b128 v[134:137], v215 offset:1024
	ds_read_b128 v[138:141], v215 offset:2048
	ds_read_b128 v[142:145], v215 offset:3072
	ds_read_b128 v[146:149], v216
	ds_read_b128 v[150:153], v216 offset:1024
	ds_read_b128 v[154:157], v216 offset:2048
	ds_read_b128 v[158:161], v216 offset:3072
	s_add_i32 s38, s34, 2
	s_add_u32 s35, s30, 0xffea0080
	s_addc_u32 s36, s31, -1
	s_cmp_eq_u32 s28, s34
	s_cselect_b32 s34, s26, s23
	s_cselect_b32 s37, s25, s36
	s_cselect_b32 s36, s24, s35
	s_cselect_b32 s35, s27, s29
	v_lshl_add_u64 v[192:193], s[30:31], 0, v[188:189]
	s_add_i32 m0, s40, 0xc000
	ds_read_b128 v[162:165], v217
	ds_read_b128 v[166:169], v217 offset:1024
	ds_read_b128 v[170:173], v217 offset:2048
	ds_read_b128 v[174:177], v217 offset:3072
	ds_read_b128 v[196:199], v217 offset:4096
	ds_read_b128 v[200:203], v217 offset:5120
	ds_read_b128 v[204:207], v217 offset:6144
	ds_read_b128 v[208:211], v217 offset:7168
	global_load_lds_dwordx4 v[192:193], off
	v_lshl_add_u64 v[192:193], s[30:31], 0, v[190:191]
	s_add_i32 m0, s40, 0xe000
	s_nop 0
	global_load_lds_dwordx4 v[192:193], off
	s_waitcnt vmcnt(8)
	s_waitcnt lgkmcnt(0)
	s_barrier
	s_setprio 1
	s_waitcnt lgkmcnt(0)
	v_mfma_f32_16x16x32_bf16 v[126:129], v[130:133], v[162:165], 0
	v_mfma_f32_16x16x32_bf16 v[122:125], v[138:141], v[162:165], 0
	v_mfma_f32_16x16x32_bf16 v[118:121], v[130:133], v[170:173], 0
	v_mfma_f32_16x16x32_bf16 v[114:117], v[138:141], v[170:173], 0
	v_mfma_f32_16x16x32_bf16 v[94:97], v[130:133], v[196:199], 0
	v_mfma_f32_16x16x32_bf16 v[90:93], v[138:141], v[196:199], 0
	v_mfma_f32_16x16x32_bf16 v[86:89], v[130:133], v[204:207], 0
	v_mfma_f32_16x16x32_bf16 v[82:85], v[138:141], v[204:207], 0
	v_mfma_f32_16x16x32_bf16 v[126:129], v[134:137], v[166:169], v[126:129]
	v_mfma_f32_16x16x32_bf16 v[122:125], v[142:145], v[166:169], v[122:125]
	v_mfma_f32_16x16x32_bf16 v[118:121], v[134:137], v[174:177], v[118:121]
	v_mfma_f32_16x16x32_bf16 v[114:117], v[142:145], v[174:177], v[114:117]
	v_mfma_f32_16x16x32_bf16 v[94:97], v[134:137], v[200:203], v[94:97]
	v_mfma_f32_16x16x32_bf16 v[90:93], v[142:145], v[200:203], v[90:93]
	v_mfma_f32_16x16x32_bf16 v[86:89], v[134:137], v[208:211], v[86:89]
	v_mfma_f32_16x16x32_bf16 v[82:85], v[142:145], v[208:211], v[82:85]
	v_mfma_f32_16x16x32_bf16 v[110:113], v[146:149], v[162:165], 0
	v_mfma_f32_16x16x32_bf16 v[106:109], v[154:157], v[162:165], 0
	v_mfma_f32_16x16x32_bf16 v[102:105], v[146:149], v[170:173], 0
	v_mfma_f32_16x16x32_bf16 v[98:101], v[154:157], v[170:173], 0
	v_mfma_f32_16x16x32_bf16 v[78:81], v[146:149], v[196:199], 0
	v_mfma_f32_16x16x32_bf16 v[74:77], v[154:157], v[196:199], 0
	v_mfma_f32_16x16x32_bf16 v[70:73], v[146:149], v[204:207], 0
	v_mfma_f32_16x16x32_bf16 v[66:69], v[154:157], v[204:207], 0
	v_mfma_f32_16x16x32_bf16 v[110:113], v[150:153], v[166:169], v[110:113]
	v_mfma_f32_16x16x32_bf16 v[106:109], v[158:161], v[166:169], v[106:109]
	v_mfma_f32_16x16x32_bf16 v[102:105], v[150:153], v[174:177], v[102:105]
	v_mfma_f32_16x16x32_bf16 v[98:101], v[158:161], v[174:177], v[98:101]
	v_mfma_f32_16x16x32_bf16 v[78:81], v[150:153], v[200:203], v[78:81]
	v_mfma_f32_16x16x32_bf16 v[74:77], v[158:161], v[200:203], v[74:77]
	v_mfma_f32_16x16x32_bf16 v[70:73], v[150:153], v[208:211], v[70:73]
	v_mfma_f32_16x16x32_bf16 v[66:69], v[158:161], v[208:211], v[66:69]
	s_setprio 2
	s_barrier
	s_add_i32 s39, s53, s33
	v_lshl_add_u64 v[192:193], s[34:35], 0, v[180:181]
	s_mov_b32 m0, s39
	ds_read_b128 v[162:165], v217 offset:16384
	ds_read_b128 v[166:169], v217 offset:17408
	ds_read_b128 v[170:173], v217 offset:18432
	ds_read_b128 v[174:177], v217 offset:19456
	ds_read_b128 v[196:199], v217 offset:20480
	ds_read_b128 v[200:203], v217 offset:21504
	ds_read_b128 v[204:207], v217 offset:22528
	ds_read_b128 v[208:211], v217 offset:23552
	global_load_lds_dwordx4 v[192:193], off
	s_add_i32 m0, s39, 0x2000
	s_add_u32 s62, s34, 0x160000
	v_lshl_add_u64 v[218:219], s[34:35], 0, v[184:185]
	s_addc_u32 s63, s35, 0
	s_add_i32 s39, s54, s33
	global_load_lds_dwordx4 v[218:219], off
	v_lshl_add_u64 v[220:221], s[62:63], 0, v[180:181]
	s_mov_b32 m0, s39
	v_lshl_add_u64 v[222:223], s[36:37], 0, v[182:183]
	global_load_lds_dwordx4 v[220:221], off
	v_lshl_add_u64 v[220:221], s[62:63], 0, v[184:185]
	s_add_i32 m0, s39, 0x2000
	s_nop 0
	global_load_lds_dwordx4 v[220:221], off
	v_lshl_add_u64 v[220:221], s[36:37], 0, v[178:179]
	s_mov_b32 m0, s40
	s_nop 0
	global_load_lds_dwordx4 v[220:221], off
	s_mov_b32 m0, s41
	s_nop 0
	global_load_lds_dwordx4 v[222:223], off
	s_waitcnt vmcnt(8)
	s_waitcnt lgkmcnt(0)
	s_barrier
	s_setprio 1
	s_waitcnt lgkmcnt(0)
	v_mfma_f32_16x16x32_bf16 v[62:65], v[130:133], v[162:165], 0
	v_mfma_f32_16x16x32_bf16 v[58:61], v[138:141], v[162:165], 0
	v_mfma_f32_16x16x32_bf16 v[54:57], v[130:133], v[170:173], 0
	v_mfma_f32_16x16x32_bf16 v[50:53], v[138:141], v[170:173], 0
	v_mfma_f32_16x16x32_bf16 v[30:33], v[130:133], v[196:199], 0
	v_mfma_f32_16x16x32_bf16 v[26:29], v[138:141], v[196:199], 0
	v_mfma_f32_16x16x32_bf16 v[22:25], v[130:133], v[204:207], 0
	v_mfma_f32_16x16x32_bf16 v[18:21], v[138:141], v[204:207], 0
	v_mfma_f32_16x16x32_bf16 v[62:65], v[134:137], v[166:169], v[62:65]
	v_mfma_f32_16x16x32_bf16 v[58:61], v[142:145], v[166:169], v[58:61]
	v_mfma_f32_16x16x32_bf16 v[54:57], v[134:137], v[174:177], v[54:57]
	v_mfma_f32_16x16x32_bf16 v[50:53], v[142:145], v[174:177], v[50:53]
	v_mfma_f32_16x16x32_bf16 v[30:33], v[134:137], v[200:203], v[30:33]
	v_mfma_f32_16x16x32_bf16 v[26:29], v[142:145], v[200:203], v[26:29]
	v_mfma_f32_16x16x32_bf16 v[22:25], v[134:137], v[208:211], v[22:25]
	v_mfma_f32_16x16x32_bf16 v[18:21], v[142:145], v[208:211], v[18:21]
	v_mfma_f32_16x16x32_bf16 v[46:49], v[146:149], v[162:165], 0
	v_mfma_f32_16x16x32_bf16 v[42:45], v[154:157], v[162:165], 0
	v_mfma_f32_16x16x32_bf16 v[38:41], v[146:149], v[170:173], 0
	v_mfma_f32_16x16x32_bf16 v[34:37], v[154:157], v[170:173], 0
	v_mfma_f32_16x16x32_bf16 v[14:17], v[146:149], v[196:199], 0
	v_mfma_f32_16x16x32_bf16 v[10:13], v[154:157], v[196:199], 0
	v_mfma_f32_16x16x32_bf16 v[6:9], v[146:149], v[204:207], 0
	v_mfma_f32_16x16x32_bf16 v[2:5], v[154:157], v[204:207], 0
	v_mfma_f32_16x16x32_bf16 v[46:49], v[150:153], v[166:169], v[46:49]
	v_mfma_f32_16x16x32_bf16 v[42:45], v[158:161], v[166:169], v[42:45]
	v_mfma_f32_16x16x32_bf16 v[38:41], v[150:153], v[174:177], v[38:41]
	v_mfma_f32_16x16x32_bf16 v[34:37], v[158:161], v[174:177], v[34:37]
	v_mfma_f32_16x16x32_bf16 v[14:17], v[150:153], v[200:203], v[14:17]
	v_mfma_f32_16x16x32_bf16 v[10:13], v[158:161], v[200:203], v[10:13]
	v_mfma_f32_16x16x32_bf16 v[6:9], v[150:153], v[208:211], v[6:9]
	v_mfma_f32_16x16x32_bf16 v[2:5], v[158:161], v[208:211], v[2:5]
	s_setprio 2
	s_barrier
	s_add_i32 s39, 0, 0x18000
	s_add_i32 s62, 0, 0x1c000
	v_add_u32_e32 v142, s39, v213
	v_add_u32_e32 v158, s62, v213
	ds_read_b128 v[130:133], v142
	ds_read_b128 v[134:137], v142 offset:1024
	ds_read_b128 v[138:141], v142 offset:2048
	ds_read_b128 v[142:145], v142 offset:3072
	ds_read_b128 v[146:149], v158
	ds_read_b128 v[150:153], v158 offset:1024
	ds_read_b128 v[154:157], v158 offset:2048
	ds_read_b128 v[158:161], v158 offset:3072
	s_add_u32 s36, s36, 0x160000
	s_addc_u32 s37, s37, 0
	s_mov_b32 m0, s42
	v_lshl_add_u64 v[224:225], s[36:37], 0, v[178:179]
	ds_read_b128 v[162:165], v217 offset:32768
	ds_read_b128 v[166:169], v217 offset:33792
	ds_read_b128 v[170:173], v217 offset:34816
	ds_read_b128 v[174:177], v217 offset:35840
	ds_read_b128 v[196:199], v217 offset:36864
	ds_read_b128 v[200:203], v217 offset:37888
	ds_read_b128 v[204:207], v217 offset:38912
	ds_read_b128 v[208:211], v217 offset:39936
	global_load_lds_dwordx4 v[224:225], off
	v_lshl_add_u64 v[224:225], s[36:37], 0, v[182:183]
	s_mov_b32 m0, s43
	s_nop 0
	global_load_lds_dwordx4 v[224:225], off
	s_waitcnt vmcnt(8)
	s_waitcnt lgkmcnt(0)
	s_barrier
	s_setprio 1
	s_waitcnt lgkmcnt(0)
	v_mfma_f32_16x16x32_bf16 v[126:129], v[130:133], v[162:165], v[126:129]
	v_mfma_f32_16x16x32_bf16 v[122:125], v[138:141], v[162:165], v[122:125]
	v_mfma_f32_16x16x32_bf16 v[118:121], v[130:133], v[170:173], v[118:121]
	v_mfma_f32_16x16x32_bf16 v[114:117], v[138:141], v[170:173], v[114:117]
	v_mfma_f32_16x16x32_bf16 v[94:97], v[130:133], v[196:199], v[94:97]
	v_mfma_f32_16x16x32_bf16 v[90:93], v[138:141], v[196:199], v[90:93]
	v_mfma_f32_16x16x32_bf16 v[86:89], v[130:133], v[204:207], v[86:89]
	v_mfma_f32_16x16x32_bf16 v[82:85], v[138:141], v[204:207], v[82:85]
	v_mfma_f32_16x16x32_bf16 v[126:129], v[134:137], v[166:169], v[126:129]
	v_mfma_f32_16x16x32_bf16 v[122:125], v[142:145], v[166:169], v[122:125]
	v_mfma_f32_16x16x32_bf16 v[118:121], v[134:137], v[174:177], v[118:121]
	v_mfma_f32_16x16x32_bf16 v[114:117], v[142:145], v[174:177], v[114:117]
	v_mfma_f32_16x16x32_bf16 v[94:97], v[134:137], v[200:203], v[94:97]
	v_mfma_f32_16x16x32_bf16 v[90:93], v[142:145], v[200:203], v[90:93]
	v_mfma_f32_16x16x32_bf16 v[86:89], v[134:137], v[208:211], v[86:89]
	v_mfma_f32_16x16x32_bf16 v[82:85], v[142:145], v[208:211], v[82:85]
	v_mfma_f32_16x16x32_bf16 v[110:113], v[146:149], v[162:165], v[110:113]
	v_mfma_f32_16x16x32_bf16 v[106:109], v[154:157], v[162:165], v[106:109]
	v_mfma_f32_16x16x32_bf16 v[102:105], v[146:149], v[170:173], v[102:105]
	v_mfma_f32_16x16x32_bf16 v[98:101], v[154:157], v[170:173], v[98:101]
	v_mfma_f32_16x16x32_bf16 v[78:81], v[146:149], v[196:199], v[78:81]
	v_mfma_f32_16x16x32_bf16 v[74:77], v[154:157], v[196:199], v[74:77]
	v_mfma_f32_16x16x32_bf16 v[70:73], v[146:149], v[204:207], v[70:73]
	v_mfma_f32_16x16x32_bf16 v[66:69], v[154:157], v[204:207], v[66:69]
	v_mfma_f32_16x16x32_bf16 v[110:113], v[150:153], v[166:169], v[110:113]
	v_mfma_f32_16x16x32_bf16 v[106:109], v[158:161], v[166:169], v[106:109]
	v_mfma_f32_16x16x32_bf16 v[102:105], v[150:153], v[174:177], v[102:105]
	v_mfma_f32_16x16x32_bf16 v[98:101], v[158:161], v[174:177], v[98:101]
	v_mfma_f32_16x16x32_bf16 v[78:81], v[150:153], v[200:203], v[78:81]
	v_mfma_f32_16x16x32_bf16 v[74:77], v[158:161], v[200:203], v[74:77]
	v_mfma_f32_16x16x32_bf16 v[70:73], v[150:153], v[208:211], v[70:73]
	v_mfma_f32_16x16x32_bf16 v[66:69], v[158:161], v[208:211], v[66:69]
	s_setprio 2
	s_barrier
	s_add_i32 s36, s39, s33
	v_lshl_add_u64 v[192:193], v[192:193], 0, s[18:19]
	s_mov_b32 m0, s36
	ds_read_b128 v[162:165], v217 offset:49152
	ds_read_b128 v[166:169], v217 offset:50176
	ds_read_b128 v[170:173], v217 offset:51200
	ds_read_b128 v[174:177], v217 offset:52224
	ds_read_b128 v[196:199], v217 offset:53248
	ds_read_b128 v[200:203], v217 offset:54272
	ds_read_b128 v[204:207], v217 offset:55296
	ds_read_b128 v[208:211], v217 offset:56320
	global_load_lds_dwordx4 v[192:193], off
	s_add_i32 m0, s36, 0x2000
	s_add_u32 s34, s34, 0x160080
	v_lshl_add_u64 v[192:193], v[218:219], 0, s[18:19]
	s_addc_u32 s35, s35, 0
	s_add_i32 s36, s62, s33
	global_load_lds_dwordx4 v[192:193], off
	v_lshl_add_u64 v[192:193], s[34:35], 0, v[180:181]
	s_mov_b32 m0, s36
	s_nop 0
	global_load_lds_dwordx4 v[192:193], off
	v_lshl_add_u64 v[192:193], s[34:35], 0, v[184:185]
	s_add_i32 m0, s36, 0x2000
	s_nop 0
	global_load_lds_dwordx4 v[192:193], off
	v_lshl_add_u64 v[192:193], v[220:221], 0, s[18:19]
	s_mov_b32 m0, s46
	s_nop 0
	global_load_lds_dwordx4 v[192:193], off
	v_lshl_add_u64 v[192:193], v[222:223], 0, s[18:19]
	s_mov_b32 m0, s47
	s_nop 0
	global_load_lds_dwordx4 v[192:193], off
	s_waitcnt vmcnt(8)
	s_waitcnt lgkmcnt(0)
	s_barrier
	s_setprio 1
	s_waitcnt lgkmcnt(0)
	v_mfma_f32_16x16x32_bf16 v[62:65], v[130:133], v[162:165], v[62:65]
	v_mfma_f32_16x16x32_bf16 v[58:61], v[138:141], v[162:165], v[58:61]
	v_mfma_f32_16x16x32_bf16 v[54:57], v[130:133], v[170:173], v[54:57]
	v_mfma_f32_16x16x32_bf16 v[50:53], v[138:141], v[170:173], v[50:53]
	v_mfma_f32_16x16x32_bf16 v[30:33], v[130:133], v[196:199], v[30:33]
	v_mfma_f32_16x16x32_bf16 v[26:29], v[138:141], v[196:199], v[26:29]
	v_mfma_f32_16x16x32_bf16 v[22:25], v[130:133], v[204:207], v[22:25]
	v_mfma_f32_16x16x32_bf16 v[18:21], v[138:141], v[204:207], v[18:21]
	v_mfma_f32_16x16x32_bf16 v[62:65], v[134:137], v[166:169], v[62:65]
	v_mfma_f32_16x16x32_bf16 v[58:61], v[142:145], v[166:169], v[58:61]
	v_mfma_f32_16x16x32_bf16 v[54:57], v[134:137], v[174:177], v[54:57]
	v_mfma_f32_16x16x32_bf16 v[50:53], v[142:145], v[174:177], v[50:53]
	v_mfma_f32_16x16x32_bf16 v[30:33], v[134:137], v[200:203], v[30:33]
	v_mfma_f32_16x16x32_bf16 v[26:29], v[142:145], v[200:203], v[26:29]
	v_mfma_f32_16x16x32_bf16 v[22:25], v[134:137], v[208:211], v[22:25]
	v_mfma_f32_16x16x32_bf16 v[18:21], v[142:145], v[208:211], v[18:21]
	v_mfma_f32_16x16x32_bf16 v[46:49], v[146:149], v[162:165], v[46:49]
	v_mfma_f32_16x16x32_bf16 v[42:45], v[154:157], v[162:165], v[42:45]
	v_mfma_f32_16x16x32_bf16 v[38:41], v[146:149], v[170:173], v[38:41]
	v_mfma_f32_16x16x32_bf16 v[34:37], v[154:157], v[170:173], v[34:37]
	v_mfma_f32_16x16x32_bf16 v[14:17], v[146:149], v[196:199], v[14:17]
	v_mfma_f32_16x16x32_bf16 v[10:13], v[154:157], v[196:199], v[10:13]
	v_mfma_f32_16x16x32_bf16 v[6:9], v[146:149], v[204:207], v[6:9]
	v_mfma_f32_16x16x32_bf16 v[2:5], v[154:157], v[204:207], v[2:5]
	v_mfma_f32_16x16x32_bf16 v[46:49], v[150:153], v[166:169], v[46:49]
	v_mfma_f32_16x16x32_bf16 v[42:45], v[158:161], v[166:169], v[42:45]
	v_mfma_f32_16x16x32_bf16 v[38:41], v[150:153], v[174:177], v[38:41]
	v_mfma_f32_16x16x32_bf16 v[34:37], v[158:161], v[174:177], v[34:37]
	v_mfma_f32_16x16x32_bf16 v[14:17], v[150:153], v[200:203], v[14:17]
	v_mfma_f32_16x16x32_bf16 v[10:13], v[158:161], v[200:203], v[10:13]
	v_mfma_f32_16x16x32_bf16 v[6:9], v[150:153], v[208:211], v[6:9]
	v_mfma_f32_16x16x32_bf16 v[2:5], v[158:161], v[208:211], v[2:5]
	s_setprio 2
	s_barrier
	s_add_u32 s30, s30, 0x100
	s_addc_u32 s31, s31, 0
	s_add_u32 s23, s23, 0x100
	s_addc_u32 s29, s29, 0
	s_cmp_ge_i32 s38, s61
	s_mov_b32 s34, s38
	s_cbranch_scc0 .LBB0_357
	s_branch .Lpeeldone_12
.LBB0_357:
	ds_read_b128 v[130:133], v215
	ds_read_b128 v[134:137], v215 offset:1024
	ds_read_b128 v[138:141], v215 offset:2048
	ds_read_b128 v[142:145], v215 offset:3072
	ds_read_b128 v[146:149], v216
	ds_read_b128 v[150:153], v216 offset:1024
	ds_read_b128 v[154:157], v216 offset:2048
	ds_read_b128 v[158:161], v216 offset:3072
	s_add_i32 s38, s34, 2
	s_add_u32 s35, s30, 0xffea0080
	s_addc_u32 s36, s31, -1
	s_cmp_eq_u32 s28, s34
	s_cselect_b32 s34, s26, s23
	s_cselect_b32 s37, s25, s36
	s_cselect_b32 s36, s24, s35
	s_cselect_b32 s35, s27, s29
	v_lshl_add_u64 v[192:193], s[30:31], 0, v[188:189]
	s_add_i32 m0, s40, 0xc000
	ds_read_b128 v[162:165], v217
	ds_read_b128 v[166:169], v217 offset:1024
	ds_read_b128 v[170:173], v217 offset:2048
	ds_read_b128 v[174:177], v217 offset:3072
	ds_read_b128 v[196:199], v217 offset:4096
	ds_read_b128 v[200:203], v217 offset:5120
	ds_read_b128 v[204:207], v217 offset:6144
	ds_read_b128 v[208:211], v217 offset:7168
	global_load_lds_dwordx4 v[192:193], off
	v_lshl_add_u64 v[192:193], s[30:31], 0, v[190:191]
	s_add_i32 m0, s40, 0xe000
	s_nop 0
	global_load_lds_dwordx4 v[192:193], off
	s_waitcnt vmcnt(8)
	s_waitcnt lgkmcnt(0)
	s_barrier
	s_setprio 1
	s_waitcnt lgkmcnt(0)
	v_mfma_f32_16x16x32_bf16 v[126:129], v[130:133], v[162:165], v[126:129]
	v_mfma_f32_16x16x32_bf16 v[122:125], v[138:141], v[162:165], v[122:125]
	v_mfma_f32_16x16x32_bf16 v[118:121], v[130:133], v[170:173], v[118:121]
	v_mfma_f32_16x16x32_bf16 v[114:117], v[138:141], v[170:173], v[114:117]
	v_mfma_f32_16x16x32_bf16 v[94:97], v[130:133], v[196:199], v[94:97]
	v_mfma_f32_16x16x32_bf16 v[90:93], v[138:141], v[196:199], v[90:93]
	v_mfma_f32_16x16x32_bf16 v[86:89], v[130:133], v[204:207], v[86:89]
	v_mfma_f32_16x16x32_bf16 v[82:85], v[138:141], v[204:207], v[82:85]
	v_mfma_f32_16x16x32_bf16 v[126:129], v[134:137], v[166:169], v[126:129]
	v_mfma_f32_16x16x32_bf16 v[122:125], v[142:145], v[166:169], v[122:125]
	v_mfma_f32_16x16x32_bf16 v[118:121], v[134:137], v[174:177], v[118:121]
	v_mfma_f32_16x16x32_bf16 v[114:117], v[142:145], v[174:177], v[114:117]
	v_mfma_f32_16x16x32_bf16 v[94:97], v[134:137], v[200:203], v[94:97]
	v_mfma_f32_16x16x32_bf16 v[90:93], v[142:145], v[200:203], v[90:93]
	v_mfma_f32_16x16x32_bf16 v[86:89], v[134:137], v[208:211], v[86:89]
	v_mfma_f32_16x16x32_bf16 v[82:85], v[142:145], v[208:211], v[82:85]
	v_mfma_f32_16x16x32_bf16 v[110:113], v[146:149], v[162:165], v[110:113]
	v_mfma_f32_16x16x32_bf16 v[106:109], v[154:157], v[162:165], v[106:109]
	v_mfma_f32_16x16x32_bf16 v[102:105], v[146:149], v[170:173], v[102:105]
	v_mfma_f32_16x16x32_bf16 v[98:101], v[154:157], v[170:173], v[98:101]
	v_mfma_f32_16x16x32_bf16 v[78:81], v[146:149], v[196:199], v[78:81]
	v_mfma_f32_16x16x32_bf16 v[74:77], v[154:157], v[196:199], v[74:77]
	v_mfma_f32_16x16x32_bf16 v[70:73], v[146:149], v[204:207], v[70:73]
	v_mfma_f32_16x16x32_bf16 v[66:69], v[154:157], v[204:207], v[66:69]
	v_mfma_f32_16x16x32_bf16 v[110:113], v[150:153], v[166:169], v[110:113]
	v_mfma_f32_16x16x32_bf16 v[106:109], v[158:161], v[166:169], v[106:109]
	v_mfma_f32_16x16x32_bf16 v[102:105], v[150:153], v[174:177], v[102:105]
	v_mfma_f32_16x16x32_bf16 v[98:101], v[158:161], v[174:177], v[98:101]
	v_mfma_f32_16x16x32_bf16 v[78:81], v[150:153], v[200:203], v[78:81]
	v_mfma_f32_16x16x32_bf16 v[74:77], v[158:161], v[200:203], v[74:77]
	v_mfma_f32_16x16x32_bf16 v[70:73], v[150:153], v[208:211], v[70:73]
	v_mfma_f32_16x16x32_bf16 v[66:69], v[158:161], v[208:211], v[66:69]
	s_setprio 2
	s_barrier
	s_add_i32 s39, s53, s33
	v_lshl_add_u64 v[192:193], s[34:35], 0, v[180:181]
	s_mov_b32 m0, s39
	ds_read_b128 v[162:165], v217 offset:16384
	ds_read_b128 v[166:169], v217 offset:17408
	ds_read_b128 v[170:173], v217 offset:18432
	ds_read_b128 v[174:177], v217 offset:19456
	ds_read_b128 v[196:199], v217 offset:20480
	ds_read_b128 v[200:203], v217 offset:21504
	ds_read_b128 v[204:207], v217 offset:22528
	ds_read_b128 v[208:211], v217 offset:23552
	global_load_lds_dwordx4 v[192:193], off
	s_add_i32 m0, s39, 0x2000
	s_add_u32 s62, s34, 0x160000
	v_lshl_add_u64 v[218:219], s[34:35], 0, v[184:185]
	s_addc_u32 s63, s35, 0
	s_add_i32 s39, s54, s33
	global_load_lds_dwordx4 v[218:219], off
	v_lshl_add_u64 v[220:221], s[62:63], 0, v[180:181]
	s_mov_b32 m0, s39
	v_lshl_add_u64 v[222:223], s[36:37], 0, v[182:183]
	global_load_lds_dwordx4 v[220:221], off
	v_lshl_add_u64 v[220:221], s[62:63], 0, v[184:185]
	s_add_i32 m0, s39, 0x2000
	s_nop 0
	global_load_lds_dwordx4 v[220:221], off
	v_lshl_add_u64 v[220:221], s[36:37], 0, v[178:179]
	s_mov_b32 m0, s40
	s_nop 0
	global_load_lds_dwordx4 v[220:221], off
	s_mov_b32 m0, s41
	s_nop 0
	global_load_lds_dwordx4 v[222:223], off
	s_waitcnt vmcnt(8)
	s_waitcnt lgkmcnt(0)
	s_barrier
	s_setprio 1
	s_waitcnt lgkmcnt(0)
	v_mfma_f32_16x16x32_bf16 v[62:65], v[130:133], v[162:165], v[62:65]
	v_mfma_f32_16x16x32_bf16 v[58:61], v[138:141], v[162:165], v[58:61]
	v_mfma_f32_16x16x32_bf16 v[54:57], v[130:133], v[170:173], v[54:57]
	v_mfma_f32_16x16x32_bf16 v[50:53], v[138:141], v[170:173], v[50:53]
	v_mfma_f32_16x16x32_bf16 v[30:33], v[130:133], v[196:199], v[30:33]
	v_mfma_f32_16x16x32_bf16 v[26:29], v[138:141], v[196:199], v[26:29]
	v_mfma_f32_16x16x32_bf16 v[22:25], v[130:133], v[204:207], v[22:25]
	v_mfma_f32_16x16x32_bf16 v[18:21], v[138:141], v[204:207], v[18:21]
	v_mfma_f32_16x16x32_bf16 v[62:65], v[134:137], v[166:169], v[62:65]
	v_mfma_f32_16x16x32_bf16 v[58:61], v[142:145], v[166:169], v[58:61]
	v_mfma_f32_16x16x32_bf16 v[54:57], v[134:137], v[174:177], v[54:57]
	v_mfma_f32_16x16x32_bf16 v[50:53], v[142:145], v[174:177], v[50:53]
	v_mfma_f32_16x16x32_bf16 v[30:33], v[134:137], v[200:203], v[30:33]
	v_mfma_f32_16x16x32_bf16 v[26:29], v[142:145], v[200:203], v[26:29]
	v_mfma_f32_16x16x32_bf16 v[22:25], v[134:137], v[208:211], v[22:25]
	v_mfma_f32_16x16x32_bf16 v[18:21], v[142:145], v[208:211], v[18:21]
	v_mfma_f32_16x16x32_bf16 v[46:49], v[146:149], v[162:165], v[46:49]
	v_mfma_f32_16x16x32_bf16 v[42:45], v[154:157], v[162:165], v[42:45]
	v_mfma_f32_16x16x32_bf16 v[38:41], v[146:149], v[170:173], v[38:41]
	v_mfma_f32_16x16x32_bf16 v[34:37], v[154:157], v[170:173], v[34:37]
	v_mfma_f32_16x16x32_bf16 v[14:17], v[146:149], v[196:199], v[14:17]
	v_mfma_f32_16x16x32_bf16 v[10:13], v[154:157], v[196:199], v[10:13]
	v_mfma_f32_16x16x32_bf16 v[6:9], v[146:149], v[204:207], v[6:9]
	v_mfma_f32_16x16x32_bf16 v[2:5], v[154:157], v[204:207], v[2:5]
	v_mfma_f32_16x16x32_bf16 v[46:49], v[150:153], v[166:169], v[46:49]
	v_mfma_f32_16x16x32_bf16 v[42:45], v[158:161], v[166:169], v[42:45]
	v_mfma_f32_16x16x32_bf16 v[38:41], v[150:153], v[174:177], v[38:41]
	v_mfma_f32_16x16x32_bf16 v[34:37], v[158:161], v[174:177], v[34:37]
	v_mfma_f32_16x16x32_bf16 v[14:17], v[150:153], v[200:203], v[14:17]
	v_mfma_f32_16x16x32_bf16 v[10:13], v[158:161], v[200:203], v[10:13]
	v_mfma_f32_16x16x32_bf16 v[6:9], v[150:153], v[208:211], v[6:9]
	v_mfma_f32_16x16x32_bf16 v[2:5], v[158:161], v[208:211], v[2:5]
	s_setprio 2
	s_barrier
	s_add_i32 s39, 0, 0x18000
	s_add_i32 s62, 0, 0x1c000
	v_add_u32_e32 v142, s39, v213
	v_add_u32_e32 v158, s62, v213
	ds_read_b128 v[130:133], v142
	ds_read_b128 v[134:137], v142 offset:1024
	ds_read_b128 v[138:141], v142 offset:2048
	ds_read_b128 v[142:145], v142 offset:3072
	ds_read_b128 v[146:149], v158
	ds_read_b128 v[150:153], v158 offset:1024
	ds_read_b128 v[154:157], v158 offset:2048
	ds_read_b128 v[158:161], v158 offset:3072
	s_add_u32 s36, s36, 0x160000
	s_addc_u32 s37, s37, 0
	s_mov_b32 m0, s42
	v_lshl_add_u64 v[224:225], s[36:37], 0, v[178:179]
	ds_read_b128 v[162:165], v217 offset:32768
	ds_read_b128 v[166:169], v217 offset:33792
	ds_read_b128 v[170:173], v217 offset:34816
	ds_read_b128 v[174:177], v217 offset:35840
	ds_read_b128 v[196:199], v217 offset:36864
	ds_read_b128 v[200:203], v217 offset:37888
	ds_read_b128 v[204:207], v217 offset:38912
	ds_read_b128 v[208:211], v217 offset:39936
	global_load_lds_dwordx4 v[224:225], off
	v_lshl_add_u64 v[224:225], s[36:37], 0, v[182:183]
	s_mov_b32 m0, s43
	s_nop 0
	global_load_lds_dwordx4 v[224:225], off
	s_waitcnt vmcnt(8)
	s_waitcnt lgkmcnt(0)
	s_barrier
	s_setprio 1
	s_waitcnt lgkmcnt(0)
	v_mfma_f32_16x16x32_bf16 v[126:129], v[130:133], v[162:165], v[126:129]
	v_mfma_f32_16x16x32_bf16 v[122:125], v[138:141], v[162:165], v[122:125]
	v_mfma_f32_16x16x32_bf16 v[118:121], v[130:133], v[170:173], v[118:121]
	v_mfma_f32_16x16x32_bf16 v[114:117], v[138:141], v[170:173], v[114:117]
	v_mfma_f32_16x16x32_bf16 v[94:97], v[130:133], v[196:199], v[94:97]
	v_mfma_f32_16x16x32_bf16 v[90:93], v[138:141], v[196:199], v[90:93]
	v_mfma_f32_16x16x32_bf16 v[86:89], v[130:133], v[204:207], v[86:89]
	v_mfma_f32_16x16x32_bf16 v[82:85], v[138:141], v[204:207], v[82:85]
	v_mfma_f32_16x16x32_bf16 v[126:129], v[134:137], v[166:169], v[126:129]
	v_mfma_f32_16x16x32_bf16 v[122:125], v[142:145], v[166:169], v[122:125]
	v_mfma_f32_16x16x32_bf16 v[118:121], v[134:137], v[174:177], v[118:121]
	v_mfma_f32_16x16x32_bf16 v[114:117], v[142:145], v[174:177], v[114:117]
	v_mfma_f32_16x16x32_bf16 v[94:97], v[134:137], v[200:203], v[94:97]
	v_mfma_f32_16x16x32_bf16 v[90:93], v[142:145], v[200:203], v[90:93]
	v_mfma_f32_16x16x32_bf16 v[86:89], v[134:137], v[208:211], v[86:89]
	v_mfma_f32_16x16x32_bf16 v[82:85], v[142:145], v[208:211], v[82:85]
	v_mfma_f32_16x16x32_bf16 v[110:113], v[146:149], v[162:165], v[110:113]
	v_mfma_f32_16x16x32_bf16 v[106:109], v[154:157], v[162:165], v[106:109]
	v_mfma_f32_16x16x32_bf16 v[102:105], v[146:149], v[170:173], v[102:105]
	v_mfma_f32_16x16x32_bf16 v[98:101], v[154:157], v[170:173], v[98:101]
	v_mfma_f32_16x16x32_bf16 v[78:81], v[146:149], v[196:199], v[78:81]
	v_mfma_f32_16x16x32_bf16 v[74:77], v[154:157], v[196:199], v[74:77]
	v_mfma_f32_16x16x32_bf16 v[70:73], v[146:149], v[204:207], v[70:73]
	v_mfma_f32_16x16x32_bf16 v[66:69], v[154:157], v[204:207], v[66:69]
	v_mfma_f32_16x16x32_bf16 v[110:113], v[150:153], v[166:169], v[110:113]
	v_mfma_f32_16x16x32_bf16 v[106:109], v[158:161], v[166:169], v[106:109]
	v_mfma_f32_16x16x32_bf16 v[102:105], v[150:153], v[174:177], v[102:105]
	v_mfma_f32_16x16x32_bf16 v[98:101], v[158:161], v[174:177], v[98:101]
	v_mfma_f32_16x16x32_bf16 v[78:81], v[150:153], v[200:203], v[78:81]
	v_mfma_f32_16x16x32_bf16 v[74:77], v[158:161], v[200:203], v[74:77]
	v_mfma_f32_16x16x32_bf16 v[70:73], v[150:153], v[208:211], v[70:73]
	v_mfma_f32_16x16x32_bf16 v[66:69], v[158:161], v[208:211], v[66:69]
	s_setprio 2
	s_barrier
	s_add_i32 s36, s39, s33
	v_lshl_add_u64 v[192:193], v[192:193], 0, s[18:19]
	s_mov_b32 m0, s36
	ds_read_b128 v[162:165], v217 offset:49152
	ds_read_b128 v[166:169], v217 offset:50176
	ds_read_b128 v[170:173], v217 offset:51200
	ds_read_b128 v[174:177], v217 offset:52224
	ds_read_b128 v[196:199], v217 offset:53248
	ds_read_b128 v[200:203], v217 offset:54272
	ds_read_b128 v[204:207], v217 offset:55296
	ds_read_b128 v[208:211], v217 offset:56320
	global_load_lds_dwordx4 v[192:193], off
	s_add_i32 m0, s36, 0x2000
	s_add_u32 s34, s34, 0x160080
	v_lshl_add_u64 v[192:193], v[218:219], 0, s[18:19]
	s_addc_u32 s35, s35, 0
	s_add_i32 s36, s62, s33
	global_load_lds_dwordx4 v[192:193], off
	v_lshl_add_u64 v[192:193], s[34:35], 0, v[180:181]
	s_mov_b32 m0, s36
	s_nop 0
	global_load_lds_dwordx4 v[192:193], off
	v_lshl_add_u64 v[192:193], s[34:35], 0, v[184:185]
	s_add_i32 m0, s36, 0x2000
	s_nop 0
	global_load_lds_dwordx4 v[192:193], off
	v_lshl_add_u64 v[192:193], v[220:221], 0, s[18:19]
	s_mov_b32 m0, s46
	s_nop 0
	global_load_lds_dwordx4 v[192:193], off
	v_lshl_add_u64 v[192:193], v[222:223], 0, s[18:19]
	s_mov_b32 m0, s47
	s_nop 0
	global_load_lds_dwordx4 v[192:193], off
	s_waitcnt vmcnt(8)
	s_waitcnt lgkmcnt(0)
	s_barrier
	s_setprio 1
	s_waitcnt lgkmcnt(0)
	v_mfma_f32_16x16x32_bf16 v[62:65], v[130:133], v[162:165], v[62:65]
	v_mfma_f32_16x16x32_bf16 v[58:61], v[138:141], v[162:165], v[58:61]
	v_mfma_f32_16x16x32_bf16 v[54:57], v[130:133], v[170:173], v[54:57]
	v_mfma_f32_16x16x32_bf16 v[50:53], v[138:141], v[170:173], v[50:53]
	v_mfma_f32_16x16x32_bf16 v[30:33], v[130:133], v[196:199], v[30:33]
	v_mfma_f32_16x16x32_bf16 v[26:29], v[138:141], v[196:199], v[26:29]
	v_mfma_f32_16x16x32_bf16 v[22:25], v[130:133], v[204:207], v[22:25]
	v_mfma_f32_16x16x32_bf16 v[18:21], v[138:141], v[204:207], v[18:21]
	v_mfma_f32_16x16x32_bf16 v[62:65], v[134:137], v[166:169], v[62:65]
	v_mfma_f32_16x16x32_bf16 v[58:61], v[142:145], v[166:169], v[58:61]
	v_mfma_f32_16x16x32_bf16 v[54:57], v[134:137], v[174:177], v[54:57]
	v_mfma_f32_16x16x32_bf16 v[50:53], v[142:145], v[174:177], v[50:53]
	v_mfma_f32_16x16x32_bf16 v[30:33], v[134:137], v[200:203], v[30:33]
	v_mfma_f32_16x16x32_bf16 v[26:29], v[142:145], v[200:203], v[26:29]
	v_mfma_f32_16x16x32_bf16 v[22:25], v[134:137], v[208:211], v[22:25]
	v_mfma_f32_16x16x32_bf16 v[18:21], v[142:145], v[208:211], v[18:21]
	v_mfma_f32_16x16x32_bf16 v[46:49], v[146:149], v[162:165], v[46:49]
	v_mfma_f32_16x16x32_bf16 v[42:45], v[154:157], v[162:165], v[42:45]
	v_mfma_f32_16x16x32_bf16 v[38:41], v[146:149], v[170:173], v[38:41]
	v_mfma_f32_16x16x32_bf16 v[34:37], v[154:157], v[170:173], v[34:37]
	v_mfma_f32_16x16x32_bf16 v[14:17], v[146:149], v[196:199], v[14:17]
	v_mfma_f32_16x16x32_bf16 v[10:13], v[154:157], v[196:199], v[10:13]
	v_mfma_f32_16x16x32_bf16 v[6:9], v[146:149], v[204:207], v[6:9]
	v_mfma_f32_16x16x32_bf16 v[2:5], v[154:157], v[204:207], v[2:5]
	v_mfma_f32_16x16x32_bf16 v[46:49], v[150:153], v[166:169], v[46:49]
	v_mfma_f32_16x16x32_bf16 v[42:45], v[158:161], v[166:169], v[42:45]
	v_mfma_f32_16x16x32_bf16 v[38:41], v[150:153], v[174:177], v[38:41]
	v_mfma_f32_16x16x32_bf16 v[34:37], v[158:161], v[174:177], v[34:37]
	v_mfma_f32_16x16x32_bf16 v[14:17], v[150:153], v[200:203], v[14:17]
	v_mfma_f32_16x16x32_bf16 v[10:13], v[158:161], v[200:203], v[10:13]
	v_mfma_f32_16x16x32_bf16 v[6:9], v[150:153], v[208:211], v[6:9]
	v_mfma_f32_16x16x32_bf16 v[2:5], v[158:161], v[208:211], v[2:5]
	s_setprio 2
	s_barrier
	s_add_u32 s30, s30, 0x100
	s_addc_u32 s31, s31, 0
	s_add_u32 s23, s23, 0x100
	s_addc_u32 s29, s29, 0
	s_cmp_ge_i32 s38, s61
	s_mov_b32 s34, s38
	s_cbranch_scc0 .LBB0_357

.Lpeel_11:
	ds_read_b128 v[148:151], v145
	ds_read_b128 v[152:155], v145 offset:1024
	s_add_u32 s36, s34, 0xfff80080
	s_addc_u32 s37, s35, -1
	s_cmp_eq_u32 s58, 28
	s_cselect_b32 s39, s21, s37
	s_cselect_b32 s38, s54, s36
	s_cselect_b32 s37, s23, s57
	s_cselect_b32 s36, s55, s56
	v_lshl_add_u64 v[192:193], s[34:35], 0, v[138:139]
	s_add_i32 m0, s27, 0xc000
	global_load_lds_dwordx4 v[192:193], off
	v_lshl_add_u64 v[192:193], s[34:35], 0, v[140:141]
	s_add_i32 m0, s27, 0xe000
	s_nop 0
	global_load_lds_dwordx4 v[192:193], off
	s_waitcnt vmcnt(8)
	s_waitcnt lgkmcnt(0)
	s_barrier
	s_setprio 1
	s_waitcnt lgkmcnt(0)
	v_mfma_f32_16x16x32_bf16 v[126:129], v[148:151], v[180:183], 0
	v_mfma_f32_16x16x32_bf16 v[122:125], v[156:159], v[180:183], 0
	v_mfma_f32_16x16x32_bf16 v[118:121], v[148:151], v[188:191], 0
	v_mfma_f32_16x16x32_bf16 v[114:117], v[156:159], v[188:191], 0
	v_mfma_f32_16x16x32_bf16 v[102:105], v[148:151], v[200:203], 0
	v_mfma_f32_16x16x32_bf16 v[98:101], v[156:159], v[200:203], 0
	v_mfma_f32_16x16x32_bf16 v[86:89], v[148:151], v[208:211], 0
	v_mfma_f32_16x16x32_bf16 v[82:85], v[156:159], v[208:211], 0
	v_mfma_f32_16x16x32_bf16 v[126:129], v[152:155], v[184:187], v[126:129]
	v_mfma_f32_16x16x32_bf16 v[122:125], v[160:163], v[184:187], v[122:125]
	v_mfma_f32_16x16x32_bf16 v[118:121], v[152:155], v[196:199], v[118:121]
	v_mfma_f32_16x16x32_bf16 v[114:117], v[160:163], v[196:199], v[114:117]
	v_mfma_f32_16x16x32_bf16 v[102:105], v[152:155], v[204:207], v[102:105]
	v_mfma_f32_16x16x32_bf16 v[98:101], v[160:163], v[204:207], v[98:101]
	v_mfma_f32_16x16x32_bf16 v[86:89], v[152:155], v[212:215], v[86:89]
	v_mfma_f32_16x16x32_bf16 v[82:85], v[160:163], v[212:215], v[82:85]
	v_mfma_f32_16x16x32_bf16 v[110:113], v[164:167], v[180:183], 0
	v_mfma_f32_16x16x32_bf16 v[106:109], v[172:175], v[180:183], 0
	v_mfma_f32_16x16x32_bf16 v[94:97], v[164:167], v[188:191], 0
	v_mfma_f32_16x16x32_bf16 v[90:93], v[172:175], v[188:191], 0
	v_mfma_f32_16x16x32_bf16 v[78:81], v[164:167], v[200:203], 0
	v_mfma_f32_16x16x32_bf16 v[74:77], v[172:175], v[200:203], 0
	v_mfma_f32_16x16x32_bf16 v[70:73], v[164:167], v[208:211], 0
	v_mfma_f32_16x16x32_bf16 v[66:69], v[172:175], v[208:211], 0
	v_mfma_f32_16x16x32_bf16 v[110:113], v[168:171], v[184:187], v[110:113]
	v_mfma_f32_16x16x32_bf16 v[106:109], v[176:179], v[184:187], v[106:109]
	v_mfma_f32_16x16x32_bf16 v[94:97], v[168:171], v[196:199], v[94:97]
	v_mfma_f32_16x16x32_bf16 v[90:93], v[176:179], v[196:199], v[90:93]
	v_mfma_f32_16x16x32_bf16 v[78:81], v[168:171], v[204:207], v[78:81]
	v_mfma_f32_16x16x32_bf16 v[74:77], v[176:179], v[204:207], v[74:77]
	v_mfma_f32_16x16x32_bf16 v[70:73], v[168:171], v[212:215], v[70:73]
	v_mfma_f32_16x16x32_bf16 v[66:69], v[176:179], v[212:215], v[66:69]
	s_setprio 2
	s_barrier
	s_add_i32 s59, s47, s33
	v_lshl_add_u64 v[192:193], s[36:37], 0, v[134:135]
	s_mov_b32 m0, s59
	ds_read_b128 v[180:183], v147 offset:16384
	ds_read_b128 v[184:187], v147 offset:17408
	ds_read_b128 v[188:191], v147 offset:18432
	ds_read_b128 v[196:199], v147 offset:19456
	ds_read_b128 v[200:203], v147 offset:20480
	ds_read_b128 v[204:207], v147 offset:21504
	ds_read_b128 v[208:211], v147 offset:22528
	ds_read_b128 v[212:215], v147 offset:23552
	global_load_lds_dwordx4 v[192:193], off
	s_add_i32 m0, s59, 0x2000
	s_add_u32 s60, s36, 0x80000
	v_lshl_add_u64 v[216:217], s[36:37], 0, v[130:131]
	s_addc_u32 s61, s37, 0
	s_add_i32 s59, s48, s33
	global_load_lds_dwordx4 v[216:217], off
	v_lshl_add_u64 v[218:219], s[60:61], 0, v[134:135]
	s_mov_b32 m0, s59
	v_lshl_add_u64 v[220:221], s[38:39], 0, v[132:133]
	global_load_lds_dwordx4 v[218:219], off
	v_lshl_add_u64 v[218:219], s[60:61], 0, v[130:131]
	s_add_i32 m0, s59, 0x2000
	s_nop 0
	global_load_lds_dwordx4 v[218:219], off
	v_lshl_add_u64 v[218:219], s[38:39], 0, v[136:137]
	s_mov_b32 m0, s27
	s_nop 0
	global_load_lds_dwordx4 v[218:219], off
	s_mov_b32 m0, s41
	s_nop 0
	global_load_lds_dwordx4 v[220:221], off
	s_waitcnt vmcnt(8)
	s_waitcnt lgkmcnt(0)
	s_barrier
	s_setprio 1
	s_waitcnt lgkmcnt(0)
	v_mfma_f32_16x16x32_bf16 v[62:65], v[148:151], v[180:183], 0
	v_mfma_f32_16x16x32_bf16 v[58:61], v[156:159], v[180:183], 0
	v_mfma_f32_16x16x32_bf16 v[54:57], v[148:151], v[188:191], 0
	v_mfma_f32_16x16x32_bf16 v[50:53], v[156:159], v[188:191], 0
	v_mfma_f32_16x16x32_bf16 v[38:41], v[148:151], v[200:203], 0
	v_mfma_f32_16x16x32_bf16 v[34:37], v[156:159], v[200:203], 0
	v_mfma_f32_16x16x32_bf16 v[22:25], v[148:151], v[208:211], 0
	v_mfma_f32_16x16x32_bf16 v[18:21], v[156:159], v[208:211], 0
	v_mfma_f32_16x16x32_bf16 v[62:65], v[152:155], v[184:187], v[62:65]
	v_mfma_f32_16x16x32_bf16 v[58:61], v[160:163], v[184:187], v[58:61]
	v_mfma_f32_16x16x32_bf16 v[54:57], v[152:155], v[196:199], v[54:57]
	v_mfma_f32_16x16x32_bf16 v[50:53], v[160:163], v[196:199], v[50:53]
	v_mfma_f32_16x16x32_bf16 v[38:41], v[152:155], v[204:207], v[38:41]
	v_mfma_f32_16x16x32_bf16 v[34:37], v[160:163], v[204:207], v[34:37]
	v_mfma_f32_16x16x32_bf16 v[22:25], v[152:155], v[212:215], v[22:25]
	v_mfma_f32_16x16x32_bf16 v[18:21], v[160:163], v[212:215], v[18:21]
	v_mfma_f32_16x16x32_bf16 v[46:49], v[164:167], v[180:183], 0
	v_mfma_f32_16x16x32_bf16 v[42:45], v[172:175], v[180:183], 0
	v_mfma_f32_16x16x32_bf16 v[30:33], v[164:167], v[188:191], 0
	v_mfma_f32_16x16x32_bf16 v[26:29], v[172:175], v[188:191], 0
	v_mfma_f32_16x16x32_bf16 v[14:17], v[164:167], v[200:203], 0
	v_mfma_f32_16x16x32_bf16 v[10:13], v[172:175], v[200:203], 0
	v_mfma_f32_16x16x32_bf16 v[6:9], v[164:167], v[208:211], 0
	v_mfma_f32_16x16x32_bf16 v[2:5], v[172:175], v[208:211], 0
	v_mfma_f32_16x16x32_bf16 v[46:49], v[168:171], v[184:187], v[46:49]
	v_mfma_f32_16x16x32_bf16 v[42:45], v[176:179], v[184:187], v[42:45]
	v_mfma_f32_16x16x32_bf16 v[30:33], v[168:171], v[196:199], v[30:33]
	v_mfma_f32_16x16x32_bf16 v[26:29], v[176:179], v[196:199], v[26:29]
	v_mfma_f32_16x16x32_bf16 v[14:17], v[168:171], v[204:207], v[14:17]
	v_mfma_f32_16x16x32_bf16 v[10:13], v[176:179], v[204:207], v[10:13]
	v_mfma_f32_16x16x32_bf16 v[6:9], v[168:171], v[212:215], v[6:9]
	v_mfma_f32_16x16x32_bf16 v[2:5], v[176:179], v[212:215], v[2:5]
	s_setprio 2
	s_barrier
	s_add_i32 s59, 0, 0x18000
	s_add_i32 s60, 0, 0x1c000
	v_add_u32_e32 v160, s59, v143
	v_add_u32_e32 v176, s60, v143
	ds_read_b128 v[148:151], v160
	ds_read_b128 v[152:155], v160 offset:1024
	ds_read_b128 v[156:159], v160 offset:2048
	ds_read_b128 v[160:163], v160 offset:3072
	ds_read_b128 v[164:167], v176
	ds_read_b128 v[168:171], v176 offset:1024
	ds_read_b128 v[172:175], v176 offset:2048
	ds_read_b128 v[176:179], v176 offset:3072
	s_add_u32 s38, s38, 0x80000
	s_addc_u32 s39, s39, 0
	s_mov_b32 m0, s42
	v_lshl_add_u64 v[222:223], s[38:39], 0, v[136:137]
	ds_read_b128 v[180:183], v147 offset:32768
	ds_read_b128 v[184:187], v147 offset:33792
	ds_read_b128 v[188:191], v147 offset:34816
	ds_read_b128 v[196:199], v147 offset:35840
	ds_read_b128 v[200:203], v147 offset:36864
	ds_read_b128 v[204:207], v147 offset:37888
	ds_read_b128 v[208:211], v147 offset:38912
	ds_read_b128 v[212:215], v147 offset:39936
	global_load_lds_dwordx4 v[222:223], off
	v_lshl_add_u64 v[222:223], s[38:39], 0, v[132:133]
	s_mov_b32 m0, s43
	s_nop 0
	global_load_lds_dwordx4 v[222:223], off
	s_waitcnt vmcnt(8)
	s_waitcnt lgkmcnt(0)
	s_barrier
	s_setprio 1
	s_waitcnt lgkmcnt(0)
	v_mfma_f32_16x16x32_bf16 v[126:129], v[148:151], v[180:183], v[126:129]
	v_mfma_f32_16x16x32_bf16 v[122:125], v[156:159], v[180:183], v[122:125]
	v_mfma_f32_16x16x32_bf16 v[118:121], v[148:151], v[188:191], v[118:121]
	v_mfma_f32_16x16x32_bf16 v[114:117], v[156:159], v[188:191], v[114:117]
	v_mfma_f32_16x16x32_bf16 v[102:105], v[148:151], v[200:203], v[102:105]
	v_mfma_f32_16x16x32_bf16 v[98:101], v[156:159], v[200:203], v[98:101]
	v_mfma_f32_16x16x32_bf16 v[86:89], v[148:151], v[208:211], v[86:89]
	v_mfma_f32_16x16x32_bf16 v[82:85], v[156:159], v[208:211], v[82:85]
	v_mfma_f32_16x16x32_bf16 v[126:129], v[152:155], v[184:187], v[126:129]
	v_mfma_f32_16x16x32_bf16 v[122:125], v[160:163], v[184:187], v[122:125]
	v_mfma_f32_16x16x32_bf16 v[118:121], v[152:155], v[196:199], v[118:121]
	v_mfma_f32_16x16x32_bf16 v[114:117], v[160:163], v[196:199], v[114:117]
	v_mfma_f32_16x16x32_bf16 v[102:105], v[152:155], v[204:207], v[102:105]
	v_mfma_f32_16x16x32_bf16 v[98:101], v[160:163], v[204:207], v[98:101]
	v_mfma_f32_16x16x32_bf16 v[86:89], v[152:155], v[212:215], v[86:89]
	v_mfma_f32_16x16x32_bf16 v[82:85], v[160:163], v[212:215], v[82:85]
	v_mfma_f32_16x16x32_bf16 v[110:113], v[164:167], v[180:183], v[110:113]
	v_mfma_f32_16x16x32_bf16 v[106:109], v[172:175], v[180:183], v[106:109]
	v_mfma_f32_16x16x32_bf16 v[94:97], v[164:167], v[188:191], v[94:97]
	v_mfma_f32_16x16x32_bf16 v[90:93], v[172:175], v[188:191], v[90:93]
	v_mfma_f32_16x16x32_bf16 v[78:81], v[164:167], v[200:203], v[78:81]
	v_mfma_f32_16x16x32_bf16 v[74:77], v[172:175], v[200:203], v[74:77]
	v_mfma_f32_16x16x32_bf16 v[70:73], v[164:167], v[208:211], v[70:73]
	v_mfma_f32_16x16x32_bf16 v[66:69], v[172:175], v[208:211], v[66:69]
	v_mfma_f32_16x16x32_bf16 v[110:113], v[168:171], v[184:187], v[110:113]
	v_mfma_f32_16x16x32_bf16 v[106:109], v[176:179], v[184:187], v[106:109]
	v_mfma_f32_16x16x32_bf16 v[94:97], v[168:171], v[196:199], v[94:97]
	v_mfma_f32_16x16x32_bf16 v[90:93], v[176:179], v[196:199], v[90:93]
	v_mfma_f32_16x16x32_bf16 v[78:81], v[168:171], v[204:207], v[78:81]
	v_mfma_f32_16x16x32_bf16 v[74:77], v[176:179], v[204:207], v[74:77]
	v_mfma_f32_16x16x32_bf16 v[70:73], v[168:171], v[212:215], v[70:73]
	v_mfma_f32_16x16x32_bf16 v[66:69], v[176:179], v[212:215], v[66:69]
	s_setprio 2
	s_barrier
	s_add_i32 s38, s59, s33
	v_lshl_add_u64 v[192:193], v[192:193], 0, s[6:7]
	s_mov_b32 m0, s38
	ds_read_b128 v[180:183], v147 offset:49152
	ds_read_b128 v[184:187], v147 offset:50176
	ds_read_b128 v[188:191], v147 offset:51200
	ds_read_b128 v[196:199], v147 offset:52224
	ds_read_b128 v[200:203], v147 offset:53248
	ds_read_b128 v[204:207], v147 offset:54272
	ds_read_b128 v[208:211], v147 offset:55296
	ds_read_b128 v[212:215], v147 offset:56320
	global_load_lds_dwordx4 v[192:193], off
	s_add_i32 m0, s38, 0x2000
	s_add_u32 s36, s36, 0x80080
	v_lshl_add_u64 v[192:193], v[216:217], 0, s[6:7]
	s_addc_u32 s37, s37, 0
	s_add_i32 s38, s60, s33
	global_load_lds_dwordx4 v[192:193], off
	v_lshl_add_u64 v[192:193], s[36:37], 0, v[134:135]
	s_mov_b32 m0, s38
	s_nop 0
	global_load_lds_dwordx4 v[192:193], off
	v_lshl_add_u64 v[192:193], s[36:37], 0, v[130:131]
	s_add_i32 m0, s38, 0x2000
	s_nop 0
	global_load_lds_dwordx4 v[192:193], off
	v_lshl_add_u64 v[192:193], v[218:219], 0, s[6:7]
	s_mov_b32 m0, s45
	s_nop 0
	global_load_lds_dwordx4 v[192:193], off
	v_lshl_add_u64 v[192:193], v[220:221], 0, s[6:7]
	s_mov_b32 m0, s46
	s_nop 0
	global_load_lds_dwordx4 v[192:193], off
	s_waitcnt vmcnt(8)
	s_waitcnt lgkmcnt(0)
	s_barrier
	s_setprio 1
	s_waitcnt lgkmcnt(0)
	v_mfma_f32_16x16x32_bf16 v[62:65], v[148:151], v[180:183], v[62:65]
	v_mfma_f32_16x16x32_bf16 v[58:61], v[156:159], v[180:183], v[58:61]
	v_mfma_f32_16x16x32_bf16 v[54:57], v[148:151], v[188:191], v[54:57]
	v_mfma_f32_16x16x32_bf16 v[50:53], v[156:159], v[188:191], v[50:53]
	v_mfma_f32_16x16x32_bf16 v[38:41], v[148:151], v[200:203], v[38:41]
	v_mfma_f32_16x16x32_bf16 v[34:37], v[156:159], v[200:203], v[34:37]
	v_mfma_f32_16x16x32_bf16 v[22:25], v[148:151], v[208:211], v[22:25]
	v_mfma_f32_16x16x32_bf16 v[18:21], v[156:159], v[208:211], v[18:21]
	v_mfma_f32_16x16x32_bf16 v[62:65], v[152:155], v[184:187], v[62:65]
	v_mfma_f32_16x16x32_bf16 v[58:61], v[160:163], v[184:187], v[58:61]
	v_mfma_f32_16x16x32_bf16 v[54:57], v[152:155], v[196:199], v[54:57]
	v_mfma_f32_16x16x32_bf16 v[50:53], v[160:163], v[196:199], v[50:53]
	v_mfma_f32_16x16x32_bf16 v[38:41], v[152:155], v[204:207], v[38:41]
	v_mfma_f32_16x16x32_bf16 v[34:37], v[160:163], v[204:207], v[34:37]
	v_mfma_f32_16x16x32_bf16 v[22:25], v[152:155], v[212:215], v[22:25]
	v_mfma_f32_16x16x32_bf16 v[18:21], v[160:163], v[212:215], v[18:21]
	v_mfma_f32_16x16x32_bf16 v[46:49], v[164:167], v[180:183], v[46:49]
	v_mfma_f32_16x16x32_bf16 v[42:45], v[172:175], v[180:183], v[42:45]
	v_mfma_f32_16x16x32_bf16 v[30:33], v[164:167], v[188:191], v[30:33]
	v_mfma_f32_16x16x32_bf16 v[26:29], v[172:175], v[188:191], v[26:29]
	v_mfma_f32_16x16x32_bf16 v[14:17], v[164:167], v[200:203], v[14:17]
	v_mfma_f32_16x16x32_bf16 v[10:13], v[172:175], v[200:203], v[10:13]
	v_mfma_f32_16x16x32_bf16 v[6:9], v[164:167], v[208:211], v[6:9]
	v_mfma_f32_16x16x32_bf16 v[2:5], v[172:175], v[208:211], v[2:5]
	v_mfma_f32_16x16x32_bf16 v[46:49], v[168:171], v[184:187], v[46:49]
	v_mfma_f32_16x16x32_bf16 v[42:45], v[176:179], v[184:187], v[42:45]
	v_mfma_f32_16x16x32_bf16 v[30:33], v[168:171], v[196:199], v[30:33]
	v_mfma_f32_16x16x32_bf16 v[26:29], v[176:179], v[196:199], v[26:29]
	v_mfma_f32_16x16x32_bf16 v[14:17], v[168:171], v[204:207], v[14:17]
	v_mfma_f32_16x16x32_bf16 v[10:13], v[176:179], v[204:207], v[10:13]
	v_mfma_f32_16x16x32_bf16 v[6:9], v[168:171], v[212:215], v[6:9]
	v_mfma_f32_16x16x32_bf16 v[2:5], v[176:179], v[212:215], v[2:5]
	s_setprio 2
	s_barrier
	s_add_i32 s58, s58, 2
	s_add_u32 s34, s34, 0x100
	s_addc_u32 s35, s35, 0
	s_add_u32 s56, s56, 0x100
	s_addc_u32 s57, s57, 0
	s_cmp_gt_u32 s58, 29
	s_cbranch_scc0 .LBB0_541
	s_branch .Lpeeldone_11
.LBB0_541:
	ds_read_b128 v[148:151], v145
	ds_read_b128 v[152:155], v145 offset:1024
	ds_read_b128 v[156:159], v145 offset:2048
	ds_read_b128 v[160:163], v145 offset:3072
	ds_read_b128 v[164:167], v146
	ds_read_b128 v[168:171], v146 offset:1024
	ds_read_b128 v[172:175], v146 offset:2048
	ds_read_b128 v[176:179], v146 offset:3072
	s_add_u32 s36, s34, 0xfff80080
	s_addc_u32 s37, s35, -1
	s_cmp_eq_u32 s58, 28
	s_cselect_b32 s39, s21, s37
	s_cselect_b32 s38, s54, s36
	s_cselect_b32 s37, s23, s57
	s_cselect_b32 s36, s55, s56
	v_lshl_add_u64 v[192:193], s[34:35], 0, v[138:139]
	s_add_i32 m0, s27, 0xc000
	ds_read_b128 v[180:183], v147
	ds_read_b128 v[184:187], v147 offset:1024
	ds_read_b128 v[188:191], v147 offset:2048
	ds_read_b128 v[196:199], v147 offset:3072
	ds_read_b128 v[200:203], v147 offset:4096
	ds_read_b128 v[204:207], v147 offset:5120
	ds_read_b128 v[208:211], v147 offset:6144
	ds_read_b128 v[212:215], v147 offset:7168
	global_load_lds_dwordx4 v[192:193], off
	v_lshl_add_u64 v[192:193], s[34:35], 0, v[140:141]
	s_add_i32 m0, s27, 0xe000
	s_nop 0
	global_load_lds_dwordx4 v[192:193], off
	s_waitcnt vmcnt(8)
	s_waitcnt lgkmcnt(0)
	s_barrier
	s_setprio 1
	s_waitcnt lgkmcnt(0)
	v_mfma_f32_16x16x32_bf16 v[126:129], v[148:151], v[180:183], v[126:129]
	v_mfma_f32_16x16x32_bf16 v[122:125], v[156:159], v[180:183], v[122:125]
	v_mfma_f32_16x16x32_bf16 v[118:121], v[148:151], v[188:191], v[118:121]
	v_mfma_f32_16x16x32_bf16 v[114:117], v[156:159], v[188:191], v[114:117]
	v_mfma_f32_16x16x32_bf16 v[102:105], v[148:151], v[200:203], v[102:105]
	v_mfma_f32_16x16x32_bf16 v[98:101], v[156:159], v[200:203], v[98:101]
	v_mfma_f32_16x16x32_bf16 v[86:89], v[148:151], v[208:211], v[86:89]
	v_mfma_f32_16x16x32_bf16 v[82:85], v[156:159], v[208:211], v[82:85]
	v_mfma_f32_16x16x32_bf16 v[126:129], v[152:155], v[184:187], v[126:129]
	v_mfma_f32_16x16x32_bf16 v[122:125], v[160:163], v[184:187], v[122:125]
	v_mfma_f32_16x16x32_bf16 v[118:121], v[152:155], v[196:199], v[118:121]
	v_mfma_f32_16x16x32_bf16 v[114:117], v[160:163], v[196:199], v[114:117]
	v_mfma_f32_16x16x32_bf16 v[102:105], v[152:155], v[204:207], v[102:105]
	v_mfma_f32_16x16x32_bf16 v[98:101], v[160:163], v[204:207], v[98:101]
	v_mfma_f32_16x16x32_bf16 v[86:89], v[152:155], v[212:215], v[86:89]
	v_mfma_f32_16x16x32_bf16 v[82:85], v[160:163], v[212:215], v[82:85]
	v_mfma_f32_16x16x32_bf16 v[110:113], v[164:167], v[180:183], v[110:113]
	v_mfma_f32_16x16x32_bf16 v[106:109], v[172:175], v[180:183], v[106:109]
	v_mfma_f32_16x16x32_bf16 v[94:97], v[164:167], v[188:191], v[94:97]
	v_mfma_f32_16x16x32_bf16 v[90:93], v[172:175], v[188:191], v[90:93]
	v_mfma_f32_16x16x32_bf16 v[78:81], v[164:167], v[200:203], v[78:81]
	v_mfma_f32_16x16x32_bf16 v[74:77], v[172:175], v[200:203], v[74:77]
	v_mfma_f32_16x16x32_bf16 v[70:73], v[164:167], v[208:211], v[70:73]
	v_mfma_f32_16x16x32_bf16 v[66:69], v[172:175], v[208:211], v[66:69]
	v_mfma_f32_16x16x32_bf16 v[110:113], v[168:171], v[184:187], v[110:113]
	v_mfma_f32_16x16x32_bf16 v[106:109], v[176:179], v[184:187], v[106:109]
	v_mfma_f32_16x16x32_bf16 v[94:97], v[168:171], v[196:199], v[94:97]
	v_mfma_f32_16x16x32_bf16 v[90:93], v[176:179], v[196:199], v[90:93]
	v_mfma_f32_16x16x32_bf16 v[78:81], v[168:171], v[204:207], v[78:81]
	v_mfma_f32_16x16x32_bf16 v[74:77], v[176:179], v[204:207], v[74:77]
	v_mfma_f32_16x16x32_bf16 v[70:73], v[168:171], v[212:215], v[70:73]
	v_mfma_f32_16x16x32_bf16 v[66:69], v[176:179], v[212:215], v[66:69]
	s_setprio 2
	s_barrier
	s_add_i32 s59, s47, s33
	v_lshl_add_u64 v[192:193], s[36:37], 0, v[134:135]
	s_mov_b32 m0, s59
	ds_read_b128 v[180:183], v147 offset:16384
	ds_read_b128 v[184:187], v147 offset:17408
	ds_read_b128 v[188:191], v147 offset:18432
	ds_read_b128 v[196:199], v147 offset:19456
	ds_read_b128 v[200:203], v147 offset:20480
	ds_read_b128 v[204:207], v147 offset:21504
	ds_read_b128 v[208:211], v147 offset:22528
	ds_read_b128 v[212:215], v147 offset:23552
	global_load_lds_dwordx4 v[192:193], off
	s_add_i32 m0, s59, 0x2000
	s_add_u32 s60, s36, 0x80000
	v_lshl_add_u64 v[216:217], s[36:37], 0, v[130:131]
	s_addc_u32 s61, s37, 0
	s_add_i32 s59, s48, s33
	global_load_lds_dwordx4 v[216:217], off
	v_lshl_add_u64 v[218:219], s[60:61], 0, v[134:135]
	s_mov_b32 m0, s59
	v_lshl_add_u64 v[220:221], s[38:39], 0, v[132:133]
	global_load_lds_dwordx4 v[218:219], off
	v_lshl_add_u64 v[218:219], s[60:61], 0, v[130:131]
	s_add_i32 m0, s59, 0x2000
	s_nop 0
	global_load_lds_dwordx4 v[218:219], off
	v_lshl_add_u64 v[218:219], s[38:39], 0, v[136:137]
	s_mov_b32 m0, s27
	s_nop 0
	global_load_lds_dwordx4 v[218:219], off
	s_mov_b32 m0, s41
	s_nop 0
	global_load_lds_dwordx4 v[220:221], off
	s_waitcnt vmcnt(8)
	s_waitcnt lgkmcnt(0)
	s_barrier
	s_setprio 1
	s_waitcnt lgkmcnt(0)
	v_mfma_f32_16x16x32_bf16 v[62:65], v[148:151], v[180:183], v[62:65]
	v_mfma_f32_16x16x32_bf16 v[58:61], v[156:159], v[180:183], v[58:61]
	v_mfma_f32_16x16x32_bf16 v[54:57], v[148:151], v[188:191], v[54:57]
	v_mfma_f32_16x16x32_bf16 v[50:53], v[156:159], v[188:191], v[50:53]
	v_mfma_f32_16x16x32_bf16 v[38:41], v[148:151], v[200:203], v[38:41]
	v_mfma_f32_16x16x32_bf16 v[34:37], v[156:159], v[200:203], v[34:37]
	v_mfma_f32_16x16x32_bf16 v[22:25], v[148:151], v[208:211], v[22:25]
	v_mfma_f32_16x16x32_bf16 v[18:21], v[156:159], v[208:211], v[18:21]
	v_mfma_f32_16x16x32_bf16 v[62:65], v[152:155], v[184:187], v[62:65]
	v_mfma_f32_16x16x32_bf16 v[58:61], v[160:163], v[184:187], v[58:61]
	v_mfma_f32_16x16x32_bf16 v[54:57], v[152:155], v[196:199], v[54:57]
	v_mfma_f32_16x16x32_bf16 v[50:53], v[160:163], v[196:199], v[50:53]
	v_mfma_f32_16x16x32_bf16 v[38:41], v[152:155], v[204:207], v[38:41]
	v_mfma_f32_16x16x32_bf16 v[34:37], v[160:163], v[204:207], v[34:37]
	v_mfma_f32_16x16x32_bf16 v[22:25], v[152:155], v[212:215], v[22:25]
	v_mfma_f32_16x16x32_bf16 v[18:21], v[160:163], v[212:215], v[18:21]
	v_mfma_f32_16x16x32_bf16 v[46:49], v[164:167], v[180:183], v[46:49]
	v_mfma_f32_16x16x32_bf16 v[42:45], v[172:175], v[180:183], v[42:45]
	v_mfma_f32_16x16x32_bf16 v[30:33], v[164:167], v[188:191], v[30:33]
	v_mfma_f32_16x16x32_bf16 v[26:29], v[172:175], v[188:191], v[26:29]
	v_mfma_f32_16x16x32_bf16 v[14:17], v[164:167], v[200:203], v[14:17]
	v_mfma_f32_16x16x32_bf16 v[10:13], v[172:175], v[200:203], v[10:13]
	v_mfma_f32_16x16x32_bf16 v[6:9], v[164:167], v[208:211], v[6:9]
	v_mfma_f32_16x16x32_bf16 v[2:5], v[172:175], v[208:211], v[2:5]
	v_mfma_f32_16x16x32_bf16 v[46:49], v[168:171], v[184:187], v[46:49]
	v_mfma_f32_16x16x32_bf16 v[42:45], v[176:179], v[184:187], v[42:45]
	v_mfma_f32_16x16x32_bf16 v[30:33], v[168:171], v[196:199], v[30:33]
	v_mfma_f32_16x16x32_bf16 v[26:29], v[176:179], v[196:199], v[26:29]
	v_mfma_f32_16x16x32_bf16 v[14:17], v[168:171], v[204:207], v[14:17]
	v_mfma_f32_16x16x32_bf16 v[10:13], v[176:179], v[204:207], v[10:13]
	v_mfma_f32_16x16x32_bf16 v[6:9], v[168:171], v[212:215], v[6:9]
	v_mfma_f32_16x16x32_bf16 v[2:5], v[176:179], v[212:215], v[2:5]
	s_setprio 2
	s_barrier
	s_add_i32 s59, 0, 0x18000
	s_add_i32 s60, 0, 0x1c000
	v_add_u32_e32 v160, s59, v143
	v_add_u32_e32 v176, s60, v143
	ds_read_b128 v[148:151], v160
	ds_read_b128 v[152:155], v160 offset:1024
	ds_read_b128 v[156:159], v160 offset:2048
	ds_read_b128 v[160:163], v160 offset:3072
	ds_read_b128 v[164:167], v176
	ds_read_b128 v[168:171], v176 offset:1024
	ds_read_b128 v[172:175], v176 offset:2048
	ds_read_b128 v[176:179], v176 offset:3072
	s_add_u32 s38, s38, 0x80000
	s_addc_u32 s39, s39, 0
	s_mov_b32 m0, s42
	v_lshl_add_u64 v[222:223], s[38:39], 0, v[136:137]
	ds_read_b128 v[180:183], v147 offset:32768
	ds_read_b128 v[184:187], v147 offset:33792
	ds_read_b128 v[188:191], v147 offset:34816
	ds_read_b128 v[196:199], v147 offset:35840
	ds_read_b128 v[200:203], v147 offset:36864
	ds_read_b128 v[204:207], v147 offset:37888
	ds_read_b128 v[208:211], v147 offset:38912
	ds_read_b128 v[212:215], v147 offset:39936
	global_load_lds_dwordx4 v[222:223], off
	v_lshl_add_u64 v[222:223], s[38:39], 0, v[132:133]
	s_mov_b32 m0, s43
	s_nop 0
	global_load_lds_dwordx4 v[222:223], off
	s_waitcnt vmcnt(8)
	s_waitcnt lgkmcnt(0)
	s_barrier
	s_setprio 1
	s_waitcnt lgkmcnt(0)
	v_mfma_f32_16x16x32_bf16 v[126:129], v[148:151], v[180:183], v[126:129]
	v_mfma_f32_16x16x32_bf16 v[122:125], v[156:159], v[180:183], v[122:125]
	v_mfma_f32_16x16x32_bf16 v[118:121], v[148:151], v[188:191], v[118:121]
	v_mfma_f32_16x16x32_bf16 v[114:117], v[156:159], v[188:191], v[114:117]
	v_mfma_f32_16x16x32_bf16 v[102:105], v[148:151], v[200:203], v[102:105]
	v_mfma_f32_16x16x32_bf16 v[98:101], v[156:159], v[200:203], v[98:101]
	v_mfma_f32_16x16x32_bf16 v[86:89], v[148:151], v[208:211], v[86:89]
	v_mfma_f32_16x16x32_bf16 v[82:85], v[156:159], v[208:211], v[82:85]
	v_mfma_f32_16x16x32_bf16 v[126:129], v[152:155], v[184:187], v[126:129]
	v_mfma_f32_16x16x32_bf16 v[122:125], v[160:163], v[184:187], v[122:125]
	v_mfma_f32_16x16x32_bf16 v[118:121], v[152:155], v[196:199], v[118:121]
	v_mfma_f32_16x16x32_bf16 v[114:117], v[160:163], v[196:199], v[114:117]
	v_mfma_f32_16x16x32_bf16 v[102:105], v[152:155], v[204:207], v[102:105]
	v_mfma_f32_16x16x32_bf16 v[98:101], v[160:163], v[204:207], v[98:101]
	v_mfma_f32_16x16x32_bf16 v[86:89], v[152:155], v[212:215], v[86:89]
	v_mfma_f32_16x16x32_bf16 v[82:85], v[160:163], v[212:215], v[82:85]
	v_mfma_f32_16x16x32_bf16 v[110:113], v[164:167], v[180:183], v[110:113]
	v_mfma_f32_16x16x32_bf16 v[106:109], v[172:175], v[180:183], v[106:109]
	v_mfma_f32_16x16x32_bf16 v[94:97], v[164:167], v[188:191], v[94:97]
	v_mfma_f32_16x16x32_bf16 v[90:93], v[172:175], v[188:191], v[90:93]
	v_mfma_f32_16x16x32_bf16 v[78:81], v[164:167], v[200:203], v[78:81]
	v_mfma_f32_16x16x32_bf16 v[74:77], v[172:175], v[200:203], v[74:77]
	v_mfma_f32_16x16x32_bf16 v[70:73], v[164:167], v[208:211], v[70:73]
	v_mfma_f32_16x16x32_bf16 v[66:69], v[172:175], v[208:211], v[66:69]
	v_mfma_f32_16x16x32_bf16 v[110:113], v[168:171], v[184:187], v[110:113]
	v_mfma_f32_16x16x32_bf16 v[106:109], v[176:179], v[184:187], v[106:109]
	v_mfma_f32_16x16x32_bf16 v[94:97], v[168:171], v[196:199], v[94:97]
	v_mfma_f32_16x16x32_bf16 v[90:93], v[176:179], v[196:199], v[90:93]
	v_mfma_f32_16x16x32_bf16 v[78:81], v[168:171], v[204:207], v[78:81]
	v_mfma_f32_16x16x32_bf16 v[74:77], v[176:179], v[204:207], v[74:77]
	v_mfma_f32_16x16x32_bf16 v[70:73], v[168:171], v[212:215], v[70:73]
	v_mfma_f32_16x16x32_bf16 v[66:69], v[176:179], v[212:215], v[66:69]
	s_setprio 2
	s_barrier
	s_add_i32 s38, s59, s33
	v_lshl_add_u64 v[192:193], v[192:193], 0, s[6:7]
	s_mov_b32 m0, s38
	ds_read_b128 v[180:183], v147 offset:49152
	ds_read_b128 v[184:187], v147 offset:50176
	ds_read_b128 v[188:191], v147 offset:51200
	ds_read_b128 v[196:199], v147 offset:52224
	ds_read_b128 v[200:203], v147 offset:53248
	ds_read_b128 v[204:207], v147 offset:54272
	ds_read_b128 v[208:211], v147 offset:55296
	ds_read_b128 v[212:215], v147 offset:56320
	global_load_lds_dwordx4 v[192:193], off
	s_add_i32 m0, s38, 0x2000
	s_add_u32 s36, s36, 0x80080
	v_lshl_add_u64 v[192:193], v[216:217], 0, s[6:7]
	s_addc_u32 s37, s37, 0
	s_add_i32 s38, s60, s33
	global_load_lds_dwordx4 v[192:193], off
	v_lshl_add_u64 v[192:193], s[36:37], 0, v[134:135]
	s_mov_b32 m0, s38
	s_nop 0
	global_load_lds_dwordx4 v[192:193], off
	v_lshl_add_u64 v[192:193], s[36:37], 0, v[130:131]
	s_add_i32 m0, s38, 0x2000
	s_nop 0
	global_load_lds_dwordx4 v[192:193], off
	v_lshl_add_u64 v[192:193], v[218:219], 0, s[6:7]
	s_mov_b32 m0, s45
	s_nop 0
	global_load_lds_dwordx4 v[192:193], off
	v_lshl_add_u64 v[192:193], v[220:221], 0, s[6:7]
	s_mov_b32 m0, s46
	s_nop 0
	global_load_lds_dwordx4 v[192:193], off
	s_waitcnt vmcnt(8)
	s_waitcnt lgkmcnt(0)
	s_barrier
	s_setprio 1
	s_waitcnt lgkmcnt(0)
	v_mfma_f32_16x16x32_bf16 v[62:65], v[148:151], v[180:183], v[62:65]
	v_mfma_f32_16x16x32_bf16 v[58:61], v[156:159], v[180:183], v[58:61]
	v_mfma_f32_16x16x32_bf16 v[54:57], v[148:151], v[188:191], v[54:57]
	v_mfma_f32_16x16x32_bf16 v[50:53], v[156:159], v[188:191], v[50:53]
	v_mfma_f32_16x16x32_bf16 v[38:41], v[148:151], v[200:203], v[38:41]
	v_mfma_f32_16x16x32_bf16 v[34:37], v[156:159], v[200:203], v[34:37]
	v_mfma_f32_16x16x32_bf16 v[22:25], v[148:151], v[208:211], v[22:25]
	v_mfma_f32_16x16x32_bf16 v[18:21], v[156:159], v[208:211], v[18:21]
	v_mfma_f32_16x16x32_bf16 v[62:65], v[152:155], v[184:187], v[62:65]
	v_mfma_f32_16x16x32_bf16 v[58:61], v[160:163], v[184:187], v[58:61]
	v_mfma_f32_16x16x32_bf16 v[54:57], v[152:155], v[196:199], v[54:57]
	v_mfma_f32_16x16x32_bf16 v[50:53], v[160:163], v[196:199], v[50:53]
	v_mfma_f32_16x16x32_bf16 v[38:41], v[152:155], v[204:207], v[38:41]
	v_mfma_f32_16x16x32_bf16 v[34:37], v[160:163], v[204:207], v[34:37]
	v_mfma_f32_16x16x32_bf16 v[22:25], v[152:155], v[212:215], v[22:25]
	v_mfma_f32_16x16x32_bf16 v[18:21], v[160:163], v[212:215], v[18:21]
	v_mfma_f32_16x16x32_bf16 v[46:49], v[164:167], v[180:183], v[46:49]
	v_mfma_f32_16x16x32_bf16 v[42:45], v[172:175], v[180:183], v[42:45]
	v_mfma_f32_16x16x32_bf16 v[30:33], v[164:167], v[188:191], v[30:33]
	v_mfma_f32_16x16x32_bf16 v[26:29], v[172:175], v[188:191], v[26:29]
	v_mfma_f32_16x16x32_bf16 v[14:17], v[164:167], v[200:203], v[14:17]
	v_mfma_f32_16x16x32_bf16 v[10:13], v[172:175], v[200:203], v[10:13]
	v_mfma_f32_16x16x32_bf16 v[6:9], v[164:167], v[208:211], v[6:9]
	v_mfma_f32_16x16x32_bf16 v[2:5], v[172:175], v[208:211], v[2:5]
	v_mfma_f32_16x16x32_bf16 v[46:49], v[168:171], v[184:187], v[46:49]
	v_mfma_f32_16x16x32_bf16 v[42:45], v[176:179], v[184:187], v[42:45]
	v_mfma_f32_16x16x32_bf16 v[30:33], v[168:171], v[196:199], v[30:33]
	v_mfma_f32_16x16x32_bf16 v[26:29], v[176:179], v[196:199], v[26:29]
	v_mfma_f32_16x16x32_bf16 v[14:17], v[168:171], v[204:207], v[14:17]
	v_mfma_f32_16x16x32_bf16 v[10:13], v[176:179], v[204:207], v[10:13]
	v_mfma_f32_16x16x32_bf16 v[6:9], v[168:171], v[212:215], v[6:9]
	v_mfma_f32_16x16x32_bf16 v[2:5], v[176:179], v[212:215], v[2:5]
	s_setprio 2
	s_barrier
	s_add_i32 s58, s58, 2
	s_add_u32 s34, s34, 0x100
	s_addc_u32 s35, s35, 0
	s_add_u32 s56, s56, 0x100
	s_addc_u32 s57, s57, 0
	s_cmp_gt_u32 s58, 29
	s_cbranch_scc0 .LBB0_541

.Lpeel_10:
	ds_read_b128 v[150:153], v147
	ds_read_b128 v[154:157], v147 offset:1024
	s_add_u32 s28, s26, 0xfffe0080
	s_addc_u32 s29, s27, -1
	s_cmp_eq_u32 s50, 4
	s_cselect_b32 s31, s13, s29
	s_cselect_b32 s30, s46, s28
	s_cselect_b32 s29, s17, s49
	s_cselect_b32 s28, s47, s48
	v_lshl_add_u64 v[202:203], s[26:27], 0, v[138:139]
	s_add_i32 m0, s36, 0xc000
	global_load_lds_dwordx4 v[202:203], off
	v_lshl_add_u64 v[202:203], s[26:27], 0, v[140:141]
	s_add_i32 m0, s36, 0xe000
	s_nop 0
	global_load_lds_dwordx4 v[202:203], off
	s_waitcnt vmcnt(8)
	s_waitcnt lgkmcnt(0)
	s_barrier
	s_setprio 1
	s_waitcnt lgkmcnt(0)
	v_mfma_f32_16x16x32_bf16 v[126:129], v[150:153], v[182:185], 0
	v_mfma_f32_16x16x32_bf16 v[122:125], v[158:161], v[182:185], 0
	v_mfma_f32_16x16x32_bf16 v[118:121], v[150:153], v[190:193], 0
	v_mfma_f32_16x16x32_bf16 v[114:117], v[158:161], v[190:193], 0
	v_mfma_f32_16x16x32_bf16 v[102:105], v[150:153], v[210:213], 0
	v_mfma_f32_16x16x32_bf16 v[98:101], v[158:161], v[210:213], 0
	v_mfma_f32_16x16x32_bf16 v[86:89], v[150:153], v[218:221], 0
	v_mfma_f32_16x16x32_bf16 v[82:85], v[158:161], v[218:221], 0
	v_mfma_f32_16x16x32_bf16 v[126:129], v[154:157], v[186:189], v[126:129]
	v_mfma_f32_16x16x32_bf16 v[122:125], v[162:165], v[186:189], v[122:125]
	v_mfma_f32_16x16x32_bf16 v[118:121], v[154:157], v[198:201], v[118:121]
	v_mfma_f32_16x16x32_bf16 v[114:117], v[162:165], v[198:201], v[114:117]
	v_mfma_f32_16x16x32_bf16 v[102:105], v[154:157], v[214:217], v[102:105]
	v_mfma_f32_16x16x32_bf16 v[98:101], v[162:165], v[214:217], v[98:101]
	v_mfma_f32_16x16x32_bf16 v[86:89], v[154:157], v[222:225], v[86:89]
	v_mfma_f32_16x16x32_bf16 v[82:85], v[162:165], v[222:225], v[82:85]
	v_mfma_f32_16x16x32_bf16 v[110:113], v[166:169], v[182:185], 0
	v_mfma_f32_16x16x32_bf16 v[106:109], v[174:177], v[182:185], 0
	v_mfma_f32_16x16x32_bf16 v[94:97], v[166:169], v[190:193], 0
	v_mfma_f32_16x16x32_bf16 v[90:93], v[174:177], v[190:193], 0
	v_mfma_f32_16x16x32_bf16 v[78:81], v[166:169], v[210:213], 0
	v_mfma_f32_16x16x32_bf16 v[74:77], v[174:177], v[210:213], 0
	v_mfma_f32_16x16x32_bf16 v[70:73], v[166:169], v[218:221], 0
	v_mfma_f32_16x16x32_bf16 v[66:69], v[174:177], v[218:221], 0
	v_mfma_f32_16x16x32_bf16 v[110:113], v[170:173], v[186:189], v[110:113]
	v_mfma_f32_16x16x32_bf16 v[106:109], v[178:181], v[186:189], v[106:109]
	v_mfma_f32_16x16x32_bf16 v[94:97], v[170:173], v[198:201], v[94:97]
	v_mfma_f32_16x16x32_bf16 v[90:93], v[178:181], v[198:201], v[90:93]
	v_mfma_f32_16x16x32_bf16 v[78:81], v[170:173], v[214:217], v[78:81]
	v_mfma_f32_16x16x32_bf16 v[74:77], v[178:181], v[214:217], v[74:77]
	v_mfma_f32_16x16x32_bf16 v[70:73], v[170:173], v[222:225], v[70:73]
	v_mfma_f32_16x16x32_bf16 v[66:69], v[178:181], v[222:225], v[66:69]
	s_setprio 2
	s_barrier
	s_add_i32 s51, s43, s35
	v_lshl_add_u64 v[202:203], s[28:29], 0, v[132:133]
	s_mov_b32 m0, s51
	ds_read_b128 v[182:185], v149 offset:16384
	ds_read_b128 v[186:189], v149 offset:17408
	ds_read_b128 v[190:193], v149 offset:18432
	ds_read_b128 v[198:201], v149 offset:19456
	ds_read_b128 v[210:213], v149 offset:20480
	ds_read_b128 v[214:217], v149 offset:21504
	ds_read_b128 v[218:221], v149 offset:22528
	ds_read_b128 v[222:225], v149 offset:23552
	global_load_lds_dwordx4 v[202:203], off
	s_add_i32 m0, s51, 0x2000
	s_add_u32 s52, s28, 0x20000
	v_lshl_add_u64 v[206:207], s[28:29], 0, v[134:135]
	s_addc_u32 s53, s29, 0
	s_add_i32 s51, s44, s35
	global_load_lds_dwordx4 v[206:207], off
	v_lshl_add_u64 v[226:227], s[52:53], 0, v[132:133]
	s_mov_b32 m0, s51
	v_lshl_add_u64 v[228:229], s[30:31], 0, v[136:137]
	global_load_lds_dwordx4 v[226:227], off
	v_lshl_add_u64 v[226:227], s[52:53], 0, v[134:135]
	s_add_i32 m0, s51, 0x2000
	s_nop 0
	global_load_lds_dwordx4 v[226:227], off
	v_lshl_add_u64 v[226:227], s[30:31], 0, v[130:131]
	s_mov_b32 m0, s36
	s_nop 0
	global_load_lds_dwordx4 v[226:227], off
	s_mov_b32 m0, s37
	s_nop 0
	global_load_lds_dwordx4 v[228:229], off
	s_waitcnt vmcnt(8)
	s_waitcnt lgkmcnt(0)
	s_barrier
	s_setprio 1
	s_waitcnt lgkmcnt(0)
	v_mfma_f32_16x16x32_bf16 v[62:65], v[150:153], v[182:185], 0
	v_mfma_f32_16x16x32_bf16 v[58:61], v[158:161], v[182:185], 0
	v_mfma_f32_16x16x32_bf16 v[54:57], v[150:153], v[190:193], 0
	v_mfma_f32_16x16x32_bf16 v[50:53], v[158:161], v[190:193], 0
	v_mfma_f32_16x16x32_bf16 v[38:41], v[150:153], v[210:213], 0
	v_mfma_f32_16x16x32_bf16 v[34:37], v[158:161], v[210:213], 0
	v_mfma_f32_16x16x32_bf16 v[22:25], v[150:153], v[218:221], 0
	v_mfma_f32_16x16x32_bf16 v[18:21], v[158:161], v[218:221], 0
	v_mfma_f32_16x16x32_bf16 v[62:65], v[154:157], v[186:189], v[62:65]
	v_mfma_f32_16x16x32_bf16 v[58:61], v[162:165], v[186:189], v[58:61]
	v_mfma_f32_16x16x32_bf16 v[54:57], v[154:157], v[198:201], v[54:57]
	v_mfma_f32_16x16x32_bf16 v[50:53], v[162:165], v[198:201], v[50:53]
	v_mfma_f32_16x16x32_bf16 v[38:41], v[154:157], v[214:217], v[38:41]
	v_mfma_f32_16x16x32_bf16 v[34:37], v[162:165], v[214:217], v[34:37]
	v_mfma_f32_16x16x32_bf16 v[22:25], v[154:157], v[222:225], v[22:25]
	v_mfma_f32_16x16x32_bf16 v[18:21], v[162:165], v[222:225], v[18:21]
	v_mfma_f32_16x16x32_bf16 v[46:49], v[166:169], v[182:185], 0
	v_mfma_f32_16x16x32_bf16 v[42:45], v[174:177], v[182:185], 0
	v_mfma_f32_16x16x32_bf16 v[30:33], v[166:169], v[190:193], 0
	v_mfma_f32_16x16x32_bf16 v[26:29], v[174:177], v[190:193], 0
	v_mfma_f32_16x16x32_bf16 v[14:17], v[166:169], v[210:213], 0
	v_mfma_f32_16x16x32_bf16 v[10:13], v[174:177], v[210:213], 0
	v_mfma_f32_16x16x32_bf16 v[6:9], v[166:169], v[218:221], 0
	v_mfma_f32_16x16x32_bf16 v[2:5], v[174:177], v[218:221], 0
	v_mfma_f32_16x16x32_bf16 v[46:49], v[170:173], v[186:189], v[46:49]
	v_mfma_f32_16x16x32_bf16 v[42:45], v[178:181], v[186:189], v[42:45]
	v_mfma_f32_16x16x32_bf16 v[30:33], v[170:173], v[198:201], v[30:33]
	v_mfma_f32_16x16x32_bf16 v[26:29], v[178:181], v[198:201], v[26:29]
	v_mfma_f32_16x16x32_bf16 v[14:17], v[170:173], v[214:217], v[14:17]
	v_mfma_f32_16x16x32_bf16 v[10:13], v[178:181], v[214:217], v[10:13]
	v_mfma_f32_16x16x32_bf16 v[6:9], v[170:173], v[222:225], v[6:9]
	v_mfma_f32_16x16x32_bf16 v[2:5], v[178:181], v[222:225], v[2:5]
	s_setprio 2
	s_barrier
	s_add_i32 s51, 0, 0x18000
	s_add_i32 s52, 0, 0x1c000
	v_add_u32_e32 v162, s51, v145
	v_add_u32_e32 v178, s52, v145
	ds_read_b128 v[150:153], v162
	ds_read_b128 v[154:157], v162 offset:1024
	ds_read_b128 v[158:161], v162 offset:2048
	ds_read_b128 v[162:165], v162 offset:3072
	ds_read_b128 v[166:169], v178
	ds_read_b128 v[170:173], v178 offset:1024
	ds_read_b128 v[174:177], v178 offset:2048
	ds_read_b128 v[178:181], v178 offset:3072
	s_add_u32 s30, s30, 0x20000
	s_addc_u32 s31, s31, 0
	s_mov_b32 m0, s38
	v_lshl_add_u64 v[230:231], s[30:31], 0, v[130:131]
	ds_read_b128 v[182:185], v149 offset:32768
	ds_read_b128 v[186:189], v149 offset:33792
	ds_read_b128 v[190:193], v149 offset:34816
	ds_read_b128 v[198:201], v149 offset:35840
	ds_read_b128 v[210:213], v149 offset:36864
	ds_read_b128 v[214:217], v149 offset:37888
	ds_read_b128 v[218:221], v149 offset:38912
	ds_read_b128 v[222:225], v149 offset:39936
	global_load_lds_dwordx4 v[230:231], off
	v_lshl_add_u64 v[230:231], s[30:31], 0, v[136:137]
	s_mov_b32 m0, s39
	s_nop 0
	global_load_lds_dwordx4 v[230:231], off
	s_waitcnt vmcnt(8)
	s_waitcnt lgkmcnt(0)
	s_barrier
	s_setprio 1
	s_waitcnt lgkmcnt(0)
	v_mfma_f32_16x16x32_bf16 v[126:129], v[150:153], v[182:185], v[126:129]
	v_mfma_f32_16x16x32_bf16 v[122:125], v[158:161], v[182:185], v[122:125]
	v_mfma_f32_16x16x32_bf16 v[118:121], v[150:153], v[190:193], v[118:121]
	v_mfma_f32_16x16x32_bf16 v[114:117], v[158:161], v[190:193], v[114:117]
	v_mfma_f32_16x16x32_bf16 v[102:105], v[150:153], v[210:213], v[102:105]
	v_mfma_f32_16x16x32_bf16 v[98:101], v[158:161], v[210:213], v[98:101]
	v_mfma_f32_16x16x32_bf16 v[86:89], v[150:153], v[218:221], v[86:89]
	v_mfma_f32_16x16x32_bf16 v[82:85], v[158:161], v[218:221], v[82:85]
	v_mfma_f32_16x16x32_bf16 v[126:129], v[154:157], v[186:189], v[126:129]
	v_mfma_f32_16x16x32_bf16 v[122:125], v[162:165], v[186:189], v[122:125]
	v_mfma_f32_16x16x32_bf16 v[118:121], v[154:157], v[198:201], v[118:121]
	v_mfma_f32_16x16x32_bf16 v[114:117], v[162:165], v[198:201], v[114:117]
	v_mfma_f32_16x16x32_bf16 v[102:105], v[154:157], v[214:217], v[102:105]
	v_mfma_f32_16x16x32_bf16 v[98:101], v[162:165], v[214:217], v[98:101]
	v_mfma_f32_16x16x32_bf16 v[86:89], v[154:157], v[222:225], v[86:89]
	v_mfma_f32_16x16x32_bf16 v[82:85], v[162:165], v[222:225], v[82:85]
	v_mfma_f32_16x16x32_bf16 v[110:113], v[166:169], v[182:185], v[110:113]
	v_mfma_f32_16x16x32_bf16 v[106:109], v[174:177], v[182:185], v[106:109]
	v_mfma_f32_16x16x32_bf16 v[94:97], v[166:169], v[190:193], v[94:97]
	v_mfma_f32_16x16x32_bf16 v[90:93], v[174:177], v[190:193], v[90:93]
	v_mfma_f32_16x16x32_bf16 v[78:81], v[166:169], v[210:213], v[78:81]
	v_mfma_f32_16x16x32_bf16 v[74:77], v[174:177], v[210:213], v[74:77]
	v_mfma_f32_16x16x32_bf16 v[70:73], v[166:169], v[218:221], v[70:73]
	v_mfma_f32_16x16x32_bf16 v[66:69], v[174:177], v[218:221], v[66:69]
	v_mfma_f32_16x16x32_bf16 v[110:113], v[170:173], v[186:189], v[110:113]
	v_mfma_f32_16x16x32_bf16 v[106:109], v[178:181], v[186:189], v[106:109]
	v_mfma_f32_16x16x32_bf16 v[94:97], v[170:173], v[198:201], v[94:97]
	v_mfma_f32_16x16x32_bf16 v[90:93], v[178:181], v[198:201], v[90:93]
	v_mfma_f32_16x16x32_bf16 v[78:81], v[170:173], v[214:217], v[78:81]
	v_mfma_f32_16x16x32_bf16 v[74:77], v[178:181], v[214:217], v[74:77]
	v_mfma_f32_16x16x32_bf16 v[70:73], v[170:173], v[222:225], v[70:73]
	v_mfma_f32_16x16x32_bf16 v[66:69], v[178:181], v[222:225], v[66:69]
	s_setprio 2
	s_barrier
	s_add_i32 s30, s51, s35
	v_lshl_add_u64 v[202:203], v[202:203], 0, s[8:9]
	s_mov_b32 m0, s30
	ds_read_b128 v[182:185], v149 offset:49152
	ds_read_b128 v[186:189], v149 offset:50176
	ds_read_b128 v[190:193], v149 offset:51200
	ds_read_b128 v[198:201], v149 offset:52224
	ds_read_b128 v[210:213], v149 offset:53248
	ds_read_b128 v[214:217], v149 offset:54272
	ds_read_b128 v[218:221], v149 offset:55296
	ds_read_b128 v[222:225], v149 offset:56320
	global_load_lds_dwordx4 v[202:203], off
	s_add_i32 m0, s30, 0x2000
	s_add_u32 s28, s28, 0x20080
	v_lshl_add_u64 v[202:203], v[206:207], 0, s[8:9]
	s_addc_u32 s29, s29, 0
	s_add_i32 s30, s52, s35
	global_load_lds_dwordx4 v[202:203], off
	v_lshl_add_u64 v[202:203], s[28:29], 0, v[132:133]
	s_mov_b32 m0, s30
	s_nop 0
	global_load_lds_dwordx4 v[202:203], off
	v_lshl_add_u64 v[202:203], s[28:29], 0, v[134:135]
	s_add_i32 m0, s30, 0x2000
	s_nop 0
	global_load_lds_dwordx4 v[202:203], off
	v_lshl_add_u64 v[202:203], v[226:227], 0, s[8:9]
	s_mov_b32 m0, s41
	s_nop 0
	global_load_lds_dwordx4 v[202:203], off
	v_lshl_add_u64 v[202:203], v[228:229], 0, s[8:9]
	s_mov_b32 m0, s42
	s_nop 0
	global_load_lds_dwordx4 v[202:203], off
	s_waitcnt vmcnt(8)
	s_waitcnt lgkmcnt(0)
	s_barrier
	s_setprio 1
	s_waitcnt lgkmcnt(0)
	v_mfma_f32_16x16x32_bf16 v[62:65], v[150:153], v[182:185], v[62:65]
	v_mfma_f32_16x16x32_bf16 v[58:61], v[158:161], v[182:185], v[58:61]
	v_mfma_f32_16x16x32_bf16 v[54:57], v[150:153], v[190:193], v[54:57]
	v_mfma_f32_16x16x32_bf16 v[50:53], v[158:161], v[190:193], v[50:53]
	v_mfma_f32_16x16x32_bf16 v[38:41], v[150:153], v[210:213], v[38:41]
	v_mfma_f32_16x16x32_bf16 v[34:37], v[158:161], v[210:213], v[34:37]
	v_mfma_f32_16x16x32_bf16 v[22:25], v[150:153], v[218:221], v[22:25]
	v_mfma_f32_16x16x32_bf16 v[18:21], v[158:161], v[218:221], v[18:21]
	v_mfma_f32_16x16x32_bf16 v[62:65], v[154:157], v[186:189], v[62:65]
	v_mfma_f32_16x16x32_bf16 v[58:61], v[162:165], v[186:189], v[58:61]
	v_mfma_f32_16x16x32_bf16 v[54:57], v[154:157], v[198:201], v[54:57]
	v_mfma_f32_16x16x32_bf16 v[50:53], v[162:165], v[198:201], v[50:53]
	v_mfma_f32_16x16x32_bf16 v[38:41], v[154:157], v[214:217], v[38:41]
	v_mfma_f32_16x16x32_bf16 v[34:37], v[162:165], v[214:217], v[34:37]
	v_mfma_f32_16x16x32_bf16 v[22:25], v[154:157], v[222:225], v[22:25]
	v_mfma_f32_16x16x32_bf16 v[18:21], v[162:165], v[222:225], v[18:21]
	v_mfma_f32_16x16x32_bf16 v[46:49], v[166:169], v[182:185], v[46:49]
	v_mfma_f32_16x16x32_bf16 v[42:45], v[174:177], v[182:185], v[42:45]
	v_mfma_f32_16x16x32_bf16 v[30:33], v[166:169], v[190:193], v[30:33]
	v_mfma_f32_16x16x32_bf16 v[26:29], v[174:177], v[190:193], v[26:29]
	v_mfma_f32_16x16x32_bf16 v[14:17], v[166:169], v[210:213], v[14:17]
	v_mfma_f32_16x16x32_bf16 v[10:13], v[174:177], v[210:213], v[10:13]
	v_mfma_f32_16x16x32_bf16 v[6:9], v[166:169], v[218:221], v[6:9]
	v_mfma_f32_16x16x32_bf16 v[2:5], v[174:177], v[218:221], v[2:5]
	v_mfma_f32_16x16x32_bf16 v[46:49], v[170:173], v[186:189], v[46:49]
	v_mfma_f32_16x16x32_bf16 v[42:45], v[178:181], v[186:189], v[42:45]
	v_mfma_f32_16x16x32_bf16 v[30:33], v[170:173], v[198:201], v[30:33]
	v_mfma_f32_16x16x32_bf16 v[26:29], v[178:181], v[198:201], v[26:29]
	v_mfma_f32_16x16x32_bf16 v[14:17], v[170:173], v[214:217], v[14:17]
	v_mfma_f32_16x16x32_bf16 v[10:13], v[178:181], v[214:217], v[10:13]
	v_mfma_f32_16x16x32_bf16 v[6:9], v[170:173], v[222:225], v[6:9]
	v_mfma_f32_16x16x32_bf16 v[2:5], v[178:181], v[222:225], v[2:5]
	s_setprio 2
	s_barrier
	s_add_i32 s50, s50, 2
	s_add_u32 s26, s26, 0x100
	s_addc_u32 s27, s27, 0
	s_add_u32 s48, s48, 0x100
	s_addc_u32 s49, s49, 0
	s_cmp_gt_u32 s50, 5
	s_cbranch_scc0 .LBB0_690
	s_branch .Lpeeldone_10
.LBB0_690:
	ds_read_b128 v[150:153], v147
	ds_read_b128 v[154:157], v147 offset:1024
	ds_read_b128 v[158:161], v147 offset:2048
	ds_read_b128 v[162:165], v147 offset:3072
	ds_read_b128 v[166:169], v148
	ds_read_b128 v[170:173], v148 offset:1024
	ds_read_b128 v[174:177], v148 offset:2048
	ds_read_b128 v[178:181], v148 offset:3072
	s_add_u32 s28, s26, 0xfffe0080
	s_addc_u32 s29, s27, -1
	s_cmp_eq_u32 s50, 4
	s_cselect_b32 s31, s13, s29
	s_cselect_b32 s30, s46, s28
	s_cselect_b32 s29, s17, s49
	s_cselect_b32 s28, s47, s48
	v_lshl_add_u64 v[202:203], s[26:27], 0, v[138:139]
	s_add_i32 m0, s36, 0xc000
	ds_read_b128 v[182:185], v149
	ds_read_b128 v[186:189], v149 offset:1024
	ds_read_b128 v[190:193], v149 offset:2048
	ds_read_b128 v[198:201], v149 offset:3072
	ds_read_b128 v[210:213], v149 offset:4096
	ds_read_b128 v[214:217], v149 offset:5120
	ds_read_b128 v[218:221], v149 offset:6144
	ds_read_b128 v[222:225], v149 offset:7168
	global_load_lds_dwordx4 v[202:203], off
	v_lshl_add_u64 v[202:203], s[26:27], 0, v[140:141]
	s_add_i32 m0, s36, 0xe000
	s_nop 0
	global_load_lds_dwordx4 v[202:203], off
	s_waitcnt vmcnt(8)
	s_waitcnt lgkmcnt(0)
	s_barrier
	s_setprio 1
	s_waitcnt lgkmcnt(0)
	v_mfma_f32_16x16x32_bf16 v[126:129], v[150:153], v[182:185], v[126:129]
	v_mfma_f32_16x16x32_bf16 v[122:125], v[158:161], v[182:185], v[122:125]
	v_mfma_f32_16x16x32_bf16 v[118:121], v[150:153], v[190:193], v[118:121]
	v_mfma_f32_16x16x32_bf16 v[114:117], v[158:161], v[190:193], v[114:117]
	v_mfma_f32_16x16x32_bf16 v[102:105], v[150:153], v[210:213], v[102:105]
	v_mfma_f32_16x16x32_bf16 v[98:101], v[158:161], v[210:213], v[98:101]
	v_mfma_f32_16x16x32_bf16 v[86:89], v[150:153], v[218:221], v[86:89]
	v_mfma_f32_16x16x32_bf16 v[82:85], v[158:161], v[218:221], v[82:85]
	v_mfma_f32_16x16x32_bf16 v[126:129], v[154:157], v[186:189], v[126:129]
	v_mfma_f32_16x16x32_bf16 v[122:125], v[162:165], v[186:189], v[122:125]
	v_mfma_f32_16x16x32_bf16 v[118:121], v[154:157], v[198:201], v[118:121]
	v_mfma_f32_16x16x32_bf16 v[114:117], v[162:165], v[198:201], v[114:117]
	v_mfma_f32_16x16x32_bf16 v[102:105], v[154:157], v[214:217], v[102:105]
	v_mfma_f32_16x16x32_bf16 v[98:101], v[162:165], v[214:217], v[98:101]
	v_mfma_f32_16x16x32_bf16 v[86:89], v[154:157], v[222:225], v[86:89]
	v_mfma_f32_16x16x32_bf16 v[82:85], v[162:165], v[222:225], v[82:85]
	v_mfma_f32_16x16x32_bf16 v[110:113], v[166:169], v[182:185], v[110:113]
	v_mfma_f32_16x16x32_bf16 v[106:109], v[174:177], v[182:185], v[106:109]
	v_mfma_f32_16x16x32_bf16 v[94:97], v[166:169], v[190:193], v[94:97]
	v_mfma_f32_16x16x32_bf16 v[90:93], v[174:177], v[190:193], v[90:93]
	v_mfma_f32_16x16x32_bf16 v[78:81], v[166:169], v[210:213], v[78:81]
	v_mfma_f32_16x16x32_bf16 v[74:77], v[174:177], v[210:213], v[74:77]
	v_mfma_f32_16x16x32_bf16 v[70:73], v[166:169], v[218:221], v[70:73]
	v_mfma_f32_16x16x32_bf16 v[66:69], v[174:177], v[218:221], v[66:69]
	v_mfma_f32_16x16x32_bf16 v[110:113], v[170:173], v[186:189], v[110:113]
	v_mfma_f32_16x16x32_bf16 v[106:109], v[178:181], v[186:189], v[106:109]
	v_mfma_f32_16x16x32_bf16 v[94:97], v[170:173], v[198:201], v[94:97]
	v_mfma_f32_16x16x32_bf16 v[90:93], v[178:181], v[198:201], v[90:93]
	v_mfma_f32_16x16x32_bf16 v[78:81], v[170:173], v[214:217], v[78:81]
	v_mfma_f32_16x16x32_bf16 v[74:77], v[178:181], v[214:217], v[74:77]
	v_mfma_f32_16x16x32_bf16 v[70:73], v[170:173], v[222:225], v[70:73]
	v_mfma_f32_16x16x32_bf16 v[66:69], v[178:181], v[222:225], v[66:69]
	s_setprio 2
	s_barrier
	s_add_i32 s51, s43, s35
	v_lshl_add_u64 v[202:203], s[28:29], 0, v[132:133]
	s_mov_b32 m0, s51
	ds_read_b128 v[182:185], v149 offset:16384
	ds_read_b128 v[186:189], v149 offset:17408
	ds_read_b128 v[190:193], v149 offset:18432
	ds_read_b128 v[198:201], v149 offset:19456
	ds_read_b128 v[210:213], v149 offset:20480
	ds_read_b128 v[214:217], v149 offset:21504
	ds_read_b128 v[218:221], v149 offset:22528
	ds_read_b128 v[222:225], v149 offset:23552
	global_load_lds_dwordx4 v[202:203], off
	s_add_i32 m0, s51, 0x2000
	s_add_u32 s52, s28, 0x20000
	v_lshl_add_u64 v[206:207], s[28:29], 0, v[134:135]
	s_addc_u32 s53, s29, 0
	s_add_i32 s51, s44, s35
	global_load_lds_dwordx4 v[206:207], off
	v_lshl_add_u64 v[226:227], s[52:53], 0, v[132:133]
	s_mov_b32 m0, s51
	v_lshl_add_u64 v[228:229], s[30:31], 0, v[136:137]
	global_load_lds_dwordx4 v[226:227], off
	v_lshl_add_u64 v[226:227], s[52:53], 0, v[134:135]
	s_add_i32 m0, s51, 0x2000
	s_nop 0
	global_load_lds_dwordx4 v[226:227], off
	v_lshl_add_u64 v[226:227], s[30:31], 0, v[130:131]
	s_mov_b32 m0, s36
	s_nop 0
	global_load_lds_dwordx4 v[226:227], off
	s_mov_b32 m0, s37
	s_nop 0
	global_load_lds_dwordx4 v[228:229], off
	s_waitcnt vmcnt(8)
	s_waitcnt lgkmcnt(0)
	s_barrier
	s_setprio 1
	s_waitcnt lgkmcnt(0)
	v_mfma_f32_16x16x32_bf16 v[62:65], v[150:153], v[182:185], v[62:65]
	v_mfma_f32_16x16x32_bf16 v[58:61], v[158:161], v[182:185], v[58:61]
	v_mfma_f32_16x16x32_bf16 v[54:57], v[150:153], v[190:193], v[54:57]
	v_mfma_f32_16x16x32_bf16 v[50:53], v[158:161], v[190:193], v[50:53]
	v_mfma_f32_16x16x32_bf16 v[38:41], v[150:153], v[210:213], v[38:41]
	v_mfma_f32_16x16x32_bf16 v[34:37], v[158:161], v[210:213], v[34:37]
	v_mfma_f32_16x16x32_bf16 v[22:25], v[150:153], v[218:221], v[22:25]
	v_mfma_f32_16x16x32_bf16 v[18:21], v[158:161], v[218:221], v[18:21]
	v_mfma_f32_16x16x32_bf16 v[62:65], v[154:157], v[186:189], v[62:65]
	v_mfma_f32_16x16x32_bf16 v[58:61], v[162:165], v[186:189], v[58:61]
	v_mfma_f32_16x16x32_bf16 v[54:57], v[154:157], v[198:201], v[54:57]
	v_mfma_f32_16x16x32_bf16 v[50:53], v[162:165], v[198:201], v[50:53]
	v_mfma_f32_16x16x32_bf16 v[38:41], v[154:157], v[214:217], v[38:41]
	v_mfma_f32_16x16x32_bf16 v[34:37], v[162:165], v[214:217], v[34:37]
	v_mfma_f32_16x16x32_bf16 v[22:25], v[154:157], v[222:225], v[22:25]
	v_mfma_f32_16x16x32_bf16 v[18:21], v[162:165], v[222:225], v[18:21]
	v_mfma_f32_16x16x32_bf16 v[46:49], v[166:169], v[182:185], v[46:49]
	v_mfma_f32_16x16x32_bf16 v[42:45], v[174:177], v[182:185], v[42:45]
	v_mfma_f32_16x16x32_bf16 v[30:33], v[166:169], v[190:193], v[30:33]
	v_mfma_f32_16x16x32_bf16 v[26:29], v[174:177], v[190:193], v[26:29]
	v_mfma_f32_16x16x32_bf16 v[14:17], v[166:169], v[210:213], v[14:17]
	v_mfma_f32_16x16x32_bf16 v[10:13], v[174:177], v[210:213], v[10:13]
	v_mfma_f32_16x16x32_bf16 v[6:9], v[166:169], v[218:221], v[6:9]
	v_mfma_f32_16x16x32_bf16 v[2:5], v[174:177], v[218:221], v[2:5]
	v_mfma_f32_16x16x32_bf16 v[46:49], v[170:173], v[186:189], v[46:49]
	v_mfma_f32_16x16x32_bf16 v[42:45], v[178:181], v[186:189], v[42:45]
	v_mfma_f32_16x16x32_bf16 v[30:33], v[170:173], v[198:201], v[30:33]
	v_mfma_f32_16x16x32_bf16 v[26:29], v[178:181], v[198:201], v[26:29]
	v_mfma_f32_16x16x32_bf16 v[14:17], v[170:173], v[214:217], v[14:17]
	v_mfma_f32_16x16x32_bf16 v[10:13], v[178:181], v[214:217], v[10:13]
	v_mfma_f32_16x16x32_bf16 v[6:9], v[170:173], v[222:225], v[6:9]
	v_mfma_f32_16x16x32_bf16 v[2:5], v[178:181], v[222:225], v[2:5]
	s_setprio 2
	s_barrier
	s_add_i32 s51, 0, 0x18000
	s_add_i32 s52, 0, 0x1c000
	v_add_u32_e32 v162, s51, v145
	v_add_u32_e32 v178, s52, v145
	ds_read_b128 v[150:153], v162
	ds_read_b128 v[154:157], v162 offset:1024
	ds_read_b128 v[158:161], v162 offset:2048
	ds_read_b128 v[162:165], v162 offset:3072
	ds_read_b128 v[166:169], v178
	ds_read_b128 v[170:173], v178 offset:1024
	ds_read_b128 v[174:177], v178 offset:2048
	ds_read_b128 v[178:181], v178 offset:3072
	s_add_u32 s30, s30, 0x20000
	s_addc_u32 s31, s31, 0
	s_mov_b32 m0, s38
	v_lshl_add_u64 v[230:231], s[30:31], 0, v[130:131]
	ds_read_b128 v[182:185], v149 offset:32768
	ds_read_b128 v[186:189], v149 offset:33792
	ds_read_b128 v[190:193], v149 offset:34816
	ds_read_b128 v[198:201], v149 offset:35840
	ds_read_b128 v[210:213], v149 offset:36864
	ds_read_b128 v[214:217], v149 offset:37888
	ds_read_b128 v[218:221], v149 offset:38912
	ds_read_b128 v[222:225], v149 offset:39936
	global_load_lds_dwordx4 v[230:231], off
	v_lshl_add_u64 v[230:231], s[30:31], 0, v[136:137]
	s_mov_b32 m0, s39
	s_nop 0
	global_load_lds_dwordx4 v[230:231], off
	s_waitcnt vmcnt(8)
	s_waitcnt lgkmcnt(0)
	s_barrier
	s_setprio 1
	s_waitcnt lgkmcnt(0)
	v_mfma_f32_16x16x32_bf16 v[126:129], v[150:153], v[182:185], v[126:129]
	v_mfma_f32_16x16x32_bf16 v[122:125], v[158:161], v[182:185], v[122:125]
	v_mfma_f32_16x16x32_bf16 v[118:121], v[150:153], v[190:193], v[118:121]
	v_mfma_f32_16x16x32_bf16 v[114:117], v[158:161], v[190:193], v[114:117]
	v_mfma_f32_16x16x32_bf16 v[102:105], v[150:153], v[210:213], v[102:105]
	v_mfma_f32_16x16x32_bf16 v[98:101], v[158:161], v[210:213], v[98:101]
	v_mfma_f32_16x16x32_bf16 v[86:89], v[150:153], v[218:221], v[86:89]
	v_mfma_f32_16x16x32_bf16 v[82:85], v[158:161], v[218:221], v[82:85]
	v_mfma_f32_16x16x32_bf16 v[126:129], v[154:157], v[186:189], v[126:129]
	v_mfma_f32_16x16x32_bf16 v[122:125], v[162:165], v[186:189], v[122:125]
	v_mfma_f32_16x16x32_bf16 v[118:121], v[154:157], v[198:201], v[118:121]
	v_mfma_f32_16x16x32_bf16 v[114:117], v[162:165], v[198:201], v[114:117]
	v_mfma_f32_16x16x32_bf16 v[102:105], v[154:157], v[214:217], v[102:105]
	v_mfma_f32_16x16x32_bf16 v[98:101], v[162:165], v[214:217], v[98:101]
	v_mfma_f32_16x16x32_bf16 v[86:89], v[154:157], v[222:225], v[86:89]
	v_mfma_f32_16x16x32_bf16 v[82:85], v[162:165], v[222:225], v[82:85]
	v_mfma_f32_16x16x32_bf16 v[110:113], v[166:169], v[182:185], v[110:113]
	v_mfma_f32_16x16x32_bf16 v[106:109], v[174:177], v[182:185], v[106:109]
	v_mfma_f32_16x16x32_bf16 v[94:97], v[166:169], v[190:193], v[94:97]
	v_mfma_f32_16x16x32_bf16 v[90:93], v[174:177], v[190:193], v[90:93]
	v_mfma_f32_16x16x32_bf16 v[78:81], v[166:169], v[210:213], v[78:81]
	v_mfma_f32_16x16x32_bf16 v[74:77], v[174:177], v[210:213], v[74:77]
	v_mfma_f32_16x16x32_bf16 v[70:73], v[166:169], v[218:221], v[70:73]
	v_mfma_f32_16x16x32_bf16 v[66:69], v[174:177], v[218:221], v[66:69]
	v_mfma_f32_16x16x32_bf16 v[110:113], v[170:173], v[186:189], v[110:113]
	v_mfma_f32_16x16x32_bf16 v[106:109], v[178:181], v[186:189], v[106:109]
	v_mfma_f32_16x16x32_bf16 v[94:97], v[170:173], v[198:201], v[94:97]
	v_mfma_f32_16x16x32_bf16 v[90:93], v[178:181], v[198:201], v[90:93]
	v_mfma_f32_16x16x32_bf16 v[78:81], v[170:173], v[214:217], v[78:81]
	v_mfma_f32_16x16x32_bf16 v[74:77], v[178:181], v[214:217], v[74:77]
	v_mfma_f32_16x16x32_bf16 v[70:73], v[170:173], v[222:225], v[70:73]
	v_mfma_f32_16x16x32_bf16 v[66:69], v[178:181], v[222:225], v[66:69]
	s_setprio 2
	s_barrier
	s_add_i32 s30, s51, s35
	v_lshl_add_u64 v[202:203], v[202:203], 0, s[8:9]
	s_mov_b32 m0, s30
	ds_read_b128 v[182:185], v149 offset:49152
	ds_read_b128 v[186:189], v149 offset:50176
	ds_read_b128 v[190:193], v149 offset:51200
	ds_read_b128 v[198:201], v149 offset:52224
	ds_read_b128 v[210:213], v149 offset:53248
	ds_read_b128 v[214:217], v149 offset:54272
	ds_read_b128 v[218:221], v149 offset:55296
	ds_read_b128 v[222:225], v149 offset:56320
	global_load_lds_dwordx4 v[202:203], off
	s_add_i32 m0, s30, 0x2000
	s_add_u32 s28, s28, 0x20080
	v_lshl_add_u64 v[202:203], v[206:207], 0, s[8:9]
	s_addc_u32 s29, s29, 0
	s_add_i32 s30, s52, s35
	global_load_lds_dwordx4 v[202:203], off
	v_lshl_add_u64 v[202:203], s[28:29], 0, v[132:133]
	s_mov_b32 m0, s30
	s_nop 0
	global_load_lds_dwordx4 v[202:203], off
	v_lshl_add_u64 v[202:203], s[28:29], 0, v[134:135]
	s_add_i32 m0, s30, 0x2000
	s_nop 0
	global_load_lds_dwordx4 v[202:203], off
	v_lshl_add_u64 v[202:203], v[226:227], 0, s[8:9]
	s_mov_b32 m0, s41
	s_nop 0
	global_load_lds_dwordx4 v[202:203], off
	v_lshl_add_u64 v[202:203], v[228:229], 0, s[8:9]
	s_mov_b32 m0, s42
	s_nop 0
	global_load_lds_dwordx4 v[202:203], off
	s_waitcnt vmcnt(8)
	s_waitcnt lgkmcnt(0)
	s_barrier
	s_setprio 1
	s_waitcnt lgkmcnt(0)
	v_mfma_f32_16x16x32_bf16 v[62:65], v[150:153], v[182:185], v[62:65]
	v_mfma_f32_16x16x32_bf16 v[58:61], v[158:161], v[182:185], v[58:61]
	v_mfma_f32_16x16x32_bf16 v[54:57], v[150:153], v[190:193], v[54:57]
	v_mfma_f32_16x16x32_bf16 v[50:53], v[158:161], v[190:193], v[50:53]
	v_mfma_f32_16x16x32_bf16 v[38:41], v[150:153], v[210:213], v[38:41]
	v_mfma_f32_16x16x32_bf16 v[34:37], v[158:161], v[210:213], v[34:37]
	v_mfma_f32_16x16x32_bf16 v[22:25], v[150:153], v[218:221], v[22:25]
	v_mfma_f32_16x16x32_bf16 v[18:21], v[158:161], v[218:221], v[18:21]
	v_mfma_f32_16x16x32_bf16 v[62:65], v[154:157], v[186:189], v[62:65]
	v_mfma_f32_16x16x32_bf16 v[58:61], v[162:165], v[186:189], v[58:61]
	v_mfma_f32_16x16x32_bf16 v[54:57], v[154:157], v[198:201], v[54:57]
	v_mfma_f32_16x16x32_bf16 v[50:53], v[162:165], v[198:201], v[50:53]
	v_mfma_f32_16x16x32_bf16 v[38:41], v[154:157], v[214:217], v[38:41]
	v_mfma_f32_16x16x32_bf16 v[34:37], v[162:165], v[214:217], v[34:37]
	v_mfma_f32_16x16x32_bf16 v[22:25], v[154:157], v[222:225], v[22:25]
	v_mfma_f32_16x16x32_bf16 v[18:21], v[162:165], v[222:225], v[18:21]
	v_mfma_f32_16x16x32_bf16 v[46:49], v[166:169], v[182:185], v[46:49]
	v_mfma_f32_16x16x32_bf16 v[42:45], v[174:177], v[182:185], v[42:45]
	v_mfma_f32_16x16x32_bf16 v[30:33], v[166:169], v[190:193], v[30:33]
	v_mfma_f32_16x16x32_bf16 v[26:29], v[174:177], v[190:193], v[26:29]
	v_mfma_f32_16x16x32_bf16 v[14:17], v[166:169], v[210:213], v[14:17]
	v_mfma_f32_16x16x32_bf16 v[10:13], v[174:177], v[210:213], v[10:13]
	v_mfma_f32_16x16x32_bf16 v[6:9], v[166:169], v[218:221], v[6:9]
	v_mfma_f32_16x16x32_bf16 v[2:5], v[174:177], v[218:221], v[2:5]
	v_mfma_f32_16x16x32_bf16 v[46:49], v[170:173], v[186:189], v[46:49]
	v_mfma_f32_16x16x32_bf16 v[42:45], v[178:181], v[186:189], v[42:45]
	v_mfma_f32_16x16x32_bf16 v[30:33], v[170:173], v[198:201], v[30:33]
	v_mfma_f32_16x16x32_bf16 v[26:29], v[178:181], v[198:201], v[26:29]
	v_mfma_f32_16x16x32_bf16 v[14:17], v[170:173], v[214:217], v[14:17]
	v_mfma_f32_16x16x32_bf16 v[10:13], v[178:181], v[214:217], v[10:13]
	v_mfma_f32_16x16x32_bf16 v[6:9], v[170:173], v[222:225], v[6:9]
	v_mfma_f32_16x16x32_bf16 v[2:5], v[178:181], v[222:225], v[2:5]
	s_setprio 2
	s_barrier
	s_add_i32 s50, s50, 2
	s_add_u32 s26, s26, 0x100
	s_addc_u32 s27, s27, 0
	s_add_u32 s48, s48, 0x100
	s_addc_u32 s49, s49, 0
	s_cmp_gt_u32 s50, 5
	s_cbranch_scc0 .LBB0_690

.Lpeel_9:
	ds_read_b128 v[144:147], v140
	ds_read_b128 v[148:151], v140 offset:1024
	s_add_u32 s36, s34, 0xfffe0080
	s_addc_u32 s37, s35, -1
	s_cmp_eq_u32 s59, 4
	s_cselect_b32 s39, s21, s37
	s_cselect_b32 s38, s55, s36
	s_cselect_b32 s37, s25, s58
	s_cselect_b32 s36, s56, s57
	v_lshl_add_u64 v[192:193], s[34:35], 0, v[130:131]
	s_add_i32 m0, s27, 0xc000
	global_load_lds_dwordx4 v[192:193], off
	v_lshl_add_u64 v[192:193], s[34:35], 0, v[136:137]
	s_add_i32 m0, s27, 0xe000
	s_nop 0
	global_load_lds_dwordx4 v[192:193], off
	s_waitcnt vmcnt(8)
	s_waitcnt lgkmcnt(0)
	s_barrier
	s_setprio 1
	s_waitcnt lgkmcnt(0)
	v_mfma_f32_16x16x32_bf16 v[126:129], v[144:147], v[176:179], 0
	v_mfma_f32_16x16x32_bf16 v[122:125], v[152:155], v[176:179], 0
	v_mfma_f32_16x16x32_bf16 v[118:121], v[144:147], v[184:187], 0
	v_mfma_f32_16x16x32_bf16 v[114:117], v[152:155], v[184:187], 0
	v_mfma_f32_16x16x32_bf16 v[102:105], v[144:147], v[198:201], 0
	v_mfma_f32_16x16x32_bf16 v[98:101], v[152:155], v[198:201], 0
	v_mfma_f32_16x16x32_bf16 v[86:89], v[144:147], v[214:217], 0
	v_mfma_f32_16x16x32_bf16 v[82:85], v[152:155], v[214:217], 0
	v_mfma_f32_16x16x32_bf16 v[126:129], v[148:151], v[180:183], v[126:129]
	v_mfma_f32_16x16x32_bf16 v[122:125], v[156:159], v[180:183], v[122:125]
	v_mfma_f32_16x16x32_bf16 v[118:121], v[148:151], v[188:191], v[118:121]
	v_mfma_f32_16x16x32_bf16 v[114:117], v[156:159], v[188:191], v[114:117]
	v_mfma_f32_16x16x32_bf16 v[102:105], v[148:151], v[210:213], v[102:105]
	v_mfma_f32_16x16x32_bf16 v[98:101], v[156:159], v[210:213], v[98:101]
	v_mfma_f32_16x16x32_bf16 v[86:89], v[148:151], v[218:221], v[86:89]
	v_mfma_f32_16x16x32_bf16 v[82:85], v[156:159], v[218:221], v[82:85]
	v_mfma_f32_16x16x32_bf16 v[110:113], v[160:163], v[176:179], 0
	v_mfma_f32_16x16x32_bf16 v[106:109], v[168:171], v[176:179], 0
	v_mfma_f32_16x16x32_bf16 v[94:97], v[160:163], v[184:187], 0
	v_mfma_f32_16x16x32_bf16 v[90:93], v[168:171], v[184:187], 0
	v_mfma_f32_16x16x32_bf16 v[78:81], v[160:163], v[198:201], 0
	v_mfma_f32_16x16x32_bf16 v[74:77], v[168:171], v[198:201], 0
	v_mfma_f32_16x16x32_bf16 v[70:73], v[160:163], v[214:217], 0
	v_mfma_f32_16x16x32_bf16 v[66:69], v[168:171], v[214:217], 0
	v_mfma_f32_16x16x32_bf16 v[110:113], v[164:167], v[180:183], v[110:113]
	v_mfma_f32_16x16x32_bf16 v[106:109], v[172:175], v[180:183], v[106:109]
	v_mfma_f32_16x16x32_bf16 v[94:97], v[164:167], v[188:191], v[94:97]
	v_mfma_f32_16x16x32_bf16 v[90:93], v[172:175], v[188:191], v[90:93]
	v_mfma_f32_16x16x32_bf16 v[78:81], v[164:167], v[210:213], v[78:81]
	v_mfma_f32_16x16x32_bf16 v[74:77], v[172:175], v[210:213], v[74:77]
	v_mfma_f32_16x16x32_bf16 v[70:73], v[164:167], v[218:221], v[70:73]
	v_mfma_f32_16x16x32_bf16 v[66:69], v[172:175], v[218:221], v[66:69]
	s_setprio 2
	s_barrier
	s_add_i32 s60, s48, s41
	v_lshl_add_u64 v[192:193], s[36:37], 0, v[132:133]
	s_mov_b32 m0, s60
	ds_read_b128 v[176:179], v142 offset:16384
	ds_read_b128 v[180:183], v142 offset:17408
	ds_read_b128 v[184:187], v142 offset:18432
	ds_read_b128 v[188:191], v142 offset:19456
	ds_read_b128 v[198:201], v142 offset:20480
	ds_read_b128 v[210:213], v142 offset:21504
	ds_read_b128 v[214:217], v142 offset:22528
	ds_read_b128 v[218:221], v142 offset:23552
	global_load_lds_dwordx4 v[192:193], off
	s_add_i32 m0, s60, 0x2000
	s_add_u32 s60, s36, 0x20000
	v_lshl_add_u64 v[202:203], s[36:37], 0, v[134:135]
	s_addc_u32 s61, s37, 0
	s_add_i32 s62, s49, s41
	global_load_lds_dwordx4 v[202:203], off
	v_lshl_add_u64 v[206:207], s[60:61], 0, v[132:133]
	s_mov_b32 m0, s62
	v_lshl_add_u64 v[222:223], s[38:39], 0, v[136:137]
	global_load_lds_dwordx4 v[206:207], off
	v_lshl_add_u64 v[206:207], s[60:61], 0, v[134:135]
	s_add_i32 m0, s62, 0x2000
	s_nop 0
	global_load_lds_dwordx4 v[206:207], off
	v_lshl_add_u64 v[206:207], s[38:39], 0, v[130:131]
	s_mov_b32 m0, s27
	s_nop 0
	global_load_lds_dwordx4 v[206:207], off
	s_mov_b32 m0, s42
	s_nop 0
	global_load_lds_dwordx4 v[222:223], off
	s_waitcnt vmcnt(8)
	s_waitcnt lgkmcnt(0)
	s_barrier
	s_setprio 1
	s_waitcnt lgkmcnt(0)
	v_mfma_f32_16x16x32_bf16 v[62:65], v[144:147], v[176:179], 0
	v_mfma_f32_16x16x32_bf16 v[58:61], v[152:155], v[176:179], 0
	v_mfma_f32_16x16x32_bf16 v[54:57], v[144:147], v[184:187], 0
	v_mfma_f32_16x16x32_bf16 v[50:53], v[152:155], v[184:187], 0
	v_mfma_f32_16x16x32_bf16 v[38:41], v[144:147], v[198:201], 0
	v_mfma_f32_16x16x32_bf16 v[34:37], v[152:155], v[198:201], 0
	v_mfma_f32_16x16x32_bf16 v[22:25], v[144:147], v[214:217], 0
	v_mfma_f32_16x16x32_bf16 v[18:21], v[152:155], v[214:217], 0
	v_mfma_f32_16x16x32_bf16 v[62:65], v[148:151], v[180:183], v[62:65]
	v_mfma_f32_16x16x32_bf16 v[58:61], v[156:159], v[180:183], v[58:61]
	v_mfma_f32_16x16x32_bf16 v[54:57], v[148:151], v[188:191], v[54:57]
	v_mfma_f32_16x16x32_bf16 v[50:53], v[156:159], v[188:191], v[50:53]
	v_mfma_f32_16x16x32_bf16 v[38:41], v[148:151], v[210:213], v[38:41]
	v_mfma_f32_16x16x32_bf16 v[34:37], v[156:159], v[210:213], v[34:37]
	v_mfma_f32_16x16x32_bf16 v[22:25], v[148:151], v[218:221], v[22:25]
	v_mfma_f32_16x16x32_bf16 v[18:21], v[156:159], v[218:221], v[18:21]
	v_mfma_f32_16x16x32_bf16 v[46:49], v[160:163], v[176:179], 0
	v_mfma_f32_16x16x32_bf16 v[42:45], v[168:171], v[176:179], 0
	v_mfma_f32_16x16x32_bf16 v[30:33], v[160:163], v[184:187], 0
	v_mfma_f32_16x16x32_bf16 v[26:29], v[168:171], v[184:187], 0
	v_mfma_f32_16x16x32_bf16 v[14:17], v[160:163], v[198:201], 0
	v_mfma_f32_16x16x32_bf16 v[10:13], v[168:171], v[198:201], 0
	v_mfma_f32_16x16x32_bf16 v[6:9], v[160:163], v[214:217], 0
	v_mfma_f32_16x16x32_bf16 v[2:5], v[168:171], v[214:217], 0
	v_mfma_f32_16x16x32_bf16 v[46:49], v[164:167], v[180:183], v[46:49]
	v_mfma_f32_16x16x32_bf16 v[42:45], v[172:175], v[180:183], v[42:45]
	v_mfma_f32_16x16x32_bf16 v[30:33], v[164:167], v[188:191], v[30:33]
	v_mfma_f32_16x16x32_bf16 v[26:29], v[172:175], v[188:191], v[26:29]
	v_mfma_f32_16x16x32_bf16 v[14:17], v[164:167], v[210:213], v[14:17]
	v_mfma_f32_16x16x32_bf16 v[10:13], v[172:175], v[210:213], v[10:13]
	v_mfma_f32_16x16x32_bf16 v[6:9], v[164:167], v[218:221], v[6:9]
	v_mfma_f32_16x16x32_bf16 v[2:5], v[172:175], v[218:221], v[2:5]
	s_setprio 2
	s_barrier
	s_add_i32 s60, 0, 0x18000
	v_add_u32_e32 v143, s60, v139
	s_add_i32 s61, 0, 0x1c000
	ds_read_b128 v[144:147], v143
	ds_read_b128 v[148:151], v143 offset:1024
	ds_read_b128 v[152:155], v143 offset:2048
	ds_read_b128 v[156:159], v143 offset:3072
	v_add_u32_e32 v143, s61, v139
	ds_read_b128 v[160:163], v143
	ds_read_b128 v[164:167], v143 offset:1024
	ds_read_b128 v[168:171], v143 offset:2048
	ds_read_b128 v[172:175], v143 offset:3072
	s_add_u32 s38, s38, 0x20000
	s_addc_u32 s39, s39, 0
	s_mov_b32 m0, s43
	v_lshl_add_u64 v[224:225], s[38:39], 0, v[130:131]
	ds_read_b128 v[176:179], v142 offset:32768
	ds_read_b128 v[180:183], v142 offset:33792
	ds_read_b128 v[184:187], v142 offset:34816
	ds_read_b128 v[188:191], v142 offset:35840
	ds_read_b128 v[198:201], v142 offset:36864
	ds_read_b128 v[210:213], v142 offset:37888
	ds_read_b128 v[214:217], v142 offset:38912
	ds_read_b128 v[218:221], v142 offset:39936
	global_load_lds_dwordx4 v[224:225], off
	v_lshl_add_u64 v[224:225], s[38:39], 0, v[136:137]
	s_mov_b32 m0, s44
	s_nop 0
	global_load_lds_dwordx4 v[224:225], off
	s_waitcnt vmcnt(8)
	s_waitcnt lgkmcnt(0)
	s_barrier
	s_setprio 1
	s_waitcnt lgkmcnt(0)
	v_mfma_f32_16x16x32_bf16 v[126:129], v[144:147], v[176:179], v[126:129]
	v_mfma_f32_16x16x32_bf16 v[122:125], v[152:155], v[176:179], v[122:125]
	v_mfma_f32_16x16x32_bf16 v[118:121], v[144:147], v[184:187], v[118:121]
	v_mfma_f32_16x16x32_bf16 v[114:117], v[152:155], v[184:187], v[114:117]
	v_mfma_f32_16x16x32_bf16 v[102:105], v[144:147], v[198:201], v[102:105]
	v_mfma_f32_16x16x32_bf16 v[98:101], v[152:155], v[198:201], v[98:101]
	v_mfma_f32_16x16x32_bf16 v[86:89], v[144:147], v[214:217], v[86:89]
	v_mfma_f32_16x16x32_bf16 v[82:85], v[152:155], v[214:217], v[82:85]
	v_mfma_f32_16x16x32_bf16 v[126:129], v[148:151], v[180:183], v[126:129]
	v_mfma_f32_16x16x32_bf16 v[122:125], v[156:159], v[180:183], v[122:125]
	v_mfma_f32_16x16x32_bf16 v[118:121], v[148:151], v[188:191], v[118:121]
	v_mfma_f32_16x16x32_bf16 v[114:117], v[156:159], v[188:191], v[114:117]
	v_mfma_f32_16x16x32_bf16 v[102:105], v[148:151], v[210:213], v[102:105]
	v_mfma_f32_16x16x32_bf16 v[98:101], v[156:159], v[210:213], v[98:101]
	v_mfma_f32_16x16x32_bf16 v[86:89], v[148:151], v[218:221], v[86:89]
	v_mfma_f32_16x16x32_bf16 v[82:85], v[156:159], v[218:221], v[82:85]
	v_mfma_f32_16x16x32_bf16 v[110:113], v[160:163], v[176:179], v[110:113]
	v_mfma_f32_16x16x32_bf16 v[106:109], v[168:171], v[176:179], v[106:109]
	v_mfma_f32_16x16x32_bf16 v[94:97], v[160:163], v[184:187], v[94:97]
	v_mfma_f32_16x16x32_bf16 v[90:93], v[168:171], v[184:187], v[90:93]
	v_mfma_f32_16x16x32_bf16 v[78:81], v[160:163], v[198:201], v[78:81]
	v_mfma_f32_16x16x32_bf16 v[74:77], v[168:171], v[198:201], v[74:77]
	v_mfma_f32_16x16x32_bf16 v[70:73], v[160:163], v[214:217], v[70:73]
	v_mfma_f32_16x16x32_bf16 v[66:69], v[168:171], v[214:217], v[66:69]
	v_mfma_f32_16x16x32_bf16 v[110:113], v[164:167], v[180:183], v[110:113]
	v_mfma_f32_16x16x32_bf16 v[106:109], v[172:175], v[180:183], v[106:109]
	v_mfma_f32_16x16x32_bf16 v[94:97], v[164:167], v[188:191], v[94:97]
	v_mfma_f32_16x16x32_bf16 v[90:93], v[172:175], v[188:191], v[90:93]
	v_mfma_f32_16x16x32_bf16 v[78:81], v[164:167], v[210:213], v[78:81]
	v_mfma_f32_16x16x32_bf16 v[74:77], v[172:175], v[210:213], v[74:77]
	v_mfma_f32_16x16x32_bf16 v[70:73], v[164:167], v[218:221], v[70:73]
	v_mfma_f32_16x16x32_bf16 v[66:69], v[172:175], v[218:221], v[66:69]
	s_setprio 2
	s_barrier
	s_add_i32 s38, s60, s41
	v_lshl_add_u64 v[192:193], v[192:193], 0, s[6:7]
	s_mov_b32 m0, s38
	ds_read_b128 v[176:179], v142 offset:49152
	ds_read_b128 v[180:183], v142 offset:50176
	ds_read_b128 v[184:187], v142 offset:51200
	ds_read_b128 v[188:191], v142 offset:52224
	ds_read_b128 v[198:201], v142 offset:53248
	ds_read_b128 v[210:213], v142 offset:54272
	ds_read_b128 v[214:217], v142 offset:55296
	ds_read_b128 v[218:221], v142 offset:56320
	global_load_lds_dwordx4 v[192:193], off
	s_add_i32 m0, s38, 0x2000
	s_add_u32 s36, s36, 0x20080
	v_lshl_add_u64 v[192:193], v[202:203], 0, s[6:7]
	s_addc_u32 s37, s37, 0
	s_add_i32 s38, s61, s41
	global_load_lds_dwordx4 v[192:193], off
	v_lshl_add_u64 v[192:193], s[36:37], 0, v[132:133]
	s_mov_b32 m0, s38
	s_nop 0
	global_load_lds_dwordx4 v[192:193], off
	v_lshl_add_u64 v[192:193], s[36:37], 0, v[134:135]
	s_add_i32 m0, s38, 0x2000
	s_nop 0
	global_load_lds_dwordx4 v[192:193], off
	v_lshl_add_u64 v[192:193], v[206:207], 0, s[6:7]
	s_mov_b32 m0, s46
	s_nop 0
	global_load_lds_dwordx4 v[192:193], off
	v_lshl_add_u64 v[192:193], v[222:223], 0, s[6:7]
	s_mov_b32 m0, s47
	s_nop 0
	global_load_lds_dwordx4 v[192:193], off
	s_waitcnt vmcnt(8)
	s_waitcnt lgkmcnt(0)
	s_barrier
	s_setprio 1
	s_waitcnt lgkmcnt(0)
	v_mfma_f32_16x16x32_bf16 v[62:65], v[144:147], v[176:179], v[62:65]
	v_mfma_f32_16x16x32_bf16 v[58:61], v[152:155], v[176:179], v[58:61]
	v_mfma_f32_16x16x32_bf16 v[54:57], v[144:147], v[184:187], v[54:57]
	v_mfma_f32_16x16x32_bf16 v[50:53], v[152:155], v[184:187], v[50:53]
	v_mfma_f32_16x16x32_bf16 v[38:41], v[144:147], v[198:201], v[38:41]
	v_mfma_f32_16x16x32_bf16 v[34:37], v[152:155], v[198:201], v[34:37]
	v_mfma_f32_16x16x32_bf16 v[22:25], v[144:147], v[214:217], v[22:25]
	v_mfma_f32_16x16x32_bf16 v[18:21], v[152:155], v[214:217], v[18:21]
	v_mfma_f32_16x16x32_bf16 v[62:65], v[148:151], v[180:183], v[62:65]
	v_mfma_f32_16x16x32_bf16 v[58:61], v[156:159], v[180:183], v[58:61]
	v_mfma_f32_16x16x32_bf16 v[54:57], v[148:151], v[188:191], v[54:57]
	v_mfma_f32_16x16x32_bf16 v[50:53], v[156:159], v[188:191], v[50:53]
	v_mfma_f32_16x16x32_bf16 v[38:41], v[148:151], v[210:213], v[38:41]
	v_mfma_f32_16x16x32_bf16 v[34:37], v[156:159], v[210:213], v[34:37]
	v_mfma_f32_16x16x32_bf16 v[22:25], v[148:151], v[218:221], v[22:25]
	v_mfma_f32_16x16x32_bf16 v[18:21], v[156:159], v[218:221], v[18:21]
	v_mfma_f32_16x16x32_bf16 v[46:49], v[160:163], v[176:179], v[46:49]
	v_mfma_f32_16x16x32_bf16 v[42:45], v[168:171], v[176:179], v[42:45]
	v_mfma_f32_16x16x32_bf16 v[30:33], v[160:163], v[184:187], v[30:33]
	v_mfma_f32_16x16x32_bf16 v[26:29], v[168:171], v[184:187], v[26:29]
	v_mfma_f32_16x16x32_bf16 v[14:17], v[160:163], v[198:201], v[14:17]
	v_mfma_f32_16x16x32_bf16 v[10:13], v[168:171], v[198:201], v[10:13]
	v_mfma_f32_16x16x32_bf16 v[6:9], v[160:163], v[214:217], v[6:9]
	v_mfma_f32_16x16x32_bf16 v[2:5], v[168:171], v[214:217], v[2:5]
	v_mfma_f32_16x16x32_bf16 v[46:49], v[164:167], v[180:183], v[46:49]
	v_mfma_f32_16x16x32_bf16 v[42:45], v[172:175], v[180:183], v[42:45]
	v_mfma_f32_16x16x32_bf16 v[30:33], v[164:167], v[188:191], v[30:33]
	v_mfma_f32_16x16x32_bf16 v[26:29], v[172:175], v[188:191], v[26:29]
	v_mfma_f32_16x16x32_bf16 v[14:17], v[164:167], v[210:213], v[14:17]
	v_mfma_f32_16x16x32_bf16 v[10:13], v[172:175], v[210:213], v[10:13]
	v_mfma_f32_16x16x32_bf16 v[6:9], v[164:167], v[218:221], v[6:9]
	v_mfma_f32_16x16x32_bf16 v[2:5], v[172:175], v[218:221], v[2:5]
	s_setprio 2
	s_barrier
	s_add_i32 s59, s59, 2
	s_add_u32 s34, s34, 0x100
	s_addc_u32 s35, s35, 0
	s_add_u32 s57, s57, 0x100
	s_addc_u32 s58, s58, 0
	s_cmp_gt_u32 s59, 5
	s_cbranch_scc0 .LBB0_714
	s_branch .Lpeeldone_9
.LBB0_714:
	ds_read_b128 v[144:147], v140
	ds_read_b128 v[148:151], v140 offset:1024
	ds_read_b128 v[152:155], v140 offset:2048
	ds_read_b128 v[156:159], v140 offset:3072
	ds_read_b128 v[160:163], v141
	ds_read_b128 v[164:167], v141 offset:1024
	ds_read_b128 v[168:171], v141 offset:2048
	ds_read_b128 v[172:175], v141 offset:3072
	s_add_u32 s36, s34, 0xfffe0080
	s_addc_u32 s37, s35, -1
	s_cmp_eq_u32 s59, 4
	s_cselect_b32 s39, s21, s37
	s_cselect_b32 s38, s55, s36
	s_cselect_b32 s37, s25, s58
	s_cselect_b32 s36, s56, s57
	v_lshl_add_u64 v[192:193], s[34:35], 0, v[130:131]
	s_add_i32 m0, s27, 0xc000
	ds_read_b128 v[176:179], v142
	ds_read_b128 v[180:183], v142 offset:1024
	ds_read_b128 v[184:187], v142 offset:2048
	ds_read_b128 v[188:191], v142 offset:3072
	ds_read_b128 v[198:201], v142 offset:4096
	ds_read_b128 v[210:213], v142 offset:5120
	ds_read_b128 v[214:217], v142 offset:6144
	ds_read_b128 v[218:221], v142 offset:7168
	global_load_lds_dwordx4 v[192:193], off
	v_lshl_add_u64 v[192:193], s[34:35], 0, v[136:137]
	s_add_i32 m0, s27, 0xe000
	s_nop 0
	global_load_lds_dwordx4 v[192:193], off
	s_waitcnt vmcnt(8)
	s_waitcnt lgkmcnt(0)
	s_barrier
	s_setprio 1
	s_waitcnt lgkmcnt(0)
	v_mfma_f32_16x16x32_bf16 v[126:129], v[144:147], v[176:179], v[126:129]
	v_mfma_f32_16x16x32_bf16 v[122:125], v[152:155], v[176:179], v[122:125]
	v_mfma_f32_16x16x32_bf16 v[118:121], v[144:147], v[184:187], v[118:121]
	v_mfma_f32_16x16x32_bf16 v[114:117], v[152:155], v[184:187], v[114:117]
	v_mfma_f32_16x16x32_bf16 v[102:105], v[144:147], v[198:201], v[102:105]
	v_mfma_f32_16x16x32_bf16 v[98:101], v[152:155], v[198:201], v[98:101]
	v_mfma_f32_16x16x32_bf16 v[86:89], v[144:147], v[214:217], v[86:89]
	v_mfma_f32_16x16x32_bf16 v[82:85], v[152:155], v[214:217], v[82:85]
	v_mfma_f32_16x16x32_bf16 v[126:129], v[148:151], v[180:183], v[126:129]
	v_mfma_f32_16x16x32_bf16 v[122:125], v[156:159], v[180:183], v[122:125]
	v_mfma_f32_16x16x32_bf16 v[118:121], v[148:151], v[188:191], v[118:121]
	v_mfma_f32_16x16x32_bf16 v[114:117], v[156:159], v[188:191], v[114:117]
	v_mfma_f32_16x16x32_bf16 v[102:105], v[148:151], v[210:213], v[102:105]
	v_mfma_f32_16x16x32_bf16 v[98:101], v[156:159], v[210:213], v[98:101]
	v_mfma_f32_16x16x32_bf16 v[86:89], v[148:151], v[218:221], v[86:89]
	v_mfma_f32_16x16x32_bf16 v[82:85], v[156:159], v[218:221], v[82:85]
	v_mfma_f32_16x16x32_bf16 v[110:113], v[160:163], v[176:179], v[110:113]
	v_mfma_f32_16x16x32_bf16 v[106:109], v[168:171], v[176:179], v[106:109]
	v_mfma_f32_16x16x32_bf16 v[94:97], v[160:163], v[184:187], v[94:97]
	v_mfma_f32_16x16x32_bf16 v[90:93], v[168:171], v[184:187], v[90:93]
	v_mfma_f32_16x16x32_bf16 v[78:81], v[160:163], v[198:201], v[78:81]
	v_mfma_f32_16x16x32_bf16 v[74:77], v[168:171], v[198:201], v[74:77]
	v_mfma_f32_16x16x32_bf16 v[70:73], v[160:163], v[214:217], v[70:73]
	v_mfma_f32_16x16x32_bf16 v[66:69], v[168:171], v[214:217], v[66:69]
	v_mfma_f32_16x16x32_bf16 v[110:113], v[164:167], v[180:183], v[110:113]
	v_mfma_f32_16x16x32_bf16 v[106:109], v[172:175], v[180:183], v[106:109]
	v_mfma_f32_16x16x32_bf16 v[94:97], v[164:167], v[188:191], v[94:97]
	v_mfma_f32_16x16x32_bf16 v[90:93], v[172:175], v[188:191], v[90:93]
	v_mfma_f32_16x16x32_bf16 v[78:81], v[164:167], v[210:213], v[78:81]
	v_mfma_f32_16x16x32_bf16 v[74:77], v[172:175], v[210:213], v[74:77]
	v_mfma_f32_16x16x32_bf16 v[70:73], v[164:167], v[218:221], v[70:73]
	v_mfma_f32_16x16x32_bf16 v[66:69], v[172:175], v[218:221], v[66:69]
	s_setprio 2
	s_barrier
	s_add_i32 s60, s48, s41
	v_lshl_add_u64 v[192:193], s[36:37], 0, v[132:133]
	s_mov_b32 m0, s60
	ds_read_b128 v[176:179], v142 offset:16384
	ds_read_b128 v[180:183], v142 offset:17408
	ds_read_b128 v[184:187], v142 offset:18432
	ds_read_b128 v[188:191], v142 offset:19456
	ds_read_b128 v[198:201], v142 offset:20480
	ds_read_b128 v[210:213], v142 offset:21504
	ds_read_b128 v[214:217], v142 offset:22528
	ds_read_b128 v[218:221], v142 offset:23552
	global_load_lds_dwordx4 v[192:193], off
	s_add_i32 m0, s60, 0x2000
	s_add_u32 s60, s36, 0x20000
	v_lshl_add_u64 v[202:203], s[36:37], 0, v[134:135]
	s_addc_u32 s61, s37, 0
	s_add_i32 s62, s49, s41
	global_load_lds_dwordx4 v[202:203], off
	v_lshl_add_u64 v[206:207], s[60:61], 0, v[132:133]
	s_mov_b32 m0, s62
	v_lshl_add_u64 v[222:223], s[38:39], 0, v[136:137]
	global_load_lds_dwordx4 v[206:207], off
	v_lshl_add_u64 v[206:207], s[60:61], 0, v[134:135]
	s_add_i32 m0, s62, 0x2000
	s_nop 0
	global_load_lds_dwordx4 v[206:207], off
	v_lshl_add_u64 v[206:207], s[38:39], 0, v[130:131]
	s_mov_b32 m0, s27
	s_nop 0
	global_load_lds_dwordx4 v[206:207], off
	s_mov_b32 m0, s42
	s_nop 0
	global_load_lds_dwordx4 v[222:223], off
	s_waitcnt vmcnt(8)
	s_waitcnt lgkmcnt(0)
	s_barrier
	s_setprio 1
	s_waitcnt lgkmcnt(0)
	v_mfma_f32_16x16x32_bf16 v[62:65], v[144:147], v[176:179], v[62:65]
	v_mfma_f32_16x16x32_bf16 v[58:61], v[152:155], v[176:179], v[58:61]
	v_mfma_f32_16x16x32_bf16 v[54:57], v[144:147], v[184:187], v[54:57]
	v_mfma_f32_16x16x32_bf16 v[50:53], v[152:155], v[184:187], v[50:53]
	v_mfma_f32_16x16x32_bf16 v[38:41], v[144:147], v[198:201], v[38:41]
	v_mfma_f32_16x16x32_bf16 v[34:37], v[152:155], v[198:201], v[34:37]
	v_mfma_f32_16x16x32_bf16 v[22:25], v[144:147], v[214:217], v[22:25]
	v_mfma_f32_16x16x32_bf16 v[18:21], v[152:155], v[214:217], v[18:21]
	v_mfma_f32_16x16x32_bf16 v[62:65], v[148:151], v[180:183], v[62:65]
	v_mfma_f32_16x16x32_bf16 v[58:61], v[156:159], v[180:183], v[58:61]
	v_mfma_f32_16x16x32_bf16 v[54:57], v[148:151], v[188:191], v[54:57]
	v_mfma_f32_16x16x32_bf16 v[50:53], v[156:159], v[188:191], v[50:53]
	v_mfma_f32_16x16x32_bf16 v[38:41], v[148:151], v[210:213], v[38:41]
	v_mfma_f32_16x16x32_bf16 v[34:37], v[156:159], v[210:213], v[34:37]
	v_mfma_f32_16x16x32_bf16 v[22:25], v[148:151], v[218:221], v[22:25]
	v_mfma_f32_16x16x32_bf16 v[18:21], v[156:159], v[218:221], v[18:21]
	v_mfma_f32_16x16x32_bf16 v[46:49], v[160:163], v[176:179], v[46:49]
	v_mfma_f32_16x16x32_bf16 v[42:45], v[168:171], v[176:179], v[42:45]
	v_mfma_f32_16x16x32_bf16 v[30:33], v[160:163], v[184:187], v[30:33]
	v_mfma_f32_16x16x32_bf16 v[26:29], v[168:171], v[184:187], v[26:29]
	v_mfma_f32_16x16x32_bf16 v[14:17], v[160:163], v[198:201], v[14:17]
	v_mfma_f32_16x16x32_bf16 v[10:13], v[168:171], v[198:201], v[10:13]
	v_mfma_f32_16x16x32_bf16 v[6:9], v[160:163], v[214:217], v[6:9]
	v_mfma_f32_16x16x32_bf16 v[2:5], v[168:171], v[214:217], v[2:5]
	v_mfma_f32_16x16x32_bf16 v[46:49], v[164:167], v[180:183], v[46:49]
	v_mfma_f32_16x16x32_bf16 v[42:45], v[172:175], v[180:183], v[42:45]
	v_mfma_f32_16x16x32_bf16 v[30:33], v[164:167], v[188:191], v[30:33]
	v_mfma_f32_16x16x32_bf16 v[26:29], v[172:175], v[188:191], v[26:29]
	v_mfma_f32_16x16x32_bf16 v[14:17], v[164:167], v[210:213], v[14:17]
	v_mfma_f32_16x16x32_bf16 v[10:13], v[172:175], v[210:213], v[10:13]
	v_mfma_f32_16x16x32_bf16 v[6:9], v[164:167], v[218:221], v[6:9]
	v_mfma_f32_16x16x32_bf16 v[2:5], v[172:175], v[218:221], v[2:5]
	s_setprio 2
	s_barrier
	s_add_i32 s60, 0, 0x18000
	v_add_u32_e32 v143, s60, v139
	s_add_i32 s61, 0, 0x1c000
	ds_read_b128 v[144:147], v143
	ds_read_b128 v[148:151], v143 offset:1024
	ds_read_b128 v[152:155], v143 offset:2048
	ds_read_b128 v[156:159], v143 offset:3072
	v_add_u32_e32 v143, s61, v139
	ds_read_b128 v[160:163], v143
	ds_read_b128 v[164:167], v143 offset:1024
	ds_read_b128 v[168:171], v143 offset:2048
	ds_read_b128 v[172:175], v143 offset:3072
	s_add_u32 s38, s38, 0x20000
	s_addc_u32 s39, s39, 0
	s_mov_b32 m0, s43
	v_lshl_add_u64 v[224:225], s[38:39], 0, v[130:131]
	ds_read_b128 v[176:179], v142 offset:32768
	ds_read_b128 v[180:183], v142 offset:33792
	ds_read_b128 v[184:187], v142 offset:34816
	ds_read_b128 v[188:191], v142 offset:35840
	ds_read_b128 v[198:201], v142 offset:36864
	ds_read_b128 v[210:213], v142 offset:37888
	ds_read_b128 v[214:217], v142 offset:38912
	ds_read_b128 v[218:221], v142 offset:39936
	global_load_lds_dwordx4 v[224:225], off
	v_lshl_add_u64 v[224:225], s[38:39], 0, v[136:137]
	s_mov_b32 m0, s44
	s_nop 0
	global_load_lds_dwordx4 v[224:225], off
	s_waitcnt vmcnt(8)
	s_waitcnt lgkmcnt(0)
	s_barrier
	s_setprio 1
	s_waitcnt lgkmcnt(0)
	v_mfma_f32_16x16x32_bf16 v[126:129], v[144:147], v[176:179], v[126:129]
	v_mfma_f32_16x16x32_bf16 v[122:125], v[152:155], v[176:179], v[122:125]
	v_mfma_f32_16x16x32_bf16 v[118:121], v[144:147], v[184:187], v[118:121]
	v_mfma_f32_16x16x32_bf16 v[114:117], v[152:155], v[184:187], v[114:117]
	v_mfma_f32_16x16x32_bf16 v[102:105], v[144:147], v[198:201], v[102:105]
	v_mfma_f32_16x16x32_bf16 v[98:101], v[152:155], v[198:201], v[98:101]
	v_mfma_f32_16x16x32_bf16 v[86:89], v[144:147], v[214:217], v[86:89]
	v_mfma_f32_16x16x32_bf16 v[82:85], v[152:155], v[214:217], v[82:85]
	v_mfma_f32_16x16x32_bf16 v[126:129], v[148:151], v[180:183], v[126:129]
	v_mfma_f32_16x16x32_bf16 v[122:125], v[156:159], v[180:183], v[122:125]
	v_mfma_f32_16x16x32_bf16 v[118:121], v[148:151], v[188:191], v[118:121]
	v_mfma_f32_16x16x32_bf16 v[114:117], v[156:159], v[188:191], v[114:117]
	v_mfma_f32_16x16x32_bf16 v[102:105], v[148:151], v[210:213], v[102:105]
	v_mfma_f32_16x16x32_bf16 v[98:101], v[156:159], v[210:213], v[98:101]
	v_mfma_f32_16x16x32_bf16 v[86:89], v[148:151], v[218:221], v[86:89]
	v_mfma_f32_16x16x32_bf16 v[82:85], v[156:159], v[218:221], v[82:85]
	v_mfma_f32_16x16x32_bf16 v[110:113], v[160:163], v[176:179], v[110:113]
	v_mfma_f32_16x16x32_bf16 v[106:109], v[168:171], v[176:179], v[106:109]
	v_mfma_f32_16x16x32_bf16 v[94:97], v[160:163], v[184:187], v[94:97]
	v_mfma_f32_16x16x32_bf16 v[90:93], v[168:171], v[184:187], v[90:93]
	v_mfma_f32_16x16x32_bf16 v[78:81], v[160:163], v[198:201], v[78:81]
	v_mfma_f32_16x16x32_bf16 v[74:77], v[168:171], v[198:201], v[74:77]
	v_mfma_f32_16x16x32_bf16 v[70:73], v[160:163], v[214:217], v[70:73]
	v_mfma_f32_16x16x32_bf16 v[66:69], v[168:171], v[214:217], v[66:69]
	v_mfma_f32_16x16x32_bf16 v[110:113], v[164:167], v[180:183], v[110:113]
	v_mfma_f32_16x16x32_bf16 v[106:109], v[172:175], v[180:183], v[106:109]
	v_mfma_f32_16x16x32_bf16 v[94:97], v[164:167], v[188:191], v[94:97]
	v_mfma_f32_16x16x32_bf16 v[90:93], v[172:175], v[188:191], v[90:93]
	v_mfma_f32_16x16x32_bf16 v[78:81], v[164:167], v[210:213], v[78:81]
	v_mfma_f32_16x16x32_bf16 v[74:77], v[172:175], v[210:213], v[74:77]
	v_mfma_f32_16x16x32_bf16 v[70:73], v[164:167], v[218:221], v[70:73]
	v_mfma_f32_16x16x32_bf16 v[66:69], v[172:175], v[218:221], v[66:69]
	s_setprio 2
	s_barrier
	s_add_i32 s38, s60, s41
	v_lshl_add_u64 v[192:193], v[192:193], 0, s[6:7]
	s_mov_b32 m0, s38
	ds_read_b128 v[176:179], v142 offset:49152
	ds_read_b128 v[180:183], v142 offset:50176
	ds_read_b128 v[184:187], v142 offset:51200
	ds_read_b128 v[188:191], v142 offset:52224
	ds_read_b128 v[198:201], v142 offset:53248
	ds_read_b128 v[210:213], v142 offset:54272
	ds_read_b128 v[214:217], v142 offset:55296
	ds_read_b128 v[218:221], v142 offset:56320
	global_load_lds_dwordx4 v[192:193], off
	s_add_i32 m0, s38, 0x2000
	s_add_u32 s36, s36, 0x20080
	v_lshl_add_u64 v[192:193], v[202:203], 0, s[6:7]
	s_addc_u32 s37, s37, 0
	s_add_i32 s38, s61, s41
	global_load_lds_dwordx4 v[192:193], off
	v_lshl_add_u64 v[192:193], s[36:37], 0, v[132:133]
	s_mov_b32 m0, s38
	s_nop 0
	global_load_lds_dwordx4 v[192:193], off
	v_lshl_add_u64 v[192:193], s[36:37], 0, v[134:135]
	s_add_i32 m0, s38, 0x2000
	s_nop 0
	global_load_lds_dwordx4 v[192:193], off
	v_lshl_add_u64 v[192:193], v[206:207], 0, s[6:7]
	s_mov_b32 m0, s46
	s_nop 0
	global_load_lds_dwordx4 v[192:193], off
	v_lshl_add_u64 v[192:193], v[222:223], 0, s[6:7]
	s_mov_b32 m0, s47
	s_nop 0
	global_load_lds_dwordx4 v[192:193], off
	s_waitcnt vmcnt(8)
	s_waitcnt lgkmcnt(0)
	s_barrier
	s_setprio 1
	s_waitcnt lgkmcnt(0)
	v_mfma_f32_16x16x32_bf16 v[62:65], v[144:147], v[176:179], v[62:65]
	v_mfma_f32_16x16x32_bf16 v[58:61], v[152:155], v[176:179], v[58:61]
	v_mfma_f32_16x16x32_bf16 v[54:57], v[144:147], v[184:187], v[54:57]
	v_mfma_f32_16x16x32_bf16 v[50:53], v[152:155], v[184:187], v[50:53]
	v_mfma_f32_16x16x32_bf16 v[38:41], v[144:147], v[198:201], v[38:41]
	v_mfma_f32_16x16x32_bf16 v[34:37], v[152:155], v[198:201], v[34:37]
	v_mfma_f32_16x16x32_bf16 v[22:25], v[144:147], v[214:217], v[22:25]
	v_mfma_f32_16x16x32_bf16 v[18:21], v[152:155], v[214:217], v[18:21]
	v_mfma_f32_16x16x32_bf16 v[62:65], v[148:151], v[180:183], v[62:65]
	v_mfma_f32_16x16x32_bf16 v[58:61], v[156:159], v[180:183], v[58:61]
	v_mfma_f32_16x16x32_bf16 v[54:57], v[148:151], v[188:191], v[54:57]
	v_mfma_f32_16x16x32_bf16 v[50:53], v[156:159], v[188:191], v[50:53]
	v_mfma_f32_16x16x32_bf16 v[38:41], v[148:151], v[210:213], v[38:41]
	v_mfma_f32_16x16x32_bf16 v[34:37], v[156:159], v[210:213], v[34:37]
	v_mfma_f32_16x16x32_bf16 v[22:25], v[148:151], v[218:221], v[22:25]
	v_mfma_f32_16x16x32_bf16 v[18:21], v[156:159], v[218:221], v[18:21]
	v_mfma_f32_16x16x32_bf16 v[46:49], v[160:163], v[176:179], v[46:49]
	v_mfma_f32_16x16x32_bf16 v[42:45], v[168:171], v[176:179], v[42:45]
	v_mfma_f32_16x16x32_bf16 v[30:33], v[160:163], v[184:187], v[30:33]
	v_mfma_f32_16x16x32_bf16 v[26:29], v[168:171], v[184:187], v[26:29]
	v_mfma_f32_16x16x32_bf16 v[14:17], v[160:163], v[198:201], v[14:17]
	v_mfma_f32_16x16x32_bf16 v[10:13], v[168:171], v[198:201], v[10:13]
	v_mfma_f32_16x16x32_bf16 v[6:9], v[160:163], v[214:217], v[6:9]
	v_mfma_f32_16x16x32_bf16 v[2:5], v[168:171], v[214:217], v[2:5]
	v_mfma_f32_16x16x32_bf16 v[46:49], v[164:167], v[180:183], v[46:49]
	v_mfma_f32_16x16x32_bf16 v[42:45], v[172:175], v[180:183], v[42:45]
	v_mfma_f32_16x16x32_bf16 v[30:33], v[164:167], v[188:191], v[30:33]
	v_mfma_f32_16x16x32_bf16 v[26:29], v[172:175], v[188:191], v[26:29]
	v_mfma_f32_16x16x32_bf16 v[14:17], v[164:167], v[210:213], v[14:17]
	v_mfma_f32_16x16x32_bf16 v[10:13], v[172:175], v[210:213], v[10:13]
	v_mfma_f32_16x16x32_bf16 v[6:9], v[164:167], v[218:221], v[6:9]
	v_mfma_f32_16x16x32_bf16 v[2:5], v[172:175], v[218:221], v[2:5]
	s_setprio 2
	s_barrier
	s_add_i32 s59, s59, 2
	s_add_u32 s34, s34, 0x100
	s_addc_u32 s35, s35, 0
	s_add_u32 s57, s57, 0x100
	s_addc_u32 s58, s58, 0
	s_cmp_gt_u32 s59, 5
	s_cbranch_scc0 .LBB0_714

.Lpeel_8:
	ds_read_b128 v[130:133], v170
	ds_read_b128 v[134:137], v170 offset:1024
	ds_read_b128 v[138:141], v170 offset:2048
	ds_read_b128 v[142:145], v170 offset:3072
	ds_read_b128 v[160:163], v171
	ds_read_b128 v[164:167], v171 offset:1024
	ds_read_b128 v[174:177], v171 offset:2048
	ds_read_b128 v[178:181], v171 offset:3072
	s_add_i32 s31, s21, 2
	s_add_u32 s36, s34, 0xfff80080
	s_addc_u32 s37, s35, -1
	s_cmp_eq_u32 s30, s21
	s_cselect_b32 s39, s23, s37
	s_cselect_b32 s38, s22, s36
	s_cselect_b32 s37, s25, s19
	s_cselect_b32 s36, s24, s17
	v_lshl_add_u64 v[202:203], s[34:35], 0, v[156:157]
	s_add_i32 m0, s27, 0xc000
	ds_read_b128 v[182:185], v172
	ds_read_b128 v[186:189], v172 offset:1024
	ds_read_b128 v[190:193], v172 offset:2048
	ds_read_b128 v[198:201], v172 offset:3072
	ds_read_b128 v[210:213], v172 offset:4096
	ds_read_b128 v[214:217], v172 offset:5120
	global_load_lds_dwordx4 v[202:203], off
	v_lshl_add_u64 v[202:203], s[34:35], 0, v[158:159]
	s_add_i32 m0, s27, 0xe000
	s_nop 0
	global_load_lds_dwordx4 v[202:203], off
	s_waitcnt vmcnt(8)
	s_waitcnt lgkmcnt(0)
	s_barrier
	s_setprio 1
	s_waitcnt lgkmcnt(0)
	v_mfma_f32_16x16x32_bf16 v[126:129], v[130:133], v[182:185], 0
	v_mfma_f32_16x16x32_bf16 v[122:125], v[138:141], v[182:185], 0
	v_mfma_f32_16x16x32_bf16 v[118:121], v[130:133], v[190:193], 0
	v_mfma_f32_16x16x32_bf16 v[110:113], v[138:141], v[190:193], 0
	v_mfma_f32_16x16x32_bf16 v[94:97], v[130:133], v[210:213], 0
	v_mfma_f32_16x16x32_bf16 v[90:93], v[138:141], v[210:213], 0
	v_mfma_f32_16x16x32_bf16 v[78:81], v[130:133], v[218:221], 0
	v_mfma_f32_16x16x32_bf16 v[74:77], v[138:141], v[218:221], 0
	v_mfma_f32_16x16x32_bf16 v[126:129], v[134:137], v[186:189], v[126:129]
	v_mfma_f32_16x16x32_bf16 v[122:125], v[142:145], v[186:189], v[122:125]
	v_mfma_f32_16x16x32_bf16 v[118:121], v[134:137], v[198:201], v[118:121]
	v_mfma_f32_16x16x32_bf16 v[110:113], v[142:145], v[198:201], v[110:113]
	v_mfma_f32_16x16x32_bf16 v[94:97], v[134:137], v[214:217], v[94:97]
	v_mfma_f32_16x16x32_bf16 v[90:93], v[142:145], v[214:217], v[90:93]
	v_mfma_f32_16x16x32_bf16 v[78:81], v[134:137], v[222:225], v[78:81]
	v_mfma_f32_16x16x32_bf16 v[74:77], v[142:145], v[222:225], v[74:77]
	v_mfma_f32_16x16x32_bf16 v[114:117], v[160:163], v[182:185], 0
	v_mfma_f32_16x16x32_bf16 v[106:109], v[174:177], v[182:185], 0
	v_mfma_f32_16x16x32_bf16 v[102:105], v[160:163], v[190:193], 0
	v_mfma_f32_16x16x32_bf16 v[98:101], v[174:177], v[190:193], 0
	v_mfma_f32_16x16x32_bf16 v[86:89], v[160:163], v[210:213], 0
	v_mfma_f32_16x16x32_bf16 v[82:85], v[174:177], v[210:213], 0
	v_mfma_f32_16x16x32_bf16 v[70:73], v[160:163], v[218:221], 0
	v_mfma_f32_16x16x32_bf16 v[66:69], v[174:177], v[218:221], 0
	v_mfma_f32_16x16x32_bf16 v[114:117], v[164:167], v[186:189], v[114:117]
	v_mfma_f32_16x16x32_bf16 v[106:109], v[178:181], v[186:189], v[106:109]
	v_mfma_f32_16x16x32_bf16 v[102:105], v[164:167], v[198:201], v[102:105]
	v_mfma_f32_16x16x32_bf16 v[98:101], v[178:181], v[198:201], v[98:101]
	v_mfma_f32_16x16x32_bf16 v[86:89], v[164:167], v[214:217], v[86:89]
	v_mfma_f32_16x16x32_bf16 v[82:85], v[178:181], v[214:217], v[82:85]
	v_mfma_f32_16x16x32_bf16 v[70:73], v[164:167], v[222:225], v[70:73]
	v_mfma_f32_16x16x32_bf16 v[66:69], v[178:181], v[222:225], v[66:69]
	s_setprio 2
	s_barrier
	s_add_i32 s21, s63, s33
	v_lshl_add_u64 v[202:203], s[36:37], 0, v[148:149]
	s_mov_b32 m0, s21
	ds_read_b128 v[182:185], v172 offset:16384
	ds_read_b128 v[186:189], v172 offset:17408
	ds_read_b128 v[190:193], v172 offset:18432
	ds_read_b128 v[198:201], v172 offset:19456
	ds_read_b128 v[210:213], v172 offset:20480
	ds_read_b128 v[214:217], v172 offset:21504
	ds_read_b128 v[218:221], v172 offset:22528
	ds_read_b128 v[222:225], v172 offset:23552
	global_load_lds_dwordx4 v[202:203], off
	s_add_i32 m0, s21, 0x2000
	s_add_u32 s40, s36, 0x80000
	v_lshl_add_u64 v[206:207], s[36:37], 0, v[152:153]
	s_addc_u32 s41, s37, 0
	s_add_i32 s21, s64, s33
	global_load_lds_dwordx4 v[206:207], off
	v_lshl_add_u64 v[226:227], s[40:41], 0, v[148:149]
	s_mov_b32 m0, s21
	v_lshl_add_u64 v[228:229], s[38:39], 0, v[150:151]
	global_load_lds_dwordx4 v[226:227], off
	v_lshl_add_u64 v[226:227], s[40:41], 0, v[152:153]
	s_add_i32 m0, s21, 0x2000
	s_nop 0
	global_load_lds_dwordx4 v[226:227], off
	v_lshl_add_u64 v[226:227], s[38:39], 0, v[146:147]
	s_mov_b32 m0, s27
	s_nop 0
	global_load_lds_dwordx4 v[226:227], off
	s_mov_b32 m0, s29
	s_nop 0
	global_load_lds_dwordx4 v[228:229], off
	s_waitcnt vmcnt(8)
	s_waitcnt lgkmcnt(0)
	s_barrier
	s_setprio 1
	s_waitcnt lgkmcnt(0)
	v_mfma_f32_16x16x32_bf16 v[62:65], v[130:133], v[182:185], 0
	v_mfma_f32_16x16x32_bf16 v[58:61], v[138:141], v[182:185], 0
	v_mfma_f32_16x16x32_bf16 v[46:49], v[130:133], v[190:193], 0
	v_mfma_f32_16x16x32_bf16 v[42:45], v[138:141], v[190:193], 0
	v_mfma_f32_16x16x32_bf16 v[30:33], v[130:133], v[210:213], 0
	v_mfma_f32_16x16x32_bf16 v[26:29], v[138:141], v[210:213], 0
	v_mfma_f32_16x16x32_bf16 v[14:17], v[130:133], v[218:221], 0
	v_mfma_f32_16x16x32_bf16 v[10:13], v[138:141], v[218:221], 0
	v_mfma_f32_16x16x32_bf16 v[62:65], v[134:137], v[186:189], v[62:65]
	v_mfma_f32_16x16x32_bf16 v[58:61], v[142:145], v[186:189], v[58:61]
	v_mfma_f32_16x16x32_bf16 v[46:49], v[134:137], v[198:201], v[46:49]
	v_mfma_f32_16x16x32_bf16 v[42:45], v[142:145], v[198:201], v[42:45]
	v_mfma_f32_16x16x32_bf16 v[30:33], v[134:137], v[214:217], v[30:33]
	v_mfma_f32_16x16x32_bf16 v[26:29], v[142:145], v[214:217], v[26:29]
	v_mfma_f32_16x16x32_bf16 v[14:17], v[134:137], v[222:225], v[14:17]
	v_mfma_f32_16x16x32_bf16 v[10:13], v[142:145], v[222:225], v[10:13]
	v_mfma_f32_16x16x32_bf16 v[54:57], v[160:163], v[182:185], 0
	v_mfma_f32_16x16x32_bf16 v[50:53], v[174:177], v[182:185], 0
	v_mfma_f32_16x16x32_bf16 v[38:41], v[160:163], v[190:193], 0
	v_mfma_f32_16x16x32_bf16 v[34:37], v[174:177], v[190:193], 0
	v_mfma_f32_16x16x32_bf16 v[22:25], v[160:163], v[210:213], 0
	v_mfma_f32_16x16x32_bf16 v[18:21], v[174:177], v[210:213], 0
	v_mfma_f32_16x16x32_bf16 v[6:9], v[160:163], v[218:221], 0
	v_mfma_f32_16x16x32_bf16 v[2:5], v[174:177], v[218:221], 0
	v_mfma_f32_16x16x32_bf16 v[54:57], v[164:167], v[186:189], v[54:57]
	v_mfma_f32_16x16x32_bf16 v[50:53], v[178:181], v[186:189], v[50:53]
	v_mfma_f32_16x16x32_bf16 v[38:41], v[164:167], v[198:201], v[38:41]
	v_mfma_f32_16x16x32_bf16 v[34:37], v[178:181], v[198:201], v[34:37]
	v_mfma_f32_16x16x32_bf16 v[22:25], v[164:167], v[214:217], v[22:25]
	v_mfma_f32_16x16x32_bf16 v[18:21], v[178:181], v[214:217], v[18:21]
	v_mfma_f32_16x16x32_bf16 v[6:9], v[164:167], v[222:225], v[6:9]
	v_mfma_f32_16x16x32_bf16 v[2:5], v[178:181], v[222:225], v[2:5]
	s_setprio 2
	s_barrier
	s_add_i32 s21, 0, 0x18000
	s_add_i32 s40, 0, 0x1c000
	v_add_u32_e32 v142, s21, v168
	v_add_u32_e32 v173, s40, v168
	ds_read_b128 v[130:133], v142
	ds_read_b128 v[134:137], v142 offset:1024
	ds_read_b128 v[138:141], v142 offset:2048
	ds_read_b128 v[142:145], v142 offset:3072
	ds_read_b128 v[160:163], v173
	ds_read_b128 v[164:167], v173 offset:1024
	ds_read_b128 v[174:177], v173 offset:2048
	ds_read_b128 v[178:181], v173 offset:3072
	s_add_u32 s38, s38, 0x80000
	s_addc_u32 s39, s39, 0
	s_mov_b32 m0, s42
	v_lshl_add_u64 v[230:231], s[38:39], 0, v[146:147]
	ds_read_b128 v[182:185], v172 offset:32768
	ds_read_b128 v[186:189], v172 offset:33792
	ds_read_b128 v[190:193], v172 offset:34816
	ds_read_b128 v[198:201], v172 offset:35840
	ds_read_b128 v[210:213], v172 offset:36864
	ds_read_b128 v[214:217], v172 offset:37888
	ds_read_b128 v[218:221], v172 offset:38912
	ds_read_b128 v[222:225], v172 offset:39936
	global_load_lds_dwordx4 v[230:231], off
	v_lshl_add_u64 v[230:231], s[38:39], 0, v[150:151]
	s_mov_b32 m0, s43
	s_nop 0
	global_load_lds_dwordx4 v[230:231], off
	s_waitcnt vmcnt(8)
	s_waitcnt lgkmcnt(0)
	s_barrier
	s_setprio 1
	s_waitcnt lgkmcnt(0)
	v_mfma_f32_16x16x32_bf16 v[126:129], v[130:133], v[182:185], v[126:129]
	v_mfma_f32_16x16x32_bf16 v[122:125], v[138:141], v[182:185], v[122:125]
	v_mfma_f32_16x16x32_bf16 v[118:121], v[130:133], v[190:193], v[118:121]
	v_mfma_f32_16x16x32_bf16 v[110:113], v[138:141], v[190:193], v[110:113]
	v_mfma_f32_16x16x32_bf16 v[94:97], v[130:133], v[210:213], v[94:97]
	v_mfma_f32_16x16x32_bf16 v[90:93], v[138:141], v[210:213], v[90:93]
	v_mfma_f32_16x16x32_bf16 v[78:81], v[130:133], v[218:221], v[78:81]
	v_mfma_f32_16x16x32_bf16 v[74:77], v[138:141], v[218:221], v[74:77]
	v_mfma_f32_16x16x32_bf16 v[126:129], v[134:137], v[186:189], v[126:129]
	v_mfma_f32_16x16x32_bf16 v[122:125], v[142:145], v[186:189], v[122:125]
	v_mfma_f32_16x16x32_bf16 v[118:121], v[134:137], v[198:201], v[118:121]
	v_mfma_f32_16x16x32_bf16 v[110:113], v[142:145], v[198:201], v[110:113]
	v_mfma_f32_16x16x32_bf16 v[94:97], v[134:137], v[214:217], v[94:97]
	v_mfma_f32_16x16x32_bf16 v[90:93], v[142:145], v[214:217], v[90:93]
	v_mfma_f32_16x16x32_bf16 v[78:81], v[134:137], v[222:225], v[78:81]
	v_mfma_f32_16x16x32_bf16 v[74:77], v[142:145], v[222:225], v[74:77]
	v_mfma_f32_16x16x32_bf16 v[114:117], v[160:163], v[182:185], v[114:117]
	v_mfma_f32_16x16x32_bf16 v[106:109], v[174:177], v[182:185], v[106:109]
	v_mfma_f32_16x16x32_bf16 v[102:105], v[160:163], v[190:193], v[102:105]
	v_mfma_f32_16x16x32_bf16 v[98:101], v[174:177], v[190:193], v[98:101]
	v_mfma_f32_16x16x32_bf16 v[86:89], v[160:163], v[210:213], v[86:89]
	v_mfma_f32_16x16x32_bf16 v[82:85], v[174:177], v[210:213], v[82:85]
	v_mfma_f32_16x16x32_bf16 v[70:73], v[160:163], v[218:221], v[70:73]
	v_mfma_f32_16x16x32_bf16 v[66:69], v[174:177], v[218:221], v[66:69]
	v_mfma_f32_16x16x32_bf16 v[114:117], v[164:167], v[186:189], v[114:117]
	v_mfma_f32_16x16x32_bf16 v[106:109], v[178:181], v[186:189], v[106:109]
	v_mfma_f32_16x16x32_bf16 v[102:105], v[164:167], v[198:201], v[102:105]
	v_mfma_f32_16x16x32_bf16 v[98:101], v[178:181], v[198:201], v[98:101]
	v_mfma_f32_16x16x32_bf16 v[86:89], v[164:167], v[214:217], v[86:89]
	v_mfma_f32_16x16x32_bf16 v[82:85], v[178:181], v[214:217], v[82:85]
	v_mfma_f32_16x16x32_bf16 v[70:73], v[164:167], v[222:225], v[70:73]
	v_mfma_f32_16x16x32_bf16 v[66:69], v[178:181], v[222:225], v[66:69]
	s_setprio 2
	s_barrier
	s_add_i32 s21, s21, s33
	v_lshl_add_u64 v[202:203], v[202:203], 0, s[12:13]
	s_mov_b32 m0, s21
	ds_read_b128 v[182:185], v172 offset:49152
	ds_read_b128 v[186:189], v172 offset:50176
	ds_read_b128 v[190:193], v172 offset:51200
	ds_read_b128 v[198:201], v172 offset:52224
	ds_read_b128 v[210:213], v172 offset:53248
	ds_read_b128 v[214:217], v172 offset:54272
	ds_read_b128 v[218:221], v172 offset:55296
	ds_read_b128 v[222:225], v172 offset:56320
	global_load_lds_dwordx4 v[202:203], off
	s_add_i32 m0, s21, 0x2000
	s_add_u32 s36, s36, 0x80080
	v_lshl_add_u64 v[202:203], v[206:207], 0, s[12:13]
	s_addc_u32 s37, s37, 0
	s_add_i32 s21, s40, s33
	global_load_lds_dwordx4 v[202:203], off
	v_lshl_add_u64 v[202:203], s[36:37], 0, v[148:149]
	s_mov_b32 m0, s21
	s_nop 0
	global_load_lds_dwordx4 v[202:203], off
	v_lshl_add_u64 v[202:203], s[36:37], 0, v[152:153]
	s_add_i32 m0, s21, 0x2000
	s_nop 0
	global_load_lds_dwordx4 v[202:203], off
	v_lshl_add_u64 v[202:203], v[226:227], 0, s[12:13]
	s_mov_b32 m0, s53
	s_nop 0
	global_load_lds_dwordx4 v[202:203], off
	v_lshl_add_u64 v[202:203], v[228:229], 0, s[12:13]
	s_mov_b32 m0, s54
	s_nop 0
	global_load_lds_dwordx4 v[202:203], off
	s_waitcnt vmcnt(8)
	s_waitcnt lgkmcnt(0)
	s_barrier
	s_setprio 1
	s_waitcnt lgkmcnt(0)
	v_mfma_f32_16x16x32_bf16 v[62:65], v[130:133], v[182:185], v[62:65]
	v_mfma_f32_16x16x32_bf16 v[58:61], v[138:141], v[182:185], v[58:61]
	v_mfma_f32_16x16x32_bf16 v[46:49], v[130:133], v[190:193], v[46:49]
	v_mfma_f32_16x16x32_bf16 v[42:45], v[138:141], v[190:193], v[42:45]
	v_mfma_f32_16x16x32_bf16 v[30:33], v[130:133], v[210:213], v[30:33]
	v_mfma_f32_16x16x32_bf16 v[26:29], v[138:141], v[210:213], v[26:29]
	v_mfma_f32_16x16x32_bf16 v[14:17], v[130:133], v[218:221], v[14:17]
	v_mfma_f32_16x16x32_bf16 v[10:13], v[138:141], v[218:221], v[10:13]
	v_mfma_f32_16x16x32_bf16 v[62:65], v[134:137], v[186:189], v[62:65]
	v_mfma_f32_16x16x32_bf16 v[58:61], v[142:145], v[186:189], v[58:61]
	v_mfma_f32_16x16x32_bf16 v[46:49], v[134:137], v[198:201], v[46:49]
	v_mfma_f32_16x16x32_bf16 v[42:45], v[142:145], v[198:201], v[42:45]
	v_mfma_f32_16x16x32_bf16 v[30:33], v[134:137], v[214:217], v[30:33]
	v_mfma_f32_16x16x32_bf16 v[26:29], v[142:145], v[214:217], v[26:29]
	v_mfma_f32_16x16x32_bf16 v[14:17], v[134:137], v[222:225], v[14:17]
	v_mfma_f32_16x16x32_bf16 v[10:13], v[142:145], v[222:225], v[10:13]
	v_mfma_f32_16x16x32_bf16 v[54:57], v[160:163], v[182:185], v[54:57]
	v_mfma_f32_16x16x32_bf16 v[50:53], v[174:177], v[182:185], v[50:53]
	v_mfma_f32_16x16x32_bf16 v[38:41], v[160:163], v[190:193], v[38:41]
	v_mfma_f32_16x16x32_bf16 v[34:37], v[174:177], v[190:193], v[34:37]
	v_mfma_f32_16x16x32_bf16 v[22:25], v[160:163], v[210:213], v[22:25]
	v_mfma_f32_16x16x32_bf16 v[18:21], v[174:177], v[210:213], v[18:21]
	v_mfma_f32_16x16x32_bf16 v[6:9], v[160:163], v[218:221], v[6:9]
	v_mfma_f32_16x16x32_bf16 v[2:5], v[174:177], v[218:221], v[2:5]
	v_mfma_f32_16x16x32_bf16 v[54:57], v[164:167], v[186:189], v[54:57]
	v_mfma_f32_16x16x32_bf16 v[50:53], v[178:181], v[186:189], v[50:53]
	v_mfma_f32_16x16x32_bf16 v[38:41], v[164:167], v[198:201], v[38:41]
	v_mfma_f32_16x16x32_bf16 v[34:37], v[178:181], v[198:201], v[34:37]
	v_mfma_f32_16x16x32_bf16 v[22:25], v[164:167], v[214:217], v[22:25]
	v_mfma_f32_16x16x32_bf16 v[18:21], v[178:181], v[214:217], v[18:21]
	v_mfma_f32_16x16x32_bf16 v[6:9], v[164:167], v[222:225], v[6:9]
	v_mfma_f32_16x16x32_bf16 v[2:5], v[178:181], v[222:225], v[2:5]
	s_setprio 2
	s_barrier
	s_add_u32 s34, s34, 0x100
	s_addc_u32 s35, s35, 0
	s_add_u32 s17, s17, 0x100
	s_addc_u32 s19, s19, 0
	s_cmp_ge_i32 s31, s69
	s_mov_b32 s21, s31
	s_cbranch_scc0 .LBB0_1122
	s_branch .Lpeeldone_8
.LBB0_1122:
	ds_read_b128 v[130:133], v170
	ds_read_b128 v[134:137], v170 offset:1024
	ds_read_b128 v[138:141], v170 offset:2048
	ds_read_b128 v[142:145], v170 offset:3072
	ds_read_b128 v[160:163], v171
	ds_read_b128 v[164:167], v171 offset:1024
	ds_read_b128 v[174:177], v171 offset:2048
	ds_read_b128 v[178:181], v171 offset:3072
	s_add_i32 s31, s21, 2
	s_add_u32 s36, s34, 0xfff80080
	s_addc_u32 s37, s35, -1
	s_cmp_eq_u32 s30, s21
	s_cselect_b32 s39, s23, s37
	s_cselect_b32 s38, s22, s36
	s_cselect_b32 s37, s25, s19
	s_cselect_b32 s36, s24, s17
	v_lshl_add_u64 v[202:203], s[34:35], 0, v[156:157]
	s_add_i32 m0, s27, 0xc000
	ds_read_b128 v[182:185], v172
	ds_read_b128 v[186:189], v172 offset:1024
	ds_read_b128 v[190:193], v172 offset:2048
	ds_read_b128 v[198:201], v172 offset:3072
	ds_read_b128 v[210:213], v172 offset:4096
	ds_read_b128 v[214:217], v172 offset:5120
	ds_read_b128 v[218:221], v172 offset:6144
	ds_read_b128 v[222:225], v172 offset:7168
	global_load_lds_dwordx4 v[202:203], off
	v_lshl_add_u64 v[202:203], s[34:35], 0, v[158:159]
	s_add_i32 m0, s27, 0xe000
	s_nop 0
	global_load_lds_dwordx4 v[202:203], off
	s_waitcnt vmcnt(8)
	s_waitcnt lgkmcnt(0)
	s_barrier
	s_setprio 1
	s_waitcnt lgkmcnt(0)
	v_mfma_f32_16x16x32_bf16 v[126:129], v[130:133], v[182:185], v[126:129]
	v_mfma_f32_16x16x32_bf16 v[122:125], v[138:141], v[182:185], v[122:125]
	v_mfma_f32_16x16x32_bf16 v[118:121], v[130:133], v[190:193], v[118:121]
	v_mfma_f32_16x16x32_bf16 v[110:113], v[138:141], v[190:193], v[110:113]
	v_mfma_f32_16x16x32_bf16 v[94:97], v[130:133], v[210:213], v[94:97]
	v_mfma_f32_16x16x32_bf16 v[90:93], v[138:141], v[210:213], v[90:93]
	v_mfma_f32_16x16x32_bf16 v[78:81], v[130:133], v[218:221], v[78:81]
	v_mfma_f32_16x16x32_bf16 v[74:77], v[138:141], v[218:221], v[74:77]
	v_mfma_f32_16x16x32_bf16 v[126:129], v[134:137], v[186:189], v[126:129]
	v_mfma_f32_16x16x32_bf16 v[122:125], v[142:145], v[186:189], v[122:125]
	v_mfma_f32_16x16x32_bf16 v[118:121], v[134:137], v[198:201], v[118:121]
	v_mfma_f32_16x16x32_bf16 v[110:113], v[142:145], v[198:201], v[110:113]
	v_mfma_f32_16x16x32_bf16 v[94:97], v[134:137], v[214:217], v[94:97]
	v_mfma_f32_16x16x32_bf16 v[90:93], v[142:145], v[214:217], v[90:93]
	v_mfma_f32_16x16x32_bf16 v[78:81], v[134:137], v[222:225], v[78:81]
	v_mfma_f32_16x16x32_bf16 v[74:77], v[142:145], v[222:225], v[74:77]
	v_mfma_f32_16x16x32_bf16 v[114:117], v[160:163], v[182:185], v[114:117]
	v_mfma_f32_16x16x32_bf16 v[106:109], v[174:177], v[182:185], v[106:109]
	v_mfma_f32_16x16x32_bf16 v[102:105], v[160:163], v[190:193], v[102:105]
	v_mfma_f32_16x16x32_bf16 v[98:101], v[174:177], v[190:193], v[98:101]
	v_mfma_f32_16x16x32_bf16 v[86:89], v[160:163], v[210:213], v[86:89]
	v_mfma_f32_16x16x32_bf16 v[82:85], v[174:177], v[210:213], v[82:85]
	v_mfma_f32_16x16x32_bf16 v[70:73], v[160:163], v[218:221], v[70:73]
	v_mfma_f32_16x16x32_bf16 v[66:69], v[174:177], v[218:221], v[66:69]
	v_mfma_f32_16x16x32_bf16 v[114:117], v[164:167], v[186:189], v[114:117]
	v_mfma_f32_16x16x32_bf16 v[106:109], v[178:181], v[186:189], v[106:109]
	v_mfma_f32_16x16x32_bf16 v[102:105], v[164:167], v[198:201], v[102:105]
	v_mfma_f32_16x16x32_bf16 v[98:101], v[178:181], v[198:201], v[98:101]
	v_mfma_f32_16x16x32_bf16 v[86:89], v[164:167], v[214:217], v[86:89]
	v_mfma_f32_16x16x32_bf16 v[82:85], v[178:181], v[214:217], v[82:85]
	v_mfma_f32_16x16x32_bf16 v[70:73], v[164:167], v[222:225], v[70:73]
	v_mfma_f32_16x16x32_bf16 v[66:69], v[178:181], v[222:225], v[66:69]
	s_setprio 2
	s_barrier
	s_add_i32 s21, s63, s33
	v_lshl_add_u64 v[202:203], s[36:37], 0, v[148:149]
	s_mov_b32 m0, s21
	ds_read_b128 v[182:185], v172 offset:16384
	ds_read_b128 v[186:189], v172 offset:17408
	ds_read_b128 v[190:193], v172 offset:18432
	ds_read_b128 v[198:201], v172 offset:19456
	ds_read_b128 v[210:213], v172 offset:20480
	ds_read_b128 v[214:217], v172 offset:21504
	ds_read_b128 v[218:221], v172 offset:22528
	ds_read_b128 v[222:225], v172 offset:23552
	global_load_lds_dwordx4 v[202:203], off
	s_add_i32 m0, s21, 0x2000
	s_add_u32 s40, s36, 0x80000
	v_lshl_add_u64 v[206:207], s[36:37], 0, v[152:153]
	s_addc_u32 s41, s37, 0
	s_add_i32 s21, s64, s33
	global_load_lds_dwordx4 v[206:207], off
	v_lshl_add_u64 v[226:227], s[40:41], 0, v[148:149]
	s_mov_b32 m0, s21
	v_lshl_add_u64 v[228:229], s[38:39], 0, v[150:151]
	global_load_lds_dwordx4 v[226:227], off
	v_lshl_add_u64 v[226:227], s[40:41], 0, v[152:153]
	s_add_i32 m0, s21, 0x2000
	s_nop 0
	global_load_lds_dwordx4 v[226:227], off
	v_lshl_add_u64 v[226:227], s[38:39], 0, v[146:147]
	s_mov_b32 m0, s27
	s_nop 0
	global_load_lds_dwordx4 v[226:227], off
	s_mov_b32 m0, s29
	s_nop 0
	global_load_lds_dwordx4 v[228:229], off
	s_waitcnt vmcnt(8)
	s_waitcnt lgkmcnt(0)
	s_barrier
	s_setprio 1
	s_waitcnt lgkmcnt(0)
	v_mfma_f32_16x16x32_bf16 v[62:65], v[130:133], v[182:185], v[62:65]
	v_mfma_f32_16x16x32_bf16 v[58:61], v[138:141], v[182:185], v[58:61]
	v_mfma_f32_16x16x32_bf16 v[46:49], v[130:133], v[190:193], v[46:49]
	v_mfma_f32_16x16x32_bf16 v[42:45], v[138:141], v[190:193], v[42:45]
	v_mfma_f32_16x16x32_bf16 v[30:33], v[130:133], v[210:213], v[30:33]
	v_mfma_f32_16x16x32_bf16 v[26:29], v[138:141], v[210:213], v[26:29]
	v_mfma_f32_16x16x32_bf16 v[14:17], v[130:133], v[218:221], v[14:17]
	v_mfma_f32_16x16x32_bf16 v[10:13], v[138:141], v[218:221], v[10:13]
	v_mfma_f32_16x16x32_bf16 v[62:65], v[134:137], v[186:189], v[62:65]
	v_mfma_f32_16x16x32_bf16 v[58:61], v[142:145], v[186:189], v[58:61]
	v_mfma_f32_16x16x32_bf16 v[46:49], v[134:137], v[198:201], v[46:49]
	v_mfma_f32_16x16x32_bf16 v[42:45], v[142:145], v[198:201], v[42:45]
	v_mfma_f32_16x16x32_bf16 v[30:33], v[134:137], v[214:217], v[30:33]
	v_mfma_f32_16x16x32_bf16 v[26:29], v[142:145], v[214:217], v[26:29]
	v_mfma_f32_16x16x32_bf16 v[14:17], v[134:137], v[222:225], v[14:17]
	v_mfma_f32_16x16x32_bf16 v[10:13], v[142:145], v[222:225], v[10:13]
	v_mfma_f32_16x16x32_bf16 v[54:57], v[160:163], v[182:185], v[54:57]
	v_mfma_f32_16x16x32_bf16 v[50:53], v[174:177], v[182:185], v[50:53]
	v_mfma_f32_16x16x32_bf16 v[38:41], v[160:163], v[190:193], v[38:41]
	v_mfma_f32_16x16x32_bf16 v[34:37], v[174:177], v[190:193], v[34:37]
	v_mfma_f32_16x16x32_bf16 v[22:25], v[160:163], v[210:213], v[22:25]
	v_mfma_f32_16x16x32_bf16 v[18:21], v[174:177], v[210:213], v[18:21]
	v_mfma_f32_16x16x32_bf16 v[6:9], v[160:163], v[218:221], v[6:9]
	v_mfma_f32_16x16x32_bf16 v[2:5], v[174:177], v[218:221], v[2:5]
	v_mfma_f32_16x16x32_bf16 v[54:57], v[164:167], v[186:189], v[54:57]
	v_mfma_f32_16x16x32_bf16 v[50:53], v[178:181], v[186:189], v[50:53]
	v_mfma_f32_16x16x32_bf16 v[38:41], v[164:167], v[198:201], v[38:41]
	v_mfma_f32_16x16x32_bf16 v[34:37], v[178:181], v[198:201], v[34:37]
	v_mfma_f32_16x16x32_bf16 v[22:25], v[164:167], v[214:217], v[22:25]
	v_mfma_f32_16x16x32_bf16 v[18:21], v[178:181], v[214:217], v[18:21]
	v_mfma_f32_16x16x32_bf16 v[6:9], v[164:167], v[222:225], v[6:9]
	v_mfma_f32_16x16x32_bf16 v[2:5], v[178:181], v[222:225], v[2:5]
	s_setprio 2
	s_barrier
	s_add_i32 s21, 0, 0x18000
	s_add_i32 s40, 0, 0x1c000
	v_add_u32_e32 v142, s21, v168
	v_add_u32_e32 v173, s40, v168
	ds_read_b128 v[130:133], v142
	ds_read_b128 v[134:137], v142 offset:1024
	ds_read_b128 v[138:141], v142 offset:2048
	ds_read_b128 v[142:145], v142 offset:3072
	ds_read_b128 v[160:163], v173
	ds_read_b128 v[164:167], v173 offset:1024
	ds_read_b128 v[174:177], v173 offset:2048
	ds_read_b128 v[178:181], v173 offset:3072
	s_add_u32 s38, s38, 0x80000
	s_addc_u32 s39, s39, 0
	s_mov_b32 m0, s42
	v_lshl_add_u64 v[230:231], s[38:39], 0, v[146:147]
	ds_read_b128 v[182:185], v172 offset:32768
	ds_read_b128 v[186:189], v172 offset:33792
	ds_read_b128 v[190:193], v172 offset:34816
	ds_read_b128 v[198:201], v172 offset:35840
	ds_read_b128 v[210:213], v172 offset:36864
	ds_read_b128 v[214:217], v172 offset:37888
	ds_read_b128 v[218:221], v172 offset:38912
	ds_read_b128 v[222:225], v172 offset:39936
	global_load_lds_dwordx4 v[230:231], off
	v_lshl_add_u64 v[230:231], s[38:39], 0, v[150:151]
	s_mov_b32 m0, s43
	s_nop 0
	global_load_lds_dwordx4 v[230:231], off
	s_waitcnt vmcnt(8)
	s_waitcnt lgkmcnt(0)
	s_barrier
	s_setprio 1
	s_waitcnt lgkmcnt(0)
	v_mfma_f32_16x16x32_bf16 v[126:129], v[130:133], v[182:185], v[126:129]
	v_mfma_f32_16x16x32_bf16 v[122:125], v[138:141], v[182:185], v[122:125]
	v_mfma_f32_16x16x32_bf16 v[118:121], v[130:133], v[190:193], v[118:121]
	v_mfma_f32_16x16x32_bf16 v[110:113], v[138:141], v[190:193], v[110:113]
	v_mfma_f32_16x16x32_bf16 v[94:97], v[130:133], v[210:213], v[94:97]
	v_mfma_f32_16x16x32_bf16 v[90:93], v[138:141], v[210:213], v[90:93]
	v_mfma_f32_16x16x32_bf16 v[78:81], v[130:133], v[218:221], v[78:81]
	v_mfma_f32_16x16x32_bf16 v[74:77], v[138:141], v[218:221], v[74:77]
	v_mfma_f32_16x16x32_bf16 v[126:129], v[134:137], v[186:189], v[126:129]
	v_mfma_f32_16x16x32_bf16 v[122:125], v[142:145], v[186:189], v[122:125]
	v_mfma_f32_16x16x32_bf16 v[118:121], v[134:137], v[198:201], v[118:121]
	v_mfma_f32_16x16x32_bf16 v[110:113], v[142:145], v[198:201], v[110:113]
	v_mfma_f32_16x16x32_bf16 v[94:97], v[134:137], v[214:217], v[94:97]
	v_mfma_f32_16x16x32_bf16 v[90:93], v[142:145], v[214:217], v[90:93]
	v_mfma_f32_16x16x32_bf16 v[78:81], v[134:137], v[222:225], v[78:81]
	v_mfma_f32_16x16x32_bf16 v[74:77], v[142:145], v[222:225], v[74:77]
	v_mfma_f32_16x16x32_bf16 v[114:117], v[160:163], v[182:185], v[114:117]
	v_mfma_f32_16x16x32_bf16 v[106:109], v[174:177], v[182:185], v[106:109]
	v_mfma_f32_16x16x32_bf16 v[102:105], v[160:163], v[190:193], v[102:105]
	v_mfma_f32_16x16x32_bf16 v[98:101], v[174:177], v[190:193], v[98:101]
	v_mfma_f32_16x16x32_bf16 v[86:89], v[160:163], v[210:213], v[86:89]
	v_mfma_f32_16x16x32_bf16 v[82:85], v[174:177], v[210:213], v[82:85]
	v_mfma_f32_16x16x32_bf16 v[70:73], v[160:163], v[218:221], v[70:73]
	v_mfma_f32_16x16x32_bf16 v[66:69], v[174:177], v[218:221], v[66:69]
	v_mfma_f32_16x16x32_bf16 v[114:117], v[164:167], v[186:189], v[114:117]
	v_mfma_f32_16x16x32_bf16 v[106:109], v[178:181], v[186:189], v[106:109]
	v_mfma_f32_16x16x32_bf16 v[102:105], v[164:167], v[198:201], v[102:105]
	v_mfma_f32_16x16x32_bf16 v[98:101], v[178:181], v[198:201], v[98:101]
	v_mfma_f32_16x16x32_bf16 v[86:89], v[164:167], v[214:217], v[86:89]
	v_mfma_f32_16x16x32_bf16 v[82:85], v[178:181], v[214:217], v[82:85]
	v_mfma_f32_16x16x32_bf16 v[70:73], v[164:167], v[222:225], v[70:73]
	v_mfma_f32_16x16x32_bf16 v[66:69], v[178:181], v[222:225], v[66:69]
	s_setprio 2
	s_barrier
	s_add_i32 s21, s21, s33
	v_lshl_add_u64 v[202:203], v[202:203], 0, s[12:13]
	s_mov_b32 m0, s21
	ds_read_b128 v[182:185], v172 offset:49152
	ds_read_b128 v[186:189], v172 offset:50176
	ds_read_b128 v[190:193], v172 offset:51200
	ds_read_b128 v[198:201], v172 offset:52224
	ds_read_b128 v[210:213], v172 offset:53248
	ds_read_b128 v[214:217], v172 offset:54272
	ds_read_b128 v[218:221], v172 offset:55296
	ds_read_b128 v[222:225], v172 offset:56320
	global_load_lds_dwordx4 v[202:203], off
	s_add_i32 m0, s21, 0x2000
	s_add_u32 s36, s36, 0x80080
	v_lshl_add_u64 v[202:203], v[206:207], 0, s[12:13]
	s_addc_u32 s37, s37, 0
	s_add_i32 s21, s40, s33
	global_load_lds_dwordx4 v[202:203], off
	v_lshl_add_u64 v[202:203], s[36:37], 0, v[148:149]
	s_mov_b32 m0, s21
	s_nop 0
	global_load_lds_dwordx4 v[202:203], off
	v_lshl_add_u64 v[202:203], s[36:37], 0, v[152:153]
	s_add_i32 m0, s21, 0x2000
	s_nop 0
	global_load_lds_dwordx4 v[202:203], off
	v_lshl_add_u64 v[202:203], v[226:227], 0, s[12:13]
	s_mov_b32 m0, s53
	s_nop 0
	global_load_lds_dwordx4 v[202:203], off
	v_lshl_add_u64 v[202:203], v[228:229], 0, s[12:13]
	s_mov_b32 m0, s54
	s_nop 0
	global_load_lds_dwordx4 v[202:203], off
	s_waitcnt vmcnt(8)
	s_waitcnt lgkmcnt(0)
	s_barrier
	s_setprio 1
	s_waitcnt lgkmcnt(0)
	v_mfma_f32_16x16x32_bf16 v[62:65], v[130:133], v[182:185], v[62:65]
	v_mfma_f32_16x16x32_bf16 v[58:61], v[138:141], v[182:185], v[58:61]
	v_mfma_f32_16x16x32_bf16 v[46:49], v[130:133], v[190:193], v[46:49]
	v_mfma_f32_16x16x32_bf16 v[42:45], v[138:141], v[190:193], v[42:45]
	v_mfma_f32_16x16x32_bf16 v[30:33], v[130:133], v[210:213], v[30:33]
	v_mfma_f32_16x16x32_bf16 v[26:29], v[138:141], v[210:213], v[26:29]
	v_mfma_f32_16x16x32_bf16 v[14:17], v[130:133], v[218:221], v[14:17]
	v_mfma_f32_16x16x32_bf16 v[10:13], v[138:141], v[218:221], v[10:13]
	v_mfma_f32_16x16x32_bf16 v[62:65], v[134:137], v[186:189], v[62:65]
	v_mfma_f32_16x16x32_bf16 v[58:61], v[142:145], v[186:189], v[58:61]
	v_mfma_f32_16x16x32_bf16 v[46:49], v[134:137], v[198:201], v[46:49]
	v_mfma_f32_16x16x32_bf16 v[42:45], v[142:145], v[198:201], v[42:45]
	v_mfma_f32_16x16x32_bf16 v[30:33], v[134:137], v[214:217], v[30:33]
	v_mfma_f32_16x16x32_bf16 v[26:29], v[142:145], v[214:217], v[26:29]
	v_mfma_f32_16x16x32_bf16 v[14:17], v[134:137], v[222:225], v[14:17]
	v_mfma_f32_16x16x32_bf16 v[10:13], v[142:145], v[222:225], v[10:13]
	v_mfma_f32_16x16x32_bf16 v[54:57], v[160:163], v[182:185], v[54:57]
	v_mfma_f32_16x16x32_bf16 v[50:53], v[174:177], v[182:185], v[50:53]
	v_mfma_f32_16x16x32_bf16 v[38:41], v[160:163], v[190:193], v[38:41]
	v_mfma_f32_16x16x32_bf16 v[34:37], v[174:177], v[190:193], v[34:37]
	v_mfma_f32_16x16x32_bf16 v[22:25], v[160:163], v[210:213], v[22:25]
	v_mfma_f32_16x16x32_bf16 v[18:21], v[174:177], v[210:213], v[18:21]
	v_mfma_f32_16x16x32_bf16 v[6:9], v[160:163], v[218:221], v[6:9]
	v_mfma_f32_16x16x32_bf16 v[2:5], v[174:177], v[218:221], v[2:5]
	v_mfma_f32_16x16x32_bf16 v[54:57], v[164:167], v[186:189], v[54:57]
	v_mfma_f32_16x16x32_bf16 v[50:53], v[178:181], v[186:189], v[50:53]
	v_mfma_f32_16x16x32_bf16 v[38:41], v[164:167], v[198:201], v[38:41]
	v_mfma_f32_16x16x32_bf16 v[34:37], v[178:181], v[198:201], v[34:37]
	v_mfma_f32_16x16x32_bf16 v[22:25], v[164:167], v[214:217], v[22:25]
	v_mfma_f32_16x16x32_bf16 v[18:21], v[178:181], v[214:217], v[18:21]
	v_mfma_f32_16x16x32_bf16 v[6:9], v[164:167], v[222:225], v[6:9]
	v_mfma_f32_16x16x32_bf16 v[2:5], v[178:181], v[222:225], v[2:5]
	s_setprio 2
	s_barrier
	s_add_u32 s34, s34, 0x100
	s_addc_u32 s35, s35, 0
	s_add_u32 s17, s17, 0x100
	s_addc_u32 s19, s19, 0
	s_cmp_ge_i32 s31, s69
	s_mov_b32 s21, s31
	s_cbranch_scc0 .LBB0_1122

.Lpeel_7:
	ds_read_b128 v[152:155], v148
	ds_read_b128 v[156:159], v148 offset:1024
	s_add_i32 s29, s19, 2
	s_add_u32 s34, s30, 0xfff80080
	s_addc_u32 s35, s31, -1
	s_cmp_eq_u32 s28, s19
	s_cselect_b32 s37, s21, s35
	s_cselect_b32 s36, s20, s34
	s_cselect_b32 s35, s23, s17
	s_cselect_b32 s34, s22, s15
	v_lshl_add_u64 v[144:145], s[30:31], 0, v[140:141]
	s_add_i32 m0, s27, 0xc000
	global_load_lds_dwordx4 v[144:145], off
	v_lshl_add_u64 v[144:145], s[30:31], 0, v[142:143]
	s_add_i32 m0, s27, 0xe000
	s_nop 0
	global_load_lds_dwordx4 v[144:145], off
	s_waitcnt vmcnt(8)
	s_waitcnt lgkmcnt(0)
	s_barrier
	s_setprio 1
	s_waitcnt lgkmcnt(0)
	v_mfma_f32_16x16x32_bf16 v[126:129], v[152:155], v[184:187], 0
	v_mfma_f32_16x16x32_bf16 v[122:125], v[160:163], v[184:187], 0
	v_mfma_f32_16x16x32_bf16 v[110:113], v[152:155], v[198:201], 0
	v_mfma_f32_16x16x32_bf16 v[106:109], v[160:163], v[198:201], 0
	v_mfma_f32_16x16x32_bf16 v[94:97], v[152:155], v[214:217], 0
	v_mfma_f32_16x16x32_bf16 v[90:93], v[160:163], v[214:217], 0
	v_mfma_f32_16x16x32_bf16 v[78:81], v[152:155], v[222:225], 0
	v_mfma_f32_16x16x32_bf16 v[74:77], v[160:163], v[222:225], 0
	v_mfma_f32_16x16x32_bf16 v[126:129], v[156:159], v[188:191], v[126:129]
	v_mfma_f32_16x16x32_bf16 v[122:125], v[164:167], v[188:191], v[122:125]
	v_mfma_f32_16x16x32_bf16 v[110:113], v[156:159], v[210:213], v[110:113]
	v_mfma_f32_16x16x32_bf16 v[106:109], v[164:167], v[210:213], v[106:109]
	v_mfma_f32_16x16x32_bf16 v[94:97], v[156:159], v[218:221], v[94:97]
	v_mfma_f32_16x16x32_bf16 v[90:93], v[164:167], v[218:221], v[90:93]
	v_mfma_f32_16x16x32_bf16 v[78:81], v[156:159], v[226:229], v[78:81]
	v_mfma_f32_16x16x32_bf16 v[74:77], v[164:167], v[226:229], v[74:77]
	v_mfma_f32_16x16x32_bf16 v[118:121], v[168:171], v[184:187], 0
	v_mfma_f32_16x16x32_bf16 v[114:117], v[176:179], v[184:187], 0
	v_mfma_f32_16x16x32_bf16 v[102:105], v[168:171], v[198:201], 0
	v_mfma_f32_16x16x32_bf16 v[98:101], v[176:179], v[198:201], 0
	v_mfma_f32_16x16x32_bf16 v[86:89], v[168:171], v[214:217], 0
	v_mfma_f32_16x16x32_bf16 v[82:85], v[176:179], v[214:217], 0
	v_mfma_f32_16x16x32_bf16 v[70:73], v[168:171], v[222:225], 0
	v_mfma_f32_16x16x32_bf16 v[66:69], v[176:179], v[222:225], 0
	v_mfma_f32_16x16x32_bf16 v[118:121], v[172:175], v[188:191], v[118:121]
	v_mfma_f32_16x16x32_bf16 v[114:117], v[180:183], v[188:191], v[114:117]
	v_mfma_f32_16x16x32_bf16 v[102:105], v[172:175], v[210:213], v[102:105]
	v_mfma_f32_16x16x32_bf16 v[98:101], v[180:183], v[210:213], v[98:101]
	v_mfma_f32_16x16x32_bf16 v[86:89], v[172:175], v[218:221], v[86:89]
	v_mfma_f32_16x16x32_bf16 v[82:85], v[180:183], v[218:221], v[82:85]
	v_mfma_f32_16x16x32_bf16 v[70:73], v[172:175], v[226:229], v[70:73]
	v_mfma_f32_16x16x32_bf16 v[66:69], v[180:183], v[226:229], v[66:69]
	s_setprio 2
	s_barrier
	s_add_i32 s19, s60, s33
	v_lshl_add_u64 v[144:145], s[34:35], 0, v[132:133]
	s_mov_b32 m0, s19
	ds_read_b128 v[184:187], v150 offset:16384
	ds_read_b128 v[188:191], v150 offset:17408
	ds_read_b128 v[198:201], v150 offset:18432
	ds_read_b128 v[210:213], v150 offset:19456
	ds_read_b128 v[214:217], v150 offset:20480
	ds_read_b128 v[218:221], v150 offset:21504
	ds_read_b128 v[222:225], v150 offset:22528
	ds_read_b128 v[226:229], v150 offset:23552
	global_load_lds_dwordx4 v[144:145], off
	s_add_i32 m0, s19, 0x2000
	s_add_u32 s38, s34, 0x80000
	v_lshl_add_u64 v[192:193], s[34:35], 0, v[136:137]
	s_addc_u32 s39, s35, 0
	s_add_i32 s19, s61, s33
	global_load_lds_dwordx4 v[192:193], off
	v_lshl_add_u64 v[202:203], s[38:39], 0, v[132:133]
	s_mov_b32 m0, s19
	v_lshl_add_u64 v[206:207], s[36:37], 0, v[134:135]
	global_load_lds_dwordx4 v[202:203], off
	v_lshl_add_u64 v[202:203], s[38:39], 0, v[136:137]
	s_add_i32 m0, s19, 0x2000
	s_nop 0
	global_load_lds_dwordx4 v[202:203], off
	v_lshl_add_u64 v[202:203], s[36:37], 0, v[130:131]
	s_mov_b32 m0, s27
	s_nop 0
	global_load_lds_dwordx4 v[202:203], off
	s_mov_b32 m0, s41
	s_nop 0
	global_load_lds_dwordx4 v[206:207], off
	s_waitcnt vmcnt(8)
	s_waitcnt lgkmcnt(0)
	s_barrier
	s_setprio 1
	s_waitcnt lgkmcnt(0)
	v_mfma_f32_16x16x32_bf16 v[62:65], v[152:155], v[184:187], 0
	v_mfma_f32_16x16x32_bf16 v[58:61], v[160:163], v[184:187], 0
	v_mfma_f32_16x16x32_bf16 v[46:49], v[152:155], v[198:201], 0
	v_mfma_f32_16x16x32_bf16 v[42:45], v[160:163], v[198:201], 0
	v_mfma_f32_16x16x32_bf16 v[30:33], v[152:155], v[214:217], 0
	v_mfma_f32_16x16x32_bf16 v[26:29], v[160:163], v[214:217], 0
	v_mfma_f32_16x16x32_bf16 v[14:17], v[152:155], v[222:225], 0
	v_mfma_f32_16x16x32_bf16 v[10:13], v[160:163], v[222:225], 0
	v_mfma_f32_16x16x32_bf16 v[62:65], v[156:159], v[188:191], v[62:65]
	v_mfma_f32_16x16x32_bf16 v[58:61], v[164:167], v[188:191], v[58:61]
	v_mfma_f32_16x16x32_bf16 v[46:49], v[156:159], v[210:213], v[46:49]
	v_mfma_f32_16x16x32_bf16 v[42:45], v[164:167], v[210:213], v[42:45]
	v_mfma_f32_16x16x32_bf16 v[30:33], v[156:159], v[218:221], v[30:33]
	v_mfma_f32_16x16x32_bf16 v[26:29], v[164:167], v[218:221], v[26:29]
	v_mfma_f32_16x16x32_bf16 v[14:17], v[156:159], v[226:229], v[14:17]
	v_mfma_f32_16x16x32_bf16 v[10:13], v[164:167], v[226:229], v[10:13]
	v_mfma_f32_16x16x32_bf16 v[54:57], v[168:171], v[184:187], 0
	v_mfma_f32_16x16x32_bf16 v[50:53], v[176:179], v[184:187], 0
	v_mfma_f32_16x16x32_bf16 v[38:41], v[168:171], v[198:201], 0
	v_mfma_f32_16x16x32_bf16 v[34:37], v[176:179], v[198:201], 0
	v_mfma_f32_16x16x32_bf16 v[22:25], v[168:171], v[214:217], 0
	v_mfma_f32_16x16x32_bf16 v[18:21], v[176:179], v[214:217], 0
	v_mfma_f32_16x16x32_bf16 v[6:9], v[168:171], v[222:225], 0
	v_mfma_f32_16x16x32_bf16 v[2:5], v[176:179], v[222:225], 0
	v_mfma_f32_16x16x32_bf16 v[54:57], v[172:175], v[188:191], v[54:57]
	v_mfma_f32_16x16x32_bf16 v[50:53], v[180:183], v[188:191], v[50:53]
	v_mfma_f32_16x16x32_bf16 v[38:41], v[172:175], v[210:213], v[38:41]
	v_mfma_f32_16x16x32_bf16 v[34:37], v[180:183], v[210:213], v[34:37]
	v_mfma_f32_16x16x32_bf16 v[22:25], v[172:175], v[218:221], v[22:25]
	v_mfma_f32_16x16x32_bf16 v[18:21], v[180:183], v[218:221], v[18:21]
	v_mfma_f32_16x16x32_bf16 v[6:9], v[172:175], v[226:229], v[6:9]
	v_mfma_f32_16x16x32_bf16 v[2:5], v[180:183], v[226:229], v[2:5]
	s_setprio 2
	s_barrier
	s_add_i32 s19, 0, 0x18000
	v_add_u32_e32 v151, s19, v146
	s_add_i32 s38, 0, 0x1c000
	ds_read_b128 v[152:155], v151
	ds_read_b128 v[156:159], v151 offset:1024
	ds_read_b128 v[160:163], v151 offset:2048
	ds_read_b128 v[164:167], v151 offset:3072
	v_add_u32_e32 v151, s38, v146
	ds_read_b128 v[168:171], v151
	ds_read_b128 v[172:175], v151 offset:1024
	ds_read_b128 v[176:179], v151 offset:2048
	ds_read_b128 v[180:183], v151 offset:3072
	s_add_u32 s36, s36, 0x80000
	s_addc_u32 s37, s37, 0
	s_mov_b32 m0, s42
	v_lshl_add_u64 v[230:231], s[36:37], 0, v[130:131]
	ds_read_b128 v[184:187], v150 offset:32768
	ds_read_b128 v[188:191], v150 offset:33792
	ds_read_b128 v[198:201], v150 offset:34816
	ds_read_b128 v[210:213], v150 offset:35840
	ds_read_b128 v[214:217], v150 offset:36864
	ds_read_b128 v[218:221], v150 offset:37888
	ds_read_b128 v[222:225], v150 offset:38912
	ds_read_b128 v[226:229], v150 offset:39936
	global_load_lds_dwordx4 v[230:231], off
	v_lshl_add_u64 v[230:231], s[36:37], 0, v[134:135]
	s_mov_b32 m0, s43
	s_nop 0
	global_load_lds_dwordx4 v[230:231], off
	s_waitcnt vmcnt(8)
	s_waitcnt lgkmcnt(0)
	s_barrier
	s_setprio 1
	s_waitcnt lgkmcnt(0)
	v_mfma_f32_16x16x32_bf16 v[126:129], v[152:155], v[184:187], v[126:129]
	v_mfma_f32_16x16x32_bf16 v[122:125], v[160:163], v[184:187], v[122:125]
	v_mfma_f32_16x16x32_bf16 v[110:113], v[152:155], v[198:201], v[110:113]
	v_mfma_f32_16x16x32_bf16 v[106:109], v[160:163], v[198:201], v[106:109]
	v_mfma_f32_16x16x32_bf16 v[94:97], v[152:155], v[214:217], v[94:97]
	v_mfma_f32_16x16x32_bf16 v[90:93], v[160:163], v[214:217], v[90:93]
	v_mfma_f32_16x16x32_bf16 v[78:81], v[152:155], v[222:225], v[78:81]
	v_mfma_f32_16x16x32_bf16 v[74:77], v[160:163], v[222:225], v[74:77]
	v_mfma_f32_16x16x32_bf16 v[126:129], v[156:159], v[188:191], v[126:129]
	v_mfma_f32_16x16x32_bf16 v[122:125], v[164:167], v[188:191], v[122:125]
	v_mfma_f32_16x16x32_bf16 v[110:113], v[156:159], v[210:213], v[110:113]
	v_mfma_f32_16x16x32_bf16 v[106:109], v[164:167], v[210:213], v[106:109]
	v_mfma_f32_16x16x32_bf16 v[94:97], v[156:159], v[218:221], v[94:97]
	v_mfma_f32_16x16x32_bf16 v[90:93], v[164:167], v[218:221], v[90:93]
	v_mfma_f32_16x16x32_bf16 v[78:81], v[156:159], v[226:229], v[78:81]
	v_mfma_f32_16x16x32_bf16 v[74:77], v[164:167], v[226:229], v[74:77]
	v_mfma_f32_16x16x32_bf16 v[118:121], v[168:171], v[184:187], v[118:121]
	v_mfma_f32_16x16x32_bf16 v[114:117], v[176:179], v[184:187], v[114:117]
	v_mfma_f32_16x16x32_bf16 v[102:105], v[168:171], v[198:201], v[102:105]
	v_mfma_f32_16x16x32_bf16 v[98:101], v[176:179], v[198:201], v[98:101]
	v_mfma_f32_16x16x32_bf16 v[86:89], v[168:171], v[214:217], v[86:89]
	v_mfma_f32_16x16x32_bf16 v[82:85], v[176:179], v[214:217], v[82:85]
	v_mfma_f32_16x16x32_bf16 v[70:73], v[168:171], v[222:225], v[70:73]
	v_mfma_f32_16x16x32_bf16 v[66:69], v[176:179], v[222:225], v[66:69]
	v_mfma_f32_16x16x32_bf16 v[118:121], v[172:175], v[188:191], v[118:121]
	v_mfma_f32_16x16x32_bf16 v[114:117], v[180:183], v[188:191], v[114:117]
	v_mfma_f32_16x16x32_bf16 v[102:105], v[172:175], v[210:213], v[102:105]
	v_mfma_f32_16x16x32_bf16 v[98:101], v[180:183], v[210:213], v[98:101]
	v_mfma_f32_16x16x32_bf16 v[86:89], v[172:175], v[218:221], v[86:89]
	v_mfma_f32_16x16x32_bf16 v[82:85], v[180:183], v[218:221], v[82:85]
	v_mfma_f32_16x16x32_bf16 v[70:73], v[172:175], v[226:229], v[70:73]
	v_mfma_f32_16x16x32_bf16 v[66:69], v[180:183], v[226:229], v[66:69]
	s_setprio 2
	s_barrier
	s_add_i32 s19, s19, s33
	v_lshl_add_u64 v[144:145], v[144:145], 0, s[10:11]
	s_mov_b32 m0, s19
	ds_read_b128 v[184:187], v150 offset:49152
	ds_read_b128 v[188:191], v150 offset:50176
	ds_read_b128 v[198:201], v150 offset:51200
	ds_read_b128 v[210:213], v150 offset:52224
	ds_read_b128 v[214:217], v150 offset:53248
	ds_read_b128 v[218:221], v150 offset:54272
	ds_read_b128 v[222:225], v150 offset:55296
	ds_read_b128 v[226:229], v150 offset:56320
	global_load_lds_dwordx4 v[144:145], off
	s_add_i32 m0, s19, 0x2000
	s_add_u32 s34, s34, 0x80080
	v_lshl_add_u64 v[144:145], v[192:193], 0, s[10:11]
	s_addc_u32 s35, s35, 0
	s_add_i32 s19, s38, s33
	global_load_lds_dwordx4 v[144:145], off
	v_lshl_add_u64 v[144:145], s[34:35], 0, v[132:133]
	s_mov_b32 m0, s19
	s_nop 0
	global_load_lds_dwordx4 v[144:145], off
	v_lshl_add_u64 v[144:145], s[34:35], 0, v[136:137]
	s_add_i32 m0, s19, 0x2000
	s_nop 0
	global_load_lds_dwordx4 v[144:145], off
	v_lshl_add_u64 v[144:145], v[202:203], 0, s[10:11]
	s_mov_b32 m0, s51
	s_nop 0
	global_load_lds_dwordx4 v[144:145], off
	v_lshl_add_u64 v[144:145], v[206:207], 0, s[10:11]
	s_mov_b32 m0, s52
	s_nop 0
	global_load_lds_dwordx4 v[144:145], off
	s_waitcnt vmcnt(8)
	s_waitcnt lgkmcnt(0)
	s_barrier
	s_setprio 1
	s_waitcnt lgkmcnt(0)
	v_mfma_f32_16x16x32_bf16 v[62:65], v[152:155], v[184:187], v[62:65]
	v_mfma_f32_16x16x32_bf16 v[58:61], v[160:163], v[184:187], v[58:61]
	v_mfma_f32_16x16x32_bf16 v[46:49], v[152:155], v[198:201], v[46:49]
	v_mfma_f32_16x16x32_bf16 v[42:45], v[160:163], v[198:201], v[42:45]
	v_mfma_f32_16x16x32_bf16 v[30:33], v[152:155], v[214:217], v[30:33]
	v_mfma_f32_16x16x32_bf16 v[26:29], v[160:163], v[214:217], v[26:29]
	v_mfma_f32_16x16x32_bf16 v[14:17], v[152:155], v[222:225], v[14:17]
	v_mfma_f32_16x16x32_bf16 v[10:13], v[160:163], v[222:225], v[10:13]
	v_mfma_f32_16x16x32_bf16 v[62:65], v[156:159], v[188:191], v[62:65]
	v_mfma_f32_16x16x32_bf16 v[58:61], v[164:167], v[188:191], v[58:61]
	v_mfma_f32_16x16x32_bf16 v[46:49], v[156:159], v[210:213], v[46:49]
	v_mfma_f32_16x16x32_bf16 v[42:45], v[164:167], v[210:213], v[42:45]
	v_mfma_f32_16x16x32_bf16 v[30:33], v[156:159], v[218:221], v[30:33]
	v_mfma_f32_16x16x32_bf16 v[26:29], v[164:167], v[218:221], v[26:29]
	v_mfma_f32_16x16x32_bf16 v[14:17], v[156:159], v[226:229], v[14:17]
	v_mfma_f32_16x16x32_bf16 v[10:13], v[164:167], v[226:229], v[10:13]
	v_mfma_f32_16x16x32_bf16 v[54:57], v[168:171], v[184:187], v[54:57]
	v_mfma_f32_16x16x32_bf16 v[50:53], v[176:179], v[184:187], v[50:53]
	v_mfma_f32_16x16x32_bf16 v[38:41], v[168:171], v[198:201], v[38:41]
	v_mfma_f32_16x16x32_bf16 v[34:37], v[176:179], v[198:201], v[34:37]
	v_mfma_f32_16x16x32_bf16 v[22:25], v[168:171], v[214:217], v[22:25]
	v_mfma_f32_16x16x32_bf16 v[18:21], v[176:179], v[214:217], v[18:21]
	v_mfma_f32_16x16x32_bf16 v[6:9], v[168:171], v[222:225], v[6:9]
	v_mfma_f32_16x16x32_bf16 v[2:5], v[176:179], v[222:225], v[2:5]
	v_mfma_f32_16x16x32_bf16 v[54:57], v[172:175], v[188:191], v[54:57]
	v_mfma_f32_16x16x32_bf16 v[50:53], v[180:183], v[188:191], v[50:53]
	v_mfma_f32_16x16x32_bf16 v[38:41], v[172:175], v[210:213], v[38:41]
	v_mfma_f32_16x16x32_bf16 v[34:37], v[180:183], v[210:213], v[34:37]
	v_mfma_f32_16x16x32_bf16 v[22:25], v[172:175], v[218:221], v[22:25]
	v_mfma_f32_16x16x32_bf16 v[18:21], v[180:183], v[218:221], v[18:21]
	v_mfma_f32_16x16x32_bf16 v[6:9], v[172:175], v[226:229], v[6:9]
	v_mfma_f32_16x16x32_bf16 v[2:5], v[180:183], v[226:229], v[2:5]
	s_setprio 2
	s_barrier
	s_add_u32 s30, s30, 0x100
	s_addc_u32 s31, s31, 0
	s_add_u32 s15, s15, 0x100
	s_addc_u32 s17, s17, 0
	s_cmp_ge_i32 s29, s68
	s_mov_b32 s19, s29
	s_cbranch_scc0 .LBB0_1315
	s_branch .Lpeeldone_7
.LBB0_1315:
	ds_read_b128 v[152:155], v148
	ds_read_b128 v[156:159], v148 offset:1024
	ds_read_b128 v[160:163], v148 offset:2048
	ds_read_b128 v[164:167], v148 offset:3072
	ds_read_b128 v[168:171], v149
	ds_read_b128 v[172:175], v149 offset:1024
	ds_read_b128 v[176:179], v149 offset:2048
	ds_read_b128 v[180:183], v149 offset:3072
	s_add_i32 s29, s19, 2
	s_add_u32 s34, s30, 0xfff80080
	s_addc_u32 s35, s31, -1
	s_cmp_eq_u32 s28, s19
	s_cselect_b32 s37, s21, s35
	s_cselect_b32 s36, s20, s34
	s_cselect_b32 s35, s23, s17
	s_cselect_b32 s34, s22, s15
	v_lshl_add_u64 v[144:145], s[30:31], 0, v[140:141]
	s_add_i32 m0, s27, 0xc000
	ds_read_b128 v[184:187], v150
	ds_read_b128 v[188:191], v150 offset:1024
	ds_read_b128 v[198:201], v150 offset:2048
	ds_read_b128 v[210:213], v150 offset:3072
	ds_read_b128 v[214:217], v150 offset:4096
	ds_read_b128 v[218:221], v150 offset:5120
	ds_read_b128 v[222:225], v150 offset:6144
	ds_read_b128 v[226:229], v150 offset:7168
	global_load_lds_dwordx4 v[144:145], off
	v_lshl_add_u64 v[144:145], s[30:31], 0, v[142:143]
	s_add_i32 m0, s27, 0xe000
	s_nop 0
	global_load_lds_dwordx4 v[144:145], off
	s_waitcnt vmcnt(8)
	s_waitcnt lgkmcnt(0)
	s_barrier
	s_setprio 1
	s_waitcnt lgkmcnt(0)
	v_mfma_f32_16x16x32_bf16 v[126:129], v[152:155], v[184:187], v[126:129]
	v_mfma_f32_16x16x32_bf16 v[122:125], v[160:163], v[184:187], v[122:125]
	v_mfma_f32_16x16x32_bf16 v[110:113], v[152:155], v[198:201], v[110:113]
	v_mfma_f32_16x16x32_bf16 v[106:109], v[160:163], v[198:201], v[106:109]
	v_mfma_f32_16x16x32_bf16 v[94:97], v[152:155], v[214:217], v[94:97]
	v_mfma_f32_16x16x32_bf16 v[90:93], v[160:163], v[214:217], v[90:93]
	v_mfma_f32_16x16x32_bf16 v[78:81], v[152:155], v[222:225], v[78:81]
	v_mfma_f32_16x16x32_bf16 v[74:77], v[160:163], v[222:225], v[74:77]
	v_mfma_f32_16x16x32_bf16 v[126:129], v[156:159], v[188:191], v[126:129]
	v_mfma_f32_16x16x32_bf16 v[122:125], v[164:167], v[188:191], v[122:125]
	v_mfma_f32_16x16x32_bf16 v[110:113], v[156:159], v[210:213], v[110:113]
	v_mfma_f32_16x16x32_bf16 v[106:109], v[164:167], v[210:213], v[106:109]
	v_mfma_f32_16x16x32_bf16 v[94:97], v[156:159], v[218:221], v[94:97]
	v_mfma_f32_16x16x32_bf16 v[90:93], v[164:167], v[218:221], v[90:93]
	v_mfma_f32_16x16x32_bf16 v[78:81], v[156:159], v[226:229], v[78:81]
	v_mfma_f32_16x16x32_bf16 v[74:77], v[164:167], v[226:229], v[74:77]
	v_mfma_f32_16x16x32_bf16 v[118:121], v[168:171], v[184:187], v[118:121]
	v_mfma_f32_16x16x32_bf16 v[114:117], v[176:179], v[184:187], v[114:117]
	v_mfma_f32_16x16x32_bf16 v[102:105], v[168:171], v[198:201], v[102:105]
	v_mfma_f32_16x16x32_bf16 v[98:101], v[176:179], v[198:201], v[98:101]
	v_mfma_f32_16x16x32_bf16 v[86:89], v[168:171], v[214:217], v[86:89]
	v_mfma_f32_16x16x32_bf16 v[82:85], v[176:179], v[214:217], v[82:85]
	v_mfma_f32_16x16x32_bf16 v[70:73], v[168:171], v[222:225], v[70:73]
	v_mfma_f32_16x16x32_bf16 v[66:69], v[176:179], v[222:225], v[66:69]
	v_mfma_f32_16x16x32_bf16 v[118:121], v[172:175], v[188:191], v[118:121]
	v_mfma_f32_16x16x32_bf16 v[114:117], v[180:183], v[188:191], v[114:117]
	v_mfma_f32_16x16x32_bf16 v[102:105], v[172:175], v[210:213], v[102:105]
	v_mfma_f32_16x16x32_bf16 v[98:101], v[180:183], v[210:213], v[98:101]
	v_mfma_f32_16x16x32_bf16 v[86:89], v[172:175], v[218:221], v[86:89]
	v_mfma_f32_16x16x32_bf16 v[82:85], v[180:183], v[218:221], v[82:85]
	v_mfma_f32_16x16x32_bf16 v[70:73], v[172:175], v[226:229], v[70:73]
	v_mfma_f32_16x16x32_bf16 v[66:69], v[180:183], v[226:229], v[66:69]
	s_setprio 2
	s_barrier
	s_add_i32 s19, s60, s33
	v_lshl_add_u64 v[144:145], s[34:35], 0, v[132:133]
	s_mov_b32 m0, s19
	ds_read_b128 v[184:187], v150 offset:16384
	ds_read_b128 v[188:191], v150 offset:17408
	ds_read_b128 v[198:201], v150 offset:18432
	ds_read_b128 v[210:213], v150 offset:19456
	ds_read_b128 v[214:217], v150 offset:20480
	ds_read_b128 v[218:221], v150 offset:21504
	ds_read_b128 v[222:225], v150 offset:22528
	ds_read_b128 v[226:229], v150 offset:23552
	global_load_lds_dwordx4 v[144:145], off
	s_add_i32 m0, s19, 0x2000
	s_add_u32 s38, s34, 0x80000
	v_lshl_add_u64 v[192:193], s[34:35], 0, v[136:137]
	s_addc_u32 s39, s35, 0
	s_add_i32 s19, s61, s33
	global_load_lds_dwordx4 v[192:193], off
	v_lshl_add_u64 v[202:203], s[38:39], 0, v[132:133]
	s_mov_b32 m0, s19
	v_lshl_add_u64 v[206:207], s[36:37], 0, v[134:135]
	global_load_lds_dwordx4 v[202:203], off
	v_lshl_add_u64 v[202:203], s[38:39], 0, v[136:137]
	s_add_i32 m0, s19, 0x2000
	s_nop 0
	global_load_lds_dwordx4 v[202:203], off
	v_lshl_add_u64 v[202:203], s[36:37], 0, v[130:131]
	s_mov_b32 m0, s27
	s_nop 0
	global_load_lds_dwordx4 v[202:203], off
	s_mov_b32 m0, s41
	s_nop 0
	global_load_lds_dwordx4 v[206:207], off
	s_waitcnt vmcnt(8)
	s_waitcnt lgkmcnt(0)
	s_barrier
	s_setprio 1
	s_waitcnt lgkmcnt(0)
	v_mfma_f32_16x16x32_bf16 v[62:65], v[152:155], v[184:187], v[62:65]
	v_mfma_f32_16x16x32_bf16 v[58:61], v[160:163], v[184:187], v[58:61]
	v_mfma_f32_16x16x32_bf16 v[46:49], v[152:155], v[198:201], v[46:49]
	v_mfma_f32_16x16x32_bf16 v[42:45], v[160:163], v[198:201], v[42:45]
	v_mfma_f32_16x16x32_bf16 v[30:33], v[152:155], v[214:217], v[30:33]
	v_mfma_f32_16x16x32_bf16 v[26:29], v[160:163], v[214:217], v[26:29]
	v_mfma_f32_16x16x32_bf16 v[14:17], v[152:155], v[222:225], v[14:17]
	v_mfma_f32_16x16x32_bf16 v[10:13], v[160:163], v[222:225], v[10:13]
	v_mfma_f32_16x16x32_bf16 v[62:65], v[156:159], v[188:191], v[62:65]
	v_mfma_f32_16x16x32_bf16 v[58:61], v[164:167], v[188:191], v[58:61]
	v_mfma_f32_16x16x32_bf16 v[46:49], v[156:159], v[210:213], v[46:49]
	v_mfma_f32_16x16x32_bf16 v[42:45], v[164:167], v[210:213], v[42:45]
	v_mfma_f32_16x16x32_bf16 v[30:33], v[156:159], v[218:221], v[30:33]
	v_mfma_f32_16x16x32_bf16 v[26:29], v[164:167], v[218:221], v[26:29]
	v_mfma_f32_16x16x32_bf16 v[14:17], v[156:159], v[226:229], v[14:17]
	v_mfma_f32_16x16x32_bf16 v[10:13], v[164:167], v[226:229], v[10:13]
	v_mfma_f32_16x16x32_bf16 v[54:57], v[168:171], v[184:187], v[54:57]
	v_mfma_f32_16x16x32_bf16 v[50:53], v[176:179], v[184:187], v[50:53]
	v_mfma_f32_16x16x32_bf16 v[38:41], v[168:171], v[198:201], v[38:41]
	v_mfma_f32_16x16x32_bf16 v[34:37], v[176:179], v[198:201], v[34:37]
	v_mfma_f32_16x16x32_bf16 v[22:25], v[168:171], v[214:217], v[22:25]
	v_mfma_f32_16x16x32_bf16 v[18:21], v[176:179], v[214:217], v[18:21]
	v_mfma_f32_16x16x32_bf16 v[6:9], v[168:171], v[222:225], v[6:9]
	v_mfma_f32_16x16x32_bf16 v[2:5], v[176:179], v[222:225], v[2:5]
	v_mfma_f32_16x16x32_bf16 v[54:57], v[172:175], v[188:191], v[54:57]
	v_mfma_f32_16x16x32_bf16 v[50:53], v[180:183], v[188:191], v[50:53]
	v_mfma_f32_16x16x32_bf16 v[38:41], v[172:175], v[210:213], v[38:41]
	v_mfma_f32_16x16x32_bf16 v[34:37], v[180:183], v[210:213], v[34:37]
	v_mfma_f32_16x16x32_bf16 v[22:25], v[172:175], v[218:221], v[22:25]
	v_mfma_f32_16x16x32_bf16 v[18:21], v[180:183], v[218:221], v[18:21]
	v_mfma_f32_16x16x32_bf16 v[6:9], v[172:175], v[226:229], v[6:9]
	v_mfma_f32_16x16x32_bf16 v[2:5], v[180:183], v[226:229], v[2:5]
	s_setprio 2
	s_barrier
	s_add_i32 s19, 0, 0x18000
	v_add_u32_e32 v151, s19, v146
	s_add_i32 s38, 0, 0x1c000
	ds_read_b128 v[152:155], v151
	ds_read_b128 v[156:159], v151 offset:1024
	ds_read_b128 v[160:163], v151 offset:2048
	ds_read_b128 v[164:167], v151 offset:3072
	v_add_u32_e32 v151, s38, v146
	ds_read_b128 v[168:171], v151
	ds_read_b128 v[172:175], v151 offset:1024
	ds_read_b128 v[176:179], v151 offset:2048
	ds_read_b128 v[180:183], v151 offset:3072
	s_add_u32 s36, s36, 0x80000
	s_addc_u32 s37, s37, 0
	s_mov_b32 m0, s42
	v_lshl_add_u64 v[230:231], s[36:37], 0, v[130:131]
	ds_read_b128 v[184:187], v150 offset:32768
	ds_read_b128 v[188:191], v150 offset:33792
	ds_read_b128 v[198:201], v150 offset:34816
	ds_read_b128 v[210:213], v150 offset:35840
	ds_read_b128 v[214:217], v150 offset:36864
	ds_read_b128 v[218:221], v150 offset:37888
	ds_read_b128 v[222:225], v150 offset:38912
	ds_read_b128 v[226:229], v150 offset:39936
	global_load_lds_dwordx4 v[230:231], off
	v_lshl_add_u64 v[230:231], s[36:37], 0, v[134:135]
	s_mov_b32 m0, s43
	s_nop 0
	global_load_lds_dwordx4 v[230:231], off
	s_waitcnt vmcnt(8)
	s_waitcnt lgkmcnt(0)
	s_barrier
	s_setprio 1
	s_waitcnt lgkmcnt(0)
	v_mfma_f32_16x16x32_bf16 v[126:129], v[152:155], v[184:187], v[126:129]
	v_mfma_f32_16x16x32_bf16 v[122:125], v[160:163], v[184:187], v[122:125]
	v_mfma_f32_16x16x32_bf16 v[110:113], v[152:155], v[198:201], v[110:113]
	v_mfma_f32_16x16x32_bf16 v[106:109], v[160:163], v[198:201], v[106:109]
	v_mfma_f32_16x16x32_bf16 v[94:97], v[152:155], v[214:217], v[94:97]
	v_mfma_f32_16x16x32_bf16 v[90:93], v[160:163], v[214:217], v[90:93]
	v_mfma_f32_16x16x32_bf16 v[78:81], v[152:155], v[222:225], v[78:81]
	v_mfma_f32_16x16x32_bf16 v[74:77], v[160:163], v[222:225], v[74:77]
	v_mfma_f32_16x16x32_bf16 v[126:129], v[156:159], v[188:191], v[126:129]
	v_mfma_f32_16x16x32_bf16 v[122:125], v[164:167], v[188:191], v[122:125]
	v_mfma_f32_16x16x32_bf16 v[110:113], v[156:159], v[210:213], v[110:113]
	v_mfma_f32_16x16x32_bf16 v[106:109], v[164:167], v[210:213], v[106:109]
	v_mfma_f32_16x16x32_bf16 v[94:97], v[156:159], v[218:221], v[94:97]
	v_mfma_f32_16x16x32_bf16 v[90:93], v[164:167], v[218:221], v[90:93]
	v_mfma_f32_16x16x32_bf16 v[78:81], v[156:159], v[226:229], v[78:81]
	v_mfma_f32_16x16x32_bf16 v[74:77], v[164:167], v[226:229], v[74:77]
	v_mfma_f32_16x16x32_bf16 v[118:121], v[168:171], v[184:187], v[118:121]
	v_mfma_f32_16x16x32_bf16 v[114:117], v[176:179], v[184:187], v[114:117]
	v_mfma_f32_16x16x32_bf16 v[102:105], v[168:171], v[198:201], v[102:105]
	v_mfma_f32_16x16x32_bf16 v[98:101], v[176:179], v[198:201], v[98:101]
	v_mfma_f32_16x16x32_bf16 v[86:89], v[168:171], v[214:217], v[86:89]
	v_mfma_f32_16x16x32_bf16 v[82:85], v[176:179], v[214:217], v[82:85]
	v_mfma_f32_16x16x32_bf16 v[70:73], v[168:171], v[222:225], v[70:73]
	v_mfma_f32_16x16x32_bf16 v[66:69], v[176:179], v[222:225], v[66:69]
	v_mfma_f32_16x16x32_bf16 v[118:121], v[172:175], v[188:191], v[118:121]
	v_mfma_f32_16x16x32_bf16 v[114:117], v[180:183], v[188:191], v[114:117]
	v_mfma_f32_16x16x32_bf16 v[102:105], v[172:175], v[210:213], v[102:105]
	v_mfma_f32_16x16x32_bf16 v[98:101], v[180:183], v[210:213], v[98:101]
	v_mfma_f32_16x16x32_bf16 v[86:89], v[172:175], v[218:221], v[86:89]
	v_mfma_f32_16x16x32_bf16 v[82:85], v[180:183], v[218:221], v[82:85]
	v_mfma_f32_16x16x32_bf16 v[70:73], v[172:175], v[226:229], v[70:73]
	v_mfma_f32_16x16x32_bf16 v[66:69], v[180:183], v[226:229], v[66:69]
	s_setprio 2
	s_barrier
	s_add_i32 s19, s19, s33
	v_lshl_add_u64 v[144:145], v[144:145], 0, s[10:11]
	s_mov_b32 m0, s19
	ds_read_b128 v[184:187], v150 offset:49152
	ds_read_b128 v[188:191], v150 offset:50176
	ds_read_b128 v[198:201], v150 offset:51200
	ds_read_b128 v[210:213], v150 offset:52224
	ds_read_b128 v[214:217], v150 offset:53248
	ds_read_b128 v[218:221], v150 offset:54272
	ds_read_b128 v[222:225], v150 offset:55296
	ds_read_b128 v[226:229], v150 offset:56320
	global_load_lds_dwordx4 v[144:145], off
	s_add_i32 m0, s19, 0x2000
	s_add_u32 s34, s34, 0x80080
	v_lshl_add_u64 v[144:145], v[192:193], 0, s[10:11]
	s_addc_u32 s35, s35, 0
	s_add_i32 s19, s38, s33
	global_load_lds_dwordx4 v[144:145], off
	v_lshl_add_u64 v[144:145], s[34:35], 0, v[132:133]
	s_mov_b32 m0, s19
	s_nop 0
	global_load_lds_dwordx4 v[144:145], off
	v_lshl_add_u64 v[144:145], s[34:35], 0, v[136:137]
	s_add_i32 m0, s19, 0x2000
	s_nop 0
	global_load_lds_dwordx4 v[144:145], off
	v_lshl_add_u64 v[144:145], v[202:203], 0, s[10:11]
	s_mov_b32 m0, s51
	s_nop 0
	global_load_lds_dwordx4 v[144:145], off
	v_lshl_add_u64 v[144:145], v[206:207], 0, s[10:11]
	s_mov_b32 m0, s52
	s_nop 0
	global_load_lds_dwordx4 v[144:145], off
	s_waitcnt vmcnt(8)
	s_waitcnt lgkmcnt(0)
	s_barrier
	s_setprio 1
	s_waitcnt lgkmcnt(0)
	v_mfma_f32_16x16x32_bf16 v[62:65], v[152:155], v[184:187], v[62:65]
	v_mfma_f32_16x16x32_bf16 v[58:61], v[160:163], v[184:187], v[58:61]
	v_mfma_f32_16x16x32_bf16 v[46:49], v[152:155], v[198:201], v[46:49]
	v_mfma_f32_16x16x32_bf16 v[42:45], v[160:163], v[198:201], v[42:45]
	v_mfma_f32_16x16x32_bf16 v[30:33], v[152:155], v[214:217], v[30:33]
	v_mfma_f32_16x16x32_bf16 v[26:29], v[160:163], v[214:217], v[26:29]
	v_mfma_f32_16x16x32_bf16 v[14:17], v[152:155], v[222:225], v[14:17]
	v_mfma_f32_16x16x32_bf16 v[10:13], v[160:163], v[222:225], v[10:13]
	v_mfma_f32_16x16x32_bf16 v[62:65], v[156:159], v[188:191], v[62:65]
	v_mfma_f32_16x16x32_bf16 v[58:61], v[164:167], v[188:191], v[58:61]
	v_mfma_f32_16x16x32_bf16 v[46:49], v[156:159], v[210:213], v[46:49]
	v_mfma_f32_16x16x32_bf16 v[42:45], v[164:167], v[210:213], v[42:45]
	v_mfma_f32_16x16x32_bf16 v[30:33], v[156:159], v[218:221], v[30:33]
	v_mfma_f32_16x16x32_bf16 v[26:29], v[164:167], v[218:221], v[26:29]
	v_mfma_f32_16x16x32_bf16 v[14:17], v[156:159], v[226:229], v[14:17]
	v_mfma_f32_16x16x32_bf16 v[10:13], v[164:167], v[226:229], v[10:13]
	v_mfma_f32_16x16x32_bf16 v[54:57], v[168:171], v[184:187], v[54:57]
	v_mfma_f32_16x16x32_bf16 v[50:53], v[176:179], v[184:187], v[50:53]
	v_mfma_f32_16x16x32_bf16 v[38:41], v[168:171], v[198:201], v[38:41]
	v_mfma_f32_16x16x32_bf16 v[34:37], v[176:179], v[198:201], v[34:37]
	v_mfma_f32_16x16x32_bf16 v[22:25], v[168:171], v[214:217], v[22:25]
	v_mfma_f32_16x16x32_bf16 v[18:21], v[176:179], v[214:217], v[18:21]
	v_mfma_f32_16x16x32_bf16 v[6:9], v[168:171], v[222:225], v[6:9]
	v_mfma_f32_16x16x32_bf16 v[2:5], v[176:179], v[222:225], v[2:5]
	v_mfma_f32_16x16x32_bf16 v[54:57], v[172:175], v[188:191], v[54:57]
	v_mfma_f32_16x16x32_bf16 v[50:53], v[180:183], v[188:191], v[50:53]
	v_mfma_f32_16x16x32_bf16 v[38:41], v[172:175], v[210:213], v[38:41]
	v_mfma_f32_16x16x32_bf16 v[34:37], v[180:183], v[210:213], v[34:37]
	v_mfma_f32_16x16x32_bf16 v[22:25], v[172:175], v[218:221], v[22:25]
	v_mfma_f32_16x16x32_bf16 v[18:21], v[180:183], v[218:221], v[18:21]
	v_mfma_f32_16x16x32_bf16 v[6:9], v[172:175], v[226:229], v[6:9]
	v_mfma_f32_16x16x32_bf16 v[2:5], v[180:183], v[226:229], v[2:5]
	s_setprio 2
	s_barrier
	s_add_u32 s30, s30, 0x100
	s_addc_u32 s31, s31, 0
	s_add_u32 s15, s15, 0x100
	s_addc_u32 s17, s17, 0
	s_cmp_ge_i32 s29, s68
	s_mov_b32 s19, s29
	s_cbranch_scc0 .LBB0_1315

.Lpeel_6:
	ds_read_b128 v[144:147], v166
	ds_read_b128 v[148:151], v166 offset:1024
	ds_read_b128 v[152:155], v166 offset:2048
	ds_read_b128 v[156:159], v166 offset:3072
	ds_read_b128 v[160:163], v167
	ds_read_b128 v[170:173], v167 offset:1024
	ds_read_b128 v[174:177], v167 offset:2048
	ds_read_b128 v[178:181], v167 offset:3072
	s_add_i32 s30, s26, 2
	s_add_u32 s27, s24, 0xffea0080
	s_addc_u32 s28, s25, -1
	s_cmp_eq_u32 s22, s26
	s_cselect_b32 s26, s20, s17
	s_cselect_b32 s29, s19, s28
	s_cselect_b32 s28, s18, s27
	s_cselect_b32 s27, s21, s23
	v_lshl_add_u64 v[202:203], s[24:25], 0, v[140:141]
	s_add_i32 m0, s34, 0xc000
	ds_read_b128 v[182:185], v168
	ds_read_b128 v[186:189], v168 offset:1024
	ds_read_b128 v[190:193], v168 offset:2048
	ds_read_b128 v[198:201], v168 offset:3072
	ds_read_b128 v[210:213], v168 offset:4096
	ds_read_b128 v[214:217], v168 offset:5120
	ds_read_b128 v[218:221], v168 offset:6144
	ds_read_b128 v[222:225], v168 offset:7168
	global_load_lds_dwordx4 v[202:203], off
	v_lshl_add_u64 v[202:203], s[24:25], 0, v[142:143]
	s_add_i32 m0, s34, 0xe000
	s_nop 0
	global_load_lds_dwordx4 v[202:203], off
	s_waitcnt vmcnt(8)
	s_waitcnt lgkmcnt(0)
	s_barrier
	s_setprio 1
	s_waitcnt lgkmcnt(0)
	v_mfma_f32_16x16x32_bf16 v[126:129], v[144:147], v[182:185], 0
	v_mfma_f32_16x16x32_bf16 v[122:125], v[152:155], v[182:185], 0
	v_mfma_f32_16x16x32_bf16 v[114:117], v[144:147], v[190:193], 0
	v_mfma_f32_16x16x32_bf16 v[106:109], v[152:155], v[190:193], 0
	v_mfma_f32_16x16x32_bf16 v[94:97], v[144:147], v[210:213], 0
	v_mfma_f32_16x16x32_bf16 v[90:93], v[152:155], v[210:213], 0
	v_mfma_f32_16x16x32_bf16 v[78:81], v[144:147], v[218:221], 0
	v_mfma_f32_16x16x32_bf16 v[74:77], v[152:155], v[218:221], 0
	v_mfma_f32_16x16x32_bf16 v[126:129], v[148:151], v[186:189], v[126:129]
	v_mfma_f32_16x16x32_bf16 v[122:125], v[156:159], v[186:189], v[122:125]
	v_mfma_f32_16x16x32_bf16 v[114:117], v[148:151], v[198:201], v[114:117]
	v_mfma_f32_16x16x32_bf16 v[106:109], v[156:159], v[198:201], v[106:109]
	v_mfma_f32_16x16x32_bf16 v[94:97], v[148:151], v[214:217], v[94:97]
	v_mfma_f32_16x16x32_bf16 v[90:93], v[156:159], v[214:217], v[90:93]
	v_mfma_f32_16x16x32_bf16 v[78:81], v[148:151], v[222:225], v[78:81]
	v_mfma_f32_16x16x32_bf16 v[74:77], v[156:159], v[222:225], v[74:77]
	v_mfma_f32_16x16x32_bf16 v[118:121], v[160:163], v[182:185], 0
	v_mfma_f32_16x16x32_bf16 v[110:113], v[174:177], v[182:185], 0
	v_mfma_f32_16x16x32_bf16 v[102:105], v[160:163], v[190:193], 0
	v_mfma_f32_16x16x32_bf16 v[98:101], v[174:177], v[190:193], 0
	v_mfma_f32_16x16x32_bf16 v[86:89], v[160:163], v[210:213], 0
	v_mfma_f32_16x16x32_bf16 v[82:85], v[174:177], v[210:213], 0
	v_mfma_f32_16x16x32_bf16 v[70:73], v[160:163], v[218:221], 0
	v_mfma_f32_16x16x32_bf16 v[66:69], v[174:177], v[218:221], 0
	v_mfma_f32_16x16x32_bf16 v[118:121], v[170:173], v[186:189], v[118:121]
	v_mfma_f32_16x16x32_bf16 v[110:113], v[178:181], v[186:189], v[110:113]
	v_mfma_f32_16x16x32_bf16 v[102:105], v[170:173], v[198:201], v[102:105]
	v_mfma_f32_16x16x32_bf16 v[98:101], v[178:181], v[198:201], v[98:101]
	v_mfma_f32_16x16x32_bf16 v[86:89], v[170:173], v[214:217], v[86:89]
	v_mfma_f32_16x16x32_bf16 v[82:85], v[178:181], v[214:217], v[82:85]
	v_mfma_f32_16x16x32_bf16 v[70:73], v[170:173], v[222:225], v[70:73]
	v_mfma_f32_16x16x32_bf16 v[66:69], v[178:181], v[222:225], v[66:69]
	s_setprio 2
	s_barrier
	s_add_i32 s31, s57, s33
	v_lshl_add_u64 v[202:203], s[26:27], 0, v[132:133]
	s_mov_b32 m0, s31
	ds_read_b128 v[182:185], v168 offset:16384
	ds_read_b128 v[186:189], v168 offset:17408
	ds_read_b128 v[190:193], v168 offset:18432
	ds_read_b128 v[198:201], v168 offset:19456
	ds_read_b128 v[210:213], v168 offset:20480
	ds_read_b128 v[214:217], v168 offset:21504
	ds_read_b128 v[218:221], v168 offset:22528
	ds_read_b128 v[222:225], v168 offset:23552
	global_load_lds_dwordx4 v[202:203], off
	s_add_i32 m0, s31, 0x2000
	s_add_u32 s68, s26, 0x160000
	v_lshl_add_u64 v[206:207], s[26:27], 0, v[136:137]
	s_addc_u32 s69, s27, 0
	s_add_i32 s31, s58, s33
	global_load_lds_dwordx4 v[206:207], off
	v_lshl_add_u64 v[226:227], s[68:69], 0, v[132:133]
	s_mov_b32 m0, s31
	v_lshl_add_u64 v[228:229], s[28:29], 0, v[134:135]
	global_load_lds_dwordx4 v[226:227], off
	v_lshl_add_u64 v[226:227], s[68:69], 0, v[136:137]
	s_add_i32 m0, s31, 0x2000
	s_nop 0
	global_load_lds_dwordx4 v[226:227], off
	v_lshl_add_u64 v[226:227], s[28:29], 0, v[130:131]
	s_mov_b32 m0, s34
	s_nop 0
	global_load_lds_dwordx4 v[226:227], off
	s_mov_b32 m0, s35
	s_nop 0
	global_load_lds_dwordx4 v[228:229], off
	s_waitcnt vmcnt(8)
	s_waitcnt lgkmcnt(0)
	s_barrier
	s_setprio 1
	s_waitcnt lgkmcnt(0)
	v_mfma_f32_16x16x32_bf16 v[62:65], v[144:147], v[182:185], 0
	v_mfma_f32_16x16x32_bf16 v[58:61], v[152:155], v[182:185], 0
	v_mfma_f32_16x16x32_bf16 v[46:49], v[144:147], v[190:193], 0
	v_mfma_f32_16x16x32_bf16 v[42:45], v[152:155], v[190:193], 0
	v_mfma_f32_16x16x32_bf16 v[30:33], v[144:147], v[210:213], 0
	v_mfma_f32_16x16x32_bf16 v[26:29], v[152:155], v[210:213], 0
	v_mfma_f32_16x16x32_bf16 v[14:17], v[144:147], v[218:221], 0
	v_mfma_f32_16x16x32_bf16 v[10:13], v[152:155], v[218:221], 0
	v_mfma_f32_16x16x32_bf16 v[62:65], v[148:151], v[186:189], v[62:65]
	v_mfma_f32_16x16x32_bf16 v[58:61], v[156:159], v[186:189], v[58:61]
	v_mfma_f32_16x16x32_bf16 v[46:49], v[148:151], v[198:201], v[46:49]
	v_mfma_f32_16x16x32_bf16 v[42:45], v[156:159], v[198:201], v[42:45]
	v_mfma_f32_16x16x32_bf16 v[30:33], v[148:151], v[214:217], v[30:33]
	v_mfma_f32_16x16x32_bf16 v[26:29], v[156:159], v[214:217], v[26:29]
	v_mfma_f32_16x16x32_bf16 v[14:17], v[148:151], v[222:225], v[14:17]
	v_mfma_f32_16x16x32_bf16 v[10:13], v[156:159], v[222:225], v[10:13]
	v_mfma_f32_16x16x32_bf16 v[54:57], v[160:163], v[182:185], 0
	v_mfma_f32_16x16x32_bf16 v[50:53], v[174:177], v[182:185], 0
	v_mfma_f32_16x16x32_bf16 v[38:41], v[160:163], v[190:193], 0
	v_mfma_f32_16x16x32_bf16 v[34:37], v[174:177], v[190:193], 0
	v_mfma_f32_16x16x32_bf16 v[22:25], v[160:163], v[210:213], 0
	v_mfma_f32_16x16x32_bf16 v[18:21], v[174:177], v[210:213], 0
	v_mfma_f32_16x16x32_bf16 v[6:9], v[160:163], v[218:221], 0
	v_mfma_f32_16x16x32_bf16 v[2:5], v[174:177], v[218:221], 0
	v_mfma_f32_16x16x32_bf16 v[54:57], v[170:173], v[186:189], v[54:57]
	v_mfma_f32_16x16x32_bf16 v[50:53], v[178:181], v[186:189], v[50:53]
	v_mfma_f32_16x16x32_bf16 v[38:41], v[170:173], v[198:201], v[38:41]
	v_mfma_f32_16x16x32_bf16 v[34:37], v[178:181], v[198:201], v[34:37]
	v_mfma_f32_16x16x32_bf16 v[22:25], v[170:173], v[214:217], v[22:25]
	v_mfma_f32_16x16x32_bf16 v[18:21], v[178:181], v[214:217], v[18:21]
	v_mfma_f32_16x16x32_bf16 v[6:9], v[170:173], v[222:225], v[6:9]
	v_mfma_f32_16x16x32_bf16 v[2:5], v[178:181], v[222:225], v[2:5]
	s_setprio 2
	s_barrier
	s_add_i32 s31, 0, 0x18000
	s_add_i32 s68, 0, 0x1c000
	v_add_u32_e32 v156, s31, v164
	v_add_u32_e32 v169, s68, v164
	ds_read_b128 v[144:147], v156
	ds_read_b128 v[148:151], v156 offset:1024
	ds_read_b128 v[152:155], v156 offset:2048
	ds_read_b128 v[156:159], v156 offset:3072
	ds_read_b128 v[160:163], v169
	ds_read_b128 v[170:173], v169 offset:1024
	ds_read_b128 v[174:177], v169 offset:2048
	ds_read_b128 v[178:181], v169 offset:3072
	s_add_u32 s28, s28, 0x160000
	s_addc_u32 s29, s29, 0
	s_mov_b32 m0, s36
	v_lshl_add_u64 v[230:231], s[28:29], 0, v[130:131]
	ds_read_b128 v[182:185], v168 offset:32768
	ds_read_b128 v[186:189], v168 offset:33792
	ds_read_b128 v[190:193], v168 offset:34816
	ds_read_b128 v[198:201], v168 offset:35840
	ds_read_b128 v[210:213], v168 offset:36864
	ds_read_b128 v[214:217], v168 offset:37888
	ds_read_b128 v[218:221], v168 offset:38912
	ds_read_b128 v[222:225], v168 offset:39936
	global_load_lds_dwordx4 v[230:231], off
	v_lshl_add_u64 v[230:231], s[28:29], 0, v[134:135]
	s_mov_b32 m0, s37
	s_nop 0
	global_load_lds_dwordx4 v[230:231], off
	s_waitcnt vmcnt(8)
	s_waitcnt lgkmcnt(0)
	s_barrier
	s_setprio 1
	s_waitcnt lgkmcnt(0)
	v_mfma_f32_16x16x32_bf16 v[126:129], v[144:147], v[182:185], v[126:129]
	v_mfma_f32_16x16x32_bf16 v[122:125], v[152:155], v[182:185], v[122:125]
	v_mfma_f32_16x16x32_bf16 v[114:117], v[144:147], v[190:193], v[114:117]
	v_mfma_f32_16x16x32_bf16 v[106:109], v[152:155], v[190:193], v[106:109]
	v_mfma_f32_16x16x32_bf16 v[94:97], v[144:147], v[210:213], v[94:97]
	v_mfma_f32_16x16x32_bf16 v[90:93], v[152:155], v[210:213], v[90:93]
	v_mfma_f32_16x16x32_bf16 v[78:81], v[144:147], v[218:221], v[78:81]
	v_mfma_f32_16x16x32_bf16 v[74:77], v[152:155], v[218:221], v[74:77]
	v_mfma_f32_16x16x32_bf16 v[126:129], v[148:151], v[186:189], v[126:129]
	v_mfma_f32_16x16x32_bf16 v[122:125], v[156:159], v[186:189], v[122:125]
	v_mfma_f32_16x16x32_bf16 v[114:117], v[148:151], v[198:201], v[114:117]
	v_mfma_f32_16x16x32_bf16 v[106:109], v[156:159], v[198:201], v[106:109]
	v_mfma_f32_16x16x32_bf16 v[94:97], v[148:151], v[214:217], v[94:97]
	v_mfma_f32_16x16x32_bf16 v[90:93], v[156:159], v[214:217], v[90:93]
	v_mfma_f32_16x16x32_bf16 v[78:81], v[148:151], v[222:225], v[78:81]
	v_mfma_f32_16x16x32_bf16 v[74:77], v[156:159], v[222:225], v[74:77]
	v_mfma_f32_16x16x32_bf16 v[118:121], v[160:163], v[182:185], v[118:121]
	v_mfma_f32_16x16x32_bf16 v[110:113], v[174:177], v[182:185], v[110:113]
	v_mfma_f32_16x16x32_bf16 v[102:105], v[160:163], v[190:193], v[102:105]
	v_mfma_f32_16x16x32_bf16 v[98:101], v[174:177], v[190:193], v[98:101]
	v_mfma_f32_16x16x32_bf16 v[86:89], v[160:163], v[210:213], v[86:89]
	v_mfma_f32_16x16x32_bf16 v[82:85], v[174:177], v[210:213], v[82:85]
	v_mfma_f32_16x16x32_bf16 v[70:73], v[160:163], v[218:221], v[70:73]
	v_mfma_f32_16x16x32_bf16 v[66:69], v[174:177], v[218:221], v[66:69]
	v_mfma_f32_16x16x32_bf16 v[118:121], v[170:173], v[186:189], v[118:121]
	v_mfma_f32_16x16x32_bf16 v[110:113], v[178:181], v[186:189], v[110:113]
	v_mfma_f32_16x16x32_bf16 v[102:105], v[170:173], v[198:201], v[102:105]
	v_mfma_f32_16x16x32_bf16 v[98:101], v[178:181], v[198:201], v[98:101]
	v_mfma_f32_16x16x32_bf16 v[86:89], v[170:173], v[214:217], v[86:89]
	v_mfma_f32_16x16x32_bf16 v[82:85], v[178:181], v[214:217], v[82:85]
	v_mfma_f32_16x16x32_bf16 v[70:73], v[170:173], v[222:225], v[70:73]
	v_mfma_f32_16x16x32_bf16 v[66:69], v[178:181], v[222:225], v[66:69]
	s_setprio 2
	s_barrier
	s_add_i32 s28, s31, s33
	v_lshl_add_u64 v[202:203], v[202:203], 0, s[12:13]
	s_mov_b32 m0, s28
	ds_read_b128 v[182:185], v168 offset:49152
	ds_read_b128 v[186:189], v168 offset:50176
	ds_read_b128 v[190:193], v168 offset:51200
	ds_read_b128 v[198:201], v168 offset:52224
	ds_read_b128 v[210:213], v168 offset:53248
	ds_read_b128 v[214:217], v168 offset:54272
	ds_read_b128 v[218:221], v168 offset:55296
	ds_read_b128 v[222:225], v168 offset:56320
	global_load_lds_dwordx4 v[202:203], off
	s_add_i32 m0, s28, 0x2000
	s_add_u32 s26, s26, 0x160080
	v_lshl_add_u64 v[202:203], v[206:207], 0, s[12:13]
	s_addc_u32 s27, s27, 0
	s_add_i32 s28, s68, s33
	global_load_lds_dwordx4 v[202:203], off
	v_lshl_add_u64 v[202:203], s[26:27], 0, v[132:133]
	s_mov_b32 m0, s28
	s_nop 0
	global_load_lds_dwordx4 v[202:203], off
	v_lshl_add_u64 v[202:203], s[26:27], 0, v[136:137]
	s_add_i32 m0, s28, 0x2000
	s_nop 0
	global_load_lds_dwordx4 v[202:203], off
	v_lshl_add_u64 v[202:203], v[226:227], 0, s[12:13]
	s_mov_b32 m0, s47
	s_nop 0
	global_load_lds_dwordx4 v[202:203], off
	v_lshl_add_u64 v[202:203], v[228:229], 0, s[12:13]
	s_mov_b32 m0, s48
	s_nop 0
	global_load_lds_dwordx4 v[202:203], off
	s_waitcnt vmcnt(8)
	s_waitcnt lgkmcnt(0)
	s_barrier
	s_setprio 1
	s_waitcnt lgkmcnt(0)
	v_mfma_f32_16x16x32_bf16 v[62:65], v[144:147], v[182:185], v[62:65]
	v_mfma_f32_16x16x32_bf16 v[58:61], v[152:155], v[182:185], v[58:61]
	v_mfma_f32_16x16x32_bf16 v[46:49], v[144:147], v[190:193], v[46:49]
	v_mfma_f32_16x16x32_bf16 v[42:45], v[152:155], v[190:193], v[42:45]
	v_mfma_f32_16x16x32_bf16 v[30:33], v[144:147], v[210:213], v[30:33]
	v_mfma_f32_16x16x32_bf16 v[26:29], v[152:155], v[210:213], v[26:29]
	v_mfma_f32_16x16x32_bf16 v[14:17], v[144:147], v[218:221], v[14:17]
	v_mfma_f32_16x16x32_bf16 v[10:13], v[152:155], v[218:221], v[10:13]
	v_mfma_f32_16x16x32_bf16 v[62:65], v[148:151], v[186:189], v[62:65]
	v_mfma_f32_16x16x32_bf16 v[58:61], v[156:159], v[186:189], v[58:61]
	v_mfma_f32_16x16x32_bf16 v[46:49], v[148:151], v[198:201], v[46:49]
	v_mfma_f32_16x16x32_bf16 v[42:45], v[156:159], v[198:201], v[42:45]
	v_mfma_f32_16x16x32_bf16 v[30:33], v[148:151], v[214:217], v[30:33]
	v_mfma_f32_16x16x32_bf16 v[26:29], v[156:159], v[214:217], v[26:29]
	v_mfma_f32_16x16x32_bf16 v[14:17], v[148:151], v[222:225], v[14:17]
	v_mfma_f32_16x16x32_bf16 v[10:13], v[156:159], v[222:225], v[10:13]
	v_mfma_f32_16x16x32_bf16 v[54:57], v[160:163], v[182:185], v[54:57]
	v_mfma_f32_16x16x32_bf16 v[50:53], v[174:177], v[182:185], v[50:53]
	v_mfma_f32_16x16x32_bf16 v[38:41], v[160:163], v[190:193], v[38:41]
	v_mfma_f32_16x16x32_bf16 v[34:37], v[174:177], v[190:193], v[34:37]
	v_mfma_f32_16x16x32_bf16 v[22:25], v[160:163], v[210:213], v[22:25]
	v_mfma_f32_16x16x32_bf16 v[18:21], v[174:177], v[210:213], v[18:21]
	v_mfma_f32_16x16x32_bf16 v[6:9], v[160:163], v[218:221], v[6:9]
	v_mfma_f32_16x16x32_bf16 v[2:5], v[174:177], v[218:221], v[2:5]
	v_mfma_f32_16x16x32_bf16 v[54:57], v[170:173], v[186:189], v[54:57]
	v_mfma_f32_16x16x32_bf16 v[50:53], v[178:181], v[186:189], v[50:53]
	v_mfma_f32_16x16x32_bf16 v[38:41], v[170:173], v[198:201], v[38:41]
	v_mfma_f32_16x16x32_bf16 v[34:37], v[178:181], v[198:201], v[34:37]
	v_mfma_f32_16x16x32_bf16 v[22:25], v[170:173], v[214:217], v[22:25]
	v_mfma_f32_16x16x32_bf16 v[18:21], v[178:181], v[214:217], v[18:21]
	v_mfma_f32_16x16x32_bf16 v[6:9], v[170:173], v[222:225], v[6:9]
	v_mfma_f32_16x16x32_bf16 v[2:5], v[178:181], v[222:225], v[2:5]
	s_setprio 2
	s_barrier
	s_add_u32 s24, s24, 0x100
	s_addc_u32 s25, s25, 0
	s_add_u32 s17, s17, 0x100
	s_addc_u32 s23, s23, 0
	s_cmp_ge_i32 s30, s67
	s_mov_b32 s26, s30
	s_cbranch_scc0 .LBB0_1451
	s_branch .Lpeeldone_6
.LBB0_1451:
	ds_read_b128 v[144:147], v166
	ds_read_b128 v[148:151], v166 offset:1024
	ds_read_b128 v[152:155], v166 offset:2048
	ds_read_b128 v[156:159], v166 offset:3072
	ds_read_b128 v[160:163], v167
	ds_read_b128 v[170:173], v167 offset:1024
	ds_read_b128 v[174:177], v167 offset:2048
	ds_read_b128 v[178:181], v167 offset:3072
	s_add_i32 s30, s26, 2
	s_add_u32 s27, s24, 0xffea0080
	s_addc_u32 s28, s25, -1
	s_cmp_eq_u32 s22, s26
	s_cselect_b32 s26, s20, s17
	s_cselect_b32 s29, s19, s28
	s_cselect_b32 s28, s18, s27
	s_cselect_b32 s27, s21, s23
	v_lshl_add_u64 v[202:203], s[24:25], 0, v[140:141]
	s_add_i32 m0, s34, 0xc000
	ds_read_b128 v[182:185], v168
	ds_read_b128 v[186:189], v168 offset:1024
	ds_read_b128 v[190:193], v168 offset:2048
	ds_read_b128 v[198:201], v168 offset:3072
	ds_read_b128 v[210:213], v168 offset:4096
	ds_read_b128 v[214:217], v168 offset:5120
	ds_read_b128 v[218:221], v168 offset:6144
	ds_read_b128 v[222:225], v168 offset:7168
	global_load_lds_dwordx4 v[202:203], off
	v_lshl_add_u64 v[202:203], s[24:25], 0, v[142:143]
	s_add_i32 m0, s34, 0xe000
	s_nop 0
	global_load_lds_dwordx4 v[202:203], off
	s_waitcnt vmcnt(8)
	s_waitcnt lgkmcnt(0)
	s_barrier
	s_setprio 1
	s_waitcnt lgkmcnt(0)
	v_mfma_f32_16x16x32_bf16 v[126:129], v[144:147], v[182:185], v[126:129]
	v_mfma_f32_16x16x32_bf16 v[122:125], v[152:155], v[182:185], v[122:125]
	v_mfma_f32_16x16x32_bf16 v[114:117], v[144:147], v[190:193], v[114:117]
	v_mfma_f32_16x16x32_bf16 v[106:109], v[152:155], v[190:193], v[106:109]
	v_mfma_f32_16x16x32_bf16 v[94:97], v[144:147], v[210:213], v[94:97]
	v_mfma_f32_16x16x32_bf16 v[90:93], v[152:155], v[210:213], v[90:93]
	v_mfma_f32_16x16x32_bf16 v[78:81], v[144:147], v[218:221], v[78:81]
	v_mfma_f32_16x16x32_bf16 v[74:77], v[152:155], v[218:221], v[74:77]
	v_mfma_f32_16x16x32_bf16 v[126:129], v[148:151], v[186:189], v[126:129]
	v_mfma_f32_16x16x32_bf16 v[122:125], v[156:159], v[186:189], v[122:125]
	v_mfma_f32_16x16x32_bf16 v[114:117], v[148:151], v[198:201], v[114:117]
	v_mfma_f32_16x16x32_bf16 v[106:109], v[156:159], v[198:201], v[106:109]
	v_mfma_f32_16x16x32_bf16 v[94:97], v[148:151], v[214:217], v[94:97]
	v_mfma_f32_16x16x32_bf16 v[90:93], v[156:159], v[214:217], v[90:93]
	v_mfma_f32_16x16x32_bf16 v[78:81], v[148:151], v[222:225], v[78:81]
	v_mfma_f32_16x16x32_bf16 v[74:77], v[156:159], v[222:225], v[74:77]
	v_mfma_f32_16x16x32_bf16 v[118:121], v[160:163], v[182:185], v[118:121]
	v_mfma_f32_16x16x32_bf16 v[110:113], v[174:177], v[182:185], v[110:113]
	v_mfma_f32_16x16x32_bf16 v[102:105], v[160:163], v[190:193], v[102:105]
	v_mfma_f32_16x16x32_bf16 v[98:101], v[174:177], v[190:193], v[98:101]
	v_mfma_f32_16x16x32_bf16 v[86:89], v[160:163], v[210:213], v[86:89]
	v_mfma_f32_16x16x32_bf16 v[82:85], v[174:177], v[210:213], v[82:85]
	v_mfma_f32_16x16x32_bf16 v[70:73], v[160:163], v[218:221], v[70:73]
	v_mfma_f32_16x16x32_bf16 v[66:69], v[174:177], v[218:221], v[66:69]
	v_mfma_f32_16x16x32_bf16 v[118:121], v[170:173], v[186:189], v[118:121]
	v_mfma_f32_16x16x32_bf16 v[110:113], v[178:181], v[186:189], v[110:113]
	v_mfma_f32_16x16x32_bf16 v[102:105], v[170:173], v[198:201], v[102:105]
	v_mfma_f32_16x16x32_bf16 v[98:101], v[178:181], v[198:201], v[98:101]
	v_mfma_f32_16x16x32_bf16 v[86:89], v[170:173], v[214:217], v[86:89]
	v_mfma_f32_16x16x32_bf16 v[82:85], v[178:181], v[214:217], v[82:85]
	v_mfma_f32_16x16x32_bf16 v[70:73], v[170:173], v[222:225], v[70:73]
	v_mfma_f32_16x16x32_bf16 v[66:69], v[178:181], v[222:225], v[66:69]
	s_setprio 2
	s_barrier
	s_add_i32 s31, s57, s33
	v_lshl_add_u64 v[202:203], s[26:27], 0, v[132:133]
	s_mov_b32 m0, s31
	ds_read_b128 v[182:185], v168 offset:16384
	ds_read_b128 v[186:189], v168 offset:17408
	ds_read_b128 v[190:193], v168 offset:18432
	ds_read_b128 v[198:201], v168 offset:19456
	ds_read_b128 v[210:213], v168 offset:20480
	ds_read_b128 v[214:217], v168 offset:21504
	ds_read_b128 v[218:221], v168 offset:22528
	ds_read_b128 v[222:225], v168 offset:23552
	global_load_lds_dwordx4 v[202:203], off
	s_add_i32 m0, s31, 0x2000
	s_add_u32 s68, s26, 0x160000
	v_lshl_add_u64 v[206:207], s[26:27], 0, v[136:137]
	s_addc_u32 s69, s27, 0
	s_add_i32 s31, s58, s33
	global_load_lds_dwordx4 v[206:207], off
	v_lshl_add_u64 v[226:227], s[68:69], 0, v[132:133]
	s_mov_b32 m0, s31
	v_lshl_add_u64 v[228:229], s[28:29], 0, v[134:135]
	global_load_lds_dwordx4 v[226:227], off
	v_lshl_add_u64 v[226:227], s[68:69], 0, v[136:137]
	s_add_i32 m0, s31, 0x2000
	s_nop 0
	global_load_lds_dwordx4 v[226:227], off
	v_lshl_add_u64 v[226:227], s[28:29], 0, v[130:131]
	s_mov_b32 m0, s34
	s_nop 0
	global_load_lds_dwordx4 v[226:227], off
	s_mov_b32 m0, s35
	s_nop 0
	global_load_lds_dwordx4 v[228:229], off
	s_waitcnt vmcnt(8)
	s_waitcnt lgkmcnt(0)
	s_barrier
	s_setprio 1
	s_waitcnt lgkmcnt(0)
	v_mfma_f32_16x16x32_bf16 v[62:65], v[144:147], v[182:185], v[62:65]
	v_mfma_f32_16x16x32_bf16 v[58:61], v[152:155], v[182:185], v[58:61]
	v_mfma_f32_16x16x32_bf16 v[46:49], v[144:147], v[190:193], v[46:49]
	v_mfma_f32_16x16x32_bf16 v[42:45], v[152:155], v[190:193], v[42:45]
	v_mfma_f32_16x16x32_bf16 v[30:33], v[144:147], v[210:213], v[30:33]
	v_mfma_f32_16x16x32_bf16 v[26:29], v[152:155], v[210:213], v[26:29]
	v_mfma_f32_16x16x32_bf16 v[14:17], v[144:147], v[218:221], v[14:17]
	v_mfma_f32_16x16x32_bf16 v[10:13], v[152:155], v[218:221], v[10:13]
	v_mfma_f32_16x16x32_bf16 v[62:65], v[148:151], v[186:189], v[62:65]
	v_mfma_f32_16x16x32_bf16 v[58:61], v[156:159], v[186:189], v[58:61]
	v_mfma_f32_16x16x32_bf16 v[46:49], v[148:151], v[198:201], v[46:49]
	v_mfma_f32_16x16x32_bf16 v[42:45], v[156:159], v[198:201], v[42:45]
	v_mfma_f32_16x16x32_bf16 v[30:33], v[148:151], v[214:217], v[30:33]
	v_mfma_f32_16x16x32_bf16 v[26:29], v[156:159], v[214:217], v[26:29]
	v_mfma_f32_16x16x32_bf16 v[14:17], v[148:151], v[222:225], v[14:17]
	v_mfma_f32_16x16x32_bf16 v[10:13], v[156:159], v[222:225], v[10:13]
	v_mfma_f32_16x16x32_bf16 v[54:57], v[160:163], v[182:185], v[54:57]
	v_mfma_f32_16x16x32_bf16 v[50:53], v[174:177], v[182:185], v[50:53]
	v_mfma_f32_16x16x32_bf16 v[38:41], v[160:163], v[190:193], v[38:41]
	v_mfma_f32_16x16x32_bf16 v[34:37], v[174:177], v[190:193], v[34:37]
	v_mfma_f32_16x16x32_bf16 v[22:25], v[160:163], v[210:213], v[22:25]
	v_mfma_f32_16x16x32_bf16 v[18:21], v[174:177], v[210:213], v[18:21]
	v_mfma_f32_16x16x32_bf16 v[6:9], v[160:163], v[218:221], v[6:9]
	v_mfma_f32_16x16x32_bf16 v[2:5], v[174:177], v[218:221], v[2:5]
	v_mfma_f32_16x16x32_bf16 v[54:57], v[170:173], v[186:189], v[54:57]
	v_mfma_f32_16x16x32_bf16 v[50:53], v[178:181], v[186:189], v[50:53]
	v_mfma_f32_16x16x32_bf16 v[38:41], v[170:173], v[198:201], v[38:41]
	v_mfma_f32_16x16x32_bf16 v[34:37], v[178:181], v[198:201], v[34:37]
	v_mfma_f32_16x16x32_bf16 v[22:25], v[170:173], v[214:217], v[22:25]
	v_mfma_f32_16x16x32_bf16 v[18:21], v[178:181], v[214:217], v[18:21]
	v_mfma_f32_16x16x32_bf16 v[6:9], v[170:173], v[222:225], v[6:9]
	v_mfma_f32_16x16x32_bf16 v[2:5], v[178:181], v[222:225], v[2:5]
	s_setprio 2
	s_barrier
	s_add_i32 s31, 0, 0x18000
	s_add_i32 s68, 0, 0x1c000
	v_add_u32_e32 v156, s31, v164
	v_add_u32_e32 v169, s68, v164
	ds_read_b128 v[144:147], v156
	ds_read_b128 v[148:151], v156 offset:1024
	ds_read_b128 v[152:155], v156 offset:2048
	ds_read_b128 v[156:159], v156 offset:3072
	ds_read_b128 v[160:163], v169
	ds_read_b128 v[170:173], v169 offset:1024
	ds_read_b128 v[174:177], v169 offset:2048
	ds_read_b128 v[178:181], v169 offset:3072
	s_add_u32 s28, s28, 0x160000
	s_addc_u32 s29, s29, 0
	s_mov_b32 m0, s36
	v_lshl_add_u64 v[230:231], s[28:29], 0, v[130:131]
	ds_read_b128 v[182:185], v168 offset:32768
	ds_read_b128 v[186:189], v168 offset:33792
	ds_read_b128 v[190:193], v168 offset:34816
	ds_read_b128 v[198:201], v168 offset:35840
	ds_read_b128 v[210:213], v168 offset:36864
	ds_read_b128 v[214:217], v168 offset:37888
	ds_read_b128 v[218:221], v168 offset:38912
	ds_read_b128 v[222:225], v168 offset:39936
	global_load_lds_dwordx4 v[230:231], off
	v_lshl_add_u64 v[230:231], s[28:29], 0, v[134:135]
	s_mov_b32 m0, s37
	s_nop 0
	global_load_lds_dwordx4 v[230:231], off
	s_waitcnt vmcnt(8)
	s_waitcnt lgkmcnt(0)
	s_barrier
	s_setprio 1
	s_waitcnt lgkmcnt(0)
	v_mfma_f32_16x16x32_bf16 v[126:129], v[144:147], v[182:185], v[126:129]
	v_mfma_f32_16x16x32_bf16 v[122:125], v[152:155], v[182:185], v[122:125]
	v_mfma_f32_16x16x32_bf16 v[114:117], v[144:147], v[190:193], v[114:117]
	v_mfma_f32_16x16x32_bf16 v[106:109], v[152:155], v[190:193], v[106:109]
	v_mfma_f32_16x16x32_bf16 v[94:97], v[144:147], v[210:213], v[94:97]
	v_mfma_f32_16x16x32_bf16 v[90:93], v[152:155], v[210:213], v[90:93]
	v_mfma_f32_16x16x32_bf16 v[78:81], v[144:147], v[218:221], v[78:81]
	v_mfma_f32_16x16x32_bf16 v[74:77], v[152:155], v[218:221], v[74:77]
	v_mfma_f32_16x16x32_bf16 v[126:129], v[148:151], v[186:189], v[126:129]
	v_mfma_f32_16x16x32_bf16 v[122:125], v[156:159], v[186:189], v[122:125]
	v_mfma_f32_16x16x32_bf16 v[114:117], v[148:151], v[198:201], v[114:117]
	v_mfma_f32_16x16x32_bf16 v[106:109], v[156:159], v[198:201], v[106:109]
	v_mfma_f32_16x16x32_bf16 v[94:97], v[148:151], v[214:217], v[94:97]
	v_mfma_f32_16x16x32_bf16 v[90:93], v[156:159], v[214:217], v[90:93]
	v_mfma_f32_16x16x32_bf16 v[78:81], v[148:151], v[222:225], v[78:81]
	v_mfma_f32_16x16x32_bf16 v[74:77], v[156:159], v[222:225], v[74:77]
	v_mfma_f32_16x16x32_bf16 v[118:121], v[160:163], v[182:185], v[118:121]
	v_mfma_f32_16x16x32_bf16 v[110:113], v[174:177], v[182:185], v[110:113]
	v_mfma_f32_16x16x32_bf16 v[102:105], v[160:163], v[190:193], v[102:105]
	v_mfma_f32_16x16x32_bf16 v[98:101], v[174:177], v[190:193], v[98:101]
	v_mfma_f32_16x16x32_bf16 v[86:89], v[160:163], v[210:213], v[86:89]
	v_mfma_f32_16x16x32_bf16 v[82:85], v[174:177], v[210:213], v[82:85]
	v_mfma_f32_16x16x32_bf16 v[70:73], v[160:163], v[218:221], v[70:73]
	v_mfma_f32_16x16x32_bf16 v[66:69], v[174:177], v[218:221], v[66:69]
	v_mfma_f32_16x16x32_bf16 v[118:121], v[170:173], v[186:189], v[118:121]
	v_mfma_f32_16x16x32_bf16 v[110:113], v[178:181], v[186:189], v[110:113]
	v_mfma_f32_16x16x32_bf16 v[102:105], v[170:173], v[198:201], v[102:105]
	v_mfma_f32_16x16x32_bf16 v[98:101], v[178:181], v[198:201], v[98:101]
	v_mfma_f32_16x16x32_bf16 v[86:89], v[170:173], v[214:217], v[86:89]
	v_mfma_f32_16x16x32_bf16 v[82:85], v[178:181], v[214:217], v[82:85]
	v_mfma_f32_16x16x32_bf16 v[70:73], v[170:173], v[222:225], v[70:73]
	v_mfma_f32_16x16x32_bf16 v[66:69], v[178:181], v[222:225], v[66:69]
	s_setprio 2
	s_barrier
	s_add_i32 s28, s31, s33
	v_lshl_add_u64 v[202:203], v[202:203], 0, s[12:13]
	s_mov_b32 m0, s28
	ds_read_b128 v[182:185], v168 offset:49152
	ds_read_b128 v[186:189], v168 offset:50176
	ds_read_b128 v[190:193], v168 offset:51200
	ds_read_b128 v[198:201], v168 offset:52224
	ds_read_b128 v[210:213], v168 offset:53248
	ds_read_b128 v[214:217], v168 offset:54272
	ds_read_b128 v[218:221], v168 offset:55296
	ds_read_b128 v[222:225], v168 offset:56320
	global_load_lds_dwordx4 v[202:203], off
	s_add_i32 m0, s28, 0x2000
	s_add_u32 s26, s26, 0x160080
	v_lshl_add_u64 v[202:203], v[206:207], 0, s[12:13]
	s_addc_u32 s27, s27, 0
	s_add_i32 s28, s68, s33
	global_load_lds_dwordx4 v[202:203], off
	v_lshl_add_u64 v[202:203], s[26:27], 0, v[132:133]
	s_mov_b32 m0, s28
	s_nop 0
	global_load_lds_dwordx4 v[202:203], off
	v_lshl_add_u64 v[202:203], s[26:27], 0, v[136:137]
	s_add_i32 m0, s28, 0x2000
	s_nop 0
	global_load_lds_dwordx4 v[202:203], off
	v_lshl_add_u64 v[202:203], v[226:227], 0, s[12:13]
	s_mov_b32 m0, s47
	s_nop 0
	global_load_lds_dwordx4 v[202:203], off
	v_lshl_add_u64 v[202:203], v[228:229], 0, s[12:13]
	s_mov_b32 m0, s48
	s_nop 0
	global_load_lds_dwordx4 v[202:203], off
	s_waitcnt vmcnt(8)
	s_waitcnt lgkmcnt(0)
	s_barrier
	s_setprio 1
	s_waitcnt lgkmcnt(0)
	v_mfma_f32_16x16x32_bf16 v[62:65], v[144:147], v[182:185], v[62:65]
	v_mfma_f32_16x16x32_bf16 v[58:61], v[152:155], v[182:185], v[58:61]
	v_mfma_f32_16x16x32_bf16 v[46:49], v[144:147], v[190:193], v[46:49]
	v_mfma_f32_16x16x32_bf16 v[42:45], v[152:155], v[190:193], v[42:45]
	v_mfma_f32_16x16x32_bf16 v[30:33], v[144:147], v[210:213], v[30:33]
	v_mfma_f32_16x16x32_bf16 v[26:29], v[152:155], v[210:213], v[26:29]
	v_mfma_f32_16x16x32_bf16 v[14:17], v[144:147], v[218:221], v[14:17]
	v_mfma_f32_16x16x32_bf16 v[10:13], v[152:155], v[218:221], v[10:13]
	v_mfma_f32_16x16x32_bf16 v[62:65], v[148:151], v[186:189], v[62:65]
	v_mfma_f32_16x16x32_bf16 v[58:61], v[156:159], v[186:189], v[58:61]
	v_mfma_f32_16x16x32_bf16 v[46:49], v[148:151], v[198:201], v[46:49]
	v_mfma_f32_16x16x32_bf16 v[42:45], v[156:159], v[198:201], v[42:45]
	v_mfma_f32_16x16x32_bf16 v[30:33], v[148:151], v[214:217], v[30:33]
	v_mfma_f32_16x16x32_bf16 v[26:29], v[156:159], v[214:217], v[26:29]
	v_mfma_f32_16x16x32_bf16 v[14:17], v[148:151], v[222:225], v[14:17]
	v_mfma_f32_16x16x32_bf16 v[10:13], v[156:159], v[222:225], v[10:13]
	v_mfma_f32_16x16x32_bf16 v[54:57], v[160:163], v[182:185], v[54:57]
	v_mfma_f32_16x16x32_bf16 v[50:53], v[174:177], v[182:185], v[50:53]
	v_mfma_f32_16x16x32_bf16 v[38:41], v[160:163], v[190:193], v[38:41]
	v_mfma_f32_16x16x32_bf16 v[34:37], v[174:177], v[190:193], v[34:37]
	v_mfma_f32_16x16x32_bf16 v[22:25], v[160:163], v[210:213], v[22:25]
	v_mfma_f32_16x16x32_bf16 v[18:21], v[174:177], v[210:213], v[18:21]
	v_mfma_f32_16x16x32_bf16 v[6:9], v[160:163], v[218:221], v[6:9]
	v_mfma_f32_16x16x32_bf16 v[2:5], v[174:177], v[218:221], v[2:5]
	v_mfma_f32_16x16x32_bf16 v[54:57], v[170:173], v[186:189], v[54:57]
	v_mfma_f32_16x16x32_bf16 v[50:53], v[178:181], v[186:189], v[50:53]
	v_mfma_f32_16x16x32_bf16 v[38:41], v[170:173], v[198:201], v[38:41]
	v_mfma_f32_16x16x32_bf16 v[34:37], v[178:181], v[198:201], v[34:37]
	v_mfma_f32_16x16x32_bf16 v[22:25], v[170:173], v[214:217], v[22:25]
	v_mfma_f32_16x16x32_bf16 v[18:21], v[178:181], v[214:217], v[18:21]
	v_mfma_f32_16x16x32_bf16 v[6:9], v[170:173], v[222:225], v[6:9]
	v_mfma_f32_16x16x32_bf16 v[2:5], v[178:181], v[222:225], v[2:5]
	s_setprio 2
	s_barrier
	s_add_u32 s24, s24, 0x100
	s_addc_u32 s25, s25, 0
	s_add_u32 s17, s17, 0x100
	s_addc_u32 s23, s23, 0
	s_cmp_ge_i32 s30, s67
	s_mov_b32 s26, s30
	s_cbranch_scc0 .LBB0_1451

.Lpeel_3:
	s_add_i32 s29, s23, 2
	s_add_u32 s34, s30, 0xfff80080
	s_addc_u32 s35, s31, -1
	s_cmp_eq_u32 s28, s23
	s_cselect_b32 s37, s25, s35
	s_cselect_b32 s36, s24, s34
	s_cselect_b32 s35, s27, s21
	s_cselect_b32 s34, s26, s19
	v_lshl_add_u64 v[202:203], s[30:31], 0, v[140:141]
	s_add_i32 m0, s15, 0xc000
	global_load_lds_dwordx4 v[202:203], off
	v_lshl_add_u64 v[202:203], s[30:31], 0, v[142:143]
	s_add_i32 m0, s15, 0xe000
	s_nop 0
	global_load_lds_dwordx4 v[202:203], off
	s_waitcnt vmcnt(8)
	s_waitcnt lgkmcnt(0)
	s_barrier
	s_setprio 1
	s_waitcnt lgkmcnt(0)
	v_mfma_f32_16x16x32_bf16 v[126:129], v[150:153], v[182:185], 0
	v_mfma_f32_16x16x32_bf16 v[122:125], v[158:161], v[182:185], 0
	v_mfma_f32_16x16x32_bf16 v[118:121], v[150:153], v[190:193], 0
	v_mfma_f32_16x16x32_bf16 v[114:117], v[158:161], v[190:193], 0
	v_mfma_f32_16x16x32_bf16 v[110:113], v[150:153], v[210:213], 0
	v_mfma_f32_16x16x32_bf16 v[106:109], v[158:161], v[210:213], 0
	v_mfma_f32_16x16x32_bf16 v[102:105], v[150:153], v[218:221], 0
	v_mfma_f32_16x16x32_bf16 v[98:101], v[158:161], v[218:221], 0
	v_mfma_f32_16x16x32_bf16 v[126:129], v[154:157], v[186:189], v[126:129]
	v_mfma_f32_16x16x32_bf16 v[122:125], v[162:165], v[186:189], v[122:125]
	v_mfma_f32_16x16x32_bf16 v[118:121], v[154:157], v[198:201], v[118:121]
	v_mfma_f32_16x16x32_bf16 v[114:117], v[162:165], v[198:201], v[114:117]
	v_mfma_f32_16x16x32_bf16 v[110:113], v[154:157], v[214:217], v[110:113]
	v_mfma_f32_16x16x32_bf16 v[106:109], v[162:165], v[214:217], v[106:109]
	v_mfma_f32_16x16x32_bf16 v[102:105], v[154:157], v[222:225], v[102:105]
	v_mfma_f32_16x16x32_bf16 v[98:101], v[162:165], v[222:225], v[98:101]
	v_mfma_f32_16x16x32_bf16 v[94:97], v[166:169], v[182:185], 0
	v_mfma_f32_16x16x32_bf16 v[90:93], v[174:177], v[182:185], 0
	v_mfma_f32_16x16x32_bf16 v[86:89], v[166:169], v[190:193], 0
	v_mfma_f32_16x16x32_bf16 v[82:85], v[174:177], v[190:193], 0
	v_mfma_f32_16x16x32_bf16 v[78:81], v[166:169], v[210:213], 0
	v_mfma_f32_16x16x32_bf16 v[74:77], v[174:177], v[210:213], 0
	v_mfma_f32_16x16x32_bf16 v[70:73], v[166:169], v[218:221], 0
	v_mfma_f32_16x16x32_bf16 v[66:69], v[174:177], v[218:221], 0
	v_mfma_f32_16x16x32_bf16 v[94:97], v[170:173], v[186:189], v[94:97]
	v_mfma_f32_16x16x32_bf16 v[90:93], v[178:181], v[186:189], v[90:93]
	v_mfma_f32_16x16x32_bf16 v[86:89], v[170:173], v[198:201], v[86:89]
	v_mfma_f32_16x16x32_bf16 v[82:85], v[178:181], v[198:201], v[82:85]
	v_mfma_f32_16x16x32_bf16 v[78:81], v[170:173], v[214:217], v[78:81]
	v_mfma_f32_16x16x32_bf16 v[74:77], v[178:181], v[214:217], v[74:77]
	v_mfma_f32_16x16x32_bf16 v[70:73], v[170:173], v[222:225], v[70:73]
	v_mfma_f32_16x16x32_bf16 v[66:69], v[178:181], v[222:225], v[66:69]
	s_setprio 2
	s_barrier
	s_add_i32 s23, s60, s33
	v_lshl_add_u64 v[202:203], s[34:35], 0, v[132:133]
	s_mov_b32 m0, s23
	ds_read_b128 v[182:185], v148 offset:16384
	ds_read_b128 v[186:189], v148 offset:17408
	ds_read_b128 v[190:193], v148 offset:18432
	ds_read_b128 v[198:201], v148 offset:19456
	ds_read_b128 v[210:213], v148 offset:20480
	ds_read_b128 v[214:217], v148 offset:21504
	ds_read_b128 v[218:221], v148 offset:22528
	ds_read_b128 v[222:225], v148 offset:23552
	global_load_lds_dwordx4 v[202:203], off
	s_add_i32 m0, s23, 0x2000
	s_add_u32 s38, s34, 0x80000
	v_lshl_add_u64 v[206:207], s[34:35], 0, v[136:137]
	s_addc_u32 s39, s35, 0
	s_add_i32 s23, s61, s33
	global_load_lds_dwordx4 v[206:207], off
	v_lshl_add_u64 v[226:227], s[38:39], 0, v[132:133]
	s_mov_b32 m0, s23
	v_lshl_add_u64 v[228:229], s[36:37], 0, v[134:135]
	global_load_lds_dwordx4 v[226:227], off
	v_lshl_add_u64 v[226:227], s[38:39], 0, v[136:137]
	s_add_i32 m0, s23, 0x2000
	s_nop 0
	global_load_lds_dwordx4 v[226:227], off
	v_lshl_add_u64 v[226:227], s[36:37], 0, v[130:131]
	s_mov_b32 m0, s15
	s_nop 0
	global_load_lds_dwordx4 v[226:227], off
	s_mov_b32 m0, s41
	s_nop 0
	global_load_lds_dwordx4 v[228:229], off
	s_waitcnt vmcnt(8)
	s_waitcnt lgkmcnt(0)
	s_barrier
	s_setprio 1
	s_waitcnt lgkmcnt(0)
	v_mfma_f32_16x16x32_bf16 v[62:65], v[150:153], v[182:185], 0
	v_mfma_f32_16x16x32_bf16 v[58:61], v[158:161], v[182:185], 0
	v_mfma_f32_16x16x32_bf16 v[54:57], v[150:153], v[190:193], 0
	v_mfma_f32_16x16x32_bf16 v[50:53], v[158:161], v[190:193], 0
	v_mfma_f32_16x16x32_bf16 v[46:49], v[150:153], v[210:213], 0
	v_mfma_f32_16x16x32_bf16 v[42:45], v[158:161], v[210:213], 0
	v_mfma_f32_16x16x32_bf16 v[38:41], v[150:153], v[218:221], 0
	v_mfma_f32_16x16x32_bf16 v[34:37], v[158:161], v[218:221], 0
	v_mfma_f32_16x16x32_bf16 v[62:65], v[154:157], v[186:189], v[62:65]
	v_mfma_f32_16x16x32_bf16 v[58:61], v[162:165], v[186:189], v[58:61]
	v_mfma_f32_16x16x32_bf16 v[54:57], v[154:157], v[198:201], v[54:57]
	v_mfma_f32_16x16x32_bf16 v[50:53], v[162:165], v[198:201], v[50:53]
	v_mfma_f32_16x16x32_bf16 v[46:49], v[154:157], v[214:217], v[46:49]
	v_mfma_f32_16x16x32_bf16 v[42:45], v[162:165], v[214:217], v[42:45]
	v_mfma_f32_16x16x32_bf16 v[38:41], v[154:157], v[222:225], v[38:41]
	v_mfma_f32_16x16x32_bf16 v[34:37], v[162:165], v[222:225], v[34:37]
	v_mfma_f32_16x16x32_bf16 v[30:33], v[166:169], v[182:185], 0
	v_mfma_f32_16x16x32_bf16 v[26:29], v[174:177], v[182:185], 0
	v_mfma_f32_16x16x32_bf16 v[22:25], v[166:169], v[190:193], 0
	v_mfma_f32_16x16x32_bf16 v[18:21], v[174:177], v[190:193], 0
	v_mfma_f32_16x16x32_bf16 v[14:17], v[166:169], v[210:213], 0
	v_mfma_f32_16x16x32_bf16 v[10:13], v[174:177], v[210:213], 0
	v_mfma_f32_16x16x32_bf16 v[6:9], v[166:169], v[218:221], 0
	v_mfma_f32_16x16x32_bf16 v[2:5], v[174:177], v[218:221], 0
	v_mfma_f32_16x16x32_bf16 v[30:33], v[170:173], v[186:189], v[30:33]
	v_mfma_f32_16x16x32_bf16 v[26:29], v[178:181], v[186:189], v[26:29]
	v_mfma_f32_16x16x32_bf16 v[22:25], v[170:173], v[198:201], v[22:25]
	v_mfma_f32_16x16x32_bf16 v[18:21], v[178:181], v[198:201], v[18:21]
	v_mfma_f32_16x16x32_bf16 v[14:17], v[170:173], v[214:217], v[14:17]
	v_mfma_f32_16x16x32_bf16 v[10:13], v[178:181], v[214:217], v[10:13]
	v_mfma_f32_16x16x32_bf16 v[6:9], v[170:173], v[222:225], v[6:9]
	v_mfma_f32_16x16x32_bf16 v[2:5], v[178:181], v[222:225], v[2:5]
	s_setprio 2
	s_barrier
	s_add_i32 s23, 0, 0x18000
	v_add_u32_e32 v149, s23, v144
	s_add_i32 s38, 0, 0x1c000
	ds_read_b128 v[150:153], v149
	ds_read_b128 v[154:157], v149 offset:1024
	ds_read_b128 v[158:161], v149 offset:2048
	ds_read_b128 v[162:165], v149 offset:3072
	v_add_u32_e32 v149, s38, v144
	ds_read_b128 v[166:169], v149
	ds_read_b128 v[170:173], v149 offset:1024
	ds_read_b128 v[174:177], v149 offset:2048
	ds_read_b128 v[178:181], v149 offset:3072
	s_add_u32 s36, s36, 0x80000
	s_addc_u32 s37, s37, 0
	s_mov_b32 m0, s42
	v_lshl_add_u64 v[230:231], s[36:37], 0, v[130:131]
	ds_read_b128 v[182:185], v148 offset:32768
	ds_read_b128 v[186:189], v148 offset:33792
	ds_read_b128 v[190:193], v148 offset:34816
	ds_read_b128 v[198:201], v148 offset:35840
	ds_read_b128 v[210:213], v148 offset:36864
	ds_read_b128 v[214:217], v148 offset:37888
	ds_read_b128 v[218:221], v148 offset:38912
	ds_read_b128 v[222:225], v148 offset:39936
	global_load_lds_dwordx4 v[230:231], off
	v_lshl_add_u64 v[230:231], s[36:37], 0, v[134:135]
	s_mov_b32 m0, s43
	s_nop 0
	global_load_lds_dwordx4 v[230:231], off
	s_waitcnt vmcnt(8)
	s_waitcnt lgkmcnt(0)
	s_barrier
	s_setprio 1
	s_waitcnt lgkmcnt(0)
	v_mfma_f32_16x16x32_bf16 v[126:129], v[150:153], v[182:185], v[126:129]
	v_mfma_f32_16x16x32_bf16 v[122:125], v[158:161], v[182:185], v[122:125]
	v_mfma_f32_16x16x32_bf16 v[118:121], v[150:153], v[190:193], v[118:121]
	v_mfma_f32_16x16x32_bf16 v[114:117], v[158:161], v[190:193], v[114:117]
	v_mfma_f32_16x16x32_bf16 v[110:113], v[150:153], v[210:213], v[110:113]
	v_mfma_f32_16x16x32_bf16 v[106:109], v[158:161], v[210:213], v[106:109]
	v_mfma_f32_16x16x32_bf16 v[102:105], v[150:153], v[218:221], v[102:105]
	v_mfma_f32_16x16x32_bf16 v[98:101], v[158:161], v[218:221], v[98:101]
	v_mfma_f32_16x16x32_bf16 v[126:129], v[154:157], v[186:189], v[126:129]
	v_mfma_f32_16x16x32_bf16 v[122:125], v[162:165], v[186:189], v[122:125]
	v_mfma_f32_16x16x32_bf16 v[118:121], v[154:157], v[198:201], v[118:121]
	v_mfma_f32_16x16x32_bf16 v[114:117], v[162:165], v[198:201], v[114:117]
	v_mfma_f32_16x16x32_bf16 v[110:113], v[154:157], v[214:217], v[110:113]
	v_mfma_f32_16x16x32_bf16 v[106:109], v[162:165], v[214:217], v[106:109]
	v_mfma_f32_16x16x32_bf16 v[102:105], v[154:157], v[222:225], v[102:105]
	v_mfma_f32_16x16x32_bf16 v[98:101], v[162:165], v[222:225], v[98:101]
	v_mfma_f32_16x16x32_bf16 v[94:97], v[166:169], v[182:185], v[94:97]
	v_mfma_f32_16x16x32_bf16 v[90:93], v[174:177], v[182:185], v[90:93]
	v_mfma_f32_16x16x32_bf16 v[86:89], v[166:169], v[190:193], v[86:89]
	v_mfma_f32_16x16x32_bf16 v[82:85], v[174:177], v[190:193], v[82:85]
	v_mfma_f32_16x16x32_bf16 v[78:81], v[166:169], v[210:213], v[78:81]
	v_mfma_f32_16x16x32_bf16 v[74:77], v[174:177], v[210:213], v[74:77]
	v_mfma_f32_16x16x32_bf16 v[70:73], v[166:169], v[218:221], v[70:73]
	v_mfma_f32_16x16x32_bf16 v[66:69], v[174:177], v[218:221], v[66:69]
	v_mfma_f32_16x16x32_bf16 v[94:97], v[170:173], v[186:189], v[94:97]
	v_mfma_f32_16x16x32_bf16 v[90:93], v[178:181], v[186:189], v[90:93]
	v_mfma_f32_16x16x32_bf16 v[86:89], v[170:173], v[198:201], v[86:89]
	v_mfma_f32_16x16x32_bf16 v[82:85], v[178:181], v[198:201], v[82:85]
	v_mfma_f32_16x16x32_bf16 v[78:81], v[170:173], v[214:217], v[78:81]
	v_mfma_f32_16x16x32_bf16 v[74:77], v[178:181], v[214:217], v[74:77]
	v_mfma_f32_16x16x32_bf16 v[70:73], v[170:173], v[222:225], v[70:73]
	v_mfma_f32_16x16x32_bf16 v[66:69], v[178:181], v[222:225], v[66:69]
	s_setprio 2
	s_barrier
	s_add_i32 s23, s23, s33
	v_lshl_add_u64 v[202:203], v[202:203], 0, s[10:11]
	s_mov_b32 m0, s23
	ds_read_b128 v[182:185], v148 offset:49152
	ds_read_b128 v[186:189], v148 offset:50176
	ds_read_b128 v[190:193], v148 offset:51200
	ds_read_b128 v[198:201], v148 offset:52224
	ds_read_b128 v[210:213], v148 offset:53248
	ds_read_b128 v[214:217], v148 offset:54272
	ds_read_b128 v[218:221], v148 offset:55296
	ds_read_b128 v[222:225], v148 offset:56320
	global_load_lds_dwordx4 v[202:203], off
	s_add_i32 m0, s23, 0x2000
	s_add_u32 s34, s34, 0x80080
	v_lshl_add_u64 v[202:203], v[206:207], 0, s[10:11]
	s_addc_u32 s35, s35, 0
	s_add_i32 s23, s38, s33
	global_load_lds_dwordx4 v[202:203], off
	v_lshl_add_u64 v[202:203], s[34:35], 0, v[132:133]
	s_mov_b32 m0, s23
	s_nop 0
	global_load_lds_dwordx4 v[202:203], off
	v_lshl_add_u64 v[202:203], s[34:35], 0, v[136:137]
	s_add_i32 m0, s23, 0x2000
	s_nop 0
	global_load_lds_dwordx4 v[202:203], off
	v_lshl_add_u64 v[202:203], v[226:227], 0, s[10:11]
	s_mov_b32 m0, s51
	s_nop 0
	global_load_lds_dwordx4 v[202:203], off
	v_lshl_add_u64 v[202:203], v[228:229], 0, s[10:11]
	s_mov_b32 m0, s52
	s_nop 0
	global_load_lds_dwordx4 v[202:203], off
	s_waitcnt vmcnt(8)
	s_waitcnt lgkmcnt(0)
	s_barrier
	s_setprio 1
	s_waitcnt lgkmcnt(0)
	v_mfma_f32_16x16x32_bf16 v[62:65], v[150:153], v[182:185], v[62:65]
	v_mfma_f32_16x16x32_bf16 v[58:61], v[158:161], v[182:185], v[58:61]
	v_mfma_f32_16x16x32_bf16 v[54:57], v[150:153], v[190:193], v[54:57]
	v_mfma_f32_16x16x32_bf16 v[50:53], v[158:161], v[190:193], v[50:53]
	v_mfma_f32_16x16x32_bf16 v[46:49], v[150:153], v[210:213], v[46:49]
	v_mfma_f32_16x16x32_bf16 v[42:45], v[158:161], v[210:213], v[42:45]
	v_mfma_f32_16x16x32_bf16 v[38:41], v[150:153], v[218:221], v[38:41]
	v_mfma_f32_16x16x32_bf16 v[34:37], v[158:161], v[218:221], v[34:37]
	v_mfma_f32_16x16x32_bf16 v[62:65], v[154:157], v[186:189], v[62:65]
	v_mfma_f32_16x16x32_bf16 v[58:61], v[162:165], v[186:189], v[58:61]
	v_mfma_f32_16x16x32_bf16 v[54:57], v[154:157], v[198:201], v[54:57]
	v_mfma_f32_16x16x32_bf16 v[50:53], v[162:165], v[198:201], v[50:53]
	v_mfma_f32_16x16x32_bf16 v[46:49], v[154:157], v[214:217], v[46:49]
	v_mfma_f32_16x16x32_bf16 v[42:45], v[162:165], v[214:217], v[42:45]
	v_mfma_f32_16x16x32_bf16 v[38:41], v[154:157], v[222:225], v[38:41]
	v_mfma_f32_16x16x32_bf16 v[34:37], v[162:165], v[222:225], v[34:37]
	v_mfma_f32_16x16x32_bf16 v[30:33], v[166:169], v[182:185], v[30:33]
	v_mfma_f32_16x16x32_bf16 v[26:29], v[174:177], v[182:185], v[26:29]
	v_mfma_f32_16x16x32_bf16 v[22:25], v[166:169], v[190:193], v[22:25]
	v_mfma_f32_16x16x32_bf16 v[18:21], v[174:177], v[190:193], v[18:21]
	v_mfma_f32_16x16x32_bf16 v[14:17], v[166:169], v[210:213], v[14:17]
	v_mfma_f32_16x16x32_bf16 v[10:13], v[174:177], v[210:213], v[10:13]
	v_mfma_f32_16x16x32_bf16 v[6:9], v[166:169], v[218:221], v[6:9]
	v_mfma_f32_16x16x32_bf16 v[2:5], v[174:177], v[218:221], v[2:5]
	v_mfma_f32_16x16x32_bf16 v[30:33], v[170:173], v[186:189], v[30:33]
	v_mfma_f32_16x16x32_bf16 v[26:29], v[178:181], v[186:189], v[26:29]
	v_mfma_f32_16x16x32_bf16 v[22:25], v[170:173], v[198:201], v[22:25]
	v_mfma_f32_16x16x32_bf16 v[18:21], v[178:181], v[198:201], v[18:21]
	v_mfma_f32_16x16x32_bf16 v[14:17], v[170:173], v[214:217], v[14:17]
	v_mfma_f32_16x16x32_bf16 v[10:13], v[178:181], v[214:217], v[10:13]
	v_mfma_f32_16x16x32_bf16 v[6:9], v[170:173], v[222:225], v[6:9]
	v_mfma_f32_16x16x32_bf16 v[2:5], v[178:181], v[222:225], v[2:5]
	s_setprio 2
	s_barrier
	s_add_u32 s30, s30, 0x100
	s_addc_u32 s31, s31, 0
	s_add_u32 s19, s19, 0x100
	s_addc_u32 s21, s21, 0
	s_cmp_ge_i32 s29, s68
	s_mov_b32 s23, s29
	s_cbranch_scc0 .LBB0_1973
	s_branch .Lpeeldone_3
.LBB0_1973:
	ds_read_b128 v[150:153], v146
	ds_read_b128 v[154:157], v146 offset:1024
	ds_read_b128 v[158:161], v146 offset:2048
	ds_read_b128 v[162:165], v146 offset:3072
	ds_read_b128 v[166:169], v147
	ds_read_b128 v[170:173], v147 offset:1024
	ds_read_b128 v[174:177], v147 offset:2048
	ds_read_b128 v[178:181], v147 offset:3072
	s_add_i32 s29, s23, 2
	s_add_u32 s34, s30, 0xfff80080
	s_addc_u32 s35, s31, -1
	s_cmp_eq_u32 s28, s23
	s_cselect_b32 s37, s25, s35
	s_cselect_b32 s36, s24, s34
	s_cselect_b32 s35, s27, s21
	s_cselect_b32 s34, s26, s19
	v_lshl_add_u64 v[202:203], s[30:31], 0, v[140:141]
	s_add_i32 m0, s15, 0xc000
	ds_read_b128 v[182:185], v148
	ds_read_b128 v[186:189], v148 offset:1024
	ds_read_b128 v[190:193], v148 offset:2048
	ds_read_b128 v[198:201], v148 offset:3072
	ds_read_b128 v[210:213], v148 offset:4096
	ds_read_b128 v[214:217], v148 offset:5120
	ds_read_b128 v[218:221], v148 offset:6144
	ds_read_b128 v[222:225], v148 offset:7168
	global_load_lds_dwordx4 v[202:203], off
	v_lshl_add_u64 v[202:203], s[30:31], 0, v[142:143]
	s_add_i32 m0, s15, 0xe000
	s_nop 0
	global_load_lds_dwordx4 v[202:203], off
	s_waitcnt vmcnt(8)
	s_waitcnt lgkmcnt(0)
	s_barrier
	s_setprio 1
	s_waitcnt lgkmcnt(0)
	v_mfma_f32_16x16x32_bf16 v[126:129], v[150:153], v[182:185], v[126:129]
	v_mfma_f32_16x16x32_bf16 v[122:125], v[158:161], v[182:185], v[122:125]
	v_mfma_f32_16x16x32_bf16 v[118:121], v[150:153], v[190:193], v[118:121]
	v_mfma_f32_16x16x32_bf16 v[114:117], v[158:161], v[190:193], v[114:117]
	v_mfma_f32_16x16x32_bf16 v[110:113], v[150:153], v[210:213], v[110:113]
	v_mfma_f32_16x16x32_bf16 v[106:109], v[158:161], v[210:213], v[106:109]
	v_mfma_f32_16x16x32_bf16 v[102:105], v[150:153], v[218:221], v[102:105]
	v_mfma_f32_16x16x32_bf16 v[98:101], v[158:161], v[218:221], v[98:101]
	v_mfma_f32_16x16x32_bf16 v[126:129], v[154:157], v[186:189], v[126:129]
	v_mfma_f32_16x16x32_bf16 v[122:125], v[162:165], v[186:189], v[122:125]
	v_mfma_f32_16x16x32_bf16 v[118:121], v[154:157], v[198:201], v[118:121]
	v_mfma_f32_16x16x32_bf16 v[114:117], v[162:165], v[198:201], v[114:117]
	v_mfma_f32_16x16x32_bf16 v[110:113], v[154:157], v[214:217], v[110:113]
	v_mfma_f32_16x16x32_bf16 v[106:109], v[162:165], v[214:217], v[106:109]
	v_mfma_f32_16x16x32_bf16 v[102:105], v[154:157], v[222:225], v[102:105]
	v_mfma_f32_16x16x32_bf16 v[98:101], v[162:165], v[222:225], v[98:101]
	v_mfma_f32_16x16x32_bf16 v[94:97], v[166:169], v[182:185], v[94:97]
	v_mfma_f32_16x16x32_bf16 v[90:93], v[174:177], v[182:185], v[90:93]
	v_mfma_f32_16x16x32_bf16 v[86:89], v[166:169], v[190:193], v[86:89]
	v_mfma_f32_16x16x32_bf16 v[82:85], v[174:177], v[190:193], v[82:85]
	v_mfma_f32_16x16x32_bf16 v[78:81], v[166:169], v[210:213], v[78:81]
	v_mfma_f32_16x16x32_bf16 v[74:77], v[174:177], v[210:213], v[74:77]
	v_mfma_f32_16x16x32_bf16 v[70:73], v[166:169], v[218:221], v[70:73]
	v_mfma_f32_16x16x32_bf16 v[66:69], v[174:177], v[218:221], v[66:69]
	v_mfma_f32_16x16x32_bf16 v[94:97], v[170:173], v[186:189], v[94:97]
	v_mfma_f32_16x16x32_bf16 v[90:93], v[178:181], v[186:189], v[90:93]
	v_mfma_f32_16x16x32_bf16 v[86:89], v[170:173], v[198:201], v[86:89]
	v_mfma_f32_16x16x32_bf16 v[82:85], v[178:181], v[198:201], v[82:85]
	v_mfma_f32_16x16x32_bf16 v[78:81], v[170:173], v[214:217], v[78:81]
	v_mfma_f32_16x16x32_bf16 v[74:77], v[178:181], v[214:217], v[74:77]
	v_mfma_f32_16x16x32_bf16 v[70:73], v[170:173], v[222:225], v[70:73]
	v_mfma_f32_16x16x32_bf16 v[66:69], v[178:181], v[222:225], v[66:69]
	s_setprio 2
	s_barrier
	s_add_i32 s23, s60, s33
	v_lshl_add_u64 v[202:203], s[34:35], 0, v[132:133]
	s_mov_b32 m0, s23
	ds_read_b128 v[182:185], v148 offset:16384
	ds_read_b128 v[186:189], v148 offset:17408
	ds_read_b128 v[190:193], v148 offset:18432
	ds_read_b128 v[198:201], v148 offset:19456
	ds_read_b128 v[210:213], v148 offset:20480
	ds_read_b128 v[214:217], v148 offset:21504
	ds_read_b128 v[218:221], v148 offset:22528
	ds_read_b128 v[222:225], v148 offset:23552
	global_load_lds_dwordx4 v[202:203], off
	s_add_i32 m0, s23, 0x2000
	s_add_u32 s38, s34, 0x80000
	v_lshl_add_u64 v[206:207], s[34:35], 0, v[136:137]
	s_addc_u32 s39, s35, 0
	s_add_i32 s23, s61, s33
	global_load_lds_dwordx4 v[206:207], off
	v_lshl_add_u64 v[226:227], s[38:39], 0, v[132:133]
	s_mov_b32 m0, s23
	v_lshl_add_u64 v[228:229], s[36:37], 0, v[134:135]
	global_load_lds_dwordx4 v[226:227], off
	v_lshl_add_u64 v[226:227], s[38:39], 0, v[136:137]
	s_add_i32 m0, s23, 0x2000
	s_nop 0
	global_load_lds_dwordx4 v[226:227], off
	v_lshl_add_u64 v[226:227], s[36:37], 0, v[130:131]
	s_mov_b32 m0, s15
	s_nop 0
	global_load_lds_dwordx4 v[226:227], off
	s_mov_b32 m0, s41
	s_nop 0
	global_load_lds_dwordx4 v[228:229], off
	s_waitcnt vmcnt(8)
	s_waitcnt lgkmcnt(0)
	s_barrier
	s_setprio 1
	s_waitcnt lgkmcnt(0)
	v_mfma_f32_16x16x32_bf16 v[62:65], v[150:153], v[182:185], v[62:65]
	v_mfma_f32_16x16x32_bf16 v[58:61], v[158:161], v[182:185], v[58:61]
	v_mfma_f32_16x16x32_bf16 v[54:57], v[150:153], v[190:193], v[54:57]
	v_mfma_f32_16x16x32_bf16 v[50:53], v[158:161], v[190:193], v[50:53]
	v_mfma_f32_16x16x32_bf16 v[46:49], v[150:153], v[210:213], v[46:49]
	v_mfma_f32_16x16x32_bf16 v[42:45], v[158:161], v[210:213], v[42:45]
	v_mfma_f32_16x16x32_bf16 v[38:41], v[150:153], v[218:221], v[38:41]
	v_mfma_f32_16x16x32_bf16 v[34:37], v[158:161], v[218:221], v[34:37]
	v_mfma_f32_16x16x32_bf16 v[62:65], v[154:157], v[186:189], v[62:65]
	v_mfma_f32_16x16x32_bf16 v[58:61], v[162:165], v[186:189], v[58:61]
	v_mfma_f32_16x16x32_bf16 v[54:57], v[154:157], v[198:201], v[54:57]
	v_mfma_f32_16x16x32_bf16 v[50:53], v[162:165], v[198:201], v[50:53]
	v_mfma_f32_16x16x32_bf16 v[46:49], v[154:157], v[214:217], v[46:49]
	v_mfma_f32_16x16x32_bf16 v[42:45], v[162:165], v[214:217], v[42:45]
	v_mfma_f32_16x16x32_bf16 v[38:41], v[154:157], v[222:225], v[38:41]
	v_mfma_f32_16x16x32_bf16 v[34:37], v[162:165], v[222:225], v[34:37]
	v_mfma_f32_16x16x32_bf16 v[30:33], v[166:169], v[182:185], v[30:33]
	v_mfma_f32_16x16x32_bf16 v[26:29], v[174:177], v[182:185], v[26:29]
	v_mfma_f32_16x16x32_bf16 v[22:25], v[166:169], v[190:193], v[22:25]
	v_mfma_f32_16x16x32_bf16 v[18:21], v[174:177], v[190:193], v[18:21]
	v_mfma_f32_16x16x32_bf16 v[14:17], v[166:169], v[210:213], v[14:17]
	v_mfma_f32_16x16x32_bf16 v[10:13], v[174:177], v[210:213], v[10:13]
	v_mfma_f32_16x16x32_bf16 v[6:9], v[166:169], v[218:221], v[6:9]
	v_mfma_f32_16x16x32_bf16 v[2:5], v[174:177], v[218:221], v[2:5]
	v_mfma_f32_16x16x32_bf16 v[30:33], v[170:173], v[186:189], v[30:33]
	v_mfma_f32_16x16x32_bf16 v[26:29], v[178:181], v[186:189], v[26:29]
	v_mfma_f32_16x16x32_bf16 v[22:25], v[170:173], v[198:201], v[22:25]
	v_mfma_f32_16x16x32_bf16 v[18:21], v[178:181], v[198:201], v[18:21]
	v_mfma_f32_16x16x32_bf16 v[14:17], v[170:173], v[214:217], v[14:17]
	v_mfma_f32_16x16x32_bf16 v[10:13], v[178:181], v[214:217], v[10:13]
	v_mfma_f32_16x16x32_bf16 v[6:9], v[170:173], v[222:225], v[6:9]
	v_mfma_f32_16x16x32_bf16 v[2:5], v[178:181], v[222:225], v[2:5]
	s_setprio 2
	s_barrier
	s_add_i32 s23, 0, 0x18000
	v_add_u32_e32 v149, s23, v144
	s_add_i32 s38, 0, 0x1c000
	ds_read_b128 v[150:153], v149
	ds_read_b128 v[154:157], v149 offset:1024
	ds_read_b128 v[158:161], v149 offset:2048
	ds_read_b128 v[162:165], v149 offset:3072
	v_add_u32_e32 v149, s38, v144
	ds_read_b128 v[166:169], v149
	ds_read_b128 v[170:173], v149 offset:1024
	ds_read_b128 v[174:177], v149 offset:2048
	ds_read_b128 v[178:181], v149 offset:3072
	s_add_u32 s36, s36, 0x80000
	s_addc_u32 s37, s37, 0
	s_mov_b32 m0, s42
	v_lshl_add_u64 v[230:231], s[36:37], 0, v[130:131]
	ds_read_b128 v[182:185], v148 offset:32768
	ds_read_b128 v[186:189], v148 offset:33792
	ds_read_b128 v[190:193], v148 offset:34816
	ds_read_b128 v[198:201], v148 offset:35840
	ds_read_b128 v[210:213], v148 offset:36864
	ds_read_b128 v[214:217], v148 offset:37888
	ds_read_b128 v[218:221], v148 offset:38912
	ds_read_b128 v[222:225], v148 offset:39936
	global_load_lds_dwordx4 v[230:231], off
	v_lshl_add_u64 v[230:231], s[36:37], 0, v[134:135]
	s_mov_b32 m0, s43
	s_nop 0
	global_load_lds_dwordx4 v[230:231], off
	s_waitcnt vmcnt(8)
	s_waitcnt lgkmcnt(0)
	s_barrier
	s_setprio 1
	s_waitcnt lgkmcnt(0)
	v_mfma_f32_16x16x32_bf16 v[126:129], v[150:153], v[182:185], v[126:129]
	v_mfma_f32_16x16x32_bf16 v[122:125], v[158:161], v[182:185], v[122:125]
	v_mfma_f32_16x16x32_bf16 v[118:121], v[150:153], v[190:193], v[118:121]
	v_mfma_f32_16x16x32_bf16 v[114:117], v[158:161], v[190:193], v[114:117]
	v_mfma_f32_16x16x32_bf16 v[110:113], v[150:153], v[210:213], v[110:113]
	v_mfma_f32_16x16x32_bf16 v[106:109], v[158:161], v[210:213], v[106:109]
	v_mfma_f32_16x16x32_bf16 v[102:105], v[150:153], v[218:221], v[102:105]
	v_mfma_f32_16x16x32_bf16 v[98:101], v[158:161], v[218:221], v[98:101]
	v_mfma_f32_16x16x32_bf16 v[126:129], v[154:157], v[186:189], v[126:129]
	v_mfma_f32_16x16x32_bf16 v[122:125], v[162:165], v[186:189], v[122:125]
	v_mfma_f32_16x16x32_bf16 v[118:121], v[154:157], v[198:201], v[118:121]
	v_mfma_f32_16x16x32_bf16 v[114:117], v[162:165], v[198:201], v[114:117]
	v_mfma_f32_16x16x32_bf16 v[110:113], v[154:157], v[214:217], v[110:113]
	v_mfma_f32_16x16x32_bf16 v[106:109], v[162:165], v[214:217], v[106:109]
	v_mfma_f32_16x16x32_bf16 v[102:105], v[154:157], v[222:225], v[102:105]
	v_mfma_f32_16x16x32_bf16 v[98:101], v[162:165], v[222:225], v[98:101]
	v_mfma_f32_16x16x32_bf16 v[94:97], v[166:169], v[182:185], v[94:97]
	v_mfma_f32_16x16x32_bf16 v[90:93], v[174:177], v[182:185], v[90:93]
	v_mfma_f32_16x16x32_bf16 v[86:89], v[166:169], v[190:193], v[86:89]
	v_mfma_f32_16x16x32_bf16 v[82:85], v[174:177], v[190:193], v[82:85]
	v_mfma_f32_16x16x32_bf16 v[78:81], v[166:169], v[210:213], v[78:81]
	v_mfma_f32_16x16x32_bf16 v[74:77], v[174:177], v[210:213], v[74:77]
	v_mfma_f32_16x16x32_bf16 v[70:73], v[166:169], v[218:221], v[70:73]
	v_mfma_f32_16x16x32_bf16 v[66:69], v[174:177], v[218:221], v[66:69]
	v_mfma_f32_16x16x32_bf16 v[94:97], v[170:173], v[186:189], v[94:97]
	v_mfma_f32_16x16x32_bf16 v[90:93], v[178:181], v[186:189], v[90:93]
	v_mfma_f32_16x16x32_bf16 v[86:89], v[170:173], v[198:201], v[86:89]
	v_mfma_f32_16x16x32_bf16 v[82:85], v[178:181], v[198:201], v[82:85]
	v_mfma_f32_16x16x32_bf16 v[78:81], v[170:173], v[214:217], v[78:81]
	v_mfma_f32_16x16x32_bf16 v[74:77], v[178:181], v[214:217], v[74:77]
	v_mfma_f32_16x16x32_bf16 v[70:73], v[170:173], v[222:225], v[70:73]
	v_mfma_f32_16x16x32_bf16 v[66:69], v[178:181], v[222:225], v[66:69]
	s_setprio 2
	s_barrier
	s_add_i32 s23, s23, s33
	v_lshl_add_u64 v[202:203], v[202:203], 0, s[10:11]
	s_mov_b32 m0, s23
	ds_read_b128 v[182:185], v148 offset:49152
	ds_read_b128 v[186:189], v148 offset:50176
	ds_read_b128 v[190:193], v148 offset:51200
	ds_read_b128 v[198:201], v148 offset:52224
	ds_read_b128 v[210:213], v148 offset:53248
	ds_read_b128 v[214:217], v148 offset:54272
	ds_read_b128 v[218:221], v148 offset:55296
	ds_read_b128 v[222:225], v148 offset:56320
	global_load_lds_dwordx4 v[202:203], off
	s_add_i32 m0, s23, 0x2000
	s_add_u32 s34, s34, 0x80080
	v_lshl_add_u64 v[202:203], v[206:207], 0, s[10:11]
	s_addc_u32 s35, s35, 0
	s_add_i32 s23, s38, s33
	global_load_lds_dwordx4 v[202:203], off
	v_lshl_add_u64 v[202:203], s[34:35], 0, v[132:133]
	s_mov_b32 m0, s23
	s_nop 0
	global_load_lds_dwordx4 v[202:203], off
	v_lshl_add_u64 v[202:203], s[34:35], 0, v[136:137]
	s_add_i32 m0, s23, 0x2000
	s_nop 0
	global_load_lds_dwordx4 v[202:203], off
	v_lshl_add_u64 v[202:203], v[226:227], 0, s[10:11]
	s_mov_b32 m0, s51
	s_nop 0
	global_load_lds_dwordx4 v[202:203], off
	v_lshl_add_u64 v[202:203], v[228:229], 0, s[10:11]
	s_mov_b32 m0, s52
	s_nop 0
	global_load_lds_dwordx4 v[202:203], off
	s_waitcnt vmcnt(8)
	s_waitcnt lgkmcnt(0)
	s_barrier
	s_setprio 1
	s_waitcnt lgkmcnt(0)
	v_mfma_f32_16x16x32_bf16 v[62:65], v[150:153], v[182:185], v[62:65]
	v_mfma_f32_16x16x32_bf16 v[58:61], v[158:161], v[182:185], v[58:61]
	v_mfma_f32_16x16x32_bf16 v[54:57], v[150:153], v[190:193], v[54:57]
	v_mfma_f32_16x16x32_bf16 v[50:53], v[158:161], v[190:193], v[50:53]
	v_mfma_f32_16x16x32_bf16 v[46:49], v[150:153], v[210:213], v[46:49]
	v_mfma_f32_16x16x32_bf16 v[42:45], v[158:161], v[210:213], v[42:45]
	v_mfma_f32_16x16x32_bf16 v[38:41], v[150:153], v[218:221], v[38:41]
	v_mfma_f32_16x16x32_bf16 v[34:37], v[158:161], v[218:221], v[34:37]
	v_mfma_f32_16x16x32_bf16 v[62:65], v[154:157], v[186:189], v[62:65]
	v_mfma_f32_16x16x32_bf16 v[58:61], v[162:165], v[186:189], v[58:61]
	v_mfma_f32_16x16x32_bf16 v[54:57], v[154:157], v[198:201], v[54:57]
	v_mfma_f32_16x16x32_bf16 v[50:53], v[162:165], v[198:201], v[50:53]
	v_mfma_f32_16x16x32_bf16 v[46:49], v[154:157], v[214:217], v[46:49]
	v_mfma_f32_16x16x32_bf16 v[42:45], v[162:165], v[214:217], v[42:45]
	v_mfma_f32_16x16x32_bf16 v[38:41], v[154:157], v[222:225], v[38:41]
	v_mfma_f32_16x16x32_bf16 v[34:37], v[162:165], v[222:225], v[34:37]
	v_mfma_f32_16x16x32_bf16 v[30:33], v[166:169], v[182:185], v[30:33]
	v_mfma_f32_16x16x32_bf16 v[26:29], v[174:177], v[182:185], v[26:29]
	v_mfma_f32_16x16x32_bf16 v[22:25], v[166:169], v[190:193], v[22:25]
	v_mfma_f32_16x16x32_bf16 v[18:21], v[174:177], v[190:193], v[18:21]
	v_mfma_f32_16x16x32_bf16 v[14:17], v[166:169], v[210:213], v[14:17]
	v_mfma_f32_16x16x32_bf16 v[10:13], v[174:177], v[210:213], v[10:13]
	v_mfma_f32_16x16x32_bf16 v[6:9], v[166:169], v[218:221], v[6:9]
	v_mfma_f32_16x16x32_bf16 v[2:5], v[174:177], v[218:221], v[2:5]
	v_mfma_f32_16x16x32_bf16 v[30:33], v[170:173], v[186:189], v[30:33]
	v_mfma_f32_16x16x32_bf16 v[26:29], v[178:181], v[186:189], v[26:29]
	v_mfma_f32_16x16x32_bf16 v[22:25], v[170:173], v[198:201], v[22:25]
	v_mfma_f32_16x16x32_bf16 v[18:21], v[178:181], v[198:201], v[18:21]
	v_mfma_f32_16x16x32_bf16 v[14:17], v[170:173], v[214:217], v[14:17]
	v_mfma_f32_16x16x32_bf16 v[10:13], v[178:181], v[214:217], v[10:13]
	v_mfma_f32_16x16x32_bf16 v[6:9], v[170:173], v[222:225], v[6:9]
	v_mfma_f32_16x16x32_bf16 v[2:5], v[178:181], v[222:225], v[2:5]
	s_setprio 2
	s_barrier
	s_add_u32 s30, s30, 0x100
	s_addc_u32 s31, s31, 0
	s_add_u32 s19, s19, 0x100
	s_addc_u32 s21, s21, 0
	s_cmp_ge_i32 s29, s68
	s_mov_b32 s23, s29
	s_cbranch_scc0 .LBB0_1973

.Lpeel_1:
	ds_read_b128 v[152:155], v148
	ds_read_b128 v[156:159], v148 offset:1024
	s_add_i32 s29, s19, 2
	s_add_u32 s34, s30, 0xfff80080
	s_addc_u32 s35, s31, -1
	s_cmp_eq_u32 s28, s19
	s_cselect_b32 s37, s21, s35
	s_cselect_b32 s36, s20, s34
	s_cselect_b32 s35, s23, s17
	s_cselect_b32 s34, s22, s15
	v_lshl_add_u64 v[144:145], s[30:31], 0, v[140:141]
	s_add_i32 m0, s27, 0xc000
	global_load_lds_dwordx4 v[144:145], off
	v_lshl_add_u64 v[144:145], s[30:31], 0, v[142:143]
	s_add_i32 m0, s27, 0xe000
	s_nop 0
	global_load_lds_dwordx4 v[144:145], off
	s_waitcnt vmcnt(8)
	s_waitcnt lgkmcnt(0)
	s_barrier
	s_setprio 1
	s_waitcnt lgkmcnt(0)
	v_mfma_f32_16x16x32_bf16 v[126:129], v[152:155], v[184:187], 0
	v_mfma_f32_16x16x32_bf16 v[122:125], v[160:163], v[184:187], 0
	v_mfma_f32_16x16x32_bf16 v[110:113], v[152:155], v[192:195], 0
	v_mfma_f32_16x16x32_bf16 v[106:109], v[160:163], v[192:195], 0
	v_mfma_f32_16x16x32_bf16 v[94:97], v[152:155], v[210:213], 0
	v_mfma_f32_16x16x32_bf16 v[90:93], v[160:163], v[210:213], 0
	v_mfma_f32_16x16x32_bf16 v[78:81], v[152:155], v[218:221], 0
	v_mfma_f32_16x16x32_bf16 v[74:77], v[160:163], v[218:221], 0
	v_mfma_f32_16x16x32_bf16 v[126:129], v[156:159], v[188:191], v[126:129]
	v_mfma_f32_16x16x32_bf16 v[122:125], v[164:167], v[188:191], v[122:125]
	v_mfma_f32_16x16x32_bf16 v[110:113], v[156:159], v[198:201], v[110:113]
	v_mfma_f32_16x16x32_bf16 v[106:109], v[164:167], v[198:201], v[106:109]
	v_mfma_f32_16x16x32_bf16 v[94:97], v[156:159], v[214:217], v[94:97]
	v_mfma_f32_16x16x32_bf16 v[90:93], v[164:167], v[214:217], v[90:93]
	v_mfma_f32_16x16x32_bf16 v[78:81], v[156:159], v[222:225], v[78:81]
	v_mfma_f32_16x16x32_bf16 v[74:77], v[164:167], v[222:225], v[74:77]
	v_mfma_f32_16x16x32_bf16 v[118:121], v[168:171], v[184:187], 0
	v_mfma_f32_16x16x32_bf16 v[114:117], v[176:179], v[184:187], 0
	v_mfma_f32_16x16x32_bf16 v[102:105], v[168:171], v[192:195], 0
	v_mfma_f32_16x16x32_bf16 v[98:101], v[176:179], v[192:195], 0
	v_mfma_f32_16x16x32_bf16 v[86:89], v[168:171], v[210:213], 0
	v_mfma_f32_16x16x32_bf16 v[82:85], v[176:179], v[210:213], 0
	v_mfma_f32_16x16x32_bf16 v[70:73], v[168:171], v[218:221], 0
	v_mfma_f32_16x16x32_bf16 v[66:69], v[176:179], v[218:221], 0
	v_mfma_f32_16x16x32_bf16 v[118:121], v[172:175], v[188:191], v[118:121]
	v_mfma_f32_16x16x32_bf16 v[114:117], v[180:183], v[188:191], v[114:117]
	v_mfma_f32_16x16x32_bf16 v[102:105], v[172:175], v[198:201], v[102:105]
	v_mfma_f32_16x16x32_bf16 v[98:101], v[180:183], v[198:201], v[98:101]
	v_mfma_f32_16x16x32_bf16 v[86:89], v[172:175], v[214:217], v[86:89]
	v_mfma_f32_16x16x32_bf16 v[82:85], v[180:183], v[214:217], v[82:85]
	v_mfma_f32_16x16x32_bf16 v[70:73], v[172:175], v[222:225], v[70:73]
	v_mfma_f32_16x16x32_bf16 v[66:69], v[180:183], v[222:225], v[66:69]
	s_setprio 2
	s_barrier
	s_add_i32 s19, s60, s33
	v_lshl_add_u64 v[144:145], s[34:35], 0, v[132:133]
	s_mov_b32 m0, s19
	ds_read_b128 v[184:187], v150 offset:16384
	ds_read_b128 v[188:191], v150 offset:17408
	ds_read_b128 v[192:195], v150 offset:18432
	ds_read_b128 v[198:201], v150 offset:19456
	ds_read_b128 v[210:213], v150 offset:20480
	ds_read_b128 v[214:217], v150 offset:21504
	ds_read_b128 v[218:221], v150 offset:22528
	ds_read_b128 v[222:225], v150 offset:23552
	global_load_lds_dwordx4 v[144:145], off
	s_add_i32 m0, s19, 0x2000
	s_add_u32 s38, s34, 0x80000
	v_lshl_add_u64 v[202:203], s[34:35], 0, v[136:137]
	s_addc_u32 s39, s35, 0
	s_add_i32 s19, s61, s33
	global_load_lds_dwordx4 v[202:203], off
	v_lshl_add_u64 v[206:207], s[38:39], 0, v[132:133]
	s_mov_b32 m0, s19
	v_lshl_add_u64 v[226:227], s[36:37], 0, v[134:135]
	global_load_lds_dwordx4 v[206:207], off
	v_lshl_add_u64 v[206:207], s[38:39], 0, v[136:137]
	s_add_i32 m0, s19, 0x2000
	s_nop 0
	global_load_lds_dwordx4 v[206:207], off
	v_lshl_add_u64 v[206:207], s[36:37], 0, v[130:131]
	s_mov_b32 m0, s27
	s_nop 0
	global_load_lds_dwordx4 v[206:207], off
	s_mov_b32 m0, s41
	s_nop 0
	global_load_lds_dwordx4 v[226:227], off
	s_waitcnt vmcnt(8)
	s_waitcnt lgkmcnt(0)
	s_barrier
	s_setprio 1
	s_waitcnt lgkmcnt(0)
	v_mfma_f32_16x16x32_bf16 v[62:65], v[152:155], v[184:187], 0
	v_mfma_f32_16x16x32_bf16 v[58:61], v[160:163], v[184:187], 0
	v_mfma_f32_16x16x32_bf16 v[46:49], v[152:155], v[192:195], 0
	v_mfma_f32_16x16x32_bf16 v[42:45], v[160:163], v[192:195], 0
	v_mfma_f32_16x16x32_bf16 v[30:33], v[152:155], v[210:213], 0
	v_mfma_f32_16x16x32_bf16 v[26:29], v[160:163], v[210:213], 0
	v_mfma_f32_16x16x32_bf16 v[14:17], v[152:155], v[218:221], 0
	v_mfma_f32_16x16x32_bf16 v[10:13], v[160:163], v[218:221], 0
	v_mfma_f32_16x16x32_bf16 v[62:65], v[156:159], v[188:191], v[62:65]
	v_mfma_f32_16x16x32_bf16 v[58:61], v[164:167], v[188:191], v[58:61]
	v_mfma_f32_16x16x32_bf16 v[46:49], v[156:159], v[198:201], v[46:49]
	v_mfma_f32_16x16x32_bf16 v[42:45], v[164:167], v[198:201], v[42:45]
	v_mfma_f32_16x16x32_bf16 v[30:33], v[156:159], v[214:217], v[30:33]
	v_mfma_f32_16x16x32_bf16 v[26:29], v[164:167], v[214:217], v[26:29]
	v_mfma_f32_16x16x32_bf16 v[14:17], v[156:159], v[222:225], v[14:17]
	v_mfma_f32_16x16x32_bf16 v[10:13], v[164:167], v[222:225], v[10:13]
	v_mfma_f32_16x16x32_bf16 v[54:57], v[168:171], v[184:187], 0
	v_mfma_f32_16x16x32_bf16 v[50:53], v[176:179], v[184:187], 0
	v_mfma_f32_16x16x32_bf16 v[38:41], v[168:171], v[192:195], 0
	v_mfma_f32_16x16x32_bf16 v[34:37], v[176:179], v[192:195], 0
	v_mfma_f32_16x16x32_bf16 v[22:25], v[168:171], v[210:213], 0
	v_mfma_f32_16x16x32_bf16 v[18:21], v[176:179], v[210:213], 0
	v_mfma_f32_16x16x32_bf16 v[6:9], v[168:171], v[218:221], 0
	v_mfma_f32_16x16x32_bf16 v[2:5], v[176:179], v[218:221], 0
	v_mfma_f32_16x16x32_bf16 v[54:57], v[172:175], v[188:191], v[54:57]
	v_mfma_f32_16x16x32_bf16 v[50:53], v[180:183], v[188:191], v[50:53]
	v_mfma_f32_16x16x32_bf16 v[38:41], v[172:175], v[198:201], v[38:41]
	v_mfma_f32_16x16x32_bf16 v[34:37], v[180:183], v[198:201], v[34:37]
	v_mfma_f32_16x16x32_bf16 v[22:25], v[172:175], v[214:217], v[22:25]
	v_mfma_f32_16x16x32_bf16 v[18:21], v[180:183], v[214:217], v[18:21]
	v_mfma_f32_16x16x32_bf16 v[6:9], v[172:175], v[222:225], v[6:9]
	v_mfma_f32_16x16x32_bf16 v[2:5], v[180:183], v[222:225], v[2:5]
	s_setprio 2
	s_barrier
	s_add_i32 s19, 0, 0x18000
	v_add_u32_e32 v151, s19, v146
	s_add_i32 s38, 0, 0x1c000
	ds_read_b128 v[152:155], v151
	ds_read_b128 v[156:159], v151 offset:1024
	ds_read_b128 v[160:163], v151 offset:2048
	ds_read_b128 v[164:167], v151 offset:3072
	v_add_u32_e32 v151, s38, v146
	ds_read_b128 v[168:171], v151
	ds_read_b128 v[172:175], v151 offset:1024
	ds_read_b128 v[176:179], v151 offset:2048
	ds_read_b128 v[180:183], v151 offset:3072
	s_add_u32 s36, s36, 0x80000
	s_addc_u32 s37, s37, 0
	s_mov_b32 m0, s42
	v_lshl_add_u64 v[228:229], s[36:37], 0, v[130:131]
	ds_read_b128 v[184:187], v150 offset:32768
	ds_read_b128 v[188:191], v150 offset:33792
	ds_read_b128 v[192:195], v150 offset:34816
	ds_read_b128 v[198:201], v150 offset:35840
	ds_read_b128 v[210:213], v150 offset:36864
	ds_read_b128 v[214:217], v150 offset:37888
	ds_read_b128 v[218:221], v150 offset:38912
	ds_read_b128 v[222:225], v150 offset:39936
	global_load_lds_dwordx4 v[228:229], off
	v_lshl_add_u64 v[228:229], s[36:37], 0, v[134:135]
	s_mov_b32 m0, s43
	s_nop 0
	global_load_lds_dwordx4 v[228:229], off
	s_waitcnt vmcnt(8)
	s_waitcnt lgkmcnt(0)
	s_barrier
	s_setprio 1
	s_waitcnt lgkmcnt(0)
	v_mfma_f32_16x16x32_bf16 v[126:129], v[152:155], v[184:187], v[126:129]
	v_mfma_f32_16x16x32_bf16 v[122:125], v[160:163], v[184:187], v[122:125]
	v_mfma_f32_16x16x32_bf16 v[110:113], v[152:155], v[192:195], v[110:113]
	v_mfma_f32_16x16x32_bf16 v[106:109], v[160:163], v[192:195], v[106:109]
	v_mfma_f32_16x16x32_bf16 v[94:97], v[152:155], v[210:213], v[94:97]
	v_mfma_f32_16x16x32_bf16 v[90:93], v[160:163], v[210:213], v[90:93]
	v_mfma_f32_16x16x32_bf16 v[78:81], v[152:155], v[218:221], v[78:81]
	v_mfma_f32_16x16x32_bf16 v[74:77], v[160:163], v[218:221], v[74:77]
	v_mfma_f32_16x16x32_bf16 v[126:129], v[156:159], v[188:191], v[126:129]
	v_mfma_f32_16x16x32_bf16 v[122:125], v[164:167], v[188:191], v[122:125]
	v_mfma_f32_16x16x32_bf16 v[110:113], v[156:159], v[198:201], v[110:113]
	v_mfma_f32_16x16x32_bf16 v[106:109], v[164:167], v[198:201], v[106:109]
	v_mfma_f32_16x16x32_bf16 v[94:97], v[156:159], v[214:217], v[94:97]
	v_mfma_f32_16x16x32_bf16 v[90:93], v[164:167], v[214:217], v[90:93]
	v_mfma_f32_16x16x32_bf16 v[78:81], v[156:159], v[222:225], v[78:81]
	v_mfma_f32_16x16x32_bf16 v[74:77], v[164:167], v[222:225], v[74:77]
	v_mfma_f32_16x16x32_bf16 v[118:121], v[168:171], v[184:187], v[118:121]
	v_mfma_f32_16x16x32_bf16 v[114:117], v[176:179], v[184:187], v[114:117]
	v_mfma_f32_16x16x32_bf16 v[102:105], v[168:171], v[192:195], v[102:105]
	v_mfma_f32_16x16x32_bf16 v[98:101], v[176:179], v[192:195], v[98:101]
	v_mfma_f32_16x16x32_bf16 v[86:89], v[168:171], v[210:213], v[86:89]
	v_mfma_f32_16x16x32_bf16 v[82:85], v[176:179], v[210:213], v[82:85]
	v_mfma_f32_16x16x32_bf16 v[70:73], v[168:171], v[218:221], v[70:73]
	v_mfma_f32_16x16x32_bf16 v[66:69], v[176:179], v[218:221], v[66:69]
	v_mfma_f32_16x16x32_bf16 v[118:121], v[172:175], v[188:191], v[118:121]
	v_mfma_f32_16x16x32_bf16 v[114:117], v[180:183], v[188:191], v[114:117]
	v_mfma_f32_16x16x32_bf16 v[102:105], v[172:175], v[198:201], v[102:105]
	v_mfma_f32_16x16x32_bf16 v[98:101], v[180:183], v[198:201], v[98:101]
	v_mfma_f32_16x16x32_bf16 v[86:89], v[172:175], v[214:217], v[86:89]
	v_mfma_f32_16x16x32_bf16 v[82:85], v[180:183], v[214:217], v[82:85]
	v_mfma_f32_16x16x32_bf16 v[70:73], v[172:175], v[222:225], v[70:73]
	v_mfma_f32_16x16x32_bf16 v[66:69], v[180:183], v[222:225], v[66:69]
	s_setprio 2
	s_barrier
	s_add_i32 s19, s19, s33
	v_lshl_add_u64 v[144:145], v[144:145], 0, s[10:11]
	s_mov_b32 m0, s19
	ds_read_b128 v[184:187], v150 offset:49152
	ds_read_b128 v[188:191], v150 offset:50176
	ds_read_b128 v[192:195], v150 offset:51200
	ds_read_b128 v[198:201], v150 offset:52224
	ds_read_b128 v[210:213], v150 offset:53248
	ds_read_b128 v[214:217], v150 offset:54272
	ds_read_b128 v[218:221], v150 offset:55296
	ds_read_b128 v[222:225], v150 offset:56320
	global_load_lds_dwordx4 v[144:145], off
	s_add_i32 m0, s19, 0x2000
	s_add_u32 s34, s34, 0x80080
	v_lshl_add_u64 v[144:145], v[202:203], 0, s[10:11]
	s_addc_u32 s35, s35, 0
	s_add_i32 s19, s38, s33
	global_load_lds_dwordx4 v[144:145], off
	v_lshl_add_u64 v[144:145], s[34:35], 0, v[132:133]
	s_mov_b32 m0, s19
	s_nop 0
	global_load_lds_dwordx4 v[144:145], off
	v_lshl_add_u64 v[144:145], s[34:35], 0, v[136:137]
	s_add_i32 m0, s19, 0x2000
	s_nop 0
	global_load_lds_dwordx4 v[144:145], off
	v_lshl_add_u64 v[144:145], v[206:207], 0, s[10:11]
	s_mov_b32 m0, s51
	s_nop 0
	global_load_lds_dwordx4 v[144:145], off
	v_lshl_add_u64 v[144:145], v[226:227], 0, s[10:11]
	s_mov_b32 m0, s52
	s_nop 0
	global_load_lds_dwordx4 v[144:145], off
	s_waitcnt vmcnt(8)
	s_waitcnt lgkmcnt(0)
	s_barrier
	s_setprio 1
	s_waitcnt lgkmcnt(0)
	v_mfma_f32_16x16x32_bf16 v[62:65], v[152:155], v[184:187], v[62:65]
	v_mfma_f32_16x16x32_bf16 v[58:61], v[160:163], v[184:187], v[58:61]
	v_mfma_f32_16x16x32_bf16 v[46:49], v[152:155], v[192:195], v[46:49]
	v_mfma_f32_16x16x32_bf16 v[42:45], v[160:163], v[192:195], v[42:45]
	v_mfma_f32_16x16x32_bf16 v[30:33], v[152:155], v[210:213], v[30:33]
	v_mfma_f32_16x16x32_bf16 v[26:29], v[160:163], v[210:213], v[26:29]
	v_mfma_f32_16x16x32_bf16 v[14:17], v[152:155], v[218:221], v[14:17]
	v_mfma_f32_16x16x32_bf16 v[10:13], v[160:163], v[218:221], v[10:13]
	v_mfma_f32_16x16x32_bf16 v[62:65], v[156:159], v[188:191], v[62:65]
	v_mfma_f32_16x16x32_bf16 v[58:61], v[164:167], v[188:191], v[58:61]
	v_mfma_f32_16x16x32_bf16 v[46:49], v[156:159], v[198:201], v[46:49]
	v_mfma_f32_16x16x32_bf16 v[42:45], v[164:167], v[198:201], v[42:45]
	v_mfma_f32_16x16x32_bf16 v[30:33], v[156:159], v[214:217], v[30:33]
	v_mfma_f32_16x16x32_bf16 v[26:29], v[164:167], v[214:217], v[26:29]
	v_mfma_f32_16x16x32_bf16 v[14:17], v[156:159], v[222:225], v[14:17]
	v_mfma_f32_16x16x32_bf16 v[10:13], v[164:167], v[222:225], v[10:13]
	v_mfma_f32_16x16x32_bf16 v[54:57], v[168:171], v[184:187], v[54:57]
	v_mfma_f32_16x16x32_bf16 v[50:53], v[176:179], v[184:187], v[50:53]
	v_mfma_f32_16x16x32_bf16 v[38:41], v[168:171], v[192:195], v[38:41]
	v_mfma_f32_16x16x32_bf16 v[34:37], v[176:179], v[192:195], v[34:37]
	v_mfma_f32_16x16x32_bf16 v[22:25], v[168:171], v[210:213], v[22:25]
	v_mfma_f32_16x16x32_bf16 v[18:21], v[176:179], v[210:213], v[18:21]
	v_mfma_f32_16x16x32_bf16 v[6:9], v[168:171], v[218:221], v[6:9]
	v_mfma_f32_16x16x32_bf16 v[2:5], v[176:179], v[218:221], v[2:5]
	v_mfma_f32_16x16x32_bf16 v[54:57], v[172:175], v[188:191], v[54:57]
	v_mfma_f32_16x16x32_bf16 v[50:53], v[180:183], v[188:191], v[50:53]
	v_mfma_f32_16x16x32_bf16 v[38:41], v[172:175], v[198:201], v[38:41]
	v_mfma_f32_16x16x32_bf16 v[34:37], v[180:183], v[198:201], v[34:37]
	v_mfma_f32_16x16x32_bf16 v[22:25], v[172:175], v[214:217], v[22:25]
	v_mfma_f32_16x16x32_bf16 v[18:21], v[180:183], v[214:217], v[18:21]
	v_mfma_f32_16x16x32_bf16 v[6:9], v[172:175], v[222:225], v[6:9]
	v_mfma_f32_16x16x32_bf16 v[2:5], v[180:183], v[222:225], v[2:5]
	s_setprio 2
	s_barrier
	s_add_u32 s30, s30, 0x100
	s_addc_u32 s31, s31, 0
	s_add_u32 s15, s15, 0x100
	s_addc_u32 s17, s17, 0
	s_cmp_ge_i32 s29, s68
	s_mov_b32 s19, s29
	s_cbranch_scc0 .LBB0_2547
	s_branch .Lpeeldone_1
.LBB0_2547:
	ds_read_b128 v[152:155], v148
	ds_read_b128 v[156:159], v148 offset:1024
	ds_read_b128 v[160:163], v148 offset:2048
	ds_read_b128 v[164:167], v148 offset:3072
	ds_read_b128 v[168:171], v149
	ds_read_b128 v[172:175], v149 offset:1024
	ds_read_b128 v[176:179], v149 offset:2048
	ds_read_b128 v[180:183], v149 offset:3072
	s_add_i32 s29, s19, 2
	s_add_u32 s34, s30, 0xfff80080
	s_addc_u32 s35, s31, -1
	s_cmp_eq_u32 s28, s19
	s_cselect_b32 s37, s21, s35
	s_cselect_b32 s36, s20, s34
	s_cselect_b32 s35, s23, s17
	s_cselect_b32 s34, s22, s15
	v_lshl_add_u64 v[144:145], s[30:31], 0, v[140:141]
	s_add_i32 m0, s27, 0xc000
	ds_read_b128 v[184:187], v150
	ds_read_b128 v[188:191], v150 offset:1024
	ds_read_b128 v[192:195], v150 offset:2048
	ds_read_b128 v[198:201], v150 offset:3072
	ds_read_b128 v[210:213], v150 offset:4096
	ds_read_b128 v[214:217], v150 offset:5120
	ds_read_b128 v[218:221], v150 offset:6144
	ds_read_b128 v[222:225], v150 offset:7168
	global_load_lds_dwordx4 v[144:145], off
	v_lshl_add_u64 v[144:145], s[30:31], 0, v[142:143]
	s_add_i32 m0, s27, 0xe000
	s_nop 0
	global_load_lds_dwordx4 v[144:145], off
	s_waitcnt vmcnt(8)
	s_waitcnt lgkmcnt(0)
	s_barrier
	s_setprio 1
	s_waitcnt lgkmcnt(0)
	v_mfma_f32_16x16x32_bf16 v[126:129], v[152:155], v[184:187], v[126:129]
	v_mfma_f32_16x16x32_bf16 v[122:125], v[160:163], v[184:187], v[122:125]
	v_mfma_f32_16x16x32_bf16 v[110:113], v[152:155], v[192:195], v[110:113]
	v_mfma_f32_16x16x32_bf16 v[106:109], v[160:163], v[192:195], v[106:109]
	v_mfma_f32_16x16x32_bf16 v[94:97], v[152:155], v[210:213], v[94:97]
	v_mfma_f32_16x16x32_bf16 v[90:93], v[160:163], v[210:213], v[90:93]
	v_mfma_f32_16x16x32_bf16 v[78:81], v[152:155], v[218:221], v[78:81]
	v_mfma_f32_16x16x32_bf16 v[74:77], v[160:163], v[218:221], v[74:77]
	v_mfma_f32_16x16x32_bf16 v[126:129], v[156:159], v[188:191], v[126:129]
	v_mfma_f32_16x16x32_bf16 v[122:125], v[164:167], v[188:191], v[122:125]
	v_mfma_f32_16x16x32_bf16 v[110:113], v[156:159], v[198:201], v[110:113]
	v_mfma_f32_16x16x32_bf16 v[106:109], v[164:167], v[198:201], v[106:109]
	v_mfma_f32_16x16x32_bf16 v[94:97], v[156:159], v[214:217], v[94:97]
	v_mfma_f32_16x16x32_bf16 v[90:93], v[164:167], v[214:217], v[90:93]
	v_mfma_f32_16x16x32_bf16 v[78:81], v[156:159], v[222:225], v[78:81]
	v_mfma_f32_16x16x32_bf16 v[74:77], v[164:167], v[222:225], v[74:77]
	v_mfma_f32_16x16x32_bf16 v[118:121], v[168:171], v[184:187], v[118:121]
	v_mfma_f32_16x16x32_bf16 v[114:117], v[176:179], v[184:187], v[114:117]
	v_mfma_f32_16x16x32_bf16 v[102:105], v[168:171], v[192:195], v[102:105]
	v_mfma_f32_16x16x32_bf16 v[98:101], v[176:179], v[192:195], v[98:101]
	v_mfma_f32_16x16x32_bf16 v[86:89], v[168:171], v[210:213], v[86:89]
	v_mfma_f32_16x16x32_bf16 v[82:85], v[176:179], v[210:213], v[82:85]
	v_mfma_f32_16x16x32_bf16 v[70:73], v[168:171], v[218:221], v[70:73]
	v_mfma_f32_16x16x32_bf16 v[66:69], v[176:179], v[218:221], v[66:69]
	v_mfma_f32_16x16x32_bf16 v[118:121], v[172:175], v[188:191], v[118:121]
	v_mfma_f32_16x16x32_bf16 v[114:117], v[180:183], v[188:191], v[114:117]
	v_mfma_f32_16x16x32_bf16 v[102:105], v[172:175], v[198:201], v[102:105]
	v_mfma_f32_16x16x32_bf16 v[98:101], v[180:183], v[198:201], v[98:101]
	v_mfma_f32_16x16x32_bf16 v[86:89], v[172:175], v[214:217], v[86:89]
	v_mfma_f32_16x16x32_bf16 v[82:85], v[180:183], v[214:217], v[82:85]
	v_mfma_f32_16x16x32_bf16 v[70:73], v[172:175], v[222:225], v[70:73]
	v_mfma_f32_16x16x32_bf16 v[66:69], v[180:183], v[222:225], v[66:69]
	s_setprio 2
	s_barrier
	s_add_i32 s19, s60, s33
	v_lshl_add_u64 v[144:145], s[34:35], 0, v[132:133]
	s_mov_b32 m0, s19
	ds_read_b128 v[184:187], v150 offset:16384
	ds_read_b128 v[188:191], v150 offset:17408
	ds_read_b128 v[192:195], v150 offset:18432
	ds_read_b128 v[198:201], v150 offset:19456
	ds_read_b128 v[210:213], v150 offset:20480
	ds_read_b128 v[214:217], v150 offset:21504
	ds_read_b128 v[218:221], v150 offset:22528
	ds_read_b128 v[222:225], v150 offset:23552
	global_load_lds_dwordx4 v[144:145], off
	s_add_i32 m0, s19, 0x2000
	s_add_u32 s38, s34, 0x80000
	v_lshl_add_u64 v[202:203], s[34:35], 0, v[136:137]
	s_addc_u32 s39, s35, 0
	s_add_i32 s19, s61, s33
	global_load_lds_dwordx4 v[202:203], off
	v_lshl_add_u64 v[206:207], s[38:39], 0, v[132:133]
	s_mov_b32 m0, s19
	v_lshl_add_u64 v[226:227], s[36:37], 0, v[134:135]
	global_load_lds_dwordx4 v[206:207], off
	v_lshl_add_u64 v[206:207], s[38:39], 0, v[136:137]
	s_add_i32 m0, s19, 0x2000
	s_nop 0
	global_load_lds_dwordx4 v[206:207], off
	v_lshl_add_u64 v[206:207], s[36:37], 0, v[130:131]
	s_mov_b32 m0, s27
	s_nop 0
	global_load_lds_dwordx4 v[206:207], off
	s_mov_b32 m0, s41
	s_nop 0
	global_load_lds_dwordx4 v[226:227], off
	s_waitcnt vmcnt(8)
	s_waitcnt lgkmcnt(0)
	s_barrier
	s_setprio 1
	s_waitcnt lgkmcnt(0)
	v_mfma_f32_16x16x32_bf16 v[62:65], v[152:155], v[184:187], v[62:65]
	v_mfma_f32_16x16x32_bf16 v[58:61], v[160:163], v[184:187], v[58:61]
	v_mfma_f32_16x16x32_bf16 v[46:49], v[152:155], v[192:195], v[46:49]
	v_mfma_f32_16x16x32_bf16 v[42:45], v[160:163], v[192:195], v[42:45]
	v_mfma_f32_16x16x32_bf16 v[30:33], v[152:155], v[210:213], v[30:33]
	v_mfma_f32_16x16x32_bf16 v[26:29], v[160:163], v[210:213], v[26:29]
	v_mfma_f32_16x16x32_bf16 v[14:17], v[152:155], v[218:221], v[14:17]
	v_mfma_f32_16x16x32_bf16 v[10:13], v[160:163], v[218:221], v[10:13]
	v_mfma_f32_16x16x32_bf16 v[62:65], v[156:159], v[188:191], v[62:65]
	v_mfma_f32_16x16x32_bf16 v[58:61], v[164:167], v[188:191], v[58:61]
	v_mfma_f32_16x16x32_bf16 v[46:49], v[156:159], v[198:201], v[46:49]
	v_mfma_f32_16x16x32_bf16 v[42:45], v[164:167], v[198:201], v[42:45]
	v_mfma_f32_16x16x32_bf16 v[30:33], v[156:159], v[214:217], v[30:33]
	v_mfma_f32_16x16x32_bf16 v[26:29], v[164:167], v[214:217], v[26:29]
	v_mfma_f32_16x16x32_bf16 v[14:17], v[156:159], v[222:225], v[14:17]
	v_mfma_f32_16x16x32_bf16 v[10:13], v[164:167], v[222:225], v[10:13]
	v_mfma_f32_16x16x32_bf16 v[54:57], v[168:171], v[184:187], v[54:57]
	v_mfma_f32_16x16x32_bf16 v[50:53], v[176:179], v[184:187], v[50:53]
	v_mfma_f32_16x16x32_bf16 v[38:41], v[168:171], v[192:195], v[38:41]
	v_mfma_f32_16x16x32_bf16 v[34:37], v[176:179], v[192:195], v[34:37]
	v_mfma_f32_16x16x32_bf16 v[22:25], v[168:171], v[210:213], v[22:25]
	v_mfma_f32_16x16x32_bf16 v[18:21], v[176:179], v[210:213], v[18:21]
	v_mfma_f32_16x16x32_bf16 v[6:9], v[168:171], v[218:221], v[6:9]
	v_mfma_f32_16x16x32_bf16 v[2:5], v[176:179], v[218:221], v[2:5]
	v_mfma_f32_16x16x32_bf16 v[54:57], v[172:175], v[188:191], v[54:57]
	v_mfma_f32_16x16x32_bf16 v[50:53], v[180:183], v[188:191], v[50:53]
	v_mfma_f32_16x16x32_bf16 v[38:41], v[172:175], v[198:201], v[38:41]
	v_mfma_f32_16x16x32_bf16 v[34:37], v[180:183], v[198:201], v[34:37]
	v_mfma_f32_16x16x32_bf16 v[22:25], v[172:175], v[214:217], v[22:25]
	v_mfma_f32_16x16x32_bf16 v[18:21], v[180:183], v[214:217], v[18:21]
	v_mfma_f32_16x16x32_bf16 v[6:9], v[172:175], v[222:225], v[6:9]
	v_mfma_f32_16x16x32_bf16 v[2:5], v[180:183], v[222:225], v[2:5]
	s_setprio 2
	s_barrier
	s_add_i32 s19, 0, 0x18000
	v_add_u32_e32 v151, s19, v146
	s_add_i32 s38, 0, 0x1c000
	ds_read_b128 v[152:155], v151
	ds_read_b128 v[156:159], v151 offset:1024
	ds_read_b128 v[160:163], v151 offset:2048
	ds_read_b128 v[164:167], v151 offset:3072
	v_add_u32_e32 v151, s38, v146
	ds_read_b128 v[168:171], v151
	ds_read_b128 v[172:175], v151 offset:1024
	ds_read_b128 v[176:179], v151 offset:2048
	ds_read_b128 v[180:183], v151 offset:3072
	s_add_u32 s36, s36, 0x80000
	s_addc_u32 s37, s37, 0
	s_mov_b32 m0, s42
	v_lshl_add_u64 v[228:229], s[36:37], 0, v[130:131]
	ds_read_b128 v[184:187], v150 offset:32768
	ds_read_b128 v[188:191], v150 offset:33792
	ds_read_b128 v[192:195], v150 offset:34816
	ds_read_b128 v[198:201], v150 offset:35840
	ds_read_b128 v[210:213], v150 offset:36864
	ds_read_b128 v[214:217], v150 offset:37888
	ds_read_b128 v[218:221], v150 offset:38912
	ds_read_b128 v[222:225], v150 offset:39936
	global_load_lds_dwordx4 v[228:229], off
	v_lshl_add_u64 v[228:229], s[36:37], 0, v[134:135]
	s_mov_b32 m0, s43
	s_nop 0
	global_load_lds_dwordx4 v[228:229], off
	s_waitcnt vmcnt(8)
	s_waitcnt lgkmcnt(0)
	s_barrier
	s_setprio 1
	s_waitcnt lgkmcnt(0)
	v_mfma_f32_16x16x32_bf16 v[126:129], v[152:155], v[184:187], v[126:129]
	v_mfma_f32_16x16x32_bf16 v[122:125], v[160:163], v[184:187], v[122:125]
	v_mfma_f32_16x16x32_bf16 v[110:113], v[152:155], v[192:195], v[110:113]
	v_mfma_f32_16x16x32_bf16 v[106:109], v[160:163], v[192:195], v[106:109]
	v_mfma_f32_16x16x32_bf16 v[94:97], v[152:155], v[210:213], v[94:97]
	v_mfma_f32_16x16x32_bf16 v[90:93], v[160:163], v[210:213], v[90:93]
	v_mfma_f32_16x16x32_bf16 v[78:81], v[152:155], v[218:221], v[78:81]
	v_mfma_f32_16x16x32_bf16 v[74:77], v[160:163], v[218:221], v[74:77]
	v_mfma_f32_16x16x32_bf16 v[126:129], v[156:159], v[188:191], v[126:129]
	v_mfma_f32_16x16x32_bf16 v[122:125], v[164:167], v[188:191], v[122:125]
	v_mfma_f32_16x16x32_bf16 v[110:113], v[156:159], v[198:201], v[110:113]
	v_mfma_f32_16x16x32_bf16 v[106:109], v[164:167], v[198:201], v[106:109]
	v_mfma_f32_16x16x32_bf16 v[94:97], v[156:159], v[214:217], v[94:97]
	v_mfma_f32_16x16x32_bf16 v[90:93], v[164:167], v[214:217], v[90:93]
	v_mfma_f32_16x16x32_bf16 v[78:81], v[156:159], v[222:225], v[78:81]
	v_mfma_f32_16x16x32_bf16 v[74:77], v[164:167], v[222:225], v[74:77]
	v_mfma_f32_16x16x32_bf16 v[118:121], v[168:171], v[184:187], v[118:121]
	v_mfma_f32_16x16x32_bf16 v[114:117], v[176:179], v[184:187], v[114:117]
	v_mfma_f32_16x16x32_bf16 v[102:105], v[168:171], v[192:195], v[102:105]
	v_mfma_f32_16x16x32_bf16 v[98:101], v[176:179], v[192:195], v[98:101]
	v_mfma_f32_16x16x32_bf16 v[86:89], v[168:171], v[210:213], v[86:89]
	v_mfma_f32_16x16x32_bf16 v[82:85], v[176:179], v[210:213], v[82:85]
	v_mfma_f32_16x16x32_bf16 v[70:73], v[168:171], v[218:221], v[70:73]
	v_mfma_f32_16x16x32_bf16 v[66:69], v[176:179], v[218:221], v[66:69]
	v_mfma_f32_16x16x32_bf16 v[118:121], v[172:175], v[188:191], v[118:121]
	v_mfma_f32_16x16x32_bf16 v[114:117], v[180:183], v[188:191], v[114:117]
	v_mfma_f32_16x16x32_bf16 v[102:105], v[172:175], v[198:201], v[102:105]
	v_mfma_f32_16x16x32_bf16 v[98:101], v[180:183], v[198:201], v[98:101]
	v_mfma_f32_16x16x32_bf16 v[86:89], v[172:175], v[214:217], v[86:89]
	v_mfma_f32_16x16x32_bf16 v[82:85], v[180:183], v[214:217], v[82:85]
	v_mfma_f32_16x16x32_bf16 v[70:73], v[172:175], v[222:225], v[70:73]
	v_mfma_f32_16x16x32_bf16 v[66:69], v[180:183], v[222:225], v[66:69]
	s_setprio 2
	s_barrier
	s_add_i32 s19, s19, s33
	v_lshl_add_u64 v[144:145], v[144:145], 0, s[10:11]
	s_mov_b32 m0, s19
	ds_read_b128 v[184:187], v150 offset:49152
	ds_read_b128 v[188:191], v150 offset:50176
	ds_read_b128 v[192:195], v150 offset:51200
	ds_read_b128 v[198:201], v150 offset:52224
	ds_read_b128 v[210:213], v150 offset:53248
	ds_read_b128 v[214:217], v150 offset:54272
	ds_read_b128 v[218:221], v150 offset:55296
	ds_read_b128 v[222:225], v150 offset:56320
	global_load_lds_dwordx4 v[144:145], off
	s_add_i32 m0, s19, 0x2000
	s_add_u32 s34, s34, 0x80080
	v_lshl_add_u64 v[144:145], v[202:203], 0, s[10:11]
	s_addc_u32 s35, s35, 0
	s_add_i32 s19, s38, s33
	global_load_lds_dwordx4 v[144:145], off
	v_lshl_add_u64 v[144:145], s[34:35], 0, v[132:133]
	s_mov_b32 m0, s19
	s_nop 0
	global_load_lds_dwordx4 v[144:145], off
	v_lshl_add_u64 v[144:145], s[34:35], 0, v[136:137]
	s_add_i32 m0, s19, 0x2000
	s_nop 0
	global_load_lds_dwordx4 v[144:145], off
	v_lshl_add_u64 v[144:145], v[206:207], 0, s[10:11]
	s_mov_b32 m0, s51
	s_nop 0
	global_load_lds_dwordx4 v[144:145], off
	v_lshl_add_u64 v[144:145], v[226:227], 0, s[10:11]
	s_mov_b32 m0, s52
	s_nop 0
	global_load_lds_dwordx4 v[144:145], off
	s_waitcnt vmcnt(8)
	s_waitcnt lgkmcnt(0)
	s_barrier
	s_setprio 1
	s_waitcnt lgkmcnt(0)
	v_mfma_f32_16x16x32_bf16 v[62:65], v[152:155], v[184:187], v[62:65]
	v_mfma_f32_16x16x32_bf16 v[58:61], v[160:163], v[184:187], v[58:61]
	v_mfma_f32_16x16x32_bf16 v[46:49], v[152:155], v[192:195], v[46:49]
	v_mfma_f32_16x16x32_bf16 v[42:45], v[160:163], v[192:195], v[42:45]
	v_mfma_f32_16x16x32_bf16 v[30:33], v[152:155], v[210:213], v[30:33]
	v_mfma_f32_16x16x32_bf16 v[26:29], v[160:163], v[210:213], v[26:29]
	v_mfma_f32_16x16x32_bf16 v[14:17], v[152:155], v[218:221], v[14:17]
	v_mfma_f32_16x16x32_bf16 v[10:13], v[160:163], v[218:221], v[10:13]
	v_mfma_f32_16x16x32_bf16 v[62:65], v[156:159], v[188:191], v[62:65]
	v_mfma_f32_16x16x32_bf16 v[58:61], v[164:167], v[188:191], v[58:61]
	v_mfma_f32_16x16x32_bf16 v[46:49], v[156:159], v[198:201], v[46:49]
	v_mfma_f32_16x16x32_bf16 v[42:45], v[164:167], v[198:201], v[42:45]
	v_mfma_f32_16x16x32_bf16 v[30:33], v[156:159], v[214:217], v[30:33]
	v_mfma_f32_16x16x32_bf16 v[26:29], v[164:167], v[214:217], v[26:29]
	v_mfma_f32_16x16x32_bf16 v[14:17], v[156:159], v[222:225], v[14:17]
	v_mfma_f32_16x16x32_bf16 v[10:13], v[164:167], v[222:225], v[10:13]
	v_mfma_f32_16x16x32_bf16 v[54:57], v[168:171], v[184:187], v[54:57]
	v_mfma_f32_16x16x32_bf16 v[50:53], v[176:179], v[184:187], v[50:53]
	v_mfma_f32_16x16x32_bf16 v[38:41], v[168:171], v[192:195], v[38:41]
	v_mfma_f32_16x16x32_bf16 v[34:37], v[176:179], v[192:195], v[34:37]
	v_mfma_f32_16x16x32_bf16 v[22:25], v[168:171], v[210:213], v[22:25]
	v_mfma_f32_16x16x32_bf16 v[18:21], v[176:179], v[210:213], v[18:21]
	v_mfma_f32_16x16x32_bf16 v[6:9], v[168:171], v[218:221], v[6:9]
	v_mfma_f32_16x16x32_bf16 v[2:5], v[176:179], v[218:221], v[2:5]
	v_mfma_f32_16x16x32_bf16 v[54:57], v[172:175], v[188:191], v[54:57]
	v_mfma_f32_16x16x32_bf16 v[50:53], v[180:183], v[188:191], v[50:53]
	v_mfma_f32_16x16x32_bf16 v[38:41], v[172:175], v[198:201], v[38:41]
	v_mfma_f32_16x16x32_bf16 v[34:37], v[180:183], v[198:201], v[34:37]
	v_mfma_f32_16x16x32_bf16 v[22:25], v[172:175], v[214:217], v[22:25]
	v_mfma_f32_16x16x32_bf16 v[18:21], v[180:183], v[214:217], v[18:21]
	v_mfma_f32_16x16x32_bf16 v[6:9], v[172:175], v[222:225], v[6:9]
	v_mfma_f32_16x16x32_bf16 v[2:5], v[180:183], v[222:225], v[2:5]
	s_setprio 2
	s_barrier
	s_add_u32 s30, s30, 0x100
	s_addc_u32 s31, s31, 0
	s_add_u32 s15, s15, 0x100
	s_addc_u32 s17, s17, 0
	s_cmp_ge_i32 s29, s68
	s_mov_b32 s19, s29
	s_cbranch_scc0 .LBB0_2547

.Lpeel_0:
	ds_read_b128 v[144:147], v170
	ds_read_b128 v[148:151], v170 offset:1024
	ds_read_b128 v[152:155], v170 offset:2048
	ds_read_b128 v[156:159], v170 offset:3072
	ds_read_b128 v[160:163], v171
	ds_read_b128 v[164:167], v171 offset:1024
	ds_read_b128 v[174:177], v171 offset:2048
	ds_read_b128 v[178:181], v171 offset:3072
	s_add_i32 s30, s26, 2
	s_add_u32 s27, s24, 0xffea0080
	s_addc_u32 s28, s25, -1
	s_cmp_eq_u32 s22, s26
	s_cselect_b32 s26, s20, s17
	s_cselect_b32 s29, s19, s28
	s_cselect_b32 s28, s18, s27
	s_cselect_b32 s27, s21, s23
	v_lshl_add_u64 v[214:215], s[24:25], 0, v[140:141]
	s_add_i32 m0, s34, 0xc000
	ds_read_b128 v[182:185], v172
	ds_read_b128 v[186:189], v172 offset:1024
	ds_read_b128 v[190:193], v172 offset:2048
	ds_read_b128 v[194:197], v172 offset:3072
	ds_read_b128 v[198:201], v172 offset:4096
	ds_read_b128 v[202:205], v172 offset:5120
	ds_read_b128 v[206:209], v172 offset:6144
	ds_read_b128 v[210:213], v172 offset:7168
	global_load_lds_dwordx4 v[214:215], off
	v_lshl_add_u64 v[214:215], s[24:25], 0, v[142:143]
	s_add_i32 m0, s34, 0xe000
	s_nop 0
	global_load_lds_dwordx4 v[214:215], off
	s_waitcnt vmcnt(8)
	s_waitcnt lgkmcnt(0)
	s_barrier
	s_setprio 1
	s_waitcnt lgkmcnt(0)
	v_mfma_f32_16x16x32_bf16 v[126:129], v[144:147], v[182:185], 0
	v_mfma_f32_16x16x32_bf16 v[122:125], v[152:155], v[182:185], 0
	v_mfma_f32_16x16x32_bf16 v[118:121], v[144:147], v[190:193], 0
	v_mfma_f32_16x16x32_bf16 v[110:113], v[152:155], v[190:193], 0
	v_mfma_f32_16x16x32_bf16 v[94:97], v[144:147], v[198:201], 0
	v_mfma_f32_16x16x32_bf16 v[90:93], v[152:155], v[198:201], 0
	v_mfma_f32_16x16x32_bf16 v[82:85], v[144:147], v[206:209], 0
	v_mfma_f32_16x16x32_bf16 v[74:77], v[152:155], v[206:209], 0
	v_mfma_f32_16x16x32_bf16 v[126:129], v[148:151], v[186:189], v[126:129]
	v_mfma_f32_16x16x32_bf16 v[122:125], v[156:159], v[186:189], v[122:125]
	v_mfma_f32_16x16x32_bf16 v[118:121], v[148:151], v[194:197], v[118:121]
	v_mfma_f32_16x16x32_bf16 v[110:113], v[156:159], v[194:197], v[110:113]
	v_mfma_f32_16x16x32_bf16 v[94:97], v[148:151], v[202:205], v[94:97]
	v_mfma_f32_16x16x32_bf16 v[90:93], v[156:159], v[202:205], v[90:93]
	v_mfma_f32_16x16x32_bf16 v[82:85], v[148:151], v[210:213], v[82:85]
	v_mfma_f32_16x16x32_bf16 v[74:77], v[156:159], v[210:213], v[74:77]
	v_mfma_f32_16x16x32_bf16 v[114:117], v[160:163], v[182:185], 0
	v_mfma_f32_16x16x32_bf16 v[106:109], v[174:177], v[182:185], 0
	v_mfma_f32_16x16x32_bf16 v[102:105], v[160:163], v[190:193], 0
	v_mfma_f32_16x16x32_bf16 v[98:101], v[174:177], v[190:193], 0
	v_mfma_f32_16x16x32_bf16 v[86:89], v[160:163], v[198:201], 0
	v_mfma_f32_16x16x32_bf16 v[78:81], v[174:177], v[198:201], 0
	v_mfma_f32_16x16x32_bf16 v[70:73], v[160:163], v[206:209], 0
	v_mfma_f32_16x16x32_bf16 v[66:69], v[174:177], v[206:209], 0
	v_mfma_f32_16x16x32_bf16 v[114:117], v[164:167], v[186:189], v[114:117]
	v_mfma_f32_16x16x32_bf16 v[106:109], v[178:181], v[186:189], v[106:109]
	v_mfma_f32_16x16x32_bf16 v[102:105], v[164:167], v[194:197], v[102:105]
	v_mfma_f32_16x16x32_bf16 v[98:101], v[178:181], v[194:197], v[98:101]
	v_mfma_f32_16x16x32_bf16 v[86:89], v[164:167], v[202:205], v[86:89]
	v_mfma_f32_16x16x32_bf16 v[78:81], v[178:181], v[202:205], v[78:81]
	v_mfma_f32_16x16x32_bf16 v[70:73], v[164:167], v[210:213], v[70:73]
	v_mfma_f32_16x16x32_bf16 v[66:69], v[178:181], v[210:213], v[66:69]
	s_setprio 2
	s_barrier
	s_add_i32 s31, s57, s33
	v_lshl_add_u64 v[214:215], s[26:27], 0, v[132:133]
	s_mov_b32 m0, s31
	ds_read_b128 v[182:185], v172 offset:16384
	ds_read_b128 v[186:189], v172 offset:17408
	ds_read_b128 v[190:193], v172 offset:18432
	ds_read_b128 v[194:197], v172 offset:19456
	ds_read_b128 v[198:201], v172 offset:20480
	ds_read_b128 v[202:205], v172 offset:21504
	ds_read_b128 v[206:209], v172 offset:22528
	ds_read_b128 v[210:213], v172 offset:23552
	global_load_lds_dwordx4 v[214:215], off
	s_add_i32 m0, s31, 0x2000
	s_add_u32 s68, s26, 0x160000
	v_lshl_add_u64 v[216:217], s[26:27], 0, v[136:137]
	s_addc_u32 s69, s27, 0
	s_add_i32 s31, s58, s33
	global_load_lds_dwordx4 v[216:217], off
	v_lshl_add_u64 v[218:219], s[68:69], 0, v[132:133]
	s_mov_b32 m0, s31
	v_lshl_add_u64 v[220:221], s[28:29], 0, v[134:135]
	global_load_lds_dwordx4 v[218:219], off
	v_lshl_add_u64 v[218:219], s[68:69], 0, v[136:137]
	s_add_i32 m0, s31, 0x2000
	s_nop 0
	global_load_lds_dwordx4 v[218:219], off
	v_lshl_add_u64 v[218:219], s[28:29], 0, v[130:131]
	s_mov_b32 m0, s34
	s_nop 0
	global_load_lds_dwordx4 v[218:219], off
	s_mov_b32 m0, s35
	s_nop 0
	global_load_lds_dwordx4 v[220:221], off
	s_waitcnt vmcnt(8)
	s_waitcnt lgkmcnt(0)
	s_barrier
	s_setprio 1
	s_waitcnt lgkmcnt(0)
	v_mfma_f32_16x16x32_bf16 v[62:65], v[144:147], v[182:185], 0
	v_mfma_f32_16x16x32_bf16 v[58:61], v[152:155], v[182:185], 0
	v_mfma_f32_16x16x32_bf16 v[50:53], v[144:147], v[190:193], 0
	v_mfma_f32_16x16x32_bf16 v[42:45], v[152:155], v[190:193], 0
	v_mfma_f32_16x16x32_bf16 v[30:33], v[144:147], v[198:201], 0
	v_mfma_f32_16x16x32_bf16 v[26:29], v[152:155], v[198:201], 0
	v_mfma_f32_16x16x32_bf16 v[18:21], v[144:147], v[206:209], 0
	v_mfma_f32_16x16x32_bf16 v[10:13], v[152:155], v[206:209], 0
	v_mfma_f32_16x16x32_bf16 v[62:65], v[148:151], v[186:189], v[62:65]
	v_mfma_f32_16x16x32_bf16 v[58:61], v[156:159], v[186:189], v[58:61]
	v_mfma_f32_16x16x32_bf16 v[50:53], v[148:151], v[194:197], v[50:53]
	v_mfma_f32_16x16x32_bf16 v[42:45], v[156:159], v[194:197], v[42:45]
	v_mfma_f32_16x16x32_bf16 v[30:33], v[148:151], v[202:205], v[30:33]
	v_mfma_f32_16x16x32_bf16 v[26:29], v[156:159], v[202:205], v[26:29]
	v_mfma_f32_16x16x32_bf16 v[18:21], v[148:151], v[210:213], v[18:21]
	v_mfma_f32_16x16x32_bf16 v[10:13], v[156:159], v[210:213], v[10:13]
	v_mfma_f32_16x16x32_bf16 v[54:57], v[160:163], v[182:185], 0
	v_mfma_f32_16x16x32_bf16 v[46:49], v[174:177], v[182:185], 0
	v_mfma_f32_16x16x32_bf16 v[38:41], v[160:163], v[190:193], 0
	v_mfma_f32_16x16x32_bf16 v[34:37], v[174:177], v[190:193], 0
	v_mfma_f32_16x16x32_bf16 v[22:25], v[160:163], v[198:201], 0
	v_mfma_f32_16x16x32_bf16 v[14:17], v[174:177], v[198:201], 0
	v_mfma_f32_16x16x32_bf16 v[6:9], v[160:163], v[206:209], 0
	v_mfma_f32_16x16x32_bf16 v[2:5], v[174:177], v[206:209], 0
	v_mfma_f32_16x16x32_bf16 v[54:57], v[164:167], v[186:189], v[54:57]
	v_mfma_f32_16x16x32_bf16 v[46:49], v[178:181], v[186:189], v[46:49]
	v_mfma_f32_16x16x32_bf16 v[38:41], v[164:167], v[194:197], v[38:41]
	v_mfma_f32_16x16x32_bf16 v[34:37], v[178:181], v[194:197], v[34:37]
	v_mfma_f32_16x16x32_bf16 v[22:25], v[164:167], v[202:205], v[22:25]
	v_mfma_f32_16x16x32_bf16 v[14:17], v[178:181], v[202:205], v[14:17]
	v_mfma_f32_16x16x32_bf16 v[6:9], v[164:167], v[210:213], v[6:9]
	v_mfma_f32_16x16x32_bf16 v[2:5], v[178:181], v[210:213], v[2:5]
	s_setprio 2
	s_barrier
	s_add_i32 s31, 0, 0x18000
	s_add_i32 s68, 0, 0x1c000
	v_add_u32_e32 v156, s31, v168
	v_add_u32_e32 v173, s68, v168
	ds_read_b128 v[144:147], v156
	ds_read_b128 v[148:151], v156 offset:1024
	ds_read_b128 v[152:155], v156 offset:2048
	ds_read_b128 v[156:159], v156 offset:3072
	ds_read_b128 v[160:163], v173
	ds_read_b128 v[164:167], v173 offset:1024
	ds_read_b128 v[174:177], v173 offset:2048
	ds_read_b128 v[178:181], v173 offset:3072
	s_add_u32 s28, s28, 0x160000
	s_addc_u32 s29, s29, 0
	s_mov_b32 m0, s36
	v_lshl_add_u64 v[222:223], s[28:29], 0, v[130:131]
	ds_read_b128 v[182:185], v172 offset:32768
	ds_read_b128 v[186:189], v172 offset:33792
	ds_read_b128 v[190:193], v172 offset:34816
	ds_read_b128 v[194:197], v172 offset:35840
	ds_read_b128 v[198:201], v172 offset:36864
	ds_read_b128 v[202:205], v172 offset:37888
	ds_read_b128 v[206:209], v172 offset:38912
	ds_read_b128 v[210:213], v172 offset:39936
	global_load_lds_dwordx4 v[222:223], off
	v_lshl_add_u64 v[222:223], s[28:29], 0, v[134:135]
	s_mov_b32 m0, s37
	s_nop 0
	global_load_lds_dwordx4 v[222:223], off
	s_waitcnt vmcnt(8)
	s_waitcnt lgkmcnt(0)
	s_barrier
	s_setprio 1
	s_waitcnt lgkmcnt(0)
	v_mfma_f32_16x16x32_bf16 v[126:129], v[144:147], v[182:185], v[126:129]
	v_mfma_f32_16x16x32_bf16 v[122:125], v[152:155], v[182:185], v[122:125]
	v_mfma_f32_16x16x32_bf16 v[118:121], v[144:147], v[190:193], v[118:121]
	v_mfma_f32_16x16x32_bf16 v[110:113], v[152:155], v[190:193], v[110:113]
	v_mfma_f32_16x16x32_bf16 v[94:97], v[144:147], v[198:201], v[94:97]
	v_mfma_f32_16x16x32_bf16 v[90:93], v[152:155], v[198:201], v[90:93]
	v_mfma_f32_16x16x32_bf16 v[82:85], v[144:147], v[206:209], v[82:85]
	v_mfma_f32_16x16x32_bf16 v[74:77], v[152:155], v[206:209], v[74:77]
	v_mfma_f32_16x16x32_bf16 v[126:129], v[148:151], v[186:189], v[126:129]
	v_mfma_f32_16x16x32_bf16 v[122:125], v[156:159], v[186:189], v[122:125]
	v_mfma_f32_16x16x32_bf16 v[118:121], v[148:151], v[194:197], v[118:121]
	v_mfma_f32_16x16x32_bf16 v[110:113], v[156:159], v[194:197], v[110:113]
	v_mfma_f32_16x16x32_bf16 v[94:97], v[148:151], v[202:205], v[94:97]
	v_mfma_f32_16x16x32_bf16 v[90:93], v[156:159], v[202:205], v[90:93]
	v_mfma_f32_16x16x32_bf16 v[82:85], v[148:151], v[210:213], v[82:85]
	v_mfma_f32_16x16x32_bf16 v[74:77], v[156:159], v[210:213], v[74:77]
	v_mfma_f32_16x16x32_bf16 v[114:117], v[160:163], v[182:185], v[114:117]
	v_mfma_f32_16x16x32_bf16 v[106:109], v[174:177], v[182:185], v[106:109]
	v_mfma_f32_16x16x32_bf16 v[102:105], v[160:163], v[190:193], v[102:105]
	v_mfma_f32_16x16x32_bf16 v[98:101], v[174:177], v[190:193], v[98:101]
	v_mfma_f32_16x16x32_bf16 v[86:89], v[160:163], v[198:201], v[86:89]
	v_mfma_f32_16x16x32_bf16 v[78:81], v[174:177], v[198:201], v[78:81]
	v_mfma_f32_16x16x32_bf16 v[70:73], v[160:163], v[206:209], v[70:73]
	v_mfma_f32_16x16x32_bf16 v[66:69], v[174:177], v[206:209], v[66:69]
	v_mfma_f32_16x16x32_bf16 v[114:117], v[164:167], v[186:189], v[114:117]
	v_mfma_f32_16x16x32_bf16 v[106:109], v[178:181], v[186:189], v[106:109]
	v_mfma_f32_16x16x32_bf16 v[102:105], v[164:167], v[194:197], v[102:105]
	v_mfma_f32_16x16x32_bf16 v[98:101], v[178:181], v[194:197], v[98:101]
	v_mfma_f32_16x16x32_bf16 v[86:89], v[164:167], v[202:205], v[86:89]
	v_mfma_f32_16x16x32_bf16 v[78:81], v[178:181], v[202:205], v[78:81]
	v_mfma_f32_16x16x32_bf16 v[70:73], v[164:167], v[210:213], v[70:73]
	v_mfma_f32_16x16x32_bf16 v[66:69], v[178:181], v[210:213], v[66:69]
	s_setprio 2
	s_barrier
	s_add_i32 s28, s31, s33
	v_lshl_add_u64 v[214:215], v[214:215], 0, s[12:13]
	s_mov_b32 m0, s28
	ds_read_b128 v[182:185], v172 offset:49152
	ds_read_b128 v[186:189], v172 offset:50176
	ds_read_b128 v[190:193], v172 offset:51200
	ds_read_b128 v[194:197], v172 offset:52224
	ds_read_b128 v[198:201], v172 offset:53248
	ds_read_b128 v[202:205], v172 offset:54272
	ds_read_b128 v[206:209], v172 offset:55296
	ds_read_b128 v[210:213], v172 offset:56320
	global_load_lds_dwordx4 v[214:215], off
	s_add_i32 m0, s28, 0x2000
	s_add_u32 s26, s26, 0x160080
	v_lshl_add_u64 v[214:215], v[216:217], 0, s[12:13]
	s_addc_u32 s27, s27, 0
	s_add_i32 s28, s68, s33
	global_load_lds_dwordx4 v[214:215], off
	v_lshl_add_u64 v[214:215], s[26:27], 0, v[132:133]
	s_mov_b32 m0, s28
	s_nop 0
	global_load_lds_dwordx4 v[214:215], off
	v_lshl_add_u64 v[214:215], s[26:27], 0, v[136:137]
	s_add_i32 m0, s28, 0x2000
	s_nop 0
	global_load_lds_dwordx4 v[214:215], off
	v_lshl_add_u64 v[214:215], v[218:219], 0, s[12:13]
	s_mov_b32 m0, s47
	s_nop 0
	global_load_lds_dwordx4 v[214:215], off
	v_lshl_add_u64 v[214:215], v[220:221], 0, s[12:13]
	s_mov_b32 m0, s48
	s_nop 0
	global_load_lds_dwordx4 v[214:215], off
	s_waitcnt vmcnt(8)
	s_waitcnt lgkmcnt(0)
	s_barrier
	s_setprio 1
	s_waitcnt lgkmcnt(0)
	v_mfma_f32_16x16x32_bf16 v[62:65], v[144:147], v[182:185], v[62:65]
	v_mfma_f32_16x16x32_bf16 v[58:61], v[152:155], v[182:185], v[58:61]
	v_mfma_f32_16x16x32_bf16 v[50:53], v[144:147], v[190:193], v[50:53]
	v_mfma_f32_16x16x32_bf16 v[42:45], v[152:155], v[190:193], v[42:45]
	v_mfma_f32_16x16x32_bf16 v[30:33], v[144:147], v[198:201], v[30:33]
	v_mfma_f32_16x16x32_bf16 v[26:29], v[152:155], v[198:201], v[26:29]
	v_mfma_f32_16x16x32_bf16 v[18:21], v[144:147], v[206:209], v[18:21]
	v_mfma_f32_16x16x32_bf16 v[10:13], v[152:155], v[206:209], v[10:13]
	v_mfma_f32_16x16x32_bf16 v[62:65], v[148:151], v[186:189], v[62:65]
	v_mfma_f32_16x16x32_bf16 v[58:61], v[156:159], v[186:189], v[58:61]
	v_mfma_f32_16x16x32_bf16 v[50:53], v[148:151], v[194:197], v[50:53]
	v_mfma_f32_16x16x32_bf16 v[42:45], v[156:159], v[194:197], v[42:45]
	v_mfma_f32_16x16x32_bf16 v[30:33], v[148:151], v[202:205], v[30:33]
	v_mfma_f32_16x16x32_bf16 v[26:29], v[156:159], v[202:205], v[26:29]
	v_mfma_f32_16x16x32_bf16 v[18:21], v[148:151], v[210:213], v[18:21]
	v_mfma_f32_16x16x32_bf16 v[10:13], v[156:159], v[210:213], v[10:13]
	v_mfma_f32_16x16x32_bf16 v[54:57], v[160:163], v[182:185], v[54:57]
	v_mfma_f32_16x16x32_bf16 v[46:49], v[174:177], v[182:185], v[46:49]
	v_mfma_f32_16x16x32_bf16 v[38:41], v[160:163], v[190:193], v[38:41]
	v_mfma_f32_16x16x32_bf16 v[34:37], v[174:177], v[190:193], v[34:37]
	v_mfma_f32_16x16x32_bf16 v[22:25], v[160:163], v[198:201], v[22:25]
	v_mfma_f32_16x16x32_bf16 v[14:17], v[174:177], v[198:201], v[14:17]
	v_mfma_f32_16x16x32_bf16 v[6:9], v[160:163], v[206:209], v[6:9]
	v_mfma_f32_16x16x32_bf16 v[2:5], v[174:177], v[206:209], v[2:5]
	v_mfma_f32_16x16x32_bf16 v[54:57], v[164:167], v[186:189], v[54:57]
	v_mfma_f32_16x16x32_bf16 v[46:49], v[178:181], v[186:189], v[46:49]
	v_mfma_f32_16x16x32_bf16 v[38:41], v[164:167], v[194:197], v[38:41]
	v_mfma_f32_16x16x32_bf16 v[34:37], v[178:181], v[194:197], v[34:37]
	v_mfma_f32_16x16x32_bf16 v[22:25], v[164:167], v[202:205], v[22:25]
	v_mfma_f32_16x16x32_bf16 v[14:17], v[178:181], v[202:205], v[14:17]
	v_mfma_f32_16x16x32_bf16 v[6:9], v[164:167], v[210:213], v[6:9]
	v_mfma_f32_16x16x32_bf16 v[2:5], v[178:181], v[210:213], v[2:5]
	s_setprio 2
	s_barrier
	s_add_u32 s24, s24, 0x100
	s_addc_u32 s25, s25, 0
	s_add_u32 s17, s17, 0x100
	s_addc_u32 s23, s23, 0
	s_cmp_ge_i32 s30, s67
	s_mov_b32 s26, s30
	s_cbranch_scc0 .LBB0_2683
	s_branch .Lpeeldone_0
.LBB0_2683:
	ds_read_b128 v[144:147], v170
	ds_read_b128 v[148:151], v170 offset:1024
	ds_read_b128 v[152:155], v170 offset:2048
	ds_read_b128 v[156:159], v170 offset:3072
	ds_read_b128 v[160:163], v171
	ds_read_b128 v[164:167], v171 offset:1024
	ds_read_b128 v[174:177], v171 offset:2048
	ds_read_b128 v[178:181], v171 offset:3072
	s_add_i32 s30, s26, 2
	s_add_u32 s27, s24, 0xffea0080
	s_addc_u32 s28, s25, -1
	s_cmp_eq_u32 s22, s26
	s_cselect_b32 s26, s20, s17
	s_cselect_b32 s29, s19, s28
	s_cselect_b32 s28, s18, s27
	s_cselect_b32 s27, s21, s23
	v_lshl_add_u64 v[214:215], s[24:25], 0, v[140:141]
	s_add_i32 m0, s34, 0xc000
	ds_read_b128 v[182:185], v172
	ds_read_b128 v[186:189], v172 offset:1024
	ds_read_b128 v[190:193], v172 offset:2048
	ds_read_b128 v[194:197], v172 offset:3072
	ds_read_b128 v[198:201], v172 offset:4096
	ds_read_b128 v[202:205], v172 offset:5120
	ds_read_b128 v[206:209], v172 offset:6144
	ds_read_b128 v[210:213], v172 offset:7168
	global_load_lds_dwordx4 v[214:215], off
	v_lshl_add_u64 v[214:215], s[24:25], 0, v[142:143]
	s_add_i32 m0, s34, 0xe000
	s_nop 0
	global_load_lds_dwordx4 v[214:215], off
	s_waitcnt vmcnt(8)
	s_waitcnt lgkmcnt(0)
	s_barrier
	s_setprio 1
	s_waitcnt lgkmcnt(0)
	v_mfma_f32_16x16x32_bf16 v[126:129], v[144:147], v[182:185], v[126:129]
	v_mfma_f32_16x16x32_bf16 v[122:125], v[152:155], v[182:185], v[122:125]
	v_mfma_f32_16x16x32_bf16 v[118:121], v[144:147], v[190:193], v[118:121]
	v_mfma_f32_16x16x32_bf16 v[110:113], v[152:155], v[190:193], v[110:113]
	v_mfma_f32_16x16x32_bf16 v[94:97], v[144:147], v[198:201], v[94:97]
	v_mfma_f32_16x16x32_bf16 v[90:93], v[152:155], v[198:201], v[90:93]
	v_mfma_f32_16x16x32_bf16 v[82:85], v[144:147], v[206:209], v[82:85]
	v_mfma_f32_16x16x32_bf16 v[74:77], v[152:155], v[206:209], v[74:77]
	v_mfma_f32_16x16x32_bf16 v[126:129], v[148:151], v[186:189], v[126:129]
	v_mfma_f32_16x16x32_bf16 v[122:125], v[156:159], v[186:189], v[122:125]
	v_mfma_f32_16x16x32_bf16 v[118:121], v[148:151], v[194:197], v[118:121]
	v_mfma_f32_16x16x32_bf16 v[110:113], v[156:159], v[194:197], v[110:113]
	v_mfma_f32_16x16x32_bf16 v[94:97], v[148:151], v[202:205], v[94:97]
	v_mfma_f32_16x16x32_bf16 v[90:93], v[156:159], v[202:205], v[90:93]
	v_mfma_f32_16x16x32_bf16 v[82:85], v[148:151], v[210:213], v[82:85]
	v_mfma_f32_16x16x32_bf16 v[74:77], v[156:159], v[210:213], v[74:77]
	v_mfma_f32_16x16x32_bf16 v[114:117], v[160:163], v[182:185], v[114:117]
	v_mfma_f32_16x16x32_bf16 v[106:109], v[174:177], v[182:185], v[106:109]
	v_mfma_f32_16x16x32_bf16 v[102:105], v[160:163], v[190:193], v[102:105]
	v_mfma_f32_16x16x32_bf16 v[98:101], v[174:177], v[190:193], v[98:101]
	v_mfma_f32_16x16x32_bf16 v[86:89], v[160:163], v[198:201], v[86:89]
	v_mfma_f32_16x16x32_bf16 v[78:81], v[174:177], v[198:201], v[78:81]
	v_mfma_f32_16x16x32_bf16 v[70:73], v[160:163], v[206:209], v[70:73]
	v_mfma_f32_16x16x32_bf16 v[66:69], v[174:177], v[206:209], v[66:69]
	v_mfma_f32_16x16x32_bf16 v[114:117], v[164:167], v[186:189], v[114:117]
	v_mfma_f32_16x16x32_bf16 v[106:109], v[178:181], v[186:189], v[106:109]
	v_mfma_f32_16x16x32_bf16 v[102:105], v[164:167], v[194:197], v[102:105]
	v_mfma_f32_16x16x32_bf16 v[98:101], v[178:181], v[194:197], v[98:101]
	v_mfma_f32_16x16x32_bf16 v[86:89], v[164:167], v[202:205], v[86:89]
	v_mfma_f32_16x16x32_bf16 v[78:81], v[178:181], v[202:205], v[78:81]
	v_mfma_f32_16x16x32_bf16 v[70:73], v[164:167], v[210:213], v[70:73]
	v_mfma_f32_16x16x32_bf16 v[66:69], v[178:181], v[210:213], v[66:69]
	s_setprio 2
	s_barrier
	s_add_i32 s31, s57, s33
	v_lshl_add_u64 v[214:215], s[26:27], 0, v[132:133]
	s_mov_b32 m0, s31
	ds_read_b128 v[182:185], v172 offset:16384
	ds_read_b128 v[186:189], v172 offset:17408
	ds_read_b128 v[190:193], v172 offset:18432
	ds_read_b128 v[194:197], v172 offset:19456
	ds_read_b128 v[198:201], v172 offset:20480
	ds_read_b128 v[202:205], v172 offset:21504
	ds_read_b128 v[206:209], v172 offset:22528
	ds_read_b128 v[210:213], v172 offset:23552
	global_load_lds_dwordx4 v[214:215], off
	s_add_i32 m0, s31, 0x2000
	s_add_u32 s68, s26, 0x160000
	v_lshl_add_u64 v[216:217], s[26:27], 0, v[136:137]
	s_addc_u32 s69, s27, 0
	s_add_i32 s31, s58, s33
	global_load_lds_dwordx4 v[216:217], off
	v_lshl_add_u64 v[218:219], s[68:69], 0, v[132:133]
	s_mov_b32 m0, s31
	v_lshl_add_u64 v[220:221], s[28:29], 0, v[134:135]
	global_load_lds_dwordx4 v[218:219], off
	v_lshl_add_u64 v[218:219], s[68:69], 0, v[136:137]
	s_add_i32 m0, s31, 0x2000
	s_nop 0
	global_load_lds_dwordx4 v[218:219], off
	v_lshl_add_u64 v[218:219], s[28:29], 0, v[130:131]
	s_mov_b32 m0, s34
	s_nop 0
	global_load_lds_dwordx4 v[218:219], off
	s_mov_b32 m0, s35
	s_nop 0
	global_load_lds_dwordx4 v[220:221], off
	s_waitcnt vmcnt(8)
	s_waitcnt lgkmcnt(0)
	s_barrier
	s_setprio 1
	s_waitcnt lgkmcnt(0)
	v_mfma_f32_16x16x32_bf16 v[62:65], v[144:147], v[182:185], v[62:65]
	v_mfma_f32_16x16x32_bf16 v[58:61], v[152:155], v[182:185], v[58:61]
	v_mfma_f32_16x16x32_bf16 v[50:53], v[144:147], v[190:193], v[50:53]
	v_mfma_f32_16x16x32_bf16 v[42:45], v[152:155], v[190:193], v[42:45]
	v_mfma_f32_16x16x32_bf16 v[30:33], v[144:147], v[198:201], v[30:33]
	v_mfma_f32_16x16x32_bf16 v[26:29], v[152:155], v[198:201], v[26:29]
	v_mfma_f32_16x16x32_bf16 v[18:21], v[144:147], v[206:209], v[18:21]
	v_mfma_f32_16x16x32_bf16 v[10:13], v[152:155], v[206:209], v[10:13]
	v_mfma_f32_16x16x32_bf16 v[62:65], v[148:151], v[186:189], v[62:65]
	v_mfma_f32_16x16x32_bf16 v[58:61], v[156:159], v[186:189], v[58:61]
	v_mfma_f32_16x16x32_bf16 v[50:53], v[148:151], v[194:197], v[50:53]
	v_mfma_f32_16x16x32_bf16 v[42:45], v[156:159], v[194:197], v[42:45]
	v_mfma_f32_16x16x32_bf16 v[30:33], v[148:151], v[202:205], v[30:33]
	v_mfma_f32_16x16x32_bf16 v[26:29], v[156:159], v[202:205], v[26:29]
	v_mfma_f32_16x16x32_bf16 v[18:21], v[148:151], v[210:213], v[18:21]
	v_mfma_f32_16x16x32_bf16 v[10:13], v[156:159], v[210:213], v[10:13]
	v_mfma_f32_16x16x32_bf16 v[54:57], v[160:163], v[182:185], v[54:57]
	v_mfma_f32_16x16x32_bf16 v[46:49], v[174:177], v[182:185], v[46:49]
	v_mfma_f32_16x16x32_bf16 v[38:41], v[160:163], v[190:193], v[38:41]
	v_mfma_f32_16x16x32_bf16 v[34:37], v[174:177], v[190:193], v[34:37]
	v_mfma_f32_16x16x32_bf16 v[22:25], v[160:163], v[198:201], v[22:25]
	v_mfma_f32_16x16x32_bf16 v[14:17], v[174:177], v[198:201], v[14:17]
	v_mfma_f32_16x16x32_bf16 v[6:9], v[160:163], v[206:209], v[6:9]
	v_mfma_f32_16x16x32_bf16 v[2:5], v[174:177], v[206:209], v[2:5]
	v_mfma_f32_16x16x32_bf16 v[54:57], v[164:167], v[186:189], v[54:57]
	v_mfma_f32_16x16x32_bf16 v[46:49], v[178:181], v[186:189], v[46:49]
	v_mfma_f32_16x16x32_bf16 v[38:41], v[164:167], v[194:197], v[38:41]
	v_mfma_f32_16x16x32_bf16 v[34:37], v[178:181], v[194:197], v[34:37]
	v_mfma_f32_16x16x32_bf16 v[22:25], v[164:167], v[202:205], v[22:25]
	v_mfma_f32_16x16x32_bf16 v[14:17], v[178:181], v[202:205], v[14:17]
	v_mfma_f32_16x16x32_bf16 v[6:9], v[164:167], v[210:213], v[6:9]
	v_mfma_f32_16x16x32_bf16 v[2:5], v[178:181], v[210:213], v[2:5]
	s_setprio 2
	s_barrier
	s_add_i32 s31, 0, 0x18000
	s_add_i32 s68, 0, 0x1c000
	v_add_u32_e32 v156, s31, v168
	v_add_u32_e32 v173, s68, v168
	ds_read_b128 v[144:147], v156
	ds_read_b128 v[148:151], v156 offset:1024
	ds_read_b128 v[152:155], v156 offset:2048
	ds_read_b128 v[156:159], v156 offset:3072
	ds_read_b128 v[160:163], v173
	ds_read_b128 v[164:167], v173 offset:1024
	ds_read_b128 v[174:177], v173 offset:2048
	ds_read_b128 v[178:181], v173 offset:3072
	s_add_u32 s28, s28, 0x160000
	s_addc_u32 s29, s29, 0
	s_mov_b32 m0, s36
	v_lshl_add_u64 v[222:223], s[28:29], 0, v[130:131]
	ds_read_b128 v[182:185], v172 offset:32768
	ds_read_b128 v[186:189], v172 offset:33792
	ds_read_b128 v[190:193], v172 offset:34816
	ds_read_b128 v[194:197], v172 offset:35840
	ds_read_b128 v[198:201], v172 offset:36864
	ds_read_b128 v[202:205], v172 offset:37888
	ds_read_b128 v[206:209], v172 offset:38912
	ds_read_b128 v[210:213], v172 offset:39936
	global_load_lds_dwordx4 v[222:223], off
	v_lshl_add_u64 v[222:223], s[28:29], 0, v[134:135]
	s_mov_b32 m0, s37
	s_nop 0
	global_load_lds_dwordx4 v[222:223], off
	s_waitcnt vmcnt(8)
	s_waitcnt lgkmcnt(0)
	s_barrier
	s_setprio 1
	s_waitcnt lgkmcnt(0)
	v_mfma_f32_16x16x32_bf16 v[126:129], v[144:147], v[182:185], v[126:129]
	v_mfma_f32_16x16x32_bf16 v[122:125], v[152:155], v[182:185], v[122:125]
	v_mfma_f32_16x16x32_bf16 v[118:121], v[144:147], v[190:193], v[118:121]
	v_mfma_f32_16x16x32_bf16 v[110:113], v[152:155], v[190:193], v[110:113]
	v_mfma_f32_16x16x32_bf16 v[94:97], v[144:147], v[198:201], v[94:97]
	v_mfma_f32_16x16x32_bf16 v[90:93], v[152:155], v[198:201], v[90:93]
	v_mfma_f32_16x16x32_bf16 v[82:85], v[144:147], v[206:209], v[82:85]
	v_mfma_f32_16x16x32_bf16 v[74:77], v[152:155], v[206:209], v[74:77]
	v_mfma_f32_16x16x32_bf16 v[126:129], v[148:151], v[186:189], v[126:129]
	v_mfma_f32_16x16x32_bf16 v[122:125], v[156:159], v[186:189], v[122:125]
	v_mfma_f32_16x16x32_bf16 v[118:121], v[148:151], v[194:197], v[118:121]
	v_mfma_f32_16x16x32_bf16 v[110:113], v[156:159], v[194:197], v[110:113]
	v_mfma_f32_16x16x32_bf16 v[94:97], v[148:151], v[202:205], v[94:97]
	v_mfma_f32_16x16x32_bf16 v[90:93], v[156:159], v[202:205], v[90:93]
	v_mfma_f32_16x16x32_bf16 v[82:85], v[148:151], v[210:213], v[82:85]
	v_mfma_f32_16x16x32_bf16 v[74:77], v[156:159], v[210:213], v[74:77]
	v_mfma_f32_16x16x32_bf16 v[114:117], v[160:163], v[182:185], v[114:117]
	v_mfma_f32_16x16x32_bf16 v[106:109], v[174:177], v[182:185], v[106:109]
	v_mfma_f32_16x16x32_bf16 v[102:105], v[160:163], v[190:193], v[102:105]
	v_mfma_f32_16x16x32_bf16 v[98:101], v[174:177], v[190:193], v[98:101]
	v_mfma_f32_16x16x32_bf16 v[86:89], v[160:163], v[198:201], v[86:89]
	v_mfma_f32_16x16x32_bf16 v[78:81], v[174:177], v[198:201], v[78:81]
	v_mfma_f32_16x16x32_bf16 v[70:73], v[160:163], v[206:209], v[70:73]
	v_mfma_f32_16x16x32_bf16 v[66:69], v[174:177], v[206:209], v[66:69]
	v_mfma_f32_16x16x32_bf16 v[114:117], v[164:167], v[186:189], v[114:117]
	v_mfma_f32_16x16x32_bf16 v[106:109], v[178:181], v[186:189], v[106:109]
	v_mfma_f32_16x16x32_bf16 v[102:105], v[164:167], v[194:197], v[102:105]
	v_mfma_f32_16x16x32_bf16 v[98:101], v[178:181], v[194:197], v[98:101]
	v_mfma_f32_16x16x32_bf16 v[86:89], v[164:167], v[202:205], v[86:89]
	v_mfma_f32_16x16x32_bf16 v[78:81], v[178:181], v[202:205], v[78:81]
	v_mfma_f32_16x16x32_bf16 v[70:73], v[164:167], v[210:213], v[70:73]
	v_mfma_f32_16x16x32_bf16 v[66:69], v[178:181], v[210:213], v[66:69]
	s_setprio 2
	s_barrier
	s_add_i32 s28, s31, s33
	v_lshl_add_u64 v[214:215], v[214:215], 0, s[12:13]
	s_mov_b32 m0, s28
	ds_read_b128 v[182:185], v172 offset:49152
	ds_read_b128 v[186:189], v172 offset:50176
	ds_read_b128 v[190:193], v172 offset:51200
	ds_read_b128 v[194:197], v172 offset:52224
	ds_read_b128 v[198:201], v172 offset:53248
	ds_read_b128 v[202:205], v172 offset:54272
	ds_read_b128 v[206:209], v172 offset:55296
	ds_read_b128 v[210:213], v172 offset:56320
	global_load_lds_dwordx4 v[214:215], off
	s_add_i32 m0, s28, 0x2000
	s_add_u32 s26, s26, 0x160080
	v_lshl_add_u64 v[214:215], v[216:217], 0, s[12:13]
	s_addc_u32 s27, s27, 0
	s_add_i32 s28, s68, s33
	global_load_lds_dwordx4 v[214:215], off
	v_lshl_add_u64 v[214:215], s[26:27], 0, v[132:133]
	s_mov_b32 m0, s28
	s_nop 0
	global_load_lds_dwordx4 v[214:215], off
	v_lshl_add_u64 v[214:215], s[26:27], 0, v[136:137]
	s_add_i32 m0, s28, 0x2000
	s_nop 0
	global_load_lds_dwordx4 v[214:215], off
	v_lshl_add_u64 v[214:215], v[218:219], 0, s[12:13]
	s_mov_b32 m0, s47
	s_nop 0
	global_load_lds_dwordx4 v[214:215], off
	v_lshl_add_u64 v[214:215], v[220:221], 0, s[12:13]
	s_mov_b32 m0, s48
	s_nop 0
	global_load_lds_dwordx4 v[214:215], off
	s_waitcnt vmcnt(8)
	s_waitcnt lgkmcnt(0)
	s_barrier
	s_setprio 1
	s_waitcnt lgkmcnt(0)
	v_mfma_f32_16x16x32_bf16 v[62:65], v[144:147], v[182:185], v[62:65]
	v_mfma_f32_16x16x32_bf16 v[58:61], v[152:155], v[182:185], v[58:61]
	v_mfma_f32_16x16x32_bf16 v[50:53], v[144:147], v[190:193], v[50:53]
	v_mfma_f32_16x16x32_bf16 v[42:45], v[152:155], v[190:193], v[42:45]
	v_mfma_f32_16x16x32_bf16 v[30:33], v[144:147], v[198:201], v[30:33]
	v_mfma_f32_16x16x32_bf16 v[26:29], v[152:155], v[198:201], v[26:29]
	v_mfma_f32_16x16x32_bf16 v[18:21], v[144:147], v[206:209], v[18:21]
	v_mfma_f32_16x16x32_bf16 v[10:13], v[152:155], v[206:209], v[10:13]
	v_mfma_f32_16x16x32_bf16 v[62:65], v[148:151], v[186:189], v[62:65]
	v_mfma_f32_16x16x32_bf16 v[58:61], v[156:159], v[186:189], v[58:61]
	v_mfma_f32_16x16x32_bf16 v[50:53], v[148:151], v[194:197], v[50:53]
	v_mfma_f32_16x16x32_bf16 v[42:45], v[156:159], v[194:197], v[42:45]
	v_mfma_f32_16x16x32_bf16 v[30:33], v[148:151], v[202:205], v[30:33]
	v_mfma_f32_16x16x32_bf16 v[26:29], v[156:159], v[202:205], v[26:29]
	v_mfma_f32_16x16x32_bf16 v[18:21], v[148:151], v[210:213], v[18:21]
	v_mfma_f32_16x16x32_bf16 v[10:13], v[156:159], v[210:213], v[10:13]
	v_mfma_f32_16x16x32_bf16 v[54:57], v[160:163], v[182:185], v[54:57]
	v_mfma_f32_16x16x32_bf16 v[46:49], v[174:177], v[182:185], v[46:49]
	v_mfma_f32_16x16x32_bf16 v[38:41], v[160:163], v[190:193], v[38:41]
	v_mfma_f32_16x16x32_bf16 v[34:37], v[174:177], v[190:193], v[34:37]
	v_mfma_f32_16x16x32_bf16 v[22:25], v[160:163], v[198:201], v[22:25]
	v_mfma_f32_16x16x32_bf16 v[14:17], v[174:177], v[198:201], v[14:17]
	v_mfma_f32_16x16x32_bf16 v[6:9], v[160:163], v[206:209], v[6:9]
	v_mfma_f32_16x16x32_bf16 v[2:5], v[174:177], v[206:209], v[2:5]
	v_mfma_f32_16x16x32_bf16 v[54:57], v[164:167], v[186:189], v[54:57]
	v_mfma_f32_16x16x32_bf16 v[46:49], v[178:181], v[186:189], v[46:49]
	v_mfma_f32_16x16x32_bf16 v[38:41], v[164:167], v[194:197], v[38:41]
	v_mfma_f32_16x16x32_bf16 v[34:37], v[178:181], v[194:197], v[34:37]
	v_mfma_f32_16x16x32_bf16 v[22:25], v[164:167], v[202:205], v[22:25]
	v_mfma_f32_16x16x32_bf16 v[14:17], v[178:181], v[202:205], v[14:17]
	v_mfma_f32_16x16x32_bf16 v[6:9], v[164:167], v[210:213], v[6:9]
	v_mfma_f32_16x16x32_bf16 v[2:5], v[178:181], v[210:213], v[2:5]
	s_setprio 2
	s_barrier
	s_add_u32 s24, s24, 0x100
	s_addc_u32 s25, s25, 0
	s_add_u32 s17, s17, 0x100
	s_addc_u32 s23, s23, 0
	s_cmp_ge_i32 s30, s67
	s_mov_b32 s26, s30
	s_cbranch_scc0 .LBB0_2683
